# instruction selection: every packed fp32 VALU op (v_pk_mul_f32 / v_pk_fma_f32, 1960 sites in the GEMM epilogues, finalize and mixers) split into two scalar f32 ops, bit-identical; on top of v17
# baseline (speedup 1.0000x reference)
;     __device__ __forceinline__ void operator()(const f32x4 (&acc)[2][2][4][2], const Unit& u, int wr, int wc, int fr, int fq, const float (&pre)[8]) const {
;         const int row0 = u.pm * 256 + wr * 64 + fr, col0 = u.pn * 256 + wc * 32 + 8 * fq;
;         const float sc = (u.pn < nsc) ? scale : 1.f;
;         float cs[2][2][4], cq[2][2][4];
; #pragma unroll
;         for (int a = 0; a < 2; ++a)
; #pragma unroll
;             for (int b = 0; b < 2; ++b)
; #pragma unroll
;                 for (int e = 0; e < 4; ++e) { cs[a][b][e] = 0.f; cq[a][b][e] = 0.f; }
;         f32x4 csc[2][2];
;         if (RS == 2) {
; #pragma unroll
;             for (int bj = 0; bj < 2; ++bj) { csc[bj][0] = *(const GAS f32x4*)(rs + col0 + bj * 128); csc[bj][1] = *(const GAS f32x4*)(rs + col0 + bj * 128 + 4); }
;         }
; #pragma unroll
;         for (int ai = 0; ai < 2; ++ai)
; #pragma unroll
;             for (int m = 0; m < 4; ++m) {
;                 const int row = row0 + ai * 128 + m * 16; bf16_t* rowp = O + (size_t)row * ldc + col0; float rs = 0.f;
;                 float rsc = 1.f; if (RS == 1) rsc = pre[ai * 4 + m];
; #pragma unroll
;                 for (int bj = 0; bj < 2; ++bj) {
;                     f32x4 v0 = acc[ai][bj][m][0], v1 = acc[ai][bj][m][1];
;                     if (RS == 1) { v0 = v0 * rsc; v1 = v1 * rsc; }
;                     if (RS == 2) { v0 = v0 * csc[bj][0]; v1 = v1 * csc[bj][1]; }
;                     if (ACT == 1) { const f32x2 a = gelu_pk((f32x2){v0[0], v0[1]}), b = gelu_pk((f32x2){v0[2], v0[3]}), c = gelu_pk((f32x2){v1[0], v1[1]}), d = gelu_pk((f32x2){v1[2], v1[3]});
;                         v0 = (f32x4){a.x, a.y, b.x, b.y}; v1 = (f32x4){c.x, c.y, d.x, d.y}; }
;                     v0 = v0 * sc; v1 = v1 * sc;
;                     if (STAT == 1) rs += (v0[0] * v0[0] + v0[1] * v0[1]) + (v0[2] * v0[2] + v0[3] * v0[3]) + (v1[0] * v1[0] + v1[1] * v1[1]) + (v1[2] * v1[2] + v1[3] * v1[3]);
;                     if (STAT == 2) {
; #pragma unroll
;                         for (int e = 0; e < 4; ++e) { cs[bj][0][e] += v0[e]; cq[bj][0][e] += v0[e] * v0[e]; cs[bj][1][e] += v1[e]; cq[bj][1][e] += v1[e] * v1[e]; } }
;                     u32x4 w; w.x = cvt_pk_bf16(v0[0], v0[1]); w.y = cvt_pk_bf16(v0[2], v0[3]); w.z = cvt_pk_bf16(v1[0], v1[1]); w.w = cvt_pk_bf16(v1[2], v1[3]);
;                     *(GAS u32x4*)(rowp + bj * 128) = w; }
.LBB0_69:
	v_lshl_add_u32 v172, s88, 8, v33
	v_lshl_or_b32 v170, s3, 8, v141
	s_cmp_lt_i32 s3, 4
	v_ashrrev_i32_e32 v173, 31, v172
	s_cselect_b64 vcc, -1, 0
	v_ashrrev_i32_e32 v171, 31, v170
	v_lshlrev_b64 v[174:175], 12, v[172:173]
	v_cndmask_b32_e32 v160, 1.0, v190, vcc
	v_lshl_add_u64 v[174:175], s[82:83], 0, v[174:175]
	v_lshlrev_b64 v[176:177], 1, v[170:171]
	v_mul_f32 v128, v158, v128
	v_mul_f32 v129, v158, v129
	v_mul_f32 v126, v158, v126
	v_mul_f32 v127, v158, v127
	v_mul_f32 v124, v158, v124
	v_mul_f32 v125, v158, v125
	v_mul_f32 v122, v158, v122
	v_mul_f32 v123, v158, v123
	v_lshl_add_u64 v[170:171], v[174:175], 0, v[176:177]
	v_mul_f32 v128, v160, v128
	v_mul_f32 v129, v160, v129
	v_mul_f32 v126, v160, v126
	v_mul_f32 v127, v160, v127
	v_mul_f32 v174, v160, v124
	v_mul_f32 v175, v160, v125
	v_mul_f32 v124, v160, v122
	v_mul_f32 v125, v160, v123
	v_cvt_pk_bf16_f32 v122, v126, v127
	v_cvt_pk_bf16_f32 v123, v128, v129
	v_mul_f32 v118, v158, v118
	v_mul_f32 v119, v158, v119
	v_mul_f32 v116, v158, v116
	v_mul_f32 v117, v158, v117
	v_mul_f32 v114, v158, v114
	v_mul_f32 v115, v158, v115
	v_cvt_pk_bf16_f32 v124, v124, v125
	v_cvt_pk_bf16_f32 v125, v174, v175
	global_store_dwordx4 v[170:171], v[122:125], off
	v_mul_f32 v120, v158, v120
	v_mul_f32 v121, v158, v121
	v_mul_f32 v118, v160, v118
	v_mul_f32 v119, v160, v119
	v_mul_f32 v122, v160, v116
	v_mul_f32 v123, v160, v117
	v_mul_f32 v116, v160, v114
	v_mul_f32 v117, v160, v115
	v_cvt_pk_bf16_f32 v114, v118, v119
	v_mul_f32 v120, v160, v120
	v_mul_f32 v121, v160, v121
	v_cvt_pk_bf16_f32 v115, v120, v121
	v_cvt_pk_bf16_f32 v116, v116, v117
	v_cvt_pk_bf16_f32 v117, v122, v123
	global_store_dwordx4 v[170:171], v[114:117], off offset:256
	v_mul_f32 v112, v156, v112
	v_mul_f32 v113, v156, v113
	v_mul_f32 v110, v156, v110
	v_mul_f32 v111, v156, v111
	v_or_b32_e32 v114, 16, v172
	v_ashrrev_i32_e32 v115, 31, v114
	v_lshlrev_b64 v[114:115], 12, v[114:115]
	v_lshl_add_u64 v[114:115], s[82:83], 0, v[114:115]
	v_mul_f32 v108, v156, v108
	v_mul_f32 v109, v156, v109
	v_mul_f32 v106, v156, v106
	v_mul_f32 v107, v156, v107
	v_lshl_add_u64 v[114:115], v[114:115], 0, v[176:177]
	v_mul_f32 v112, v160, v112
	v_mul_f32 v113, v160, v113
	v_mul_f32 v110, v160, v110
	v_mul_f32 v111, v160, v111
	v_mul_f32 v116, v160, v108
	v_mul_f32 v117, v160, v109
	v_mul_f32 v108, v160, v106
	v_mul_f32 v109, v160, v107
	v_cvt_pk_bf16_f32 v106, v110, v111
	v_cvt_pk_bf16_f32 v107, v112, v113
	v_mul_f32 v102, v156, v102
	v_mul_f32 v103, v156, v103
	v_mul_f32 v100, v156, v100
	v_mul_f32 v101, v156, v101
	v_mul_f32 v98, v156, v98
	v_mul_f32 v99, v156, v99
	v_cvt_pk_bf16_f32 v108, v108, v109
	v_cvt_pk_bf16_f32 v109, v116, v117
	global_store_dwordx4 v[114:115], v[106:109], off
	v_mul_f32 v104, v156, v104
	v_mul_f32 v105, v156, v105
	v_mul_f32 v102, v160, v102
	v_mul_f32 v103, v160, v103
	v_mul_f32 v106, v160, v100
	v_mul_f32 v107, v160, v101
	v_mul_f32 v100, v160, v98
	v_mul_f32 v101, v160, v99
	v_cvt_pk_bf16_f32 v98, v102, v103
	v_mul_f32 v104, v160, v104
	v_mul_f32 v105, v160, v105
	v_cvt_pk_bf16_f32 v99, v104, v105
	v_cvt_pk_bf16_f32 v100, v100, v101
	v_cvt_pk_bf16_f32 v101, v106, v107
	global_store_dwordx4 v[114:115], v[98:101], off offset:256
	v_mul_f32 v96, v154, v96
	v_mul_f32 v97, v154, v97
	v_mul_f32 v94, v154, v94
	v_mul_f32 v95, v154, v95
	v_or_b32_e32 v98, 32, v172
	v_ashrrev_i32_e32 v99, 31, v98
	v_lshlrev_b64 v[98:99], 12, v[98:99]
	v_lshl_add_u64 v[98:99], s[82:83], 0, v[98:99]
	v_mul_f32 v92, v154, v92
	v_mul_f32 v93, v154, v93
	v_mul_f32 v90, v154, v90
	v_mul_f32 v91, v154, v91
	v_lshl_add_u64 v[98:99], v[98:99], 0, v[176:177]
	v_mul_f32 v96, v160, v96
	v_mul_f32 v97, v160, v97
	v_mul_f32 v94, v160, v94
	v_mul_f32 v95, v160, v95
	v_mul_f32 v100, v160, v92
	v_mul_f32 v101, v160, v93
	v_mul_f32 v92, v160, v90
	v_mul_f32 v93, v160, v91
	v_cvt_pk_bf16_f32 v90, v94, v95
	v_cvt_pk_bf16_f32 v91, v96, v97
	v_mul_f32 v86, v154, v86
	v_mul_f32 v87, v154, v87
	v_mul_f32 v84, v154, v84
	v_mul_f32 v85, v154, v85
	v_mul_f32 v82, v154, v82
	v_mul_f32 v83, v154, v83
	v_cvt_pk_bf16_f32 v92, v92, v93
	v_cvt_pk_bf16_f32 v93, v100, v101
	global_store_dwordx4 v[98:99], v[90:93], off
	v_mul_f32 v88, v154, v88
	v_mul_f32 v89, v154, v89
	v_mul_f32 v86, v160, v86
	v_mul_f32 v87, v160, v87
	v_mul_f32 v90, v160, v84
	v_mul_f32 v91, v160, v85
	v_mul_f32 v84, v160, v82
	v_mul_f32 v85, v160, v83
	v_cvt_pk_bf16_f32 v82, v86, v87
	v_mul_f32 v88, v160, v88
	v_mul_f32 v89, v160, v89
	v_cvt_pk_bf16_f32 v83, v88, v89
	v_cvt_pk_bf16_f32 v84, v84, v85
	v_cvt_pk_bf16_f32 v85, v90, v91
	global_store_dwordx4 v[98:99], v[82:85], off offset:256
	v_mul_f32 v80, v152, v80
	v_mul_f32 v81, v152, v81
	v_mul_f32 v78, v152, v78
	v_mul_f32 v79, v152, v79
	v_or_b32_e32 v82, 48, v172
	v_ashrrev_i32_e32 v83, 31, v82
	v_lshlrev_b64 v[82:83], 12, v[82:83]
	v_lshl_add_u64 v[82:83], s[82:83], 0, v[82:83]
	v_mul_f32 v76, v152, v76
	v_mul_f32 v77, v152, v77
	v_mul_f32 v74, v152, v74
	v_mul_f32 v75, v152, v75
	v_lshl_add_u64 v[82:83], v[82:83], 0, v[176:177]
	v_mul_f32 v80, v160, v80
	v_mul_f32 v81, v160, v81
	v_mul_f32 v78, v160, v78
	v_mul_f32 v79, v160, v79
	v_mul_f32 v84, v160, v76
	v_mul_f32 v85, v160, v77
	v_mul_f32 v76, v160, v74
	v_mul_f32 v77, v160, v75
	v_cvt_pk_bf16_f32 v74, v78, v79
	v_cvt_pk_bf16_f32 v75, v80, v81
	v_mul_f32 v68, v152, v68
	v_mul_f32 v69, v152, v69
	v_mul_f32 v66, v152, v66
	v_mul_f32 v67, v152, v67
	v_cvt_pk_bf16_f32 v76, v76, v77
	v_cvt_pk_bf16_f32 v77, v84, v85
	global_store_dwordx4 v[82:83], v[74:77], off
	v_mul_f32 v72, v152, v72
	v_mul_f32 v73, v152, v73
	v_mul_f32 v70, v152, v70
	v_mul_f32 v71, v152, v71
	v_mul_f32 v74, v160, v68
;     __device__ __forceinline__ void operator()(const f32x4 (&acc)[2][2][4][2], const Unit& u, int wr, int wc, int fr, int fq, const float (&pre)[8]) const {
;         const int row0 = u.pm * 256 + wr * 64 + fr, col0 = u.pn * 256 + wc * 32 + 8 * fq;
;         const float sc = (u.pn < nsc) ? scale : 1.f;
;         float cs[2][2][4], cq[2][2][4];
; #pragma unroll
;         for (int a = 0; a < 2; ++a)
; #pragma unroll
;             for (int b = 0; b < 2; ++b)
; #pragma unroll
;                 for (int e = 0; e < 4; ++e) { cs[a][b][e] = 0.f; cq[a][b][e] = 0.f; }
;         f32x4 csc[2][2];
;         if (RS == 2) {
; #pragma unroll
;             for (int bj = 0; bj < 2; ++bj) { csc[bj][0] = *(const GAS f32x4*)(rs + col0 + bj * 128); csc[bj][1] = *(const GAS f32x4*)(rs + col0 + bj * 128 + 4); }
;         }
; #pragma unroll
;         for (int ai = 0; ai < 2; ++ai)
; #pragma unroll
;             for (int m = 0; m < 4; ++m) {
;                 const int row = row0 + ai * 128 + m * 16; bf16_t* rowp = O + (size_t)row * ldc + col0; float rs = 0.f;
;                 float rsc = 1.f; if (RS == 1) rsc = pre[ai * 4 + m];
; #pragma unroll
;                 for (int bj = 0; bj < 2; ++bj) {
;                     f32x4 v0 = acc[ai][bj][m][0], v1 = acc[ai][bj][m][1];
;                     if (RS == 1) { v0 = v0 * rsc; v1 = v1 * rsc; }
;                     if (RS == 2) { v0 = v0 * csc[bj][0]; v1 = v1 * csc[bj][1]; }
;                     if (ACT == 1) { const f32x2 a = gelu_pk((f32x2){v0[0], v0[1]}), b = gelu_pk((f32x2){v0[2], v0[3]}), c = gelu_pk((f32x2){v1[0], v1[1]}), d = gelu_pk((f32x2){v1[2], v1[3]});
;                         v0 = (f32x4){a.x, a.y, b.x, b.y}; v1 = (f32x4){c.x, c.y, d.x, d.y}; }
;                     v0 = v0 * sc; v1 = v1 * sc;
;                     if (STAT == 1) rs += (v0[0] * v0[0] + v0[1] * v0[1]) + (v0[2] * v0[2] + v0[3] * v0[3]) + (v1[0] * v1[0] + v1[1] * v1[1]) + (v1[2] * v1[2] + v1[3] * v1[3]);
;                     if (STAT == 2) {
; #pragma unroll
;                         for (int e = 0; e < 4; ++e) { cs[bj][0][e] += v0[e]; cq[bj][0][e] += v0[e] * v0[e]; cs[bj][1][e] += v1[e]; cq[bj][1][e] += v1[e] * v1[e]; } }
;                     u32x4 w; w.x = cvt_pk_bf16(v0[0], v0[1]); w.y = cvt_pk_bf16(v0[2], v0[3]); w.z = cvt_pk_bf16(v1[0], v1[1]); w.w = cvt_pk_bf16(v1[2], v1[3]);
;                     *(GAS u32x4*)(rowp + bj * 128) = w; }
	v_mul_f32 v75, v160, v69
	v_mul_f32 v68, v160, v66
	v_mul_f32 v69, v160, v67
	v_mul_f32 v62, v146, v62
	v_mul_f32 v63, v146, v63
	v_mul_f32 v72, v160, v72
	v_mul_f32 v73, v160, v73
	v_mul_f32 v70, v160, v70
	v_mul_f32 v71, v160, v71
	v_cvt_pk_bf16_f32 v66, v70, v71
	v_cvt_pk_bf16_f32 v67, v72, v73
	v_cvt_pk_bf16_f32 v68, v68, v69
	v_cvt_pk_bf16_f32 v69, v74, v75
	v_mul_f32 v60, v146, v60
	v_mul_f32 v61, v146, v61
	v_mul_f32 v58, v146, v58
	v_mul_f32 v59, v146, v59
	v_mul_f32 v62, v160, v62
	v_mul_f32 v63, v160, v63
	s_mov_b32 s3, 0x80000
	global_store_dwordx4 v[82:83], v[66:69], off offset:256
	v_mul_f32 v64, v146, v64
	v_mul_f32 v65, v146, v65
	v_mul_f32 v64, v160, v64
	v_mul_f32 v65, v160, v65
	v_mul_f32 v68, v160, v60
	v_mul_f32 v69, v160, v61
	v_mul_f32 v60, v160, v58
	v_mul_f32 v61, v160, v59
	v_cvt_pk_bf16_f32 v58, v62, v63
	v_add_co_u32_e32 v62, vcc, s3, v170
	v_cvt_pk_bf16_f32 v59, v64, v65
	v_mul_f32 v48, v146, v48
	v_mul_f32 v49, v146, v49
	s_nop 0
	v_addc_co_u32_e32 v63, vcc, 0, v171, vcc
	v_mul_f32 v46, v146, v46
	v_mul_f32 v47, v146, v47
	s_mov_b64 s[76:77], 0x80000
	v_cvt_pk_bf16_f32 v60, v60, v61
	v_cvt_pk_bf16_f32 v61, v68, v69
	global_store_dwordx4 v[62:63], v[58:61], off
	v_mul_f32 v56, v146, v56
	v_mul_f32 v57, v146, v57
	v_mul_f32 v54, v146, v54
	v_mul_f32 v55, v146, v55
	v_mul_f32 v58, v160, v48
	v_mul_f32 v59, v160, v49
	v_mul_f32 v48, v160, v46
	v_mul_f32 v49, v160, v47
	v_lshl_add_u64 v[66:67], v[170:171], 0, s[76:77]
	v_mul_f32 v56, v160, v56
	v_mul_f32 v57, v160, v57
	v_mul_f32 v54, v160, v54
	v_mul_f32 v55, v160, v55
	v_cvt_pk_bf16_f32 v46, v54, v55
	v_cvt_pk_bf16_f32 v47, v56, v57
	v_cvt_pk_bf16_f32 v48, v48, v49
	v_cvt_pk_bf16_f32 v49, v58, v59
	global_store_dwordx4 v[66:67], v[46:49], off offset:256
	v_mul_f32 v50, v142, v50
	v_mul_f32 v51, v142, v51
	v_mul_f32 v44, v142, v44
	v_mul_f32 v45, v142, v45
	v_mul_f32 v48, v142, v52
	v_mul_f32 v49, v142, v53
	v_mul_f32 v42, v142, v42
	v_mul_f32 v43, v142, v43
	v_mul_f32 v48, v160, v48
	v_mul_f32 v49, v160, v49
	s_mov_b32 s3, 0x90000
	v_mul_f32 v50, v160, v50
	v_mul_f32 v51, v160, v51
	v_mul_f32 v52, v160, v44
	v_mul_f32 v53, v160, v45
	v_mul_f32 v44, v160, v42
	v_mul_f32 v45, v160, v43
	v_cvt_pk_bf16_f32 v42, v50, v51
	v_cvt_pk_bf16_f32 v43, v48, v49
	v_add_co_u32_e32 v48, vcc, s3, v170
	v_mul_f32 v30, v142, v30
	v_mul_f32 v31, v142, v31
	s_nop 0
	v_addc_co_u32_e32 v49, vcc, 0, v171, vcc
	v_mul_f32 v28, v142, v28
	v_mul_f32 v29, v142, v29
	s_mov_b64 s[76:77], 0x90000
	v_cvt_pk_bf16_f32 v44, v44, v45
	v_cvt_pk_bf16_f32 v45, v52, v53
	global_store_dwordx4 v[48:49], v[42:45], off
	v_mul_f32 v40, v142, v40
	v_mul_f32 v41, v142, v41
	v_mul_f32 v38, v142, v38
	v_mul_f32 v39, v142, v39
	v_mul_f32 v42, v160, v30
	v_mul_f32 v43, v160, v31
	v_mul_f32 v30, v160, v28
	v_mul_f32 v31, v160, v29
	v_lshl_add_u64 v[46:47], v[170:171], 0, s[76:77]
	v_mul_f32 v40, v160, v40
	v_mul_f32 v41, v160, v41
	v_mul_f32 v38, v160, v38
	v_mul_f32 v39, v160, v39
	v_cvt_pk_bf16_f32 v28, v38, v39
	v_cvt_pk_bf16_f32 v29, v40, v41
	v_cvt_pk_bf16_f32 v30, v30, v31
	v_cvt_pk_bf16_f32 v31, v42, v43
	global_store_dwordx4 v[46:47], v[28:31], off offset:256
	v_mul_f32 v34, v140, v34
	v_mul_f32 v35, v140, v35
	v_mul_f32 v26, v140, v26
	v_mul_f32 v27, v140, v27
	v_mul_f32 v30, v140, v36
	v_mul_f32 v31, v140, v37
	v_mul_f32 v24, v140, v24
	v_mul_f32 v25, v140, v25
	v_mul_f32 v30, v160, v30
	v_mul_f32 v31, v160, v31
	s_mov_b32 s3, 0xa0000
	v_mul_f32 v34, v160, v34
	v_mul_f32 v35, v160, v35
	v_mul_f32 v36, v160, v26
	v_mul_f32 v37, v160, v27
	v_mul_f32 v26, v160, v24
	v_mul_f32 v27, v160, v25
	v_cvt_pk_bf16_f32 v24, v34, v35
	v_cvt_pk_bf16_f32 v25, v30, v31
	v_add_co_u32_e32 v30, vcc, s3, v170
	v_mul_f32 v14, v140, v14
	v_mul_f32 v15, v140, v15
	s_nop 0
	v_addc_co_u32_e32 v31, vcc, 0, v171, vcc
	v_mul_f32 v12, v140, v12
	v_mul_f32 v13, v140, v13
	s_mov_b64 s[76:77], 0xa0000
	v_cvt_pk_bf16_f32 v26, v26, v27
	v_cvt_pk_bf16_f32 v27, v36, v37
	global_store_dwordx4 v[30:31], v[24:27], off
	v_mul_f32 v22, v140, v22
	v_mul_f32 v23, v140, v23
	v_mul_f32 v20, v140, v20
	v_mul_f32 v21, v140, v21
	v_mul_f32 v24, v160, v14
	v_mul_f32 v25, v160, v15
	v_mul_f32 v14, v160, v12
	v_mul_f32 v15, v160, v13
	v_lshl_add_u64 v[28:29], v[170:171], 0, s[76:77]
	v_mul_f32 v22, v160, v22
	v_mul_f32 v23, v160, v23
	v_mul_f32 v20, v160, v20
	v_mul_f32 v21, v160, v21
	v_cvt_pk_bf16_f32 v12, v20, v21
	v_cvt_pk_bf16_f32 v13, v22, v23
	v_cvt_pk_bf16_f32 v14, v14, v15
	v_cvt_pk_bf16_f32 v15, v24, v25
	global_store_dwordx4 v[28:29], v[12:15], off offset:256
	v_mul_f32 v16, v138, v16
	v_mul_f32 v17, v138, v17
	v_mul_f32 v10, v138, v10
	v_mul_f32 v11, v138, v11
	v_mul_f32 v14, v138, v18
	v_mul_f32 v15, v138, v19
	v_mul_f32 v8, v138, v8
	v_mul_f32 v9, v138, v9
	v_mul_f32 v14, v160, v14
	v_mul_f32 v15, v160, v15
	s_mov_b32 s3, 0xb0000
	v_mul_f32 v16, v160, v16
	v_mul_f32 v17, v160, v17
	v_mul_f32 v18, v160, v10
	v_mul_f32 v19, v160, v11
	v_mul_f32 v10, v160, v8
	v_mul_f32 v11, v160, v9
	v_cvt_pk_bf16_f32 v8, v16, v17
	v_cvt_pk_bf16_f32 v9, v14, v15
	v_add_co_u32_e32 v14, vcc, s3, v170
	s_mov_b64 s[76:77], 0xb0000
	s_nop 0
	v_addc_co_u32_e32 v15, vcc, 0, v171, vcc
	v_mul_f32 v2, v138, v2
	v_mul_f32 v3, v138, v3
	v_mul_f32 v0, v138, v0
	v_mul_f32 v1, v138, v1
	v_lshl_add_u64 v[12:13], v[170:171], 0, s[76:77]
	v_cvt_pk_bf16_f32 v10, v10, v11
	v_cvt_pk_bf16_f32 v11, v18, v19
	global_store_dwordx4 v[14:15], v[8:11], off
	v_mul_f32 v6, v138, v6
	v_mul_f32 v7, v138, v7
	v_mul_f32 v4, v138, v4
	v_mul_f32 v5, v138, v5
	v_mul_f32 v8, v160, v2
	v_mul_f32 v9, v160, v3
	v_mul_f32 v2, v160, v0
	v_mul_f32 v3, v160, v1
	s_andn2_b64 vcc, exec, s[86:87]
	s_mov_b64 s[86:87], -1
	v_mul_f32 v6, v160, v6
	v_mul_f32 v7, v160, v7
	v_mul_f32 v4, v160, v4
	v_mul_f32 v5, v160, v5
	v_cvt_pk_bf16_f32 v0, v4, v5
	v_cvt_pk_bf16_f32 v1, v6, v7
	v_cvt_pk_bf16_f32 v2, v2, v3
	v_cvt_pk_bf16_f32 v3, v8, v9
	global_store_dwordx4 v[12:13], v[0:3], off offset:256
	s_cbranch_vccnz .LBB0_57
	s_lshl_b32 s76, s46, 8
	s_ashr_i32 s77, s76, 31
	v_lshl_add_u64 v[0:1], s[76:77], 2, v[144:145]
	global_load_dword v158, v[0:1], off
	global_load_dword v156, v[0:1], off offset:64
	global_load_dword v154, v[0:1], off offset:128
	global_load_dword v152, v[0:1], off offset:192
	global_load_dword v146, v[0:1], off offset:512
	global_load_dword v142, v[0:1], off offset:576
	global_load_dword v140, v[0:1], off offset:640
	global_load_dword v138, v[0:1], off offset:704
	v_readlane_b32 s72, v254, 49
	v_readlane_b32 s73, v254, 50
	s_andn2_b64 vcc, exec, s[72:73]
	s_cbranch_vccnz .LBB0_56
	s_barrier
	s_branch .LBB0_56

; __device__ __forceinline__ unsigned cvt_pk_bf16(float lo, float hi) { unsigned r; asm volatile("v_cvt_pk_bf16_f32 %0, %1, %2" : "=v"(r) : "v"(lo), "v"(hi)); return r; }
; #define GAS __attribute__((address_space(1)))
;     __device__ __forceinline__ void operator()(const f32x4 (&acc)[2][2][4][2], const Unit& u, int wr, int wc, int fr, int fq, const float (&pre)[8]) const {
;     ...
;         if (RS == 2) {
; #pragma unroll
;             for (int bj = 0; bj < 2; ++bj) { csc[bj][0] = *(const GAS f32x4*)(rs + col0 + bj * 128); csc[bj][1] = *(const GAS f32x4*)(rs + col0 + bj * 128 + 4); }
;         }
;     ...
;                     if (RS == 2) { v0 = v0 * csc[bj][0]; v1 = v1 * csc[bj][1]; }
;     ...
;                     u32x4 w; w.x = cvt_pk_bf16(v0[0], v0[1]); w.y = cvt_pk_bf16(v0[2], v0[3]); w.z = cvt_pk_bf16(v1[0], v1[1]); w.w = cvt_pk_bf16(v1[2], v1[3]);
;                     *(GAS u32x4*)(rowp + bj * 128) = w; }
.LBB0_94:
	v_lshl_or_b32 v160, s45, 8, v171
	v_ashrrev_i32_e32 v161, 31, v160
	v_lshl_add_u64 v[102:103], v[160:161], 2, s[66:67]
	global_load_dwordx4 v[106:109], v[102:103], off offset:16
	global_load_dwordx4 v[110:113], v[102:103], off
	global_load_dwordx4 v[98:101], v[102:103], off offset:528
	s_nop 0
	global_load_dwordx4 v[102:105], v[102:103], off offset:512
	v_lshl_add_u32 v158, s44, 8, v33
	v_ashrrev_i32_e32 v159, 31, v158
	v_readlane_b32 s5, v253, 2
	v_lshlrev_b64 v[160:161], 1, v[160:161]
	s_mov_b64 s[44:45], -1
	v_lshlrev_b64 v[174:175], s5, v[158:159]
	v_lshl_add_u64 v[174:175], v[174:175], 1, s[84:85]
	v_lshl_add_u64 v[174:175], v[174:175], 0, v[160:161]
	s_andn2_b64 vcc, exec, s[90:91]
	s_waitcnt vmcnt(0)
	v_mul_f32 v176, v140, v108
	v_mul_f32 v177, v141, v109
	v_mul_f32 v144, v144, v112
	v_mul_f32 v145, v145, v113
	v_mul_f32 v142, v142, v110
	v_mul_f32 v143, v143, v111
	v_mul_f32 v140, v138, v106
	v_mul_f32 v141, v139, v107
	v_cvt_pk_bf16_f32 v138, v142, v143
	v_cvt_pk_bf16_f32 v139, v144, v145
	v_mul_f32 v134, v134, v102
	v_mul_f32 v135, v135, v103
	v_cvt_pk_bf16_f32 v140, v140, v141
	v_cvt_pk_bf16_f32 v141, v176, v177
	global_store_dwordx4 v[174:175], v[138:141], off
	v_mul_f32 v136, v136, v104
	v_mul_f32 v137, v137, v105
	v_mul_f32 v128, v128, v112
	v_mul_f32 v129, v129, v113
	v_mul_f32 v138, v132, v100
	v_mul_f32 v139, v133, v101
	v_mul_f32 v132, v130, v98
	v_mul_f32 v133, v131, v99
	v_cvt_pk_bf16_f32 v130, v134, v135
	v_cvt_pk_bf16_f32 v131, v136, v137
	v_mul_f32 v126, v126, v110
	v_mul_f32 v127, v127, v111
	v_cvt_pk_bf16_f32 v132, v132, v133
	v_cvt_pk_bf16_f32 v133, v138, v139
	global_store_dwordx4 v[174:175], v[130:133], off offset:256
	v_mul_f32 v118, v118, v102
	v_mul_f32 v119, v119, v103
	v_mul_f32 v120, v120, v104
	v_mul_f32 v121, v121, v105
	v_or_b32_e32 v130, 16, v158
	v_ashrrev_i32_e32 v131, 31, v130
	v_lshlrev_b64 v[130:131], s5, v[130:131]
	v_lshl_add_u64 v[130:131], v[130:131], 1, s[84:85]
	v_lshl_add_u64 v[130:131], v[130:131], 0, v[160:161]
	v_mul_f32 v132, v124, v108
	v_mul_f32 v133, v125, v109
	v_mul_f32 v124, v122, v106
	v_mul_f32 v125, v123, v107
	v_cvt_pk_bf16_f32 v122, v126, v127
	v_cvt_pk_bf16_f32 v123, v128, v129
	v_mul_f32 v96, v96, v112
	v_mul_f32 v97, v97, v113
	v_cvt_pk_bf16_f32 v124, v124, v125
	v_cvt_pk_bf16_f32 v125, v132, v133
	global_store_dwordx4 v[130:131], v[122:125], off
	v_mul_f32 v94, v94, v110
	v_mul_f32 v95, v95, v111
	v_mul_f32 v86, v86, v102
	v_mul_f32 v87, v87, v103
	v_mul_f32 v122, v116, v100
	v_mul_f32 v123, v117, v101
	v_mul_f32 v116, v114, v98
	v_mul_f32 v117, v115, v99
	v_cvt_pk_bf16_f32 v114, v118, v119
	v_cvt_pk_bf16_f32 v115, v120, v121
	v_mul_f32 v88, v88, v104
	v_mul_f32 v89, v89, v105
	v_cvt_pk_bf16_f32 v116, v116, v117
	v_cvt_pk_bf16_f32 v117, v122, v123
	global_store_dwordx4 v[130:131], v[114:117], off offset:256
	v_mul_f32 v80, v80, v112
	v_mul_f32 v81, v81, v113
	v_mul_f32 v78, v78, v110
	v_mul_f32 v79, v79, v111
	v_or_b32_e32 v114, 32, v158
	v_ashrrev_i32_e32 v115, 31, v114
	v_lshlrev_b64 v[114:115], s5, v[114:115]
	v_lshl_add_u64 v[114:115], v[114:115], 1, s[84:85]
	v_lshl_add_u64 v[114:115], v[114:115], 0, v[160:161]
	v_mul_f32 v116, v92, v108
	v_mul_f32 v117, v93, v109
	v_mul_f32 v92, v90, v106
	v_mul_f32 v93, v91, v107
	v_cvt_pk_bf16_f32 v90, v94, v95
	v_cvt_pk_bf16_f32 v91, v96, v97
	v_mul_f32 v70, v70, v102
	v_mul_f32 v71, v71, v103
	v_cvt_pk_bf16_f32 v92, v92, v93
	v_cvt_pk_bf16_f32 v93, v116, v117
	global_store_dwordx4 v[114:115], v[90:93], off
	v_mul_f32 v72, v72, v104
	v_mul_f32 v73, v73, v105
	v_mul_f32 v64, v64, v112
	v_mul_f32 v65, v65, v113
	v_mul_f32 v90, v84, v100
	v_mul_f32 v91, v85, v101
	v_mul_f32 v84, v82, v98
	v_mul_f32 v85, v83, v99
	v_cvt_pk_bf16_f32 v82, v86, v87
	v_cvt_pk_bf16_f32 v83, v88, v89
	v_mul_f32 v62, v62, v110
	v_mul_f32 v63, v63, v111
	v_cvt_pk_bf16_f32 v84, v84, v85
	v_cvt_pk_bf16_f32 v85, v90, v91
	global_store_dwordx4 v[114:115], v[82:85], off offset:256
	v_mul_f32 v54, v54, v102
	v_mul_f32 v55, v55, v103
	v_mul_f32 v56, v56, v104
	v_mul_f32 v57, v57, v105
	v_or_b32_e32 v82, 48, v158
	v_ashrrev_i32_e32 v83, 31, v82
	v_lshlrev_b64 v[82:83], s5, v[82:83]
	v_lshl_add_u64 v[82:83], v[82:83], 1, s[84:85]
	v_lshl_add_u64 v[82:83], v[82:83], 0, v[160:161]
	v_mul_f32 v84, v76, v108
	v_mul_f32 v85, v77, v109
	v_mul_f32 v76, v74, v106
	v_mul_f32 v77, v75, v107
	v_cvt_pk_bf16_f32 v74, v78, v79
; __device__ __forceinline__ unsigned cvt_pk_bf16(float lo, float hi) { unsigned r; asm volatile("v_cvt_pk_bf16_f32 %0, %1, %2" : "=v"(r) : "v"(lo), "v"(hi)); return r; }
; #define GAS __attribute__((address_space(1)))
;     __device__ __forceinline__ void operator()(const f32x4 (&acc)[2][2][4][2], const Unit& u, int wr, int wc, int fr, int fq, const float (&pre)[8]) const {
;     ...
;         for (int ai = 0; ai < 2; ++ai)
; #pragma unroll
;             for (int m = 0; m < 4; ++m) {
;                 const int row = row0 + ai * 128 + m * 16; bf16_t* rowp = O + (size_t)row * ldc + col0; float rs = 0.f;
;                 float rsc = 1.f; if (RS == 1) rsc = pre[ai * 4 + m];
; #pragma unroll
;                 for (int bj = 0; bj < 2; ++bj) {
;                     f32x4 v0 = acc[ai][bj][m][0], v1 = acc[ai][bj][m][1];
;                     if (RS == 1) { v0 = v0 * rsc; v1 = v1 * rsc; }
;                     if (RS == 2) { v0 = v0 * csc[bj][0]; v1 = v1 * csc[bj][1]; }
;                     if (ACT == 1) { const f32x2 a = gelu_pk((f32x2){v0[0], v0[1]}), b = gelu_pk((f32x2){v0[2], v0[3]}), c = gelu_pk((f32x2){v1[0], v1[1]}), d = gelu_pk((f32x2){v1[2], v1[3]});
;                         v0 = (f32x4){a.x, a.y, b.x, b.y}; v1 = (f32x4){c.x, c.y, d.x, d.y}; }
;                     v0 = v0 * sc; v1 = v1 * sc;
;                     if (STAT == 1) rs += (v0[0] * v0[0] + v0[1] * v0[1]) + (v0[2] * v0[2] + v0[3] * v0[3]) + (v1[0] * v1[0] + v1[1] * v1[1]) + (v1[2] * v1[2] + v1[3] * v1[3]);
;                     if (STAT == 2) {
; #pragma unroll
;                         for (int e = 0; e < 4; ++e) { cs[bj][0][e] += v0[e]; cq[bj][0][e] += v0[e] * v0[e]; cs[bj][1][e] += v1[e]; cq[bj][1][e] += v1[e] * v1[e]; } }
;                     u32x4 w; w.x = cvt_pk_bf16(v0[0], v0[1]); w.y = cvt_pk_bf16(v0[2], v0[3]); w.z = cvt_pk_bf16(v1[0], v1[1]); w.w = cvt_pk_bf16(v1[2], v1[3]);
;                     *(GAS u32x4*)(rowp + bj * 128) = w; }
	v_cvt_pk_bf16_f32 v75, v80, v81
	v_mul_f32 v50, v50, v110
	v_mul_f32 v51, v51, v111
	v_cvt_pk_bf16_f32 v76, v76, v77
	v_cvt_pk_bf16_f32 v77, v84, v85
	global_store_dwordx4 v[82:83], v[74:77], off
	v_mul_f32 v38, v38, v102
	v_mul_f32 v39, v39, v103
	v_mul_f32 v40, v40, v104
	v_mul_f32 v41, v41, v105
	v_mul_f32 v74, v68, v100
	v_mul_f32 v75, v69, v101
	v_mul_f32 v68, v66, v98
	v_mul_f32 v69, v67, v99
	v_cvt_pk_bf16_f32 v66, v70, v71
	v_cvt_pk_bf16_f32 v67, v72, v73
	v_mul_f32 v34, v34, v110
	v_mul_f32 v35, v35, v111
	v_cvt_pk_bf16_f32 v68, v68, v69
	v_cvt_pk_bf16_f32 v69, v74, v75
	global_store_dwordx4 v[82:83], v[66:69], off offset:256
	v_mul_f32 v20, v20, v102
	v_mul_f32 v21, v21, v103
	v_mul_f32 v22, v22, v104
	v_mul_f32 v23, v23, v105
	v_add_u32_e32 v66, 0x80, v158
	v_ashrrev_i32_e32 v67, 31, v66
	v_lshlrev_b64 v[66:67], s5, v[66:67]
	v_lshl_add_u64 v[66:67], v[66:67], 1, s[84:85]
	v_lshl_add_u64 v[66:67], v[66:67], 0, v[160:161]
	v_mul_f32 v68, v60, v108
	v_mul_f32 v69, v61, v109
	v_mul_f32 v60, v58, v106
	v_mul_f32 v61, v59, v107
	v_cvt_pk_bf16_f32 v58, v62, v63
	v_cvt_pk_bf16_f32 v59, v64, v65
	v_mul_f32 v14, v14, v112
	v_mul_f32 v15, v15, v113
	v_cvt_pk_bf16_f32 v60, v60, v61
	v_cvt_pk_bf16_f32 v61, v68, v69
	global_store_dwordx4 v[66:67], v[58:61], off
	v_mul_f32 v12, v12, v110
	v_mul_f32 v13, v13, v111
	v_mul_f32 v6, v6, v104
	v_mul_f32 v7, v7, v105
	v_mul_f32 v58, v48, v100
	v_mul_f32 v59, v49, v101
	v_mul_f32 v48, v46, v98
	v_mul_f32 v49, v47, v99
	v_cvt_pk_bf16_f32 v46, v54, v55
	v_cvt_pk_bf16_f32 v47, v56, v57
	v_mul_f32 v4, v4, v102
	v_mul_f32 v5, v5, v103
	v_cvt_pk_bf16_f32 v48, v48, v49
	v_cvt_pk_bf16_f32 v49, v58, v59
	global_store_dwordx4 v[66:67], v[46:49], off offset:256
	s_nop 1
	v_add_u32_e32 v46, 0x90, v158
	v_ashrrev_i32_e32 v47, 31, v46
	v_lshlrev_b64 v[46:47], s5, v[46:47]
	v_lshl_add_u64 v[46:47], v[46:47], 1, s[84:85]
	v_lshl_add_u64 v[46:47], v[46:47], 0, v[160:161]
	v_mul_f32 v48, v52, v112
	v_mul_f32 v49, v53, v113
	v_mul_f32 v52, v44, v108
	v_mul_f32 v53, v45, v109
	v_mul_f32 v44, v42, v106
	v_mul_f32 v45, v43, v107
	v_cvt_pk_bf16_f32 v42, v50, v51
	v_cvt_pk_bf16_f32 v43, v48, v49
	s_nop 0
	v_cvt_pk_bf16_f32 v44, v44, v45
	v_cvt_pk_bf16_f32 v45, v52, v53
	global_store_dwordx4 v[46:47], v[42:45], off
	s_nop 1
	v_mul_f32 v42, v30, v100
	v_mul_f32 v43, v31, v101
	v_mul_f32 v30, v28, v98
	v_mul_f32 v31, v29, v99
	v_cvt_pk_bf16_f32 v28, v38, v39
	v_cvt_pk_bf16_f32 v29, v40, v41
	s_nop 0
	v_cvt_pk_bf16_f32 v30, v30, v31
	v_cvt_pk_bf16_f32 v31, v42, v43
	global_store_dwordx4 v[46:47], v[28:31], off offset:256
	s_nop 1
	v_add_u32_e32 v28, 0xa0, v158
	v_ashrrev_i32_e32 v29, 31, v28
	v_lshlrev_b64 v[28:29], s5, v[28:29]
	v_lshl_add_u64 v[28:29], v[28:29], 1, s[84:85]
	v_lshl_add_u64 v[28:29], v[28:29], 0, v[160:161]
	v_mul_f32 v30, v36, v112
	v_mul_f32 v31, v37, v113
	v_mul_f32 v36, v26, v108
	v_mul_f32 v37, v27, v109
	v_mul_f32 v26, v24, v106
	v_mul_f32 v27, v25, v107
	v_cvt_pk_bf16_f32 v24, v34, v35
	v_cvt_pk_bf16_f32 v25, v30, v31
	s_nop 0
	v_cvt_pk_bf16_f32 v26, v26, v27
	v_cvt_pk_bf16_f32 v27, v36, v37
	global_store_dwordx4 v[28:29], v[24:27], off
	s_nop 1
	v_mul_f32 v24, v18, v100
	v_mul_f32 v25, v19, v101
	v_mul_f32 v18, v16, v98
	v_mul_f32 v19, v17, v99
	v_cvt_pk_bf16_f32 v16, v20, v21
	v_cvt_pk_bf16_f32 v17, v22, v23
	s_nop 0
	v_cvt_pk_bf16_f32 v18, v18, v19
	v_cvt_pk_bf16_f32 v19, v24, v25
	global_store_dwordx4 v[28:29], v[16:19], off offset:256
	s_nop 1
	v_add_u32_e32 v16, 0xb0, v158
	v_ashrrev_i32_e32 v17, 31, v16
	v_lshlrev_b64 v[16:17], s5, v[16:17]
	v_lshl_add_u64 v[16:17], v[16:17], 1, s[84:85]
	v_lshl_add_u64 v[16:17], v[16:17], 0, v[160:161]
	v_mul_f32 v18, v10, v108
	v_mul_f32 v19, v11, v109
	v_mul_f32 v10, v8, v106
	v_mul_f32 v11, v9, v107
	v_cvt_pk_bf16_f32 v8, v12, v13
	v_cvt_pk_bf16_f32 v9, v14, v15
	s_nop 0
	v_cvt_pk_bf16_f32 v10, v10, v11
	v_cvt_pk_bf16_f32 v11, v18, v19
	global_store_dwordx4 v[16:17], v[8:11], off
	s_nop 1
	v_mul_f32 v8, v2, v100
	v_mul_f32 v9, v3, v101
	v_mul_f32 v2, v0, v98
	v_mul_f32 v3, v1, v99
	v_cvt_pk_bf16_f32 v0, v4, v5
	v_cvt_pk_bf16_f32 v1, v6, v7
	s_nop 0
	v_cvt_pk_bf16_f32 v2, v2, v3
	v_cvt_pk_bf16_f32 v3, v8, v9
	global_store_dwordx4 v[16:17], v[0:3], off offset:256
	s_cbranch_vccnz .LBB0_82
	v_readlane_b32 s44, v254, 43
	v_readlane_b32 s45, v254, 44
	s_andn2_b64 vcc, exec, s[44:45]
	s_cbranch_vccnz .LBB0_81
	s_barrier
	s_branch .LBB0_81

; __device__ __forceinline__ f32x2 gelu_pk(f32x2 v) {
;     const f32x2 av = __builtin_elementwise_abs(v), d = av * 0.2316418882f + 1.0f;
;     f32x2 t; t.x = __builtin_amdgcn_rcpf(d.x); t.y = __builtin_amdgcn_rcpf(d.y);
;     f32x2 q = t * 0.5307027145f + (-0.7265760135f); q = q * t + 0.7107068705f; q = q * t + (-0.142248368f); q = q * t + 0.127414796f; q = q * t;
;     const f32x2 s = (v * v) * (-0.72134752044f);
;     f32x2 e; e.x = __builtin_amdgcn_exp2f(s.x); e.y = __builtin_amdgcn_exp2f(s.y);
;     const f32x2 m = v * (q * e), r = v - m;
;     f32x2 o; o.x = v.x < 0.f ? m.x : r.x; o.y = v.y < 0.f ? m.y : r.y; return o;
; }
;     __device__ __forceinline__ void operator()(const f32x4 (&acc)[2][2][4][2], const Unit& u, int wr, int wc, int fr, int fq, const float (&pre)[8]) const {
;     ...
;         for (int ai = 0; ai < 2; ++ai)
; #pragma unroll
;             for (int m = 0; m < 4; ++m) {
;                 const int row = row0 + ai * 128 + m * 16; bf16_t* rowp = O + (size_t)row * ldc + col0; float rs = 0.f;
;                 float rsc = 1.f; if (RS == 1) rsc = pre[ai * 4 + m];
; #pragma unroll
;                 for (int bj = 0; bj < 2; ++bj) {
;                     f32x4 v0 = acc[ai][bj][m][0], v1 = acc[ai][bj][m][1];
;                     if (RS == 1) { v0 = v0 * rsc; v1 = v1 * rsc; }
;                     if (RS == 2) { v0 = v0 * csc[bj][0]; v1 = v1 * csc[bj][1]; }
;                     if (ACT == 1) { const f32x2 a = gelu_pk((f32x2){v0[0], v0[1]}), b = gelu_pk((f32x2){v0[2], v0[3]}), c = gelu_pk((f32x2){v1[0], v1[1]}), d = gelu_pk((f32x2){v1[2], v1[3]});
;                         v0 = (f32x4){a.x, a.y, b.x, b.y}; v1 = (f32x4){c.x, c.y, d.x, d.y}; }
;                     v0 = v0 * sc; v1 = v1 * sc;
.LBB0_121:
	v_lshl_add_u32 v160, s44, 8, v33
	v_lshl_or_b32 v150, s4, 8, v147
	v_ashrrev_i32_e32 v161, 31, v160
	v_ashrrev_i32_e32 v151, 31, v150
	v_lshlrev_b64 v[170:171], 11, v[160:161]
	v_lshl_add_u64 v[174:175], s[40:41], 0, v[170:171]
	v_lshlrev_b64 v[170:171], 1, v[150:151]
	v_mul_f32 v126, v172, v126
	v_mul_f32 v127, v172, v127
	v_lshl_add_u64 v[150:151], v[174:175], 0, v[170:171]
	v_mul_f32 v174, v172, v122
	v_mul_f32 v175, v172, v123
	v_and_b32_e32 v123, 0x7fffffff, v127
	v_and_b32_e32 v122, 0x7fffffff, v126
	v_fma_f32 v122, v122, s28, 1.0
	v_fma_f32 v123, v123, s28, 1.0
	s_mov_b32 s4, 0xbf3a00e3
	v_rcp_f32_e32 v176, v122
	v_rcp_f32_e32 v177, v123
	v_mov_b64_e32 v[122:123], s[4:5]
	v_mul_f32 v180, v126, v126
	v_mul_f32 v181, v127, v127
	v_mul_f32 v128, v172, v128
	v_mul_f32 v129, v172, v129
	v_fma_f32 v178, v176, s30, v122
	v_fma_f32 v179, v177, s30, v122
	v_mul_f32 v180, v180, s58
	v_mul_f32 v181, v181, s58
	v_fma_f32 v178, v176, v178, s52
	v_fma_f32 v179, v177, v179, s52
	v_exp_f32_e32 v180, v180
	v_exp_f32_e32 v181, v181
	v_fma_f32 v178, v176, v178, s54
	v_fma_f32 v179, v177, v179, s54
	v_cmp_gt_f32_e32 vcc, 0, v126
	v_fma_f32 v178, v176, v178, s56
	v_fma_f32 v179, v177, v179, s56
	v_mul_f32 v124, v172, v124
	v_mul_f32 v125, v172, v125
	v_mul_f32 v176, v176, v178
	v_mul_f32 v177, v177, v179
	v_mul_f32 v178, v128, v128
	v_mul_f32 v179, v129, v129
	v_mul_f32 v176, v180, v176
	v_mul_f32 v177, v181, v177
	s_mov_b64 s[4:5], 0x40000
	v_mul_f32 v180, v126, v176
	v_mul_f32 v181, v127, v177
	v_fma_f32 v176, -v126, v176, v126
	v_fma_f32 v177, -v127, v177, v127
	v_and_b32_e32 v126, 0x7fffffff, v128
	v_cndmask_b32_e32 v153, v176, v180, vcc
	v_cmp_gt_f32_e32 vcc, 0, v127
	v_and_b32_e32 v127, 0x7fffffff, v129
	v_fma_f32 v126, v126, s28, 1.0
	v_fma_f32 v127, v127, s28, 1.0
	v_cndmask_b32_e32 v155, v177, v181, vcc
	v_rcp_f32_e32 v126, v126
	v_rcp_f32_e32 v127, v127
	v_cmp_gt_f32_e32 vcc, 0, v128
	v_mul_f32 v78, v154, v78
	v_mul_f32 v79, v154, v79
	v_mul_f32 v80, v154, v80
	v_mul_f32 v81, v154, v81
	v_fma_f32 v176, v126, s30, v122
	v_fma_f32 v177, v127, s30, v122
	v_mul_f32 v74, v154, v74
	v_mul_f32 v75, v154, v75
	v_fma_f32 v176, v126, v176, s52
	v_fma_f32 v177, v127, v177, s52
	v_mul_f32 v76, v154, v76
	v_mul_f32 v77, v154, v77
	v_fma_f32 v176, v126, v176, s54
	v_fma_f32 v177, v127, v177, s54
	v_mul_f32 v70, v154, v70
	v_mul_f32 v71, v154, v71
	v_fma_f32 v176, v126, v176, s56
	v_fma_f32 v177, v127, v177, s56
	v_mul_f32 v72, v154, v72
	v_mul_f32 v73, v154, v73
	v_mul_f32 v126, v126, v176
	v_mul_f32 v127, v127, v177
	v_mul_f32 v176, v178, s58
	v_mul_f32 v177, v179, s58
	v_mul_f32 v66, v154, v66
	v_mul_f32 v67, v154, v67
	v_exp_f32_e32 v176, v176
	v_exp_f32_e32 v177, v177
	v_mul_f32 v68, v154, v68
	v_mul_f32 v69, v154, v69
	v_mul_f32 v62, v152, v62
	v_mul_f32 v63, v152, v63
	v_mul_f32 v64, v152, v64
	v_mul_f32 v65, v152, v65
	v_mul_f32 v126, v176, v126
	v_mul_f32 v127, v177, v127
	v_mul_f32 v58, v152, v58
	v_mul_f32 v59, v152, v59
	v_mul_f32 v176, v128, v126
	v_mul_f32 v177, v129, v127
	v_fma_f32 v126, -v128, v126, v128
	v_fma_f32 v127, -v129, v127, v129
	v_mul_f32 v60, v152, v60
	v_mul_f32 v61, v152, v61
	v_cndmask_b32_e32 v157, v126, v176, vcc
	v_cmp_gt_f32_e32 vcc, 0, v129
	v_and_b32_e32 v126, 0x7fffffff, v174
	v_mul_f32 v94, v156, v94
	v_mul_f32 v95, v156, v95
	v_cndmask_b32_e32 v159, v127, v177, vcc
	v_and_b32_e32 v127, 0x7fffffff, v175
	v_fma_f32 v126, v126, s28, 1.0
	v_fma_f32 v127, v127, s28, 1.0
	v_mul_f32 v176, v174, v174
	v_mul_f32 v177, v175, v175
	v_rcp_f32_e32 v126, v126
	v_rcp_f32_e32 v127, v127
	v_mul_f32 v176, v176, s58
	v_mul_f32 v177, v177, s58
	v_cmp_gt_f32_e32 vcc, 0, v174
	v_exp_f32_e32 v176, v176
	v_fma_f32 v128, v126, s30, v122
	v_fma_f32 v129, v127, s30, v122
	v_exp_f32_e32 v177, v177
	v_fma_f32 v128, v126, v128, s52
	v_fma_f32 v129, v127, v129, s52
	v_mul_f32 v110, v158, v110
	v_mul_f32 v111, v158, v111
	v_fma_f32 v128, v126, v128, s54
	v_fma_f32 v129, v127, v129, s54
	v_mul_f32 v112, v158, v112
	v_mul_f32 v113, v158, v113
	v_fma_f32 v128, v126, v128, s56
	v_fma_f32 v129, v127, v129, s56
	v_mul_f32 v106, v158, v106
	v_mul_f32 v107, v158, v107
	v_mul_f32 v126, v126, v128
	v_mul_f32 v127, v127, v129
	v_mul_f32 v128, v124, v124
	v_mul_f32 v129, v125, v125
	v_mul_f32 v126, v176, v126
	v_mul_f32 v127, v177, v127
	v_mul_f32 v128, v128, s58
	v_mul_f32 v129, v129, s58
	v_mul_f32 v176, v174, v126
	v_mul_f32 v177, v175, v127
	v_fma_f32 v126, -v174, v126, v174
	v_fma_f32 v127, -v175, v127, v175
	v_exp_f32_e32 v128, v128
	v_cndmask_b32_e32 v161, v126, v176, vcc
	v_cmp_gt_f32_e32 vcc, 0, v175
	v_and_b32_e32 v126, 0x7fffffff, v124
	v_exp_f32_e32 v129, v129
	v_cndmask_b32_e32 v173, v127, v177, vcc
	v_and_b32_e32 v127, 0x7fffffff, v125
	v_fma_f32 v126, v126, s28, 1.0
	v_fma_f32 v127, v127, s28, 1.0
	v_cmp_gt_f32_e32 vcc, 0, v124
	v_rcp_f32_e32 v126, v126
	v_rcp_f32_e32 v127, v127
	v_mul_f32 v118, v172, v118
	v_mul_f32 v119, v172, v119
	v_mul_f32 v120, v172, v120
	v_mul_f32 v121, v172, v121
	v_mul_f32 v114, v172, v114
	v_mul_f32 v115, v172, v115
	v_fma_f32 v174, v126, s30, v122
	v_fma_f32 v175, v127, s30, v122
	v_mul_f32 v116, v172, v116
	v_mul_f32 v117, v172, v117
	v_fma_f32 v174, v126, v174, s52
	v_fma_f32 v175, v127, v175, s52
	v_mul_f32 v108, v158, v108
	v_mul_f32 v109, v158, v109
	v_fma_f32 v174, v126, v174, s54
	v_fma_f32 v175, v127, v175, s54
	v_mul_f32 v102, v158, v102
	v_mul_f32 v103, v158, v103
	v_fma_f32 v174, v126, v174, s56
	v_fma_f32 v175, v127, v175, s56
	v_mul_f32 v104, v158, v104
	v_mul_f32 v105, v158, v105
	v_mul_f32 v126, v126, v174
	v_mul_f32 v127, v127, v175
	v_mul_f32 v98, v158, v98
	v_mul_f32 v99, v158, v99
; __device__ __forceinline__ f32x2 gelu_pk(f32x2 v) {
;     const f32x2 av = __builtin_elementwise_abs(v), d = av * 0.2316418882f + 1.0f;
;     f32x2 t; t.x = __builtin_amdgcn_rcpf(d.x); t.y = __builtin_amdgcn_rcpf(d.y);
;     f32x2 q = t * 0.5307027145f + (-0.7265760135f); q = q * t + 0.7107068705f; q = q * t + (-0.142248368f); q = q * t + 0.127414796f; q = q * t;
;     const f32x2 s = (v * v) * (-0.72134752044f);
;     f32x2 e; e.x = __builtin_amdgcn_exp2f(s.x); e.y = __builtin_amdgcn_exp2f(s.y);
;     const f32x2 m = v * (q * e), r = v - m;
;     f32x2 o; o.x = v.x < 0.f ? m.x : r.x; o.y = v.y < 0.f ? m.y : r.y; return o;
; }
;     __device__ __forceinline__ void operator()(const f32x4 (&acc)[2][2][4][2], const Unit& u, int wr, int wc, int fr, int fq, const float (&pre)[8]) const {
;     ...
;         for (int ai = 0; ai < 2; ++ai)
; #pragma unroll
;             for (int m = 0; m < 4; ++m) {
;                 const int row = row0 + ai * 128 + m * 16; bf16_t* rowp = O + (size_t)row * ldc + col0; float rs = 0.f;
;                 float rsc = 1.f; if (RS == 1) rsc = pre[ai * 4 + m];
; #pragma unroll
;                 for (int bj = 0; bj < 2; ++bj) {
;                     f32x4 v0 = acc[ai][bj][m][0], v1 = acc[ai][bj][m][1];
;                     if (RS == 1) { v0 = v0 * rsc; v1 = v1 * rsc; }
;                     if (RS == 2) { v0 = v0 * csc[bj][0]; v1 = v1 * csc[bj][1]; }
;                     if (ACT == 1) { const f32x2 a = gelu_pk((f32x2){v0[0], v0[1]}), b = gelu_pk((f32x2){v0[2], v0[3]}), c = gelu_pk((f32x2){v1[0], v1[1]}), d = gelu_pk((f32x2){v1[2], v1[3]});
;                         v0 = (f32x4){a.x, a.y, b.x, b.y}; v1 = (f32x4){c.x, c.y, d.x, d.y}; }
;                     v0 = v0 * sc; v1 = v1 * sc;
	v_mul_f32 v126, v128, v126
	v_mul_f32 v127, v129, v127
	v_mul_f32 v100, v158, v100
	v_mul_f32 v101, v158, v101
	v_mul_f32 v128, v124, v126
	v_mul_f32 v129, v125, v127
	v_fma_f32 v126, -v124, v126, v124
	v_fma_f32 v127, -v125, v127, v125
	v_cvt_pk_bf16_f32 v124, v153, v155
	v_mul_f32 v96, v156, v96
	v_mul_f32 v97, v156, v97
	v_cndmask_b32_e32 v128, v126, v128, vcc
	v_cmp_gt_f32_e32 vcc, 0, v125
	v_cvt_pk_bf16_f32 v125, v157, v159
	v_cvt_pk_bf16_f32 v126, v161, v173
	v_mul_f32 v90, v156, v90
	v_mul_f32 v91, v156, v91
	v_mul_f32 v92, v156, v92
	v_mul_f32 v93, v156, v93
	v_cndmask_b32_e32 v127, v127, v129, vcc
	v_cvt_pk_bf16_f32 v127, v128, v127
	global_store_dwordx4 v[150:151], v[124:127], off
	v_mul_f32 v128, v118, v118
	v_mul_f32 v129, v119, v119
	v_cmp_gt_f32_e32 vcc, 0, v118
	v_and_b32_e32 v125, 0x7fffffff, v119
	v_and_b32_e32 v124, 0x7fffffff, v118
	v_fma_f32 v124, v124, s28, 1.0
	v_fma_f32 v125, v125, s28, 1.0
	v_mul_f32 v128, v128, s58
	v_mul_f32 v129, v129, s58
	v_rcp_f32_e32 v124, v124
	v_rcp_f32_e32 v125, v125
	v_exp_f32_e32 v128, v128
	v_exp_f32_e32 v129, v129
	v_mul_f32 v86, v156, v86
	v_mul_f32 v87, v156, v87
	v_fma_f32 v126, v124, s30, v122
	v_fma_f32 v127, v125, s30, v122
	v_mul_f32 v88, v156, v88
	v_mul_f32 v89, v156, v89
	v_fma_f32 v126, v124, v126, s52
	v_fma_f32 v127, v125, v127, s52
	v_mul_f32 v82, v156, v82
	v_mul_f32 v83, v156, v83
	v_fma_f32 v126, v124, v126, s54
	v_fma_f32 v127, v125, v127, s54
	v_mul_f32 v84, v156, v84
	v_mul_f32 v85, v156, v85
	v_fma_f32 v126, v124, v126, s56
	v_fma_f32 v127, v125, v127, s56
	v_mul_f32 v54, v152, v54
	v_mul_f32 v55, v152, v55
	v_mul_f32 v124, v124, v126
	v_mul_f32 v125, v125, v127
	v_mul_f32 v126, v120, v120
	v_mul_f32 v127, v121, v121
	v_mul_f32 v124, v128, v124
	v_mul_f32 v125, v129, v125
	v_mul_f32 v56, v152, v56
	v_mul_f32 v57, v152, v57
	v_mul_f32 v128, v118, v124
	v_mul_f32 v129, v119, v125
	v_fma_f32 v124, -v118, v124, v118
	v_fma_f32 v125, -v119, v125, v119
	v_and_b32_e32 v118, 0x7fffffff, v120
	v_cndmask_b32_e32 v128, v124, v128, vcc
	v_cmp_gt_f32_e32 vcc, 0, v119
	v_and_b32_e32 v119, 0x7fffffff, v121
	v_fma_f32 v118, v118, s28, 1.0
	v_fma_f32 v119, v119, s28, 1.0
	v_cndmask_b32_e32 v129, v125, v129, vcc
	v_rcp_f32_e32 v118, v118
	v_rcp_f32_e32 v119, v119
	v_cmp_gt_f32_e32 vcc, 0, v120
	v_mul_f32 v50, v152, v50
	v_mul_f32 v51, v152, v51
	v_mul_f32 v52, v152, v52
	v_mul_f32 v53, v152, v53
	v_fma_f32 v124, v118, s30, v122
	v_fma_f32 v125, v119, s30, v122
	v_mul_f32 v46, v148, v46
	v_mul_f32 v47, v148, v47
	v_fma_f32 v124, v118, v124, s52
	v_fma_f32 v125, v119, v125, s52
	v_mul_f32 v48, v148, v48
	v_mul_f32 v49, v148, v49
	v_fma_f32 v124, v118, v124, s54
	v_fma_f32 v125, v119, v125, s54
	v_mul_f32 v42, v148, v42
	v_mul_f32 v43, v148, v43
	v_fma_f32 v124, v118, v124, s56
	v_fma_f32 v125, v119, v125, s56
	v_mul_f32 v44, v148, v44
	v_mul_f32 v45, v148, v45
	v_mul_f32 v118, v118, v124
	v_mul_f32 v119, v119, v125
	v_mul_f32 v124, v126, s58
	v_mul_f32 v125, v127, s58
	v_mul_f32 v38, v148, v38
	v_mul_f32 v39, v148, v39
	v_exp_f32_e32 v124, v124
	v_exp_f32_e32 v125, v125
	v_mul_f32 v40, v148, v40
	v_mul_f32 v41, v148, v41
	v_mul_f32 v34, v148, v34
	v_mul_f32 v35, v148, v35
	v_mul_f32 v36, v148, v36
	v_mul_f32 v37, v148, v37
	v_mul_f32 v118, v124, v118
	v_mul_f32 v119, v125, v119
	v_mul_f32 v28, v146, v28
	v_mul_f32 v29, v146, v29
	v_mul_f32 v124, v120, v118
	v_mul_f32 v125, v121, v119
	v_fma_f32 v118, -v120, v118, v120
	v_fma_f32 v119, -v121, v119, v121
	v_mul_f32 v30, v146, v30
	v_mul_f32 v31, v146, v31
	v_cndmask_b32_e32 v126, v118, v124, vcc
	v_cmp_gt_f32_e32 vcc, 0, v121
	v_and_b32_e32 v118, 0x7fffffff, v114
	v_mul_f32 v24, v146, v24
	v_mul_f32 v25, v146, v25
	v_cndmask_b32_e32 v127, v119, v125, vcc
	v_and_b32_e32 v119, 0x7fffffff, v115
	v_fma_f32 v118, v118, s28, 1.0
	v_fma_f32 v119, v119, s28, 1.0
	v_mul_f32 v124, v114, v114
	v_mul_f32 v125, v115, v115
	v_rcp_f32_e32 v118, v118
	v_rcp_f32_e32 v119, v119
	v_mul_f32 v124, v124, s58
	v_mul_f32 v125, v125, s58
	v_cmp_gt_f32_e32 vcc, 0, v114
	v_exp_f32_e32 v124, v124
	v_fma_f32 v120, v118, s30, v122
	v_fma_f32 v121, v119, s30, v122
	v_exp_f32_e32 v125, v125
	v_fma_f32 v120, v118, v120, s52
	v_fma_f32 v121, v119, v121, s52
	v_mul_f32 v26, v146, v26
	v_mul_f32 v27, v146, v27
	v_fma_f32 v120, v118, v120, s54
	v_fma_f32 v121, v119, v121, s54
	v_mul_f32 v20, v146, v20
	v_mul_f32 v21, v146, v21
	v_fma_f32 v120, v118, v120, s56
	v_fma_f32 v121, v119, v121, s56
	v_mul_f32 v22, v146, v22
	v_mul_f32 v23, v146, v23
	v_mul_f32 v118, v118, v120
	v_mul_f32 v119, v119, v121
	v_mul_f32 v120, v116, v116
	v_mul_f32 v121, v117, v117
	v_mul_f32 v118, v124, v118
	v_mul_f32 v119, v125, v119
	v_mul_f32 v16, v146, v16
	v_mul_f32 v17, v146, v17
	v_mul_f32 v124, v114, v118
	v_mul_f32 v125, v115, v119
	v_fma_f32 v118, -v114, v118, v114
	v_fma_f32 v119, -v115, v119, v115
	v_and_b32_e32 v114, 0x7fffffff, v116
	v_cndmask_b32_e32 v124, v118, v124, vcc
	v_cmp_gt_f32_e32 vcc, 0, v115
	v_and_b32_e32 v115, 0x7fffffff, v117
	v_fma_f32 v114, v114, s28, 1.0
	v_fma_f32 v115, v115, s28, 1.0
	v_cndmask_b32_e32 v125, v119, v125, vcc
	v_rcp_f32_e32 v114, v114
	v_rcp_f32_e32 v115, v115
	v_cmp_gt_f32_e32 vcc, 0, v116
	v_mul_f32 v18, v146, v18
	v_mul_f32 v19, v146, v19
	v_mul_f32 v12, v144, v12
	v_mul_f32 v13, v144, v13
	v_fma_f32 v118, v114, s30, v122
	v_fma_f32 v119, v115, s30, v122
	v_mul_f32 v14, v144, v14
	v_mul_f32 v15, v144, v15
	v_fma_f32 v118, v114, v118, s52
	v_fma_f32 v119, v115, v119, s52
	v_mul_f32 v8, v144, v8
	v_mul_f32 v9, v144, v9
	v_fma_f32 v118, v114, v118, s54
	v_fma_f32 v119, v115, v119, s54
	v_mul_f32 v10, v144, v10
	v_mul_f32 v11, v144, v11
; __device__ __forceinline__ f32x2 gelu_pk(f32x2 v) {
;     const f32x2 av = __builtin_elementwise_abs(v), d = av * 0.2316418882f + 1.0f;
;     f32x2 t; t.x = __builtin_amdgcn_rcpf(d.x); t.y = __builtin_amdgcn_rcpf(d.y);
;     f32x2 q = t * 0.5307027145f + (-0.7265760135f); q = q * t + 0.7107068705f; q = q * t + (-0.142248368f); q = q * t + 0.127414796f; q = q * t;
;     const f32x2 s = (v * v) * (-0.72134752044f);
;     f32x2 e; e.x = __builtin_amdgcn_exp2f(s.x); e.y = __builtin_amdgcn_exp2f(s.y);
;     const f32x2 m = v * (q * e), r = v - m;
;     f32x2 o; o.x = v.x < 0.f ? m.x : r.x; o.y = v.y < 0.f ? m.y : r.y; return o;
; }
;     __device__ __forceinline__ void operator()(const f32x4 (&acc)[2][2][4][2], const Unit& u, int wr, int wc, int fr, int fq, const float (&pre)[8]) const {
;     ...
;         for (int ai = 0; ai < 2; ++ai)
; #pragma unroll
;             for (int m = 0; m < 4; ++m) {
;                 const int row = row0 + ai * 128 + m * 16; bf16_t* rowp = O + (size_t)row * ldc + col0; float rs = 0.f;
;                 float rsc = 1.f; if (RS == 1) rsc = pre[ai * 4 + m];
; #pragma unroll
;                 for (int bj = 0; bj < 2; ++bj) {
;                     f32x4 v0 = acc[ai][bj][m][0], v1 = acc[ai][bj][m][1];
;                     if (RS == 1) { v0 = v0 * rsc; v1 = v1 * rsc; }
;                     if (RS == 2) { v0 = v0 * csc[bj][0]; v1 = v1 * csc[bj][1]; }
;                     if (ACT == 1) { const f32x2 a = gelu_pk((f32x2){v0[0], v0[1]}), b = gelu_pk((f32x2){v0[2], v0[3]}), c = gelu_pk((f32x2){v1[0], v1[1]}), d = gelu_pk((f32x2){v1[2], v1[3]});
;                         v0 = (f32x4){a.x, a.y, b.x, b.y}; v1 = (f32x4){c.x, c.y, d.x, d.y}; }
;                     v0 = v0 * sc; v1 = v1 * sc;
	v_fma_f32 v118, v114, v118, s56
	v_fma_f32 v119, v115, v119, s56
	v_mul_f32 v4, v144, v4
	v_mul_f32 v5, v144, v5
	v_mul_f32 v114, v114, v118
	v_mul_f32 v115, v115, v119
	v_mul_f32 v118, v120, s58
	v_mul_f32 v119, v121, s58
	v_mul_f32 v120, v110, v110
	v_mul_f32 v121, v111, v111
	v_exp_f32_e32 v118, v118
	v_exp_f32_e32 v119, v119
	v_mul_f32 v120, v120, s58
	v_mul_f32 v121, v121, s58
	v_mul_f32 v6, v144, v6
	v_mul_f32 v7, v144, v7
	v_exp_f32_e32 v120, v120
	v_mul_f32 v114, v118, v114
	v_mul_f32 v115, v119, v115
	v_exp_f32_e32 v121, v121
	v_mul_f32 v118, v116, v114
	v_mul_f32 v119, v117, v115
	v_fma_f32 v114, -v116, v114, v116
	v_fma_f32 v115, -v117, v115, v117
	v_mul_f32 v0, v144, v0
	v_mul_f32 v1, v144, v1
	v_cndmask_b32_e32 v118, v114, v118, vcc
	v_cmp_gt_f32_e32 vcc, 0, v117
	v_cvt_pk_bf16_f32 v114, v128, v129
	v_mul_f32 v2, v144, v2
	v_mul_f32 v3, v144, v3
	s_mov_b64 s[44:45], -1
	v_cndmask_b32_e32 v117, v115, v119, vcc
	v_cvt_pk_bf16_f32 v115, v126, v127
	v_cvt_pk_bf16_f32 v116, v124, v125
	v_cvt_pk_bf16_f32 v117, v118, v117
	global_store_dwordx4 v[150:151], v[114:117], off offset:256
	v_cmp_gt_f32_e32 vcc, 0, v110
	s_nop 0
	v_and_b32_e32 v117, 0x7fffffff, v111
	v_and_b32_e32 v116, 0x7fffffff, v110
	v_fma_f32 v116, v116, s28, 1.0
	v_fma_f32 v117, v117, s28, 1.0
	v_or_b32_e32 v114, 16, v160
	v_rcp_f32_e32 v116, v116
	v_rcp_f32_e32 v117, v117
	v_ashrrev_i32_e32 v115, 31, v114
	v_lshlrev_b64 v[114:115], 11, v[114:115]
	v_lshl_add_u64 v[114:115], s[40:41], 0, v[114:115]
	v_fma_f32 v118, v116, s30, v122
	v_fma_f32 v119, v117, s30, v122
	v_lshl_add_u64 v[114:115], v[114:115], 0, v[170:171]
	v_fma_f32 v118, v116, v118, s52
	v_fma_f32 v119, v117, v119, s52
	s_nop 0
	v_fma_f32 v118, v116, v118, s54
	v_fma_f32 v119, v117, v119, s54
	s_nop 0
	v_fma_f32 v118, v116, v118, s56
	v_fma_f32 v119, v117, v119, s56
	s_nop 0
	v_mul_f32 v116, v116, v118
	v_mul_f32 v117, v117, v119
	v_mul_f32 v118, v112, v112
	v_mul_f32 v119, v113, v113
	v_mul_f32 v116, v120, v116
	v_mul_f32 v117, v121, v117
	s_nop 0
	v_mul_f32 v120, v110, v116
	v_mul_f32 v121, v111, v117
	v_fma_f32 v116, -v110, v116, v110
	v_fma_f32 v117, -v111, v117, v111
	v_and_b32_e32 v110, 0x7fffffff, v112
	v_cndmask_b32_e32 v120, v116, v120, vcc
	v_cmp_gt_f32_e32 vcc, 0, v111
	v_and_b32_e32 v111, 0x7fffffff, v113
	v_fma_f32 v110, v110, s28, 1.0
	v_fma_f32 v111, v111, s28, 1.0
	v_cndmask_b32_e32 v121, v117, v121, vcc
	v_rcp_f32_e32 v110, v110
	v_rcp_f32_e32 v111, v111
	v_cmp_gt_f32_e32 vcc, 0, v112
	v_fma_f32 v116, v110, s30, v122
	v_fma_f32 v117, v111, s30, v122
	s_nop 0
	v_fma_f32 v116, v110, v116, s52
	v_fma_f32 v117, v111, v117, s52
	s_nop 0
	v_fma_f32 v116, v110, v116, s54
	v_fma_f32 v117, v111, v117, s54
	s_nop 0
	v_fma_f32 v116, v110, v116, s56
	v_fma_f32 v117, v111, v117, s56
	s_nop 0
	v_mul_f32 v110, v110, v116
	v_mul_f32 v111, v111, v117
	v_mul_f32 v116, v118, s58
	v_mul_f32 v117, v119, s58
	s_nop 0
	v_exp_f32_e32 v116, v116
	v_exp_f32_e32 v117, v117
	s_nop 0
	v_mul_f32 v110, v116, v110
	v_mul_f32 v111, v117, v111
	s_nop 0
	v_mul_f32 v116, v112, v110
	v_mul_f32 v117, v113, v111
	v_fma_f32 v110, -v112, v110, v112
	v_fma_f32 v111, -v113, v111, v113
	s_nop 0
	v_cndmask_b32_e32 v118, v110, v116, vcc
	v_cmp_gt_f32_e32 vcc, 0, v113
	v_and_b32_e32 v110, 0x7fffffff, v106
	s_nop 0
	v_cndmask_b32_e32 v119, v111, v117, vcc
	v_and_b32_e32 v111, 0x7fffffff, v107
	v_fma_f32 v110, v110, s28, 1.0
	v_fma_f32 v111, v111, s28, 1.0
	v_mul_f32 v116, v106, v106
	v_mul_f32 v117, v107, v107
	v_rcp_f32_e32 v110, v110
	v_rcp_f32_e32 v111, v111
	v_mul_f32 v116, v116, s58
	v_mul_f32 v117, v117, s58
	v_cmp_gt_f32_e32 vcc, 0, v106
	v_exp_f32_e32 v116, v116
	v_fma_f32 v112, v110, s30, v122
	v_fma_f32 v113, v111, s30, v122
	v_exp_f32_e32 v117, v117
	v_fma_f32 v112, v110, v112, s52
	v_fma_f32 v113, v111, v113, s52
	s_nop 0
	v_fma_f32 v112, v110, v112, s54
	v_fma_f32 v113, v111, v113, s54
	s_nop 0
	v_fma_f32 v112, v110, v112, s56
	v_fma_f32 v113, v111, v113, s56
	s_nop 0
	v_mul_f32 v110, v110, v112
	v_mul_f32 v111, v111, v113
	v_mul_f32 v112, v108, v108
	v_mul_f32 v113, v109, v109
	v_mul_f32 v110, v116, v110
	v_mul_f32 v111, v117, v111
	s_nop 0
	v_mul_f32 v116, v106, v110
	v_mul_f32 v117, v107, v111
	v_fma_f32 v110, -v106, v110, v106
	v_fma_f32 v111, -v107, v111, v107
	v_and_b32_e32 v106, 0x7fffffff, v108
	v_cndmask_b32_e32 v116, v110, v116, vcc
	v_cmp_gt_f32_e32 vcc, 0, v107
	v_and_b32_e32 v107, 0x7fffffff, v109
	v_fma_f32 v106, v106, s28, 1.0
	v_fma_f32 v107, v107, s28, 1.0
	v_cndmask_b32_e32 v117, v111, v117, vcc
	v_rcp_f32_e32 v106, v106
	v_rcp_f32_e32 v107, v107
	v_cmp_gt_f32_e32 vcc, 0, v108
	v_fma_f32 v110, v106, s30, v122
	v_fma_f32 v111, v107, s30, v122
	s_nop 0
	v_fma_f32 v110, v106, v110, s52
	v_fma_f32 v111, v107, v111, s52
	s_nop 0
	v_fma_f32 v110, v106, v110, s54
	v_fma_f32 v111, v107, v111, s54
	s_nop 0
	v_fma_f32 v110, v106, v110, s56
	v_fma_f32 v111, v107, v111, s56
	s_nop 0
	v_mul_f32 v106, v106, v110
	v_mul_f32 v107, v107, v111
	v_mul_f32 v110, v112, s58
	v_mul_f32 v111, v113, s58
	s_nop 0
	v_exp_f32_e32 v110, v110
	v_exp_f32_e32 v111, v111
	s_nop 0
	v_mul_f32 v106, v110, v106
	v_mul_f32 v107, v111, v107
	s_nop 0
	v_mul_f32 v110, v108, v106
	v_mul_f32 v111, v109, v107
	v_fma_f32 v106, -v108, v106, v108
	v_fma_f32 v107, -v109, v107, v109
	s_nop 0
	v_cndmask_b32_e32 v110, v106, v110, vcc
	v_cmp_gt_f32_e32 vcc, 0, v109
	v_cvt_pk_bf16_f32 v106, v120, v121
	s_nop 1
	v_cndmask_b32_e32 v109, v107, v111, vcc
	v_cvt_pk_bf16_f32 v107, v118, v119
	v_cvt_pk_bf16_f32 v108, v116, v117
	v_cvt_pk_bf16_f32 v109, v110, v109
	global_store_dwordx4 v[114:115], v[106:109], off
	v_mul_f32 v110, v102, v102
	v_mul_f32 v111, v103, v103
; __device__ __forceinline__ f32x2 gelu_pk(f32x2 v) {
;     const f32x2 av = __builtin_elementwise_abs(v), d = av * 0.2316418882f + 1.0f;
;     f32x2 t; t.x = __builtin_amdgcn_rcpf(d.x); t.y = __builtin_amdgcn_rcpf(d.y);
;     f32x2 q = t * 0.5307027145f + (-0.7265760135f); q = q * t + 0.7107068705f; q = q * t + (-0.142248368f); q = q * t + 0.127414796f; q = q * t;
;     const f32x2 s = (v * v) * (-0.72134752044f);
;     f32x2 e; e.x = __builtin_amdgcn_exp2f(s.x); e.y = __builtin_amdgcn_exp2f(s.y);
;     const f32x2 m = v * (q * e), r = v - m;
;     f32x2 o; o.x = v.x < 0.f ? m.x : r.x; o.y = v.y < 0.f ? m.y : r.y; return o;
; }
;     __device__ __forceinline__ void operator()(const f32x4 (&acc)[2][2][4][2], const Unit& u, int wr, int wc, int fr, int fq, const float (&pre)[8]) const {
;     ...
;         for (int ai = 0; ai < 2; ++ai)
; #pragma unroll
;             for (int m = 0; m < 4; ++m) {
;                 const int row = row0 + ai * 128 + m * 16; bf16_t* rowp = O + (size_t)row * ldc + col0; float rs = 0.f;
;                 float rsc = 1.f; if (RS == 1) rsc = pre[ai * 4 + m];
; #pragma unroll
;                 for (int bj = 0; bj < 2; ++bj) {
;                     f32x4 v0 = acc[ai][bj][m][0], v1 = acc[ai][bj][m][1];
;                     if (RS == 1) { v0 = v0 * rsc; v1 = v1 * rsc; }
;                     if (RS == 2) { v0 = v0 * csc[bj][0]; v1 = v1 * csc[bj][1]; }
;                     if (ACT == 1) { const f32x2 a = gelu_pk((f32x2){v0[0], v0[1]}), b = gelu_pk((f32x2){v0[2], v0[3]}), c = gelu_pk((f32x2){v1[0], v1[1]}), d = gelu_pk((f32x2){v1[2], v1[3]});
;                         v0 = (f32x4){a.x, a.y, b.x, b.y}; v1 = (f32x4){c.x, c.y, d.x, d.y}; }
;                     v0 = v0 * sc; v1 = v1 * sc;
	v_cmp_gt_f32_e32 vcc, 0, v102
	v_and_b32_e32 v107, 0x7fffffff, v103
	v_and_b32_e32 v106, 0x7fffffff, v102
	v_fma_f32 v106, v106, s28, 1.0
	v_fma_f32 v107, v107, s28, 1.0
	v_mul_f32 v110, v110, s58
	v_mul_f32 v111, v111, s58
	v_rcp_f32_e32 v106, v106
	v_rcp_f32_e32 v107, v107
	v_exp_f32_e32 v110, v110
	v_exp_f32_e32 v111, v111
	v_fma_f32 v108, v106, s30, v122
	v_fma_f32 v109, v107, s30, v122
	s_nop 0
	v_fma_f32 v108, v106, v108, s52
	v_fma_f32 v109, v107, v109, s52
	s_nop 0
	v_fma_f32 v108, v106, v108, s54
	v_fma_f32 v109, v107, v109, s54
	s_nop 0
	v_fma_f32 v108, v106, v108, s56
	v_fma_f32 v109, v107, v109, s56
	s_nop 0
	v_mul_f32 v106, v106, v108
	v_mul_f32 v107, v107, v109
	v_mul_f32 v108, v104, v104
	v_mul_f32 v109, v105, v105
	v_mul_f32 v106, v110, v106
	v_mul_f32 v107, v111, v107
	s_nop 0
	v_mul_f32 v110, v102, v106
	v_mul_f32 v111, v103, v107
	v_fma_f32 v106, -v102, v106, v102
	v_fma_f32 v107, -v103, v107, v103
	v_and_b32_e32 v102, 0x7fffffff, v104
	v_cndmask_b32_e32 v110, v106, v110, vcc
	v_cmp_gt_f32_e32 vcc, 0, v103
	v_and_b32_e32 v103, 0x7fffffff, v105
	v_fma_f32 v102, v102, s28, 1.0
	v_fma_f32 v103, v103, s28, 1.0
	v_cndmask_b32_e32 v111, v107, v111, vcc
	v_rcp_f32_e32 v102, v102
	v_rcp_f32_e32 v103, v103
	v_cmp_gt_f32_e32 vcc, 0, v104
	v_fma_f32 v106, v102, s30, v122
	v_fma_f32 v107, v103, s30, v122
	s_nop 0
	v_fma_f32 v106, v102, v106, s52
	v_fma_f32 v107, v103, v107, s52
	s_nop 0
	v_fma_f32 v106, v102, v106, s54
	v_fma_f32 v107, v103, v107, s54
	s_nop 0
	v_fma_f32 v106, v102, v106, s56
	v_fma_f32 v107, v103, v107, s56
	s_nop 0
	v_mul_f32 v102, v102, v106
	v_mul_f32 v103, v103, v107
	v_mul_f32 v106, v108, s58
	v_mul_f32 v107, v109, s58
	s_nop 0
	v_exp_f32_e32 v106, v106
	v_exp_f32_e32 v107, v107
	s_nop 0
	v_mul_f32 v102, v106, v102
	v_mul_f32 v103, v107, v103
	s_nop 0
	v_mul_f32 v106, v104, v102
	v_mul_f32 v107, v105, v103
	v_fma_f32 v102, -v104, v102, v104
	v_fma_f32 v103, -v105, v103, v105
	s_nop 0
	v_cndmask_b32_e32 v108, v102, v106, vcc
	v_cmp_gt_f32_e32 vcc, 0, v105
	v_and_b32_e32 v102, 0x7fffffff, v98
	s_nop 0
	v_cndmask_b32_e32 v109, v103, v107, vcc
	v_and_b32_e32 v103, 0x7fffffff, v99
	v_fma_f32 v102, v102, s28, 1.0
	v_fma_f32 v103, v103, s28, 1.0
	v_mul_f32 v106, v98, v98
	v_mul_f32 v107, v99, v99
	v_rcp_f32_e32 v102, v102
	v_rcp_f32_e32 v103, v103
	v_mul_f32 v106, v106, s58
	v_mul_f32 v107, v107, s58
	v_cmp_gt_f32_e32 vcc, 0, v98
	v_exp_f32_e32 v106, v106
	v_fma_f32 v104, v102, s30, v122
	v_fma_f32 v105, v103, s30, v122
	v_exp_f32_e32 v107, v107
	v_fma_f32 v104, v102, v104, s52
	v_fma_f32 v105, v103, v105, s52
	s_nop 0
	v_fma_f32 v104, v102, v104, s54
	v_fma_f32 v105, v103, v105, s54
	s_nop 0
	v_fma_f32 v104, v102, v104, s56
	v_fma_f32 v105, v103, v105, s56
	s_nop 0
	v_mul_f32 v102, v102, v104
	v_mul_f32 v103, v103, v105
	v_mul_f32 v104, v100, v100
	v_mul_f32 v105, v101, v101
	v_mul_f32 v102, v106, v102
	v_mul_f32 v103, v107, v103
	s_nop 0
	v_mul_f32 v106, v98, v102
	v_mul_f32 v107, v99, v103
	v_fma_f32 v102, -v98, v102, v98
	v_fma_f32 v103, -v99, v103, v99
	v_and_b32_e32 v98, 0x7fffffff, v100
	v_cndmask_b32_e32 v106, v102, v106, vcc
	v_cmp_gt_f32_e32 vcc, 0, v99
	v_and_b32_e32 v99, 0x7fffffff, v101
	v_fma_f32 v98, v98, s28, 1.0
	v_fma_f32 v99, v99, s28, 1.0
	v_cndmask_b32_e32 v107, v103, v107, vcc
	v_rcp_f32_e32 v98, v98
	v_rcp_f32_e32 v99, v99
	v_cmp_gt_f32_e32 vcc, 0, v100
	v_fma_f32 v102, v98, s30, v122
	v_fma_f32 v103, v99, s30, v122
	s_nop 0
	v_fma_f32 v102, v98, v102, s52
	v_fma_f32 v103, v99, v103, s52
	s_nop 0
	v_fma_f32 v102, v98, v102, s54
	v_fma_f32 v103, v99, v103, s54
	s_nop 0
	v_fma_f32 v102, v98, v102, s56
	v_fma_f32 v103, v99, v103, s56
	s_nop 0
	v_mul_f32 v98, v98, v102
	v_mul_f32 v99, v99, v103
	v_mul_f32 v102, v104, s58
	v_mul_f32 v103, v105, s58
	v_mul_f32 v104, v94, v94
	v_mul_f32 v105, v95, v95
	v_exp_f32_e32 v102, v102
	v_exp_f32_e32 v103, v103
	v_mul_f32 v104, v104, s58
	v_mul_f32 v105, v105, s58
	v_mul_f32 v98, v102, v98
	v_mul_f32 v99, v103, v99
	s_nop 0
	v_mul_f32 v102, v100, v98
	v_mul_f32 v103, v101, v99
	v_fma_f32 v98, -v100, v98, v100
	v_fma_f32 v99, -v101, v99, v101
	v_exp_f32_e32 v104, v104
	v_cndmask_b32_e32 v102, v98, v102, vcc
	v_cmp_gt_f32_e32 vcc, 0, v101
	v_cvt_pk_bf16_f32 v98, v110, v111
	v_exp_f32_e32 v105, v105
	s_nop 0
	v_cndmask_b32_e32 v101, v99, v103, vcc
	v_cvt_pk_bf16_f32 v99, v108, v109
	v_cvt_pk_bf16_f32 v100, v106, v107
	v_cvt_pk_bf16_f32 v101, v102, v101
	global_store_dwordx4 v[114:115], v[98:101], off offset:256
	v_cmp_gt_f32_e32 vcc, 0, v94
	s_nop 0
	v_and_b32_e32 v101, 0x7fffffff, v95
	v_and_b32_e32 v100, 0x7fffffff, v94
	v_fma_f32 v100, v100, s28, 1.0
	v_fma_f32 v101, v101, s28, 1.0
	v_or_b32_e32 v98, 32, v160
	v_rcp_f32_e32 v100, v100
	v_rcp_f32_e32 v101, v101
	v_ashrrev_i32_e32 v99, 31, v98
	v_lshlrev_b64 v[98:99], 11, v[98:99]
	v_lshl_add_u64 v[98:99], s[40:41], 0, v[98:99]
	v_fma_f32 v102, v100, s30, v122
	v_fma_f32 v103, v101, s30, v122
	v_lshl_add_u64 v[98:99], v[98:99], 0, v[170:171]
	v_fma_f32 v102, v100, v102, s52
	v_fma_f32 v103, v101, v103, s52
	s_nop 0
	v_fma_f32 v102, v100, v102, s54
	v_fma_f32 v103, v101, v103, s54
	s_nop 0
	v_fma_f32 v102, v100, v102, s56
	v_fma_f32 v103, v101, v103, s56
	s_nop 0
	v_mul_f32 v100, v100, v102
	v_mul_f32 v101, v101, v103
	v_mul_f32 v102, v96, v96
	v_mul_f32 v103, v97, v97
	v_mul_f32 v100, v104, v100
	v_mul_f32 v101, v105, v101
	s_nop 0
	v_mul_f32 v104, v94, v100
	v_mul_f32 v105, v95, v101
	v_fma_f32 v100, -v94, v100, v94
	v_fma_f32 v101, -v95, v101, v95
	v_and_b32_e32 v94, 0x7fffffff, v96
	v_cndmask_b32_e32 v104, v100, v104, vcc
	v_cmp_gt_f32_e32 vcc, 0, v95
	v_and_b32_e32 v95, 0x7fffffff, v97
	v_fma_f32 v94, v94, s28, 1.0
; #define GAS __attribute__((address_space(1)))
; __device__ __forceinline__ f32x2 gelu_pk(f32x2 v) {
;     const f32x2 av = __builtin_elementwise_abs(v), d = av * 0.2316418882f + 1.0f;
;     f32x2 t; t.x = __builtin_amdgcn_rcpf(d.x); t.y = __builtin_amdgcn_rcpf(d.y);
;     f32x2 q = t * 0.5307027145f + (-0.7265760135f); q = q * t + 0.7107068705f; q = q * t + (-0.142248368f); q = q * t + 0.127414796f; q = q * t;
;     const f32x2 s = (v * v) * (-0.72134752044f);
;     f32x2 e; e.x = __builtin_amdgcn_exp2f(s.x); e.y = __builtin_amdgcn_exp2f(s.y);
;     const f32x2 m = v * (q * e), r = v - m;
;     f32x2 o; o.x = v.x < 0.f ? m.x : r.x; o.y = v.y < 0.f ? m.y : r.y; return o;
; }
;     __device__ __forceinline__ void operator()(const f32x4 (&acc)[2][2][4][2], const Unit& u, int wr, int wc, int fr, int fq, const float (&pre)[8]) const {
;     ...
;         for (int ai = 0; ai < 2; ++ai)
; #pragma unroll
;             for (int m = 0; m < 4; ++m) {
;                 const int row = row0 + ai * 128 + m * 16; bf16_t* rowp = O + (size_t)row * ldc + col0; float rs = 0.f;
;                 float rsc = 1.f; if (RS == 1) rsc = pre[ai * 4 + m];
; #pragma unroll
;                 for (int bj = 0; bj < 2; ++bj) {
;                     f32x4 v0 = acc[ai][bj][m][0], v1 = acc[ai][bj][m][1];
;                     if (RS == 1) { v0 = v0 * rsc; v1 = v1 * rsc; }
;                     if (RS == 2) { v0 = v0 * csc[bj][0]; v1 = v1 * csc[bj][1]; }
;                     if (ACT == 1) { const f32x2 a = gelu_pk((f32x2){v0[0], v0[1]}), b = gelu_pk((f32x2){v0[2], v0[3]}), c = gelu_pk((f32x2){v1[0], v1[1]}), d = gelu_pk((f32x2){v1[2], v1[3]});
;                         v0 = (f32x4){a.x, a.y, b.x, b.y}; v1 = (f32x4){c.x, c.y, d.x, d.y}; }
;                     v0 = v0 * sc; v1 = v1 * sc;
;                     if (STAT == 1) rs += (v0[0] * v0[0] + v0[1] * v0[1]) + (v0[2] * v0[2] + v0[3] * v0[3]) + (v1[0] * v1[0] + v1[1] * v1[1]) + (v1[2] * v1[2] + v1[3] * v1[3]);
;                     if (STAT == 2) {
; #pragma unroll
;                         for (int e = 0; e < 4; ++e) { cs[bj][0][e] += v0[e]; cq[bj][0][e] += v0[e] * v0[e]; cs[bj][1][e] += v1[e]; cq[bj][1][e] += v1[e] * v1[e]; } }
;                     u32x4 w; w.x = cvt_pk_bf16(v0[0], v0[1]); w.y = cvt_pk_bf16(v0[2], v0[3]); w.z = cvt_pk_bf16(v1[0], v1[1]); w.w = cvt_pk_bf16(v1[2], v1[3]);
;                     *(GAS u32x4*)(rowp + bj * 128) = w; }
	v_fma_f32 v95, v95, s28, 1.0
	v_cndmask_b32_e32 v105, v101, v105, vcc
	v_rcp_f32_e32 v94, v94
	v_rcp_f32_e32 v95, v95
	v_cmp_gt_f32_e32 vcc, 0, v96
	v_fma_f32 v100, v94, s30, v122
	v_fma_f32 v101, v95, s30, v122
	s_nop 0
	v_fma_f32 v100, v94, v100, s52
	v_fma_f32 v101, v95, v101, s52
	s_nop 0
	v_fma_f32 v100, v94, v100, s54
	v_fma_f32 v101, v95, v101, s54
	s_nop 0
	v_fma_f32 v100, v94, v100, s56
	v_fma_f32 v101, v95, v101, s56
	s_nop 0
	v_mul_f32 v94, v94, v100
	v_mul_f32 v95, v95, v101
	v_mul_f32 v100, v102, s58
	v_mul_f32 v101, v103, s58
	s_nop 0
	v_exp_f32_e32 v100, v100
	v_exp_f32_e32 v101, v101
	s_nop 0
	v_mul_f32 v94, v100, v94
	v_mul_f32 v95, v101, v95
	s_nop 0
	v_mul_f32 v100, v96, v94
	v_mul_f32 v101, v97, v95
	v_fma_f32 v94, -v96, v94, v96
	v_fma_f32 v95, -v97, v95, v97
	s_nop 0
	v_cndmask_b32_e32 v102, v94, v100, vcc
	v_cmp_gt_f32_e32 vcc, 0, v97
	v_and_b32_e32 v94, 0x7fffffff, v90
	s_nop 0
	v_cndmask_b32_e32 v103, v95, v101, vcc
	v_and_b32_e32 v95, 0x7fffffff, v91
	v_fma_f32 v94, v94, s28, 1.0
	v_fma_f32 v95, v95, s28, 1.0
	v_mul_f32 v100, v90, v90
	v_mul_f32 v101, v91, v91
	v_rcp_f32_e32 v94, v94
	v_rcp_f32_e32 v95, v95
	v_mul_f32 v100, v100, s58
	v_mul_f32 v101, v101, s58
	v_cmp_gt_f32_e32 vcc, 0, v90
	v_exp_f32_e32 v100, v100
	v_fma_f32 v96, v94, s30, v122
	v_fma_f32 v97, v95, s30, v122
	v_exp_f32_e32 v101, v101
	v_fma_f32 v96, v94, v96, s52
	v_fma_f32 v97, v95, v97, s52
	s_nop 0
	v_fma_f32 v96, v94, v96, s54
	v_fma_f32 v97, v95, v97, s54
	s_nop 0
	v_fma_f32 v96, v94, v96, s56
	v_fma_f32 v97, v95, v97, s56
	s_nop 0
	v_mul_f32 v94, v94, v96
	v_mul_f32 v95, v95, v97
	v_mul_f32 v96, v92, v92
	v_mul_f32 v97, v93, v93
	v_mul_f32 v94, v100, v94
	v_mul_f32 v95, v101, v95
	s_nop 0
	v_mul_f32 v100, v90, v94
	v_mul_f32 v101, v91, v95
	v_fma_f32 v94, -v90, v94, v90
	v_fma_f32 v95, -v91, v95, v91
	v_and_b32_e32 v90, 0x7fffffff, v92
	v_cndmask_b32_e32 v100, v94, v100, vcc
	v_cmp_gt_f32_e32 vcc, 0, v91
	v_and_b32_e32 v91, 0x7fffffff, v93
	v_fma_f32 v90, v90, s28, 1.0
	v_fma_f32 v91, v91, s28, 1.0
	v_cndmask_b32_e32 v101, v95, v101, vcc
	v_rcp_f32_e32 v90, v90
	v_rcp_f32_e32 v91, v91
	v_cmp_gt_f32_e32 vcc, 0, v92
	v_fma_f32 v94, v90, s30, v122
	v_fma_f32 v95, v91, s30, v122
	s_nop 0
	v_fma_f32 v94, v90, v94, s52
	v_fma_f32 v95, v91, v95, s52
	s_nop 0
	v_fma_f32 v94, v90, v94, s54
	v_fma_f32 v95, v91, v95, s54
	s_nop 0
	v_fma_f32 v94, v90, v94, s56
	v_fma_f32 v95, v91, v95, s56
	s_nop 0
	v_mul_f32 v90, v90, v94
	v_mul_f32 v91, v91, v95
	v_mul_f32 v94, v96, s58
	v_mul_f32 v95, v97, s58
	s_nop 0
	v_exp_f32_e32 v94, v94
	v_exp_f32_e32 v95, v95
	s_nop 0
	v_mul_f32 v90, v94, v90
	v_mul_f32 v91, v95, v91
	s_nop 0
	v_mul_f32 v94, v92, v90
	v_mul_f32 v95, v93, v91
	v_fma_f32 v90, -v92, v90, v92
	v_fma_f32 v91, -v93, v91, v93
	s_nop 0
	v_cndmask_b32_e32 v94, v90, v94, vcc
	v_cmp_gt_f32_e32 vcc, 0, v93
	v_cvt_pk_bf16_f32 v90, v104, v105
	s_nop 1
	v_cndmask_b32_e32 v93, v91, v95, vcc
	v_cvt_pk_bf16_f32 v91, v102, v103
	v_cvt_pk_bf16_f32 v92, v100, v101
	v_cvt_pk_bf16_f32 v93, v94, v93
	global_store_dwordx4 v[98:99], v[90:93], off
	v_mul_f32 v94, v86, v86
	v_mul_f32 v95, v87, v87
	v_cmp_gt_f32_e32 vcc, 0, v86
	v_and_b32_e32 v91, 0x7fffffff, v87
	v_and_b32_e32 v90, 0x7fffffff, v86
	v_fma_f32 v90, v90, s28, 1.0
	v_fma_f32 v91, v91, s28, 1.0
	v_mul_f32 v94, v94, s58
	v_mul_f32 v95, v95, s58
	v_rcp_f32_e32 v90, v90
	v_rcp_f32_e32 v91, v91
	v_exp_f32_e32 v94, v94
	v_exp_f32_e32 v95, v95
	v_fma_f32 v92, v90, s30, v122
	v_fma_f32 v93, v91, s30, v122
	s_nop 0
	v_fma_f32 v92, v90, v92, s52
	v_fma_f32 v93, v91, v93, s52
	s_nop 0
	v_fma_f32 v92, v90, v92, s54
	v_fma_f32 v93, v91, v93, s54
	s_nop 0
	v_fma_f32 v92, v90, v92, s56
	v_fma_f32 v93, v91, v93, s56
	s_nop 0
	v_mul_f32 v90, v90, v92
	v_mul_f32 v91, v91, v93
	v_mul_f32 v92, v88, v88
	v_mul_f32 v93, v89, v89
	v_mul_f32 v90, v94, v90
	v_mul_f32 v91, v95, v91
	s_nop 0
	v_mul_f32 v94, v86, v90
	v_mul_f32 v95, v87, v91
	v_fma_f32 v90, -v86, v90, v86
	v_fma_f32 v91, -v87, v91, v87
	v_and_b32_e32 v86, 0x7fffffff, v88
	v_cndmask_b32_e32 v94, v90, v94, vcc
	v_cmp_gt_f32_e32 vcc, 0, v87
	v_and_b32_e32 v87, 0x7fffffff, v89
	v_fma_f32 v86, v86, s28, 1.0
	v_fma_f32 v87, v87, s28, 1.0
	v_cndmask_b32_e32 v95, v91, v95, vcc
	v_rcp_f32_e32 v86, v86
	v_rcp_f32_e32 v87, v87
	v_cmp_gt_f32_e32 vcc, 0, v88
	v_fma_f32 v90, v86, s30, v122
	v_fma_f32 v91, v87, s30, v122
	s_nop 0
	v_fma_f32 v90, v86, v90, s52
	v_fma_f32 v91, v87, v91, s52
	s_nop 0
	v_fma_f32 v90, v86, v90, s54
	v_fma_f32 v91, v87, v91, s54
	s_nop 0
	v_fma_f32 v90, v86, v90, s56
	v_fma_f32 v91, v87, v91, s56
	s_nop 0
	v_mul_f32 v86, v86, v90
	v_mul_f32 v87, v87, v91
	v_mul_f32 v90, v92, s58
	v_mul_f32 v91, v93, s58
	s_nop 0
	v_exp_f32_e32 v90, v90
	v_exp_f32_e32 v91, v91
	s_nop 0
	v_mul_f32 v86, v90, v86
	v_mul_f32 v87, v91, v87
	s_nop 0
	v_mul_f32 v90, v88, v86
	v_mul_f32 v91, v89, v87
	v_fma_f32 v86, -v88, v86, v88
	v_fma_f32 v87, -v89, v87, v89
	s_nop 0
	v_cndmask_b32_e32 v92, v86, v90, vcc
	v_cmp_gt_f32_e32 vcc, 0, v89
	v_and_b32_e32 v86, 0x7fffffff, v82
	s_nop 0
	v_cndmask_b32_e32 v93, v87, v91, vcc
	v_and_b32_e32 v87, 0x7fffffff, v83
	v_fma_f32 v86, v86, s28, 1.0
	v_fma_f32 v87, v87, s28, 1.0
	v_mul_f32 v90, v82, v82
	v_mul_f32 v91, v83, v83
	v_rcp_f32_e32 v86, v86
	v_rcp_f32_e32 v87, v87
	v_mul_f32 v90, v90, s58
	v_mul_f32 v91, v91, s58
	v_cmp_gt_f32_e32 vcc, 0, v82
	v_exp_f32_e32 v90, v90
	v_fma_f32 v88, v86, s30, v122
	v_fma_f32 v89, v87, s30, v122
	v_exp_f32_e32 v91, v91
	v_fma_f32 v88, v86, v88, s52
	v_fma_f32 v89, v87, v89, s52
	s_nop 0
	v_fma_f32 v88, v86, v88, s54
	v_fma_f32 v89, v87, v89, s54
	s_nop 0
	v_fma_f32 v88, v86, v88, s56
; #define GAS __attribute__((address_space(1)))
; __device__ __forceinline__ f32x2 gelu_pk(f32x2 v) {
;     const f32x2 av = __builtin_elementwise_abs(v), d = av * 0.2316418882f + 1.0f;
;     f32x2 t; t.x = __builtin_amdgcn_rcpf(d.x); t.y = __builtin_amdgcn_rcpf(d.y);
;     f32x2 q = t * 0.5307027145f + (-0.7265760135f); q = q * t + 0.7107068705f; q = q * t + (-0.142248368f); q = q * t + 0.127414796f; q = q * t;
;     const f32x2 s = (v * v) * (-0.72134752044f);
;     f32x2 e; e.x = __builtin_amdgcn_exp2f(s.x); e.y = __builtin_amdgcn_exp2f(s.y);
;     const f32x2 m = v * (q * e), r = v - m;
;     f32x2 o; o.x = v.x < 0.f ? m.x : r.x; o.y = v.y < 0.f ? m.y : r.y; return o;
; }
;     __device__ __forceinline__ void operator()(const f32x4 (&acc)[2][2][4][2], const Unit& u, int wr, int wc, int fr, int fq, const float (&pre)[8]) const {
;     ...
;         for (int ai = 0; ai < 2; ++ai)
; #pragma unroll
;             for (int m = 0; m < 4; ++m) {
;                 const int row = row0 + ai * 128 + m * 16; bf16_t* rowp = O + (size_t)row * ldc + col0; float rs = 0.f;
;                 float rsc = 1.f; if (RS == 1) rsc = pre[ai * 4 + m];
; #pragma unroll
;                 for (int bj = 0; bj < 2; ++bj) {
;                     f32x4 v0 = acc[ai][bj][m][0], v1 = acc[ai][bj][m][1];
;                     if (RS == 1) { v0 = v0 * rsc; v1 = v1 * rsc; }
;                     if (RS == 2) { v0 = v0 * csc[bj][0]; v1 = v1 * csc[bj][1]; }
;                     if (ACT == 1) { const f32x2 a = gelu_pk((f32x2){v0[0], v0[1]}), b = gelu_pk((f32x2){v0[2], v0[3]}), c = gelu_pk((f32x2){v1[0], v1[1]}), d = gelu_pk((f32x2){v1[2], v1[3]});
;                         v0 = (f32x4){a.x, a.y, b.x, b.y}; v1 = (f32x4){c.x, c.y, d.x, d.y}; }
;                     v0 = v0 * sc; v1 = v1 * sc;
;                     if (STAT == 1) rs += (v0[0] * v0[0] + v0[1] * v0[1]) + (v0[2] * v0[2] + v0[3] * v0[3]) + (v1[0] * v1[0] + v1[1] * v1[1]) + (v1[2] * v1[2] + v1[3] * v1[3]);
;                     if (STAT == 2) {
; #pragma unroll
;                         for (int e = 0; e < 4; ++e) { cs[bj][0][e] += v0[e]; cq[bj][0][e] += v0[e] * v0[e]; cs[bj][1][e] += v1[e]; cq[bj][1][e] += v1[e] * v1[e]; } }
;                     u32x4 w; w.x = cvt_pk_bf16(v0[0], v0[1]); w.y = cvt_pk_bf16(v0[2], v0[3]); w.z = cvt_pk_bf16(v1[0], v1[1]); w.w = cvt_pk_bf16(v1[2], v1[3]);
;                     *(GAS u32x4*)(rowp + bj * 128) = w; }
	v_fma_f32 v89, v87, v89, s56
	s_nop 0
	v_mul_f32 v86, v86, v88
	v_mul_f32 v87, v87, v89
	v_mul_f32 v88, v84, v84
	v_mul_f32 v89, v85, v85
	v_mul_f32 v86, v90, v86
	v_mul_f32 v87, v91, v87
	s_nop 0
	v_mul_f32 v90, v82, v86
	v_mul_f32 v91, v83, v87
	v_fma_f32 v86, -v82, v86, v82
	v_fma_f32 v87, -v83, v87, v83
	v_and_b32_e32 v82, 0x7fffffff, v84
	v_cndmask_b32_e32 v90, v86, v90, vcc
	v_cmp_gt_f32_e32 vcc, 0, v83
	v_and_b32_e32 v83, 0x7fffffff, v85
	v_fma_f32 v82, v82, s28, 1.0
	v_fma_f32 v83, v83, s28, 1.0
	v_cndmask_b32_e32 v91, v87, v91, vcc
	v_rcp_f32_e32 v82, v82
	v_rcp_f32_e32 v83, v83
	v_cmp_gt_f32_e32 vcc, 0, v84
	v_fma_f32 v86, v82, s30, v122
	v_fma_f32 v87, v83, s30, v122
	s_nop 0
	v_fma_f32 v86, v82, v86, s52
	v_fma_f32 v87, v83, v87, s52
	s_nop 0
	v_fma_f32 v86, v82, v86, s54
	v_fma_f32 v87, v83, v87, s54
	s_nop 0
	v_fma_f32 v86, v82, v86, s56
	v_fma_f32 v87, v83, v87, s56
	s_nop 0
	v_mul_f32 v82, v82, v86
	v_mul_f32 v83, v83, v87
	v_mul_f32 v86, v88, s58
	v_mul_f32 v87, v89, s58
	v_mul_f32 v88, v78, v78
	v_mul_f32 v89, v79, v79
	v_exp_f32_e32 v86, v86
	v_exp_f32_e32 v87, v87
	v_mul_f32 v88, v88, s58
	v_mul_f32 v89, v89, s58
	v_mul_f32 v82, v86, v82
	v_mul_f32 v83, v87, v83
	s_nop 0
	v_mul_f32 v86, v84, v82
	v_mul_f32 v87, v85, v83
	v_fma_f32 v82, -v84, v82, v84
	v_fma_f32 v83, -v85, v83, v85
	v_exp_f32_e32 v88, v88
	v_cndmask_b32_e32 v86, v82, v86, vcc
	v_cmp_gt_f32_e32 vcc, 0, v85
	v_cvt_pk_bf16_f32 v82, v94, v95
	v_exp_f32_e32 v89, v89
	s_nop 0
	v_cndmask_b32_e32 v85, v83, v87, vcc
	v_cvt_pk_bf16_f32 v83, v92, v93
	v_cvt_pk_bf16_f32 v84, v90, v91
	v_cvt_pk_bf16_f32 v85, v86, v85
	global_store_dwordx4 v[98:99], v[82:85], off offset:256
	v_cmp_gt_f32_e32 vcc, 0, v78
	s_nop 0
	v_and_b32_e32 v85, 0x7fffffff, v79
	v_and_b32_e32 v84, 0x7fffffff, v78
	v_fma_f32 v84, v84, s28, 1.0
	v_fma_f32 v85, v85, s28, 1.0
	v_or_b32_e32 v82, 48, v160
	v_rcp_f32_e32 v84, v84
	v_rcp_f32_e32 v85, v85
	v_ashrrev_i32_e32 v83, 31, v82
	v_lshlrev_b64 v[82:83], 11, v[82:83]
	v_lshl_add_u64 v[82:83], s[40:41], 0, v[82:83]
	v_fma_f32 v86, v84, s30, v122
	v_fma_f32 v87, v85, s30, v122
	v_lshl_add_u64 v[82:83], v[82:83], 0, v[170:171]
	v_fma_f32 v86, v84, v86, s52
	v_fma_f32 v87, v85, v87, s52
	s_nop 0
	v_fma_f32 v86, v84, v86, s54
	v_fma_f32 v87, v85, v87, s54
	s_nop 0
	v_fma_f32 v86, v84, v86, s56
	v_fma_f32 v87, v85, v87, s56
	s_nop 0
	v_mul_f32 v84, v84, v86
	v_mul_f32 v85, v85, v87
	v_mul_f32 v86, v80, v80
	v_mul_f32 v87, v81, v81
	v_mul_f32 v84, v88, v84
	v_mul_f32 v85, v89, v85
	s_nop 0
	v_mul_f32 v88, v78, v84
	v_mul_f32 v89, v79, v85
	v_fma_f32 v84, -v78, v84, v78
	v_fma_f32 v85, -v79, v85, v79
	v_and_b32_e32 v78, 0x7fffffff, v80
	v_cndmask_b32_e32 v88, v84, v88, vcc
	v_cmp_gt_f32_e32 vcc, 0, v79
	v_and_b32_e32 v79, 0x7fffffff, v81
	v_fma_f32 v78, v78, s28, 1.0
	v_fma_f32 v79, v79, s28, 1.0
	v_cndmask_b32_e32 v89, v85, v89, vcc
	v_rcp_f32_e32 v78, v78
	v_rcp_f32_e32 v79, v79
	v_cmp_gt_f32_e32 vcc, 0, v80
	v_fma_f32 v84, v78, s30, v122
	v_fma_f32 v85, v79, s30, v122
	s_nop 0
	v_fma_f32 v84, v78, v84, s52
	v_fma_f32 v85, v79, v85, s52
	s_nop 0
	v_fma_f32 v84, v78, v84, s54
	v_fma_f32 v85, v79, v85, s54
	s_nop 0
	v_fma_f32 v84, v78, v84, s56
	v_fma_f32 v85, v79, v85, s56
	s_nop 0
	v_mul_f32 v78, v78, v84
	v_mul_f32 v79, v79, v85
	v_mul_f32 v84, v86, s58
	v_mul_f32 v85, v87, s58
	s_nop 0
	v_exp_f32_e32 v84, v84
	v_exp_f32_e32 v85, v85
	s_nop 0
	v_mul_f32 v78, v84, v78
	v_mul_f32 v79, v85, v79
	s_nop 0
	v_mul_f32 v84, v80, v78
	v_mul_f32 v85, v81, v79
	v_fma_f32 v78, -v80, v78, v80
	v_fma_f32 v79, -v81, v79, v81
	s_nop 0
	v_cndmask_b32_e32 v86, v78, v84, vcc
	v_cmp_gt_f32_e32 vcc, 0, v81
	v_and_b32_e32 v78, 0x7fffffff, v74
	s_nop 0
	v_cndmask_b32_e32 v87, v79, v85, vcc
	v_and_b32_e32 v79, 0x7fffffff, v75
	v_fma_f32 v78, v78, s28, 1.0
	v_fma_f32 v79, v79, s28, 1.0
	v_mul_f32 v84, v74, v74
	v_mul_f32 v85, v75, v75
	v_rcp_f32_e32 v78, v78
	v_rcp_f32_e32 v79, v79
	v_mul_f32 v84, v84, s58
	v_mul_f32 v85, v85, s58
	v_cmp_gt_f32_e32 vcc, 0, v74
	v_exp_f32_e32 v84, v84
	v_fma_f32 v80, v78, s30, v122
	v_fma_f32 v81, v79, s30, v122
	v_exp_f32_e32 v85, v85
	v_fma_f32 v80, v78, v80, s52
	v_fma_f32 v81, v79, v81, s52
	s_nop 0
	v_fma_f32 v80, v78, v80, s54
	v_fma_f32 v81, v79, v81, s54
	s_nop 0
	v_fma_f32 v80, v78, v80, s56
	v_fma_f32 v81, v79, v81, s56
	s_nop 0
	v_mul_f32 v78, v78, v80
	v_mul_f32 v79, v79, v81
	v_mul_f32 v80, v76, v76
	v_mul_f32 v81, v77, v77
	v_mul_f32 v78, v84, v78
	v_mul_f32 v79, v85, v79
	s_nop 0
	v_mul_f32 v84, v74, v78
	v_mul_f32 v85, v75, v79
	v_fma_f32 v78, -v74, v78, v74
	v_fma_f32 v79, -v75, v79, v75
	v_and_b32_e32 v74, 0x7fffffff, v76
	v_cndmask_b32_e32 v84, v78, v84, vcc
	v_cmp_gt_f32_e32 vcc, 0, v75
	v_and_b32_e32 v75, 0x7fffffff, v77
	v_fma_f32 v74, v74, s28, 1.0
	v_fma_f32 v75, v75, s28, 1.0
	v_cndmask_b32_e32 v85, v79, v85, vcc
	v_rcp_f32_e32 v74, v74
	v_rcp_f32_e32 v75, v75
	v_cmp_gt_f32_e32 vcc, 0, v76
	v_fma_f32 v78, v74, s30, v122
	v_fma_f32 v79, v75, s30, v122
	s_nop 0
	v_fma_f32 v78, v74, v78, s52
	v_fma_f32 v79, v75, v79, s52
	s_nop 0
	v_fma_f32 v78, v74, v78, s54
	v_fma_f32 v79, v75, v79, s54
	s_nop 0
	v_fma_f32 v78, v74, v78, s56
	v_fma_f32 v79, v75, v79, s56
	s_nop 0
	v_mul_f32 v74, v74, v78
	v_mul_f32 v75, v75, v79
	v_mul_f32 v78, v80, s58
	v_mul_f32 v79, v81, s58
	s_nop 0
	v_exp_f32_e32 v78, v78
	v_exp_f32_e32 v79, v79
	s_nop 0
	v_mul_f32 v74, v78, v74
	v_mul_f32 v75, v79, v75
	s_nop 0
	v_mul_f32 v78, v76, v74
	v_mul_f32 v79, v77, v75
	v_fma_f32 v74, -v76, v74, v76
	v_fma_f32 v75, -v77, v75, v77
	s_nop 0
	v_cndmask_b32_e32 v78, v74, v78, vcc
	v_cmp_gt_f32_e32 vcc, 0, v77
	v_cvt_pk_bf16_f32 v74, v88, v89
	s_nop 1
; #define GAS __attribute__((address_space(1)))
; __device__ __forceinline__ f32x2 gelu_pk(f32x2 v) {
;     const f32x2 av = __builtin_elementwise_abs(v), d = av * 0.2316418882f + 1.0f;
;     f32x2 t; t.x = __builtin_amdgcn_rcpf(d.x); t.y = __builtin_amdgcn_rcpf(d.y);
;     f32x2 q = t * 0.5307027145f + (-0.7265760135f); q = q * t + 0.7107068705f; q = q * t + (-0.142248368f); q = q * t + 0.127414796f; q = q * t;
;     const f32x2 s = (v * v) * (-0.72134752044f);
;     f32x2 e; e.x = __builtin_amdgcn_exp2f(s.x); e.y = __builtin_amdgcn_exp2f(s.y);
;     const f32x2 m = v * (q * e), r = v - m;
;     f32x2 o; o.x = v.x < 0.f ? m.x : r.x; o.y = v.y < 0.f ? m.y : r.y; return o;
; }
;     __device__ __forceinline__ void operator()(const f32x4 (&acc)[2][2][4][2], const Unit& u, int wr, int wc, int fr, int fq, const float (&pre)[8]) const {
;     ...
;         for (int ai = 0; ai < 2; ++ai)
; #pragma unroll
;             for (int m = 0; m < 4; ++m) {
;                 const int row = row0 + ai * 128 + m * 16; bf16_t* rowp = O + (size_t)row * ldc + col0; float rs = 0.f;
;                 float rsc = 1.f; if (RS == 1) rsc = pre[ai * 4 + m];
; #pragma unroll
;                 for (int bj = 0; bj < 2; ++bj) {
;                     f32x4 v0 = acc[ai][bj][m][0], v1 = acc[ai][bj][m][1];
;                     if (RS == 1) { v0 = v0 * rsc; v1 = v1 * rsc; }
;                     if (RS == 2) { v0 = v0 * csc[bj][0]; v1 = v1 * csc[bj][1]; }
;                     if (ACT == 1) { const f32x2 a = gelu_pk((f32x2){v0[0], v0[1]}), b = gelu_pk((f32x2){v0[2], v0[3]}), c = gelu_pk((f32x2){v1[0], v1[1]}), d = gelu_pk((f32x2){v1[2], v1[3]});
;                         v0 = (f32x4){a.x, a.y, b.x, b.y}; v1 = (f32x4){c.x, c.y, d.x, d.y}; }
;                     v0 = v0 * sc; v1 = v1 * sc;
;                     if (STAT == 1) rs += (v0[0] * v0[0] + v0[1] * v0[1]) + (v0[2] * v0[2] + v0[3] * v0[3]) + (v1[0] * v1[0] + v1[1] * v1[1]) + (v1[2] * v1[2] + v1[3] * v1[3]);
;                     if (STAT == 2) {
; #pragma unroll
;                         for (int e = 0; e < 4; ++e) { cs[bj][0][e] += v0[e]; cq[bj][0][e] += v0[e] * v0[e]; cs[bj][1][e] += v1[e]; cq[bj][1][e] += v1[e] * v1[e]; } }
;                     u32x4 w; w.x = cvt_pk_bf16(v0[0], v0[1]); w.y = cvt_pk_bf16(v0[2], v0[3]); w.z = cvt_pk_bf16(v1[0], v1[1]); w.w = cvt_pk_bf16(v1[2], v1[3]);
;                     *(GAS u32x4*)(rowp + bj * 128) = w; }
	v_cndmask_b32_e32 v77, v75, v79, vcc
	v_cvt_pk_bf16_f32 v75, v86, v87
	v_cvt_pk_bf16_f32 v76, v84, v85
	v_cvt_pk_bf16_f32 v77, v78, v77
	global_store_dwordx4 v[82:83], v[74:77], off
	v_mul_f32 v78, v70, v70
	v_mul_f32 v79, v71, v71
	v_cmp_gt_f32_e32 vcc, 0, v70
	v_and_b32_e32 v75, 0x7fffffff, v71
	v_and_b32_e32 v74, 0x7fffffff, v70
	v_fma_f32 v74, v74, s28, 1.0
	v_fma_f32 v75, v75, s28, 1.0
	v_mul_f32 v78, v78, s58
	v_mul_f32 v79, v79, s58
	v_rcp_f32_e32 v74, v74
	v_rcp_f32_e32 v75, v75
	v_exp_f32_e32 v78, v78
	v_exp_f32_e32 v79, v79
	v_fma_f32 v76, v74, s30, v122
	v_fma_f32 v77, v75, s30, v122
	s_nop 0
	v_fma_f32 v76, v74, v76, s52
	v_fma_f32 v77, v75, v77, s52
	s_nop 0
	v_fma_f32 v76, v74, v76, s54
	v_fma_f32 v77, v75, v77, s54
	s_nop 0
	v_fma_f32 v76, v74, v76, s56
	v_fma_f32 v77, v75, v77, s56
	s_nop 0
	v_mul_f32 v74, v74, v76
	v_mul_f32 v75, v75, v77
	v_mul_f32 v76, v72, v72
	v_mul_f32 v77, v73, v73
	v_mul_f32 v74, v78, v74
	v_mul_f32 v75, v79, v75
	s_nop 0
	v_mul_f32 v78, v70, v74
	v_mul_f32 v79, v71, v75
	v_fma_f32 v74, -v70, v74, v70
	v_fma_f32 v75, -v71, v75, v71
	v_and_b32_e32 v70, 0x7fffffff, v72
	v_cndmask_b32_e32 v78, v74, v78, vcc
	v_cmp_gt_f32_e32 vcc, 0, v71
	v_and_b32_e32 v71, 0x7fffffff, v73
	v_fma_f32 v70, v70, s28, 1.0
	v_fma_f32 v71, v71, s28, 1.0
	v_cndmask_b32_e32 v79, v75, v79, vcc
	v_rcp_f32_e32 v70, v70
	v_rcp_f32_e32 v71, v71
	v_cmp_gt_f32_e32 vcc, 0, v72
	v_fma_f32 v74, v70, s30, v122
	v_fma_f32 v75, v71, s30, v122
	s_nop 0
	v_fma_f32 v74, v70, v74, s52
	v_fma_f32 v75, v71, v75, s52
	s_nop 0
	v_fma_f32 v74, v70, v74, s54
	v_fma_f32 v75, v71, v75, s54
	s_nop 0
	v_fma_f32 v74, v70, v74, s56
	v_fma_f32 v75, v71, v75, s56
	s_nop 0
	v_mul_f32 v70, v70, v74
	v_mul_f32 v71, v71, v75
	v_mul_f32 v74, v76, s58
	v_mul_f32 v75, v77, s58
	s_nop 0
	v_exp_f32_e32 v74, v74
	v_exp_f32_e32 v75, v75
	s_nop 0
	v_mul_f32 v70, v74, v70
	v_mul_f32 v71, v75, v71
	s_nop 0
	v_mul_f32 v74, v72, v70
	v_mul_f32 v75, v73, v71
	v_fma_f32 v70, -v72, v70, v72
	v_fma_f32 v71, -v73, v71, v73
	s_nop 0
	v_cndmask_b32_e32 v76, v70, v74, vcc
	v_cmp_gt_f32_e32 vcc, 0, v73
	v_and_b32_e32 v70, 0x7fffffff, v66
	s_nop 0
	v_cndmask_b32_e32 v77, v71, v75, vcc
	v_and_b32_e32 v71, 0x7fffffff, v67
	v_fma_f32 v70, v70, s28, 1.0
	v_fma_f32 v71, v71, s28, 1.0
	v_mul_f32 v74, v66, v66
	v_mul_f32 v75, v67, v67
	v_rcp_f32_e32 v70, v70
	v_rcp_f32_e32 v71, v71
	v_mul_f32 v74, v74, s58
	v_mul_f32 v75, v75, s58
	v_cmp_gt_f32_e32 vcc, 0, v66
	v_exp_f32_e32 v74, v74
	v_fma_f32 v72, v70, s30, v122
	v_fma_f32 v73, v71, s30, v122
	v_exp_f32_e32 v75, v75
	v_fma_f32 v72, v70, v72, s52
	v_fma_f32 v73, v71, v73, s52
	s_nop 0
	v_fma_f32 v72, v70, v72, s54
	v_fma_f32 v73, v71, v73, s54
	s_nop 0
	v_fma_f32 v72, v70, v72, s56
	v_fma_f32 v73, v71, v73, s56
	s_nop 0
	v_mul_f32 v70, v70, v72
	v_mul_f32 v71, v71, v73
	v_mul_f32 v72, v68, v68
	v_mul_f32 v73, v69, v69
	v_mul_f32 v70, v74, v70
	v_mul_f32 v71, v75, v71
	s_nop 0
	v_mul_f32 v74, v66, v70
	v_mul_f32 v75, v67, v71
	v_fma_f32 v70, -v66, v70, v66
	v_fma_f32 v71, -v67, v71, v67
	v_and_b32_e32 v66, 0x7fffffff, v68
	v_cndmask_b32_e32 v74, v70, v74, vcc
	v_cmp_gt_f32_e32 vcc, 0, v67
	v_and_b32_e32 v67, 0x7fffffff, v69
	v_fma_f32 v66, v66, s28, 1.0
	v_fma_f32 v67, v67, s28, 1.0
	v_cndmask_b32_e32 v75, v71, v75, vcc
	v_rcp_f32_e32 v66, v66
	v_rcp_f32_e32 v67, v67
	v_cmp_gt_f32_e32 vcc, 0, v68
	v_fma_f32 v70, v66, s30, v122
	v_fma_f32 v71, v67, s30, v122
	s_nop 0
	v_fma_f32 v70, v66, v70, s52
	v_fma_f32 v71, v67, v71, s52
	s_nop 0
	v_fma_f32 v70, v66, v70, s54
	v_fma_f32 v71, v67, v71, s54
	s_nop 0
	v_fma_f32 v70, v66, v70, s56
	v_fma_f32 v71, v67, v71, s56
	s_nop 0
	v_mul_f32 v66, v66, v70
	v_mul_f32 v67, v67, v71
	v_mul_f32 v70, v72, s58
	v_mul_f32 v71, v73, s58
	v_mul_f32 v72, v62, v62
	v_mul_f32 v73, v63, v63
	v_exp_f32_e32 v70, v70
	v_exp_f32_e32 v71, v71
	v_mul_f32 v72, v72, s58
	v_mul_f32 v73, v73, s58
	v_mul_f32 v66, v70, v66
	v_mul_f32 v67, v71, v67
	s_nop 0
	v_mul_f32 v70, v68, v66
	v_mul_f32 v71, v69, v67
	v_fma_f32 v66, -v68, v66, v68
	v_fma_f32 v67, -v69, v67, v69
	v_exp_f32_e32 v72, v72
	v_cndmask_b32_e32 v70, v66, v70, vcc
	v_cmp_gt_f32_e32 vcc, 0, v69
	v_cvt_pk_bf16_f32 v66, v78, v79
	v_exp_f32_e32 v73, v73
	s_nop 0
	v_cndmask_b32_e32 v69, v67, v71, vcc
	v_cvt_pk_bf16_f32 v67, v76, v77
	v_cvt_pk_bf16_f32 v68, v74, v75
	v_cvt_pk_bf16_f32 v69, v70, v69
	global_store_dwordx4 v[82:83], v[66:69], off offset:256
	v_cmp_gt_f32_e32 vcc, 0, v62
	s_nop 0
	v_and_b32_e32 v69, 0x7fffffff, v63
	v_and_b32_e32 v68, 0x7fffffff, v62
	v_fma_f32 v68, v68, s28, 1.0
	v_fma_f32 v69, v69, s28, 1.0
	v_lshl_add_u64 v[66:67], v[150:151], 0, s[4:5]
	v_rcp_f32_e32 v68, v68
	v_rcp_f32_e32 v69, v69
	s_mov_b32 s4, 0x40000
	v_fma_f32 v70, v68, s30, v122
	v_fma_f32 v71, v69, s30, v122
	s_nop 0
	v_fma_f32 v70, v68, v70, s52
	v_fma_f32 v71, v69, v71, s52
	s_nop 0
	v_fma_f32 v70, v68, v70, s54
	v_fma_f32 v71, v69, v71, s54
	s_nop 0
	v_fma_f32 v70, v68, v70, s56
	v_fma_f32 v71, v69, v71, s56
	s_nop 0
	v_mul_f32 v68, v68, v70
	v_mul_f32 v69, v69, v71
	v_mul_f32 v70, v64, v64
	v_mul_f32 v71, v65, v65
	v_mul_f32 v68, v72, v68
	v_mul_f32 v69, v73, v69
	s_nop 0
	v_mul_f32 v72, v62, v68
	v_mul_f32 v73, v63, v69
	v_fma_f32 v68, -v62, v68, v62
	v_fma_f32 v69, -v63, v69, v63
	v_and_b32_e32 v62, 0x7fffffff, v64
	v_cndmask_b32_e32 v72, v68, v72, vcc
	v_cmp_gt_f32_e32 vcc, 0, v63
	v_and_b32_e32 v63, 0x7fffffff, v65
	v_fma_f32 v62, v62, s28, 1.0
	v_fma_f32 v63, v63, s28, 1.0
	v_cndmask_b32_e32 v73, v69, v73, vcc
	v_rcp_f32_e32 v62, v62
	v_rcp_f32_e32 v63, v63
	v_cmp_gt_f32_e32 vcc, 0, v64
	v_fma_f32 v68, v62, s30, v122
	v_fma_f32 v69, v63, s30, v122
	s_nop 0
; #define GAS __attribute__((address_space(1)))
; __device__ __forceinline__ f32x2 gelu_pk(f32x2 v) {
;     const f32x2 av = __builtin_elementwise_abs(v), d = av * 0.2316418882f + 1.0f;
;     f32x2 t; t.x = __builtin_amdgcn_rcpf(d.x); t.y = __builtin_amdgcn_rcpf(d.y);
;     f32x2 q = t * 0.5307027145f + (-0.7265760135f); q = q * t + 0.7107068705f; q = q * t + (-0.142248368f); q = q * t + 0.127414796f; q = q * t;
;     const f32x2 s = (v * v) * (-0.72134752044f);
;     f32x2 e; e.x = __builtin_amdgcn_exp2f(s.x); e.y = __builtin_amdgcn_exp2f(s.y);
;     const f32x2 m = v * (q * e), r = v - m;
;     f32x2 o; o.x = v.x < 0.f ? m.x : r.x; o.y = v.y < 0.f ? m.y : r.y; return o;
; }
;     __device__ __forceinline__ void operator()(const f32x4 (&acc)[2][2][4][2], const Unit& u, int wr, int wc, int fr, int fq, const float (&pre)[8]) const {
;     ...
;         for (int ai = 0; ai < 2; ++ai)
; #pragma unroll
;             for (int m = 0; m < 4; ++m) {
;                 const int row = row0 + ai * 128 + m * 16; bf16_t* rowp = O + (size_t)row * ldc + col0; float rs = 0.f;
;                 float rsc = 1.f; if (RS == 1) rsc = pre[ai * 4 + m];
; #pragma unroll
;                 for (int bj = 0; bj < 2; ++bj) {
;                     f32x4 v0 = acc[ai][bj][m][0], v1 = acc[ai][bj][m][1];
;                     if (RS == 1) { v0 = v0 * rsc; v1 = v1 * rsc; }
;                     if (RS == 2) { v0 = v0 * csc[bj][0]; v1 = v1 * csc[bj][1]; }
;                     if (ACT == 1) { const f32x2 a = gelu_pk((f32x2){v0[0], v0[1]}), b = gelu_pk((f32x2){v0[2], v0[3]}), c = gelu_pk((f32x2){v1[0], v1[1]}), d = gelu_pk((f32x2){v1[2], v1[3]});
;                         v0 = (f32x4){a.x, a.y, b.x, b.y}; v1 = (f32x4){c.x, c.y, d.x, d.y}; }
;                     v0 = v0 * sc; v1 = v1 * sc;
;                     if (STAT == 1) rs += (v0[0] * v0[0] + v0[1] * v0[1]) + (v0[2] * v0[2] + v0[3] * v0[3]) + (v1[0] * v1[0] + v1[1] * v1[1]) + (v1[2] * v1[2] + v1[3] * v1[3]);
;                     if (STAT == 2) {
; #pragma unroll
;                         for (int e = 0; e < 4; ++e) { cs[bj][0][e] += v0[e]; cq[bj][0][e] += v0[e] * v0[e]; cs[bj][1][e] += v1[e]; cq[bj][1][e] += v1[e] * v1[e]; } }
;                     u32x4 w; w.x = cvt_pk_bf16(v0[0], v0[1]); w.y = cvt_pk_bf16(v0[2], v0[3]); w.z = cvt_pk_bf16(v1[0], v1[1]); w.w = cvt_pk_bf16(v1[2], v1[3]);
;                     *(GAS u32x4*)(rowp + bj * 128) = w; }
	v_fma_f32 v68, v62, v68, s52
	v_fma_f32 v69, v63, v69, s52
	s_nop 0
	v_fma_f32 v68, v62, v68, s54
	v_fma_f32 v69, v63, v69, s54
	s_nop 0
	v_fma_f32 v68, v62, v68, s56
	v_fma_f32 v69, v63, v69, s56
	s_nop 0
	v_mul_f32 v62, v62, v68
	v_mul_f32 v63, v63, v69
	v_mul_f32 v68, v70, s58
	v_mul_f32 v69, v71, s58
	s_nop 0
	v_exp_f32_e32 v68, v68
	v_exp_f32_e32 v69, v69
	s_nop 0
	v_mul_f32 v62, v68, v62
	v_mul_f32 v63, v69, v63
	s_nop 0
	v_mul_f32 v68, v64, v62
	v_mul_f32 v69, v65, v63
	v_fma_f32 v62, -v64, v62, v64
	v_fma_f32 v63, -v65, v63, v65
	s_nop 0
	v_cndmask_b32_e32 v70, v62, v68, vcc
	v_cmp_gt_f32_e32 vcc, 0, v65
	v_and_b32_e32 v62, 0x7fffffff, v58
	s_nop 0
	v_cndmask_b32_e32 v71, v63, v69, vcc
	v_and_b32_e32 v63, 0x7fffffff, v59
	v_fma_f32 v62, v62, s28, 1.0
	v_fma_f32 v63, v63, s28, 1.0
	v_mul_f32 v68, v58, v58
	v_mul_f32 v69, v59, v59
	v_rcp_f32_e32 v62, v62
	v_rcp_f32_e32 v63, v63
	v_mul_f32 v68, v68, s58
	v_mul_f32 v69, v69, s58
	v_cmp_gt_f32_e32 vcc, 0, v58
	v_exp_f32_e32 v68, v68
	v_fma_f32 v64, v62, s30, v122
	v_fma_f32 v65, v63, s30, v122
	v_exp_f32_e32 v69, v69
	v_fma_f32 v64, v62, v64, s52
	v_fma_f32 v65, v63, v65, s52
	s_nop 0
	v_fma_f32 v64, v62, v64, s54
	v_fma_f32 v65, v63, v65, s54
	s_nop 0
	v_fma_f32 v64, v62, v64, s56
	v_fma_f32 v65, v63, v65, s56
	s_nop 0
	v_mul_f32 v62, v62, v64
	v_mul_f32 v63, v63, v65
	v_mul_f32 v64, v60, v60
	v_mul_f32 v65, v61, v61
	v_mul_f32 v62, v68, v62
	v_mul_f32 v63, v69, v63
	s_nop 0
	v_mul_f32 v68, v58, v62
	v_mul_f32 v69, v59, v63
	v_fma_f32 v62, -v58, v62, v58
	v_fma_f32 v63, -v59, v63, v59
	v_and_b32_e32 v58, 0x7fffffff, v60
	v_cndmask_b32_e32 v68, v62, v68, vcc
	v_cmp_gt_f32_e32 vcc, 0, v59
	v_and_b32_e32 v59, 0x7fffffff, v61
	v_fma_f32 v58, v58, s28, 1.0
	v_fma_f32 v59, v59, s28, 1.0
	v_cndmask_b32_e32 v69, v63, v69, vcc
	v_rcp_f32_e32 v58, v58
	v_rcp_f32_e32 v59, v59
	v_cmp_gt_f32_e32 vcc, 0, v60
	v_fma_f32 v62, v58, s30, v122
	v_fma_f32 v63, v59, s30, v122
	s_nop 0
	v_fma_f32 v62, v58, v62, s52
	v_fma_f32 v63, v59, v63, s52
	s_nop 0
	v_fma_f32 v62, v58, v62, s54
	v_fma_f32 v63, v59, v63, s54
	s_nop 0
	v_fma_f32 v62, v58, v62, s56
	v_fma_f32 v63, v59, v63, s56
	s_nop 0
	v_mul_f32 v58, v58, v62
	v_mul_f32 v59, v59, v63
	v_mul_f32 v62, v64, s58
	v_mul_f32 v63, v65, s58
	s_nop 0
	v_exp_f32_e32 v62, v62
	v_exp_f32_e32 v63, v63
	s_nop 0
	v_mul_f32 v58, v62, v58
	v_mul_f32 v59, v63, v59
	s_nop 0
	v_mul_f32 v62, v60, v58
	v_mul_f32 v63, v61, v59
	v_fma_f32 v58, -v60, v58, v60
	v_fma_f32 v59, -v61, v59, v61
	s_nop 0
	v_cndmask_b32_e32 v62, v58, v62, vcc
	v_cmp_gt_f32_e32 vcc, 0, v61
	v_cvt_pk_bf16_f32 v58, v72, v73
	s_nop 1
	v_cndmask_b32_e32 v61, v59, v63, vcc
	v_cvt_pk_bf16_f32 v59, v70, v71
	v_cvt_pk_bf16_f32 v60, v68, v69
	v_cvt_pk_bf16_f32 v61, v62, v61
	v_add_co_u32_e32 v62, vcc, s4, v150
	s_mov_b64 s[4:5], 0x48000
	s_nop 0
	v_addc_co_u32_e32 v63, vcc, 0, v151, vcc
	global_store_dwordx4 v[62:63], v[58:61], off
	v_mul_f32 v62, v54, v54
	v_mul_f32 v63, v55, v55
	v_cmp_gt_f32_e32 vcc, 0, v54
	v_and_b32_e32 v59, 0x7fffffff, v55
	v_and_b32_e32 v58, 0x7fffffff, v54
	v_fma_f32 v58, v58, s28, 1.0
	v_fma_f32 v59, v59, s28, 1.0
	v_mul_f32 v62, v62, s58
	v_mul_f32 v63, v63, s58
	v_rcp_f32_e32 v58, v58
	v_rcp_f32_e32 v59, v59
	v_exp_f32_e32 v62, v62
	v_exp_f32_e32 v63, v63
	v_fma_f32 v60, v58, s30, v122
	v_fma_f32 v61, v59, s30, v122
	s_nop 0
	v_fma_f32 v60, v58, v60, s52
	v_fma_f32 v61, v59, v61, s52
	s_nop 0
	v_fma_f32 v60, v58, v60, s54
	v_fma_f32 v61, v59, v61, s54
	s_nop 0
	v_fma_f32 v60, v58, v60, s56
	v_fma_f32 v61, v59, v61, s56
	s_nop 0
	v_mul_f32 v58, v58, v60
	v_mul_f32 v59, v59, v61
	v_mul_f32 v60, v56, v56
	v_mul_f32 v61, v57, v57
	v_mul_f32 v58, v62, v58
	v_mul_f32 v59, v63, v59
	s_nop 0
	v_mul_f32 v62, v54, v58
	v_mul_f32 v63, v55, v59
	v_fma_f32 v58, -v54, v58, v54
	v_fma_f32 v59, -v55, v59, v55
	v_and_b32_e32 v54, 0x7fffffff, v56
	v_cndmask_b32_e32 v62, v58, v62, vcc
	v_cmp_gt_f32_e32 vcc, 0, v55
	v_and_b32_e32 v55, 0x7fffffff, v57
	v_fma_f32 v54, v54, s28, 1.0
	v_fma_f32 v55, v55, s28, 1.0
	v_cndmask_b32_e32 v63, v59, v63, vcc
	v_rcp_f32_e32 v54, v54
	v_rcp_f32_e32 v55, v55
	v_cmp_gt_f32_e32 vcc, 0, v56
	v_fma_f32 v58, v54, s30, v122
	v_fma_f32 v59, v55, s30, v122
	s_nop 0
	v_fma_f32 v58, v54, v58, s52
	v_fma_f32 v59, v55, v59, s52
	s_nop 0
	v_fma_f32 v58, v54, v58, s54
	v_fma_f32 v59, v55, v59, s54
	s_nop 0
	v_fma_f32 v58, v54, v58, s56
	v_fma_f32 v59, v55, v59, s56
	s_nop 0
	v_mul_f32 v54, v54, v58
	v_mul_f32 v55, v55, v59
	v_mul_f32 v58, v60, s58
	v_mul_f32 v59, v61, s58
	s_nop 0
	v_exp_f32_e32 v58, v58
	v_exp_f32_e32 v59, v59
	s_nop 0
	v_mul_f32 v54, v58, v54
	v_mul_f32 v55, v59, v55
	s_nop 0
	v_mul_f32 v58, v56, v54
	v_mul_f32 v59, v57, v55
	v_fma_f32 v54, -v56, v54, v56
	v_fma_f32 v55, -v57, v55, v57
	s_nop 0
	v_cndmask_b32_e32 v60, v54, v58, vcc
	v_cmp_gt_f32_e32 vcc, 0, v57
	v_and_b32_e32 v54, 0x7fffffff, v50
	s_nop 0
	v_cndmask_b32_e32 v61, v55, v59, vcc
	v_and_b32_e32 v55, 0x7fffffff, v51
	v_fma_f32 v54, v54, s28, 1.0
	v_fma_f32 v55, v55, s28, 1.0
	v_mul_f32 v58, v50, v50
	v_mul_f32 v59, v51, v51
	v_rcp_f32_e32 v54, v54
	v_rcp_f32_e32 v55, v55
	v_mul_f32 v58, v58, s58
	v_mul_f32 v59, v59, s58
	v_cmp_gt_f32_e32 vcc, 0, v50
	v_exp_f32_e32 v58, v58
	v_fma_f32 v56, v54, s30, v122
	v_fma_f32 v57, v55, s30, v122
	v_exp_f32_e32 v59, v59
	v_fma_f32 v56, v54, v56, s52
	v_fma_f32 v57, v55, v57, s52
	s_nop 0
	v_fma_f32 v56, v54, v56, s54
	v_fma_f32 v57, v55, v57, s54
	s_nop 0
	v_fma_f32 v56, v54, v56, s56
	v_fma_f32 v57, v55, v57, s56
	s_nop 0
	v_mul_f32 v54, v54, v56
	v_mul_f32 v55, v55, v57
	v_mul_f32 v56, v52, v52
	v_mul_f32 v57, v53, v53
	v_mul_f32 v54, v58, v54
; #define GAS __attribute__((address_space(1)))
; __device__ __forceinline__ f32x2 gelu_pk(f32x2 v) {
;     const f32x2 av = __builtin_elementwise_abs(v), d = av * 0.2316418882f + 1.0f;
;     f32x2 t; t.x = __builtin_amdgcn_rcpf(d.x); t.y = __builtin_amdgcn_rcpf(d.y);
;     f32x2 q = t * 0.5307027145f + (-0.7265760135f); q = q * t + 0.7107068705f; q = q * t + (-0.142248368f); q = q * t + 0.127414796f; q = q * t;
;     const f32x2 s = (v * v) * (-0.72134752044f);
;     f32x2 e; e.x = __builtin_amdgcn_exp2f(s.x); e.y = __builtin_amdgcn_exp2f(s.y);
;     const f32x2 m = v * (q * e), r = v - m;
;     f32x2 o; o.x = v.x < 0.f ? m.x : r.x; o.y = v.y < 0.f ? m.y : r.y; return o;
; }
;     __device__ __forceinline__ void operator()(const f32x4 (&acc)[2][2][4][2], const Unit& u, int wr, int wc, int fr, int fq, const float (&pre)[8]) const {
;     ...
;         for (int ai = 0; ai < 2; ++ai)
; #pragma unroll
;             for (int m = 0; m < 4; ++m) {
;                 const int row = row0 + ai * 128 + m * 16; bf16_t* rowp = O + (size_t)row * ldc + col0; float rs = 0.f;
;                 float rsc = 1.f; if (RS == 1) rsc = pre[ai * 4 + m];
; #pragma unroll
;                 for (int bj = 0; bj < 2; ++bj) {
;                     f32x4 v0 = acc[ai][bj][m][0], v1 = acc[ai][bj][m][1];
;                     if (RS == 1) { v0 = v0 * rsc; v1 = v1 * rsc; }
;                     if (RS == 2) { v0 = v0 * csc[bj][0]; v1 = v1 * csc[bj][1]; }
;                     if (ACT == 1) { const f32x2 a = gelu_pk((f32x2){v0[0], v0[1]}), b = gelu_pk((f32x2){v0[2], v0[3]}), c = gelu_pk((f32x2){v1[0], v1[1]}), d = gelu_pk((f32x2){v1[2], v1[3]});
;                         v0 = (f32x4){a.x, a.y, b.x, b.y}; v1 = (f32x4){c.x, c.y, d.x, d.y}; }
;                     v0 = v0 * sc; v1 = v1 * sc;
;                     if (STAT == 1) rs += (v0[0] * v0[0] + v0[1] * v0[1]) + (v0[2] * v0[2] + v0[3] * v0[3]) + (v1[0] * v1[0] + v1[1] * v1[1]) + (v1[2] * v1[2] + v1[3] * v1[3]);
;                     if (STAT == 2) {
; #pragma unroll
;                         for (int e = 0; e < 4; ++e) { cs[bj][0][e] += v0[e]; cq[bj][0][e] += v0[e] * v0[e]; cs[bj][1][e] += v1[e]; cq[bj][1][e] += v1[e] * v1[e]; } }
;                     u32x4 w; w.x = cvt_pk_bf16(v0[0], v0[1]); w.y = cvt_pk_bf16(v0[2], v0[3]); w.z = cvt_pk_bf16(v1[0], v1[1]); w.w = cvt_pk_bf16(v1[2], v1[3]);
;                     *(GAS u32x4*)(rowp + bj * 128) = w; }
	v_mul_f32 v55, v59, v55
	s_nop 0
	v_mul_f32 v58, v50, v54
	v_mul_f32 v59, v51, v55
	v_fma_f32 v54, -v50, v54, v50
	v_fma_f32 v55, -v51, v55, v51
	v_and_b32_e32 v50, 0x7fffffff, v52
	v_cndmask_b32_e32 v58, v54, v58, vcc
	v_cmp_gt_f32_e32 vcc, 0, v51
	v_and_b32_e32 v51, 0x7fffffff, v53
	v_fma_f32 v50, v50, s28, 1.0
	v_fma_f32 v51, v51, s28, 1.0
	v_cndmask_b32_e32 v59, v55, v59, vcc
	v_rcp_f32_e32 v50, v50
	v_rcp_f32_e32 v51, v51
	v_cmp_gt_f32_e32 vcc, 0, v52
	v_fma_f32 v54, v50, s30, v122
	v_fma_f32 v55, v51, s30, v122
	s_nop 0
	v_fma_f32 v54, v50, v54, s52
	v_fma_f32 v55, v51, v55, s52
	s_nop 0
	v_fma_f32 v54, v50, v54, s54
	v_fma_f32 v55, v51, v55, s54
	s_nop 0
	v_fma_f32 v54, v50, v54, s56
	v_fma_f32 v55, v51, v55, s56
	s_nop 0
	v_mul_f32 v50, v50, v54
	v_mul_f32 v51, v51, v55
	v_mul_f32 v54, v56, s58
	v_mul_f32 v55, v57, s58
	v_mul_f32 v56, v46, v46
	v_mul_f32 v57, v47, v47
	v_exp_f32_e32 v54, v54
	v_exp_f32_e32 v55, v55
	v_mul_f32 v56, v56, s58
	v_mul_f32 v57, v57, s58
	v_mul_f32 v50, v54, v50
	v_mul_f32 v51, v55, v51
	s_nop 0
	v_mul_f32 v54, v52, v50
	v_mul_f32 v55, v53, v51
	v_fma_f32 v50, -v52, v50, v52
	v_fma_f32 v51, -v53, v51, v53
	v_exp_f32_e32 v56, v56
	v_cndmask_b32_e32 v54, v50, v54, vcc
	v_cmp_gt_f32_e32 vcc, 0, v53
	v_cvt_pk_bf16_f32 v50, v62, v63
	v_exp_f32_e32 v57, v57
	s_nop 0
	v_cndmask_b32_e32 v53, v51, v55, vcc
	v_cvt_pk_bf16_f32 v51, v60, v61
	v_cvt_pk_bf16_f32 v52, v58, v59
	v_cvt_pk_bf16_f32 v53, v54, v53
	global_store_dwordx4 v[66:67], v[50:53], off offset:256
	v_cmp_gt_f32_e32 vcc, 0, v46
	s_nop 0
	v_and_b32_e32 v53, 0x7fffffff, v47
	v_and_b32_e32 v52, 0x7fffffff, v46
	v_fma_f32 v52, v52, s28, 1.0
	v_fma_f32 v53, v53, s28, 1.0
	v_lshl_add_u64 v[50:51], v[150:151], 0, s[4:5]
	v_rcp_f32_e32 v52, v52
	v_rcp_f32_e32 v53, v53
	s_mov_b32 s4, 0x48000
	v_fma_f32 v54, v52, s30, v122
	v_fma_f32 v55, v53, s30, v122
	s_nop 0
	v_fma_f32 v54, v52, v54, s52
	v_fma_f32 v55, v53, v55, s52
	s_nop 0
	v_fma_f32 v54, v52, v54, s54
	v_fma_f32 v55, v53, v55, s54
	s_nop 0
	v_fma_f32 v54, v52, v54, s56
	v_fma_f32 v55, v53, v55, s56
	s_nop 0
	v_mul_f32 v52, v52, v54
	v_mul_f32 v53, v53, v55
	v_mul_f32 v54, v48, v48
	v_mul_f32 v55, v49, v49
	v_mul_f32 v52, v56, v52
	v_mul_f32 v53, v57, v53
	s_nop 0
	v_mul_f32 v56, v46, v52
	v_mul_f32 v57, v47, v53
	v_fma_f32 v52, -v46, v52, v46
	v_fma_f32 v53, -v47, v53, v47
	v_and_b32_e32 v46, 0x7fffffff, v48
	v_cndmask_b32_e32 v56, v52, v56, vcc
	v_cmp_gt_f32_e32 vcc, 0, v47
	v_and_b32_e32 v47, 0x7fffffff, v49
	v_fma_f32 v46, v46, s28, 1.0
	v_fma_f32 v47, v47, s28, 1.0
	v_cndmask_b32_e32 v57, v53, v57, vcc
	v_rcp_f32_e32 v46, v46
	v_rcp_f32_e32 v47, v47
	v_cmp_gt_f32_e32 vcc, 0, v48
	v_fma_f32 v52, v46, s30, v122
	v_fma_f32 v53, v47, s30, v122
	s_nop 0
	v_fma_f32 v52, v46, v52, s52
	v_fma_f32 v53, v47, v53, s52
	s_nop 0
	v_fma_f32 v52, v46, v52, s54
	v_fma_f32 v53, v47, v53, s54
	s_nop 0
	v_fma_f32 v52, v46, v52, s56
	v_fma_f32 v53, v47, v53, s56
	s_nop 0
	v_mul_f32 v46, v46, v52
	v_mul_f32 v47, v47, v53
	v_mul_f32 v52, v54, s58
	v_mul_f32 v53, v55, s58
	s_nop 0
	v_exp_f32_e32 v52, v52
	v_exp_f32_e32 v53, v53
	s_nop 0
	v_mul_f32 v46, v52, v46
	v_mul_f32 v47, v53, v47
	s_nop 0
	v_mul_f32 v52, v48, v46
	v_mul_f32 v53, v49, v47
	v_fma_f32 v46, -v48, v46, v48
	v_fma_f32 v47, -v49, v47, v49
	s_nop 0
	v_cndmask_b32_e32 v54, v46, v52, vcc
	v_cmp_gt_f32_e32 vcc, 0, v49
	v_and_b32_e32 v46, 0x7fffffff, v42
	s_nop 0
	v_cndmask_b32_e32 v55, v47, v53, vcc
	v_and_b32_e32 v47, 0x7fffffff, v43
	v_fma_f32 v46, v46, s28, 1.0
	v_fma_f32 v47, v47, s28, 1.0
	v_mul_f32 v52, v42, v42
	v_mul_f32 v53, v43, v43
	v_rcp_f32_e32 v46, v46
	v_rcp_f32_e32 v47, v47
	v_mul_f32 v52, v52, s58
	v_mul_f32 v53, v53, s58
	v_cmp_gt_f32_e32 vcc, 0, v42
	v_exp_f32_e32 v52, v52
	v_fma_f32 v48, v46, s30, v122
	v_fma_f32 v49, v47, s30, v122
	v_exp_f32_e32 v53, v53
	v_fma_f32 v48, v46, v48, s52
	v_fma_f32 v49, v47, v49, s52
	s_nop 0
	v_fma_f32 v48, v46, v48, s54
	v_fma_f32 v49, v47, v49, s54
	s_nop 0
	v_fma_f32 v48, v46, v48, s56
	v_fma_f32 v49, v47, v49, s56
	s_nop 0
	v_mul_f32 v46, v46, v48
	v_mul_f32 v47, v47, v49
	v_mul_f32 v48, v44, v44
	v_mul_f32 v49, v45, v45
	v_mul_f32 v46, v52, v46
	v_mul_f32 v47, v53, v47
	s_nop 0
	v_mul_f32 v52, v42, v46
	v_mul_f32 v53, v43, v47
	v_fma_f32 v46, -v42, v46, v42
	v_fma_f32 v47, -v43, v47, v43
	v_and_b32_e32 v42, 0x7fffffff, v44
	v_cndmask_b32_e32 v52, v46, v52, vcc
	v_cmp_gt_f32_e32 vcc, 0, v43
	v_and_b32_e32 v43, 0x7fffffff, v45
	v_fma_f32 v42, v42, s28, 1.0
	v_fma_f32 v43, v43, s28, 1.0
	v_cndmask_b32_e32 v53, v47, v53, vcc
	v_rcp_f32_e32 v42, v42
	v_rcp_f32_e32 v43, v43
	v_cmp_gt_f32_e32 vcc, 0, v44
	v_fma_f32 v46, v42, s30, v122
	v_fma_f32 v47, v43, s30, v122
	s_nop 0
	v_fma_f32 v46, v42, v46, s52
	v_fma_f32 v47, v43, v47, s52
	s_nop 0
	v_fma_f32 v46, v42, v46, s54
	v_fma_f32 v47, v43, v47, s54
	s_nop 0
	v_fma_f32 v46, v42, v46, s56
	v_fma_f32 v47, v43, v47, s56
	s_nop 0
	v_mul_f32 v42, v42, v46
	v_mul_f32 v43, v43, v47
	v_mul_f32 v46, v48, s58
	v_mul_f32 v47, v49, s58
	s_nop 0
	v_exp_f32_e32 v46, v46
	v_exp_f32_e32 v47, v47
	s_nop 0
	v_mul_f32 v42, v46, v42
	v_mul_f32 v43, v47, v43
	s_nop 0
	v_mul_f32 v46, v44, v42
	v_mul_f32 v47, v45, v43
	v_fma_f32 v42, -v44, v42, v44
	v_fma_f32 v43, -v45, v43, v45
	s_nop 0
	v_cndmask_b32_e32 v46, v42, v46, vcc
	v_cmp_gt_f32_e32 vcc, 0, v45
	v_cvt_pk_bf16_f32 v42, v56, v57
	s_nop 1
	v_cndmask_b32_e32 v45, v43, v47, vcc
	v_cvt_pk_bf16_f32 v43, v54, v55
	v_cvt_pk_bf16_f32 v44, v52, v53
	v_cvt_pk_bf16_f32 v45, v46, v45
	v_add_co_u32_e32 v46, vcc, s4, v150
	s_mov_b64 s[4:5], 0x50000
	s_nop 0
	v_addc_co_u32_e32 v47, vcc, 0, v151, vcc
	global_store_dwordx4 v[46:47], v[42:45], off
; #define GAS __attribute__((address_space(1)))
; __device__ __forceinline__ f32x2 gelu_pk(f32x2 v) {
;     const f32x2 av = __builtin_elementwise_abs(v), d = av * 0.2316418882f + 1.0f;
;     f32x2 t; t.x = __builtin_amdgcn_rcpf(d.x); t.y = __builtin_amdgcn_rcpf(d.y);
;     f32x2 q = t * 0.5307027145f + (-0.7265760135f); q = q * t + 0.7107068705f; q = q * t + (-0.142248368f); q = q * t + 0.127414796f; q = q * t;
;     const f32x2 s = (v * v) * (-0.72134752044f);
;     f32x2 e; e.x = __builtin_amdgcn_exp2f(s.x); e.y = __builtin_amdgcn_exp2f(s.y);
;     const f32x2 m = v * (q * e), r = v - m;
;     f32x2 o; o.x = v.x < 0.f ? m.x : r.x; o.y = v.y < 0.f ? m.y : r.y; return o;
; }
;     __device__ __forceinline__ void operator()(const f32x4 (&acc)[2][2][4][2], const Unit& u, int wr, int wc, int fr, int fq, const float (&pre)[8]) const {
;     ...
;         for (int ai = 0; ai < 2; ++ai)
; #pragma unroll
;             for (int m = 0; m < 4; ++m) {
;                 const int row = row0 + ai * 128 + m * 16; bf16_t* rowp = O + (size_t)row * ldc + col0; float rs = 0.f;
;                 float rsc = 1.f; if (RS == 1) rsc = pre[ai * 4 + m];
; #pragma unroll
;                 for (int bj = 0; bj < 2; ++bj) {
;                     f32x4 v0 = acc[ai][bj][m][0], v1 = acc[ai][bj][m][1];
;                     if (RS == 1) { v0 = v0 * rsc; v1 = v1 * rsc; }
;                     if (RS == 2) { v0 = v0 * csc[bj][0]; v1 = v1 * csc[bj][1]; }
;                     if (ACT == 1) { const f32x2 a = gelu_pk((f32x2){v0[0], v0[1]}), b = gelu_pk((f32x2){v0[2], v0[3]}), c = gelu_pk((f32x2){v1[0], v1[1]}), d = gelu_pk((f32x2){v1[2], v1[3]});
;                         v0 = (f32x4){a.x, a.y, b.x, b.y}; v1 = (f32x4){c.x, c.y, d.x, d.y}; }
;                     v0 = v0 * sc; v1 = v1 * sc;
;                     if (STAT == 1) rs += (v0[0] * v0[0] + v0[1] * v0[1]) + (v0[2] * v0[2] + v0[3] * v0[3]) + (v1[0] * v1[0] + v1[1] * v1[1]) + (v1[2] * v1[2] + v1[3] * v1[3]);
;                     if (STAT == 2) {
; #pragma unroll
;                         for (int e = 0; e < 4; ++e) { cs[bj][0][e] += v0[e]; cq[bj][0][e] += v0[e] * v0[e]; cs[bj][1][e] += v1[e]; cq[bj][1][e] += v1[e] * v1[e]; } }
;                     u32x4 w; w.x = cvt_pk_bf16(v0[0], v0[1]); w.y = cvt_pk_bf16(v0[2], v0[3]); w.z = cvt_pk_bf16(v1[0], v1[1]); w.w = cvt_pk_bf16(v1[2], v1[3]);
;                     *(GAS u32x4*)(rowp + bj * 128) = w; }
	v_mul_f32 v46, v38, v38
	v_mul_f32 v47, v39, v39
	v_cmp_gt_f32_e32 vcc, 0, v38
	v_and_b32_e32 v43, 0x7fffffff, v39
	v_and_b32_e32 v42, 0x7fffffff, v38
	v_fma_f32 v42, v42, s28, 1.0
	v_fma_f32 v43, v43, s28, 1.0
	v_mul_f32 v46, v46, s58
	v_mul_f32 v47, v47, s58
	v_rcp_f32_e32 v42, v42
	v_rcp_f32_e32 v43, v43
	v_exp_f32_e32 v46, v46
	v_exp_f32_e32 v47, v47
	v_fma_f32 v44, v42, s30, v122
	v_fma_f32 v45, v43, s30, v122
	s_nop 0
	v_fma_f32 v44, v42, v44, s52
	v_fma_f32 v45, v43, v45, s52
	s_nop 0
	v_fma_f32 v44, v42, v44, s54
	v_fma_f32 v45, v43, v45, s54
	s_nop 0
	v_fma_f32 v44, v42, v44, s56
	v_fma_f32 v45, v43, v45, s56
	s_nop 0
	v_mul_f32 v42, v42, v44
	v_mul_f32 v43, v43, v45
	v_mul_f32 v44, v40, v40
	v_mul_f32 v45, v41, v41
	v_mul_f32 v42, v46, v42
	v_mul_f32 v43, v47, v43
	s_nop 0
	v_mul_f32 v46, v38, v42
	v_mul_f32 v47, v39, v43
	v_fma_f32 v42, -v38, v42, v38
	v_fma_f32 v43, -v39, v43, v39
	v_and_b32_e32 v38, 0x7fffffff, v40
	v_cndmask_b32_e32 v46, v42, v46, vcc
	v_cmp_gt_f32_e32 vcc, 0, v39
	v_and_b32_e32 v39, 0x7fffffff, v41
	v_fma_f32 v38, v38, s28, 1.0
	v_fma_f32 v39, v39, s28, 1.0
	v_cndmask_b32_e32 v47, v43, v47, vcc
	v_rcp_f32_e32 v38, v38
	v_rcp_f32_e32 v39, v39
	v_cmp_gt_f32_e32 vcc, 0, v40
	v_fma_f32 v42, v38, s30, v122
	v_fma_f32 v43, v39, s30, v122
	s_nop 0
	v_fma_f32 v42, v38, v42, s52
	v_fma_f32 v43, v39, v43, s52
	s_nop 0
	v_fma_f32 v42, v38, v42, s54
	v_fma_f32 v43, v39, v43, s54
	s_nop 0
	v_fma_f32 v42, v38, v42, s56
	v_fma_f32 v43, v39, v43, s56
	s_nop 0
	v_mul_f32 v38, v38, v42
	v_mul_f32 v39, v39, v43
	v_mul_f32 v42, v44, s58
	v_mul_f32 v43, v45, s58
	s_nop 0
	v_exp_f32_e32 v42, v42
	v_exp_f32_e32 v43, v43
	s_nop 0
	v_mul_f32 v38, v42, v38
	v_mul_f32 v39, v43, v39
	s_nop 0
	v_mul_f32 v42, v40, v38
	v_mul_f32 v43, v41, v39
	v_fma_f32 v38, -v40, v38, v40
	v_fma_f32 v39, -v41, v39, v41
	s_nop 0
	v_cndmask_b32_e32 v44, v38, v42, vcc
	v_cmp_gt_f32_e32 vcc, 0, v41
	v_and_b32_e32 v38, 0x7fffffff, v34
	s_nop 0
	v_cndmask_b32_e32 v45, v39, v43, vcc
	v_and_b32_e32 v39, 0x7fffffff, v35
	v_fma_f32 v38, v38, s28, 1.0
	v_fma_f32 v39, v39, s28, 1.0
	v_mul_f32 v42, v34, v34
	v_mul_f32 v43, v35, v35
	v_rcp_f32_e32 v38, v38
	v_rcp_f32_e32 v39, v39
	v_mul_f32 v42, v42, s58
	v_mul_f32 v43, v43, s58
	v_cmp_gt_f32_e32 vcc, 0, v34
	v_exp_f32_e32 v42, v42
	v_fma_f32 v40, v38, s30, v122
	v_fma_f32 v41, v39, s30, v122
	v_exp_f32_e32 v43, v43
	v_fma_f32 v40, v38, v40, s52
	v_fma_f32 v41, v39, v41, s52
	s_nop 0
	v_fma_f32 v40, v38, v40, s54
	v_fma_f32 v41, v39, v41, s54
	s_nop 0
	v_fma_f32 v40, v38, v40, s56
	v_fma_f32 v41, v39, v41, s56
	s_nop 0
	v_mul_f32 v38, v38, v40
	v_mul_f32 v39, v39, v41
	v_mul_f32 v40, v36, v36
	v_mul_f32 v41, v37, v37
	v_mul_f32 v38, v42, v38
	v_mul_f32 v39, v43, v39
	s_nop 0
	v_mul_f32 v42, v34, v38
	v_mul_f32 v43, v35, v39
	v_fma_f32 v38, -v34, v38, v34
	v_fma_f32 v39, -v35, v39, v35
	v_and_b32_e32 v34, 0x7fffffff, v36
	v_cndmask_b32_e32 v42, v38, v42, vcc
	v_cmp_gt_f32_e32 vcc, 0, v35
	v_and_b32_e32 v35, 0x7fffffff, v37
	v_fma_f32 v34, v34, s28, 1.0
	v_fma_f32 v35, v35, s28, 1.0
	v_cndmask_b32_e32 v43, v39, v43, vcc
	v_rcp_f32_e32 v34, v34
	v_rcp_f32_e32 v35, v35
	v_cmp_gt_f32_e32 vcc, 0, v36
	v_fma_f32 v38, v34, s30, v122
	v_fma_f32 v39, v35, s30, v122
	s_nop 0
	v_fma_f32 v38, v34, v38, s52
	v_fma_f32 v39, v35, v39, s52
	s_nop 0
	v_fma_f32 v38, v34, v38, s54
	v_fma_f32 v39, v35, v39, s54
	s_nop 0
	v_fma_f32 v38, v34, v38, s56
	v_fma_f32 v39, v35, v39, s56
	s_nop 0
	v_mul_f32 v34, v34, v38
	v_mul_f32 v35, v35, v39
	v_mul_f32 v38, v40, s58
	v_mul_f32 v39, v41, s58
	v_mul_f32 v40, v28, v28
	v_mul_f32 v41, v29, v29
	v_exp_f32_e32 v38, v38
	v_exp_f32_e32 v39, v39
	v_mul_f32 v40, v40, s58
	v_mul_f32 v41, v41, s58
	v_mul_f32 v34, v38, v34
	v_mul_f32 v35, v39, v35
	s_nop 0
	v_mul_f32 v38, v36, v34
	v_mul_f32 v39, v37, v35
	v_fma_f32 v34, -v36, v34, v36
	v_fma_f32 v35, -v37, v35, v37
	v_exp_f32_e32 v40, v40
	v_cndmask_b32_e32 v38, v34, v38, vcc
	v_cmp_gt_f32_e32 vcc, 0, v37
	v_cvt_pk_bf16_f32 v34, v46, v47
	v_exp_f32_e32 v41, v41
	s_nop 0
	v_cndmask_b32_e32 v37, v35, v39, vcc
	v_cvt_pk_bf16_f32 v35, v44, v45
	v_cvt_pk_bf16_f32 v36, v42, v43
	v_cvt_pk_bf16_f32 v37, v38, v37
	global_store_dwordx4 v[50:51], v[34:37], off offset:256
	v_cmp_gt_f32_e32 vcc, 0, v28
	s_nop 0
	v_and_b32_e32 v37, 0x7fffffff, v29
	v_and_b32_e32 v36, 0x7fffffff, v28
	v_fma_f32 v36, v36, s28, 1.0
	v_fma_f32 v37, v37, s28, 1.0
	v_lshl_add_u64 v[34:35], v[150:151], 0, s[4:5]
	v_rcp_f32_e32 v36, v36
	v_rcp_f32_e32 v37, v37
	s_mov_b32 s4, 0x50000
	v_fma_f32 v38, v36, s30, v122
	v_fma_f32 v39, v37, s30, v122
	s_nop 0
	v_fma_f32 v38, v36, v38, s52
	v_fma_f32 v39, v37, v39, s52
	s_nop 0
	v_fma_f32 v38, v36, v38, s54
	v_fma_f32 v39, v37, v39, s54
	s_nop 0
	v_fma_f32 v38, v36, v38, s56
	v_fma_f32 v39, v37, v39, s56
	s_nop 0
	v_mul_f32 v36, v36, v38
	v_mul_f32 v37, v37, v39
	v_mul_f32 v38, v30, v30
	v_mul_f32 v39, v31, v31
	v_mul_f32 v36, v40, v36
	v_mul_f32 v37, v41, v37
	s_nop 0
	v_mul_f32 v40, v28, v36
	v_mul_f32 v41, v29, v37
	v_fma_f32 v36, -v28, v36, v28
	v_fma_f32 v37, -v29, v37, v29
	v_and_b32_e32 v28, 0x7fffffff, v30
	v_cndmask_b32_e32 v40, v36, v40, vcc
	v_cmp_gt_f32_e32 vcc, 0, v29
	v_and_b32_e32 v29, 0x7fffffff, v31
	v_fma_f32 v28, v28, s28, 1.0
	v_fma_f32 v29, v29, s28, 1.0
	v_cndmask_b32_e32 v41, v37, v41, vcc
	v_rcp_f32_e32 v28, v28
	v_rcp_f32_e32 v29, v29
	v_cmp_gt_f32_e32 vcc, 0, v30
	v_fma_f32 v36, v28, s30, v122
	v_fma_f32 v37, v29, s30, v122
	s_nop 0
	v_fma_f32 v36, v28, v36, s52
	v_fma_f32 v37, v29, v37, s52
	s_nop 0
	v_fma_f32 v36, v28, v36, s54
	v_fma_f32 v37, v29, v37, s54
	s_nop 0
	v_fma_f32 v36, v28, v36, s56
	v_fma_f32 v37, v29, v37, s56
; #define GAS __attribute__((address_space(1)))
; __device__ __forceinline__ f32x2 gelu_pk(f32x2 v) {
;     const f32x2 av = __builtin_elementwise_abs(v), d = av * 0.2316418882f + 1.0f;
;     f32x2 t; t.x = __builtin_amdgcn_rcpf(d.x); t.y = __builtin_amdgcn_rcpf(d.y);
;     f32x2 q = t * 0.5307027145f + (-0.7265760135f); q = q * t + 0.7107068705f; q = q * t + (-0.142248368f); q = q * t + 0.127414796f; q = q * t;
;     const f32x2 s = (v * v) * (-0.72134752044f);
;     f32x2 e; e.x = __builtin_amdgcn_exp2f(s.x); e.y = __builtin_amdgcn_exp2f(s.y);
;     const f32x2 m = v * (q * e), r = v - m;
;     f32x2 o; o.x = v.x < 0.f ? m.x : r.x; o.y = v.y < 0.f ? m.y : r.y; return o;
; }
;     __device__ __forceinline__ void operator()(const f32x4 (&acc)[2][2][4][2], const Unit& u, int wr, int wc, int fr, int fq, const float (&pre)[8]) const {
;     ...
;         for (int ai = 0; ai < 2; ++ai)
; #pragma unroll
;             for (int m = 0; m < 4; ++m) {
;                 const int row = row0 + ai * 128 + m * 16; bf16_t* rowp = O + (size_t)row * ldc + col0; float rs = 0.f;
;                 float rsc = 1.f; if (RS == 1) rsc = pre[ai * 4 + m];
; #pragma unroll
;                 for (int bj = 0; bj < 2; ++bj) {
;                     f32x4 v0 = acc[ai][bj][m][0], v1 = acc[ai][bj][m][1];
;                     if (RS == 1) { v0 = v0 * rsc; v1 = v1 * rsc; }
;                     if (RS == 2) { v0 = v0 * csc[bj][0]; v1 = v1 * csc[bj][1]; }
;                     if (ACT == 1) { const f32x2 a = gelu_pk((f32x2){v0[0], v0[1]}), b = gelu_pk((f32x2){v0[2], v0[3]}), c = gelu_pk((f32x2){v1[0], v1[1]}), d = gelu_pk((f32x2){v1[2], v1[3]});
;                         v0 = (f32x4){a.x, a.y, b.x, b.y}; v1 = (f32x4){c.x, c.y, d.x, d.y}; }
;                     v0 = v0 * sc; v1 = v1 * sc;
;                     if (STAT == 1) rs += (v0[0] * v0[0] + v0[1] * v0[1]) + (v0[2] * v0[2] + v0[3] * v0[3]) + (v1[0] * v1[0] + v1[1] * v1[1]) + (v1[2] * v1[2] + v1[3] * v1[3]);
;                     if (STAT == 2) {
; #pragma unroll
;                         for (int e = 0; e < 4; ++e) { cs[bj][0][e] += v0[e]; cq[bj][0][e] += v0[e] * v0[e]; cs[bj][1][e] += v1[e]; cq[bj][1][e] += v1[e] * v1[e]; } }
;                     u32x4 w; w.x = cvt_pk_bf16(v0[0], v0[1]); w.y = cvt_pk_bf16(v0[2], v0[3]); w.z = cvt_pk_bf16(v1[0], v1[1]); w.w = cvt_pk_bf16(v1[2], v1[3]);
;                     *(GAS u32x4*)(rowp + bj * 128) = w; }
	s_nop 0
	v_mul_f32 v28, v28, v36
	v_mul_f32 v29, v29, v37
	v_mul_f32 v36, v38, s58
	v_mul_f32 v37, v39, s58
	s_nop 0
	v_exp_f32_e32 v36, v36
	v_exp_f32_e32 v37, v37
	s_nop 0
	v_mul_f32 v28, v36, v28
	v_mul_f32 v29, v37, v29
	s_nop 0
	v_mul_f32 v36, v30, v28
	v_mul_f32 v37, v31, v29
	v_fma_f32 v28, -v30, v28, v30
	v_fma_f32 v29, -v31, v29, v31
	s_nop 0
	v_cndmask_b32_e32 v38, v28, v36, vcc
	v_cmp_gt_f32_e32 vcc, 0, v31
	v_and_b32_e32 v28, 0x7fffffff, v24
	s_nop 0
	v_cndmask_b32_e32 v39, v29, v37, vcc
	v_and_b32_e32 v29, 0x7fffffff, v25
	v_fma_f32 v28, v28, s28, 1.0
	v_fma_f32 v29, v29, s28, 1.0
	v_mul_f32 v36, v24, v24
	v_mul_f32 v37, v25, v25
	v_rcp_f32_e32 v28, v28
	v_rcp_f32_e32 v29, v29
	v_mul_f32 v36, v36, s58
	v_mul_f32 v37, v37, s58
	v_cmp_gt_f32_e32 vcc, 0, v24
	v_exp_f32_e32 v36, v36
	v_fma_f32 v30, v28, s30, v122
	v_fma_f32 v31, v29, s30, v122
	v_exp_f32_e32 v37, v37
	v_fma_f32 v30, v28, v30, s52
	v_fma_f32 v31, v29, v31, s52
	s_nop 0
	v_fma_f32 v30, v28, v30, s54
	v_fma_f32 v31, v29, v31, s54
	s_nop 0
	v_fma_f32 v30, v28, v30, s56
	v_fma_f32 v31, v29, v31, s56
	s_nop 0
	v_mul_f32 v28, v28, v30
	v_mul_f32 v29, v29, v31
	v_mul_f32 v30, v26, v26
	v_mul_f32 v31, v27, v27
	v_mul_f32 v28, v36, v28
	v_mul_f32 v29, v37, v29
	s_nop 0
	v_mul_f32 v36, v24, v28
	v_mul_f32 v37, v25, v29
	v_fma_f32 v28, -v24, v28, v24
	v_fma_f32 v29, -v25, v29, v25
	v_and_b32_e32 v24, 0x7fffffff, v26
	v_cndmask_b32_e32 v36, v28, v36, vcc
	v_cmp_gt_f32_e32 vcc, 0, v25
	v_and_b32_e32 v25, 0x7fffffff, v27
	v_fma_f32 v24, v24, s28, 1.0
	v_fma_f32 v25, v25, s28, 1.0
	v_cndmask_b32_e32 v37, v29, v37, vcc
	v_rcp_f32_e32 v24, v24
	v_rcp_f32_e32 v25, v25
	v_cmp_gt_f32_e32 vcc, 0, v26
	v_fma_f32 v28, v24, s30, v122
	v_fma_f32 v29, v25, s30, v122
	s_nop 0
	v_fma_f32 v28, v24, v28, s52
	v_fma_f32 v29, v25, v29, s52
	s_nop 0
	v_fma_f32 v28, v24, v28, s54
	v_fma_f32 v29, v25, v29, s54
	s_nop 0
	v_fma_f32 v28, v24, v28, s56
	v_fma_f32 v29, v25, v29, s56
	s_nop 0
	v_mul_f32 v24, v24, v28
	v_mul_f32 v25, v25, v29
	v_mul_f32 v28, v30, s58
	v_mul_f32 v29, v31, s58
	s_nop 0
	v_exp_f32_e32 v28, v28
	v_exp_f32_e32 v29, v29
	s_nop 0
	v_mul_f32 v24, v28, v24
	v_mul_f32 v25, v29, v25
	s_nop 0
	v_mul_f32 v28, v26, v24
	v_mul_f32 v29, v27, v25
	v_fma_f32 v24, -v26, v24, v26
	v_fma_f32 v25, -v27, v25, v27
	s_nop 0
	v_cndmask_b32_e32 v28, v24, v28, vcc
	v_cmp_gt_f32_e32 vcc, 0, v27
	v_cvt_pk_bf16_f32 v24, v40, v41
	s_nop 1
	v_cndmask_b32_e32 v27, v25, v29, vcc
	v_cvt_pk_bf16_f32 v25, v38, v39
	v_cvt_pk_bf16_f32 v26, v36, v37
	v_cvt_pk_bf16_f32 v27, v28, v27
	v_add_co_u32_e32 v28, vcc, s4, v150
	s_mov_b64 s[4:5], 0x58000
	s_nop 0
	v_addc_co_u32_e32 v29, vcc, 0, v151, vcc
	global_store_dwordx4 v[28:29], v[24:27], off
	v_mul_f32 v28, v20, v20
	v_mul_f32 v29, v21, v21
	v_cmp_gt_f32_e32 vcc, 0, v20
	v_and_b32_e32 v25, 0x7fffffff, v21
	v_and_b32_e32 v24, 0x7fffffff, v20
	v_fma_f32 v24, v24, s28, 1.0
	v_fma_f32 v25, v25, s28, 1.0
	v_mul_f32 v28, v28, s58
	v_mul_f32 v29, v29, s58
	v_rcp_f32_e32 v24, v24
	v_rcp_f32_e32 v25, v25
	v_exp_f32_e32 v28, v28
	v_exp_f32_e32 v29, v29
	v_fma_f32 v26, v24, s30, v122
	v_fma_f32 v27, v25, s30, v122
	s_nop 0
	v_fma_f32 v26, v24, v26, s52
	v_fma_f32 v27, v25, v27, s52
	s_nop 0
	v_fma_f32 v26, v24, v26, s54
	v_fma_f32 v27, v25, v27, s54
	s_nop 0
	v_fma_f32 v26, v24, v26, s56
	v_fma_f32 v27, v25, v27, s56
	s_nop 0
	v_mul_f32 v24, v24, v26
	v_mul_f32 v25, v25, v27
	v_mul_f32 v26, v22, v22
	v_mul_f32 v27, v23, v23
	v_mul_f32 v24, v28, v24
	v_mul_f32 v25, v29, v25
	s_nop 0
	v_mul_f32 v28, v20, v24
	v_mul_f32 v29, v21, v25
	v_fma_f32 v24, -v20, v24, v20
	v_fma_f32 v25, -v21, v25, v21
	v_and_b32_e32 v20, 0x7fffffff, v22
	v_cndmask_b32_e32 v28, v24, v28, vcc
	v_cmp_gt_f32_e32 vcc, 0, v21
	v_and_b32_e32 v21, 0x7fffffff, v23
	v_fma_f32 v20, v20, s28, 1.0
	v_fma_f32 v21, v21, s28, 1.0
	v_cndmask_b32_e32 v29, v25, v29, vcc
	v_rcp_f32_e32 v20, v20
	v_rcp_f32_e32 v21, v21
	v_cmp_gt_f32_e32 vcc, 0, v22
	v_fma_f32 v24, v20, s30, v122
	v_fma_f32 v25, v21, s30, v122
	s_nop 0
	v_fma_f32 v24, v20, v24, s52
	v_fma_f32 v25, v21, v25, s52
	s_nop 0
	v_fma_f32 v24, v20, v24, s54
	v_fma_f32 v25, v21, v25, s54
	s_nop 0
	v_fma_f32 v24, v20, v24, s56
	v_fma_f32 v25, v21, v25, s56
	s_nop 0
	v_mul_f32 v20, v20, v24
	v_mul_f32 v21, v21, v25
	v_mul_f32 v24, v26, s58
	v_mul_f32 v25, v27, s58
	s_nop 0
	v_exp_f32_e32 v24, v24
	v_exp_f32_e32 v25, v25
	s_nop 0
	v_mul_f32 v20, v24, v20
	v_mul_f32 v21, v25, v21
	s_nop 0
	v_mul_f32 v24, v22, v20
	v_mul_f32 v25, v23, v21
	v_fma_f32 v20, -v22, v20, v22
	v_fma_f32 v21, -v23, v21, v23
	s_nop 0
	v_cndmask_b32_e32 v26, v20, v24, vcc
	v_cmp_gt_f32_e32 vcc, 0, v23
	v_and_b32_e32 v20, 0x7fffffff, v16
	s_nop 0
	v_cndmask_b32_e32 v27, v21, v25, vcc
	v_and_b32_e32 v21, 0x7fffffff, v17
	v_fma_f32 v20, v20, s28, 1.0
	v_fma_f32 v21, v21, s28, 1.0
	v_mul_f32 v24, v16, v16
	v_mul_f32 v25, v17, v17
	v_rcp_f32_e32 v20, v20
	v_rcp_f32_e32 v21, v21
	v_mul_f32 v24, v24, s58
	v_mul_f32 v25, v25, s58
	v_cmp_gt_f32_e32 vcc, 0, v16
	v_exp_f32_e32 v24, v24
	v_fma_f32 v22, v20, s30, v122
	v_fma_f32 v23, v21, s30, v122
	v_exp_f32_e32 v25, v25
	v_fma_f32 v22, v20, v22, s52
	v_fma_f32 v23, v21, v23, s52
	s_nop 0
	v_fma_f32 v22, v20, v22, s54
	v_fma_f32 v23, v21, v23, s54
	s_nop 0
	v_fma_f32 v22, v20, v22, s56
	v_fma_f32 v23, v21, v23, s56
	s_nop 0
	v_mul_f32 v20, v20, v22
	v_mul_f32 v21, v21, v23
	v_mul_f32 v22, v18, v18
	v_mul_f32 v23, v19, v19
	v_mul_f32 v20, v24, v20
	v_mul_f32 v21, v25, v21
	s_nop 0
	v_mul_f32 v24, v16, v20
	v_mul_f32 v25, v17, v21
	v_fma_f32 v20, -v16, v20, v16
	v_fma_f32 v21, -v17, v21, v17
	v_and_b32_e32 v16, 0x7fffffff, v18
	v_cndmask_b32_e32 v24, v20, v24, vcc
; #define GAS __attribute__((address_space(1)))
; __device__ __forceinline__ f32x2 gelu_pk(f32x2 v) {
;     const f32x2 av = __builtin_elementwise_abs(v), d = av * 0.2316418882f + 1.0f;
;     f32x2 t; t.x = __builtin_amdgcn_rcpf(d.x); t.y = __builtin_amdgcn_rcpf(d.y);
;     f32x2 q = t * 0.5307027145f + (-0.7265760135f); q = q * t + 0.7107068705f; q = q * t + (-0.142248368f); q = q * t + 0.127414796f; q = q * t;
;     const f32x2 s = (v * v) * (-0.72134752044f);
;     f32x2 e; e.x = __builtin_amdgcn_exp2f(s.x); e.y = __builtin_amdgcn_exp2f(s.y);
;     const f32x2 m = v * (q * e), r = v - m;
;     f32x2 o; o.x = v.x < 0.f ? m.x : r.x; o.y = v.y < 0.f ? m.y : r.y; return o;
; }
;     __device__ __forceinline__ void operator()(const f32x4 (&acc)[2][2][4][2], const Unit& u, int wr, int wc, int fr, int fq, const float (&pre)[8]) const {
;     ...
;         for (int ai = 0; ai < 2; ++ai)
; #pragma unroll
;             for (int m = 0; m < 4; ++m) {
;                 const int row = row0 + ai * 128 + m * 16; bf16_t* rowp = O + (size_t)row * ldc + col0; float rs = 0.f;
;                 float rsc = 1.f; if (RS == 1) rsc = pre[ai * 4 + m];
; #pragma unroll
;                 for (int bj = 0; bj < 2; ++bj) {
;                     f32x4 v0 = acc[ai][bj][m][0], v1 = acc[ai][bj][m][1];
;                     if (RS == 1) { v0 = v0 * rsc; v1 = v1 * rsc; }
;                     if (RS == 2) { v0 = v0 * csc[bj][0]; v1 = v1 * csc[bj][1]; }
;                     if (ACT == 1) { const f32x2 a = gelu_pk((f32x2){v0[0], v0[1]}), b = gelu_pk((f32x2){v0[2], v0[3]}), c = gelu_pk((f32x2){v1[0], v1[1]}), d = gelu_pk((f32x2){v1[2], v1[3]});
;                         v0 = (f32x4){a.x, a.y, b.x, b.y}; v1 = (f32x4){c.x, c.y, d.x, d.y}; }
;                     v0 = v0 * sc; v1 = v1 * sc;
;                     if (STAT == 1) rs += (v0[0] * v0[0] + v0[1] * v0[1]) + (v0[2] * v0[2] + v0[3] * v0[3]) + (v1[0] * v1[0] + v1[1] * v1[1]) + (v1[2] * v1[2] + v1[3] * v1[3]);
;                     if (STAT == 2) {
; #pragma unroll
;                         for (int e = 0; e < 4; ++e) { cs[bj][0][e] += v0[e]; cq[bj][0][e] += v0[e] * v0[e]; cs[bj][1][e] += v1[e]; cq[bj][1][e] += v1[e] * v1[e]; } }
;                     u32x4 w; w.x = cvt_pk_bf16(v0[0], v0[1]); w.y = cvt_pk_bf16(v0[2], v0[3]); w.z = cvt_pk_bf16(v1[0], v1[1]); w.w = cvt_pk_bf16(v1[2], v1[3]);
;                     *(GAS u32x4*)(rowp + bj * 128) = w; }
	v_cmp_gt_f32_e32 vcc, 0, v17
	v_and_b32_e32 v17, 0x7fffffff, v19
	v_fma_f32 v16, v16, s28, 1.0
	v_fma_f32 v17, v17, s28, 1.0
	v_cndmask_b32_e32 v25, v21, v25, vcc
	v_rcp_f32_e32 v16, v16
	v_rcp_f32_e32 v17, v17
	v_cmp_gt_f32_e32 vcc, 0, v18
	v_fma_f32 v20, v16, s30, v122
	v_fma_f32 v21, v17, s30, v122
	s_nop 0
	v_fma_f32 v20, v16, v20, s52
	v_fma_f32 v21, v17, v21, s52
	s_nop 0
	v_fma_f32 v20, v16, v20, s54
	v_fma_f32 v21, v17, v21, s54
	s_nop 0
	v_fma_f32 v20, v16, v20, s56
	v_fma_f32 v21, v17, v21, s56
	s_nop 0
	v_mul_f32 v16, v16, v20
	v_mul_f32 v17, v17, v21
	v_mul_f32 v20, v22, s58
	v_mul_f32 v21, v23, s58
	v_mul_f32 v22, v12, v12
	v_mul_f32 v23, v13, v13
	v_exp_f32_e32 v20, v20
	v_exp_f32_e32 v21, v21
	v_mul_f32 v22, v22, s58
	v_mul_f32 v23, v23, s58
	v_mul_f32 v16, v20, v16
	v_mul_f32 v17, v21, v17
	s_nop 0
	v_mul_f32 v20, v18, v16
	v_mul_f32 v21, v19, v17
	v_fma_f32 v16, -v18, v16, v18
	v_fma_f32 v17, -v19, v17, v19
	v_exp_f32_e32 v22, v22
	v_cndmask_b32_e32 v20, v16, v20, vcc
	v_cmp_gt_f32_e32 vcc, 0, v19
	v_cvt_pk_bf16_f32 v16, v28, v29
	v_exp_f32_e32 v23, v23
	s_nop 0
	v_cndmask_b32_e32 v19, v17, v21, vcc
	v_cvt_pk_bf16_f32 v17, v26, v27
	v_cvt_pk_bf16_f32 v18, v24, v25
	v_cvt_pk_bf16_f32 v19, v20, v19
	global_store_dwordx4 v[34:35], v[16:19], off offset:256
	v_cmp_gt_f32_e32 vcc, 0, v12
	s_nop 0
	v_and_b32_e32 v19, 0x7fffffff, v13
	v_and_b32_e32 v18, 0x7fffffff, v12
	v_fma_f32 v18, v18, s28, 1.0
	v_fma_f32 v19, v19, s28, 1.0
	v_lshl_add_u64 v[16:17], v[150:151], 0, s[4:5]
	v_rcp_f32_e32 v18, v18
	v_rcp_f32_e32 v19, v19
	s_mov_b32 s4, 0x58000
	v_fma_f32 v20, v18, s30, v122
	v_fma_f32 v21, v19, s30, v122
	s_nop 0
	v_fma_f32 v20, v18, v20, s52
	v_fma_f32 v21, v19, v21, s52
	s_nop 0
	v_fma_f32 v20, v18, v20, s54
	v_fma_f32 v21, v19, v21, s54
	s_nop 0
	v_fma_f32 v20, v18, v20, s56
	v_fma_f32 v21, v19, v21, s56
	s_nop 0
	v_mul_f32 v18, v18, v20
	v_mul_f32 v19, v19, v21
	v_mul_f32 v20, v14, v14
	v_mul_f32 v21, v15, v15
	v_mul_f32 v18, v22, v18
	v_mul_f32 v19, v23, v19
	s_nop 0
	v_mul_f32 v22, v12, v18
	v_mul_f32 v23, v13, v19
	v_fma_f32 v18, -v12, v18, v12
	v_fma_f32 v19, -v13, v19, v13
	v_and_b32_e32 v12, 0x7fffffff, v14
	v_cndmask_b32_e32 v22, v18, v22, vcc
	v_cmp_gt_f32_e32 vcc, 0, v13
	v_and_b32_e32 v13, 0x7fffffff, v15
	v_fma_f32 v12, v12, s28, 1.0
	v_fma_f32 v13, v13, s28, 1.0
	v_cndmask_b32_e32 v23, v19, v23, vcc
	v_rcp_f32_e32 v12, v12
	v_rcp_f32_e32 v13, v13
	v_cmp_gt_f32_e32 vcc, 0, v14
	v_fma_f32 v18, v12, s30, v122
	v_fma_f32 v19, v13, s30, v122
	s_nop 0
	v_fma_f32 v18, v12, v18, s52
	v_fma_f32 v19, v13, v19, s52
	s_nop 0
	v_fma_f32 v18, v12, v18, s54
	v_fma_f32 v19, v13, v19, s54
	s_nop 0
	v_fma_f32 v18, v12, v18, s56
	v_fma_f32 v19, v13, v19, s56
	s_nop 0
	v_mul_f32 v12, v12, v18
	v_mul_f32 v13, v13, v19
	v_mul_f32 v18, v20, s58
	v_mul_f32 v19, v21, s58
	s_nop 0
	v_exp_f32_e32 v18, v18
	v_exp_f32_e32 v19, v19
	s_nop 0
	v_mul_f32 v12, v18, v12
	v_mul_f32 v13, v19, v13
	s_nop 0
	v_mul_f32 v18, v14, v12
	v_mul_f32 v19, v15, v13
	v_fma_f32 v12, -v14, v12, v14
	v_fma_f32 v13, -v15, v13, v15
	s_nop 0
	v_cndmask_b32_e32 v20, v12, v18, vcc
	v_cmp_gt_f32_e32 vcc, 0, v15
	v_and_b32_e32 v12, 0x7fffffff, v8
	s_nop 0
	v_cndmask_b32_e32 v21, v13, v19, vcc
	v_and_b32_e32 v13, 0x7fffffff, v9
	v_fma_f32 v12, v12, s28, 1.0
	v_fma_f32 v13, v13, s28, 1.0
	v_mul_f32 v18, v8, v8
	v_mul_f32 v19, v9, v9
	v_rcp_f32_e32 v12, v12
	v_rcp_f32_e32 v13, v13
	v_mul_f32 v18, v18, s58
	v_mul_f32 v19, v19, s58
	v_cmp_gt_f32_e32 vcc, 0, v8
	v_exp_f32_e32 v18, v18
	v_fma_f32 v14, v12, s30, v122
	v_fma_f32 v15, v13, s30, v122
	v_exp_f32_e32 v19, v19
	v_fma_f32 v14, v12, v14, s52
	v_fma_f32 v15, v13, v15, s52
	s_nop 0
	v_fma_f32 v14, v12, v14, s54
	v_fma_f32 v15, v13, v15, s54
	s_nop 0
	v_fma_f32 v14, v12, v14, s56
	v_fma_f32 v15, v13, v15, s56
	s_nop 0
	v_mul_f32 v12, v12, v14
	v_mul_f32 v13, v13, v15
	v_mul_f32 v14, v10, v10
	v_mul_f32 v15, v11, v11
	v_mul_f32 v12, v18, v12
	v_mul_f32 v13, v19, v13
	s_nop 0
	v_mul_f32 v18, v8, v12
	v_mul_f32 v19, v9, v13
	v_fma_f32 v12, -v8, v12, v8
	v_fma_f32 v13, -v9, v13, v9
	v_and_b32_e32 v8, 0x7fffffff, v10
	v_cndmask_b32_e32 v18, v12, v18, vcc
	v_cmp_gt_f32_e32 vcc, 0, v9
	v_and_b32_e32 v9, 0x7fffffff, v11
	v_fma_f32 v8, v8, s28, 1.0
	v_fma_f32 v9, v9, s28, 1.0
	v_cndmask_b32_e32 v19, v13, v19, vcc
	v_rcp_f32_e32 v8, v8
	v_rcp_f32_e32 v9, v9
	v_cmp_gt_f32_e32 vcc, 0, v10
	v_fma_f32 v12, v8, s30, v122
	v_fma_f32 v13, v9, s30, v122
	s_nop 0
	v_fma_f32 v12, v8, v12, s52
	v_fma_f32 v13, v9, v13, s52
	s_nop 0
	v_fma_f32 v12, v8, v12, s54
	v_fma_f32 v13, v9, v13, s54
	s_nop 0
	v_fma_f32 v12, v8, v12, s56
	v_fma_f32 v13, v9, v13, s56
	s_nop 0
	v_mul_f32 v8, v8, v12
	v_mul_f32 v9, v9, v13
	v_mul_f32 v12, v14, s58
	v_mul_f32 v13, v15, s58
	s_nop 0
	v_exp_f32_e32 v12, v12
	v_exp_f32_e32 v13, v13
	s_nop 0
	v_mul_f32 v8, v12, v8
	v_mul_f32 v9, v13, v9
	s_nop 0
	v_mul_f32 v12, v10, v8
	v_mul_f32 v13, v11, v9
; #define GAS __attribute__((address_space(1)))
; __device__ __forceinline__ f32x2 gelu_pk(f32x2 v) {
;     const f32x2 av = __builtin_elementwise_abs(v), d = av * 0.2316418882f + 1.0f;
;     f32x2 t; t.x = __builtin_amdgcn_rcpf(d.x); t.y = __builtin_amdgcn_rcpf(d.y);
;     f32x2 q = t * 0.5307027145f + (-0.7265760135f); q = q * t + 0.7107068705f; q = q * t + (-0.142248368f); q = q * t + 0.127414796f; q = q * t;
;     const f32x2 s = (v * v) * (-0.72134752044f);
;     f32x2 e; e.x = __builtin_amdgcn_exp2f(s.x); e.y = __builtin_amdgcn_exp2f(s.y);
;     const f32x2 m = v * (q * e), r = v - m;
;     f32x2 o; o.x = v.x < 0.f ? m.x : r.x; o.y = v.y < 0.f ? m.y : r.y; return o;
; }
;     __device__ __forceinline__ void operator()(const f32x4 (&acc)[2][2][4][2], const Unit& u, int wr, int wc, int fr, int fq, const float (&pre)[8]) const {
;     ...
;         for (int ai = 0; ai < 2; ++ai)
; #pragma unroll
;             for (int m = 0; m < 4; ++m) {
;                 const int row = row0 + ai * 128 + m * 16; bf16_t* rowp = O + (size_t)row * ldc + col0; float rs = 0.f;
;                 float rsc = 1.f; if (RS == 1) rsc = pre[ai * 4 + m];
; #pragma unroll
;                 for (int bj = 0; bj < 2; ++bj) {
;                     f32x4 v0 = acc[ai][bj][m][0], v1 = acc[ai][bj][m][1];
;                     if (RS == 1) { v0 = v0 * rsc; v1 = v1 * rsc; }
;                     if (RS == 2) { v0 = v0 * csc[bj][0]; v1 = v1 * csc[bj][1]; }
;                     if (ACT == 1) { const f32x2 a = gelu_pk((f32x2){v0[0], v0[1]}), b = gelu_pk((f32x2){v0[2], v0[3]}), c = gelu_pk((f32x2){v1[0], v1[1]}), d = gelu_pk((f32x2){v1[2], v1[3]});
;                         v0 = (f32x4){a.x, a.y, b.x, b.y}; v1 = (f32x4){c.x, c.y, d.x, d.y}; }
;                     v0 = v0 * sc; v1 = v1 * sc;
;                     if (STAT == 1) rs += (v0[0] * v0[0] + v0[1] * v0[1]) + (v0[2] * v0[2] + v0[3] * v0[3]) + (v1[0] * v1[0] + v1[1] * v1[1]) + (v1[2] * v1[2] + v1[3] * v1[3]);
;                     if (STAT == 2) {
; #pragma unroll
;                         for (int e = 0; e < 4; ++e) { cs[bj][0][e] += v0[e]; cq[bj][0][e] += v0[e] * v0[e]; cs[bj][1][e] += v1[e]; cq[bj][1][e] += v1[e] * v1[e]; } }
;                     u32x4 w; w.x = cvt_pk_bf16(v0[0], v0[1]); w.y = cvt_pk_bf16(v0[2], v0[3]); w.z = cvt_pk_bf16(v1[0], v1[1]); w.w = cvt_pk_bf16(v1[2], v1[3]);
;                     *(GAS u32x4*)(rowp + bj * 128) = w; }
	v_fma_f32 v8, -v10, v8, v10
	v_fma_f32 v9, -v11, v9, v11
	s_nop 0
	v_cndmask_b32_e32 v12, v8, v12, vcc
	v_cmp_gt_f32_e32 vcc, 0, v11
	v_cvt_pk_bf16_f32 v8, v22, v23
	s_nop 1
	v_cndmask_b32_e32 v11, v9, v13, vcc
	v_cvt_pk_bf16_f32 v9, v20, v21
	v_cvt_pk_bf16_f32 v10, v18, v19
	v_cvt_pk_bf16_f32 v11, v12, v11
	v_add_co_u32_e32 v12, vcc, s4, v150
	s_nop 1
	v_addc_co_u32_e32 v13, vcc, 0, v151, vcc
	global_store_dwordx4 v[12:13], v[8:11], off
	v_mul_f32 v12, v4, v4
	v_mul_f32 v13, v5, v5
	v_cmp_gt_f32_e32 vcc, 0, v4
	v_and_b32_e32 v9, 0x7fffffff, v5
	v_and_b32_e32 v8, 0x7fffffff, v4
	v_fma_f32 v8, v8, s28, 1.0
	v_fma_f32 v9, v9, s28, 1.0
	v_mul_f32 v12, v12, s58
	v_mul_f32 v13, v13, s58
	v_rcp_f32_e32 v8, v8
	v_rcp_f32_e32 v9, v9
	v_exp_f32_e32 v12, v12
	v_exp_f32_e32 v13, v13
	v_fma_f32 v10, v8, s30, v122
	v_fma_f32 v11, v9, s30, v122
	s_nop 0
	v_fma_f32 v10, v8, v10, s52
	v_fma_f32 v11, v9, v11, s52
	s_nop 0
	v_fma_f32 v10, v8, v10, s54
	v_fma_f32 v11, v9, v11, s54
	s_nop 0
	v_fma_f32 v10, v8, v10, s56
	v_fma_f32 v11, v9, v11, s56
	s_nop 0
	v_mul_f32 v8, v8, v10
	v_mul_f32 v9, v9, v11
	v_mul_f32 v10, v6, v6
	v_mul_f32 v11, v7, v7
	v_mul_f32 v8, v12, v8
	v_mul_f32 v9, v13, v9
	s_nop 0
	v_mul_f32 v12, v4, v8
	v_mul_f32 v13, v5, v9
	v_fma_f32 v8, -v4, v8, v4
	v_fma_f32 v9, -v5, v9, v5
	v_and_b32_e32 v4, 0x7fffffff, v6
	v_cndmask_b32_e32 v12, v8, v12, vcc
	v_cmp_gt_f32_e32 vcc, 0, v5
	v_and_b32_e32 v5, 0x7fffffff, v7
	v_fma_f32 v4, v4, s28, 1.0
	v_fma_f32 v5, v5, s28, 1.0
	v_cndmask_b32_e32 v13, v9, v13, vcc
	v_rcp_f32_e32 v4, v4
	v_rcp_f32_e32 v5, v5
	v_cmp_gt_f32_e32 vcc, 0, v6
	v_fma_f32 v8, v4, s30, v122
	v_fma_f32 v9, v5, s30, v122
	s_nop 0
	v_fma_f32 v8, v4, v8, s52
	v_fma_f32 v9, v5, v9, s52
	s_nop 0
	v_fma_f32 v8, v4, v8, s54
	v_fma_f32 v9, v5, v9, s54
	s_nop 0
	v_fma_f32 v8, v4, v8, s56
	v_fma_f32 v9, v5, v9, s56
	s_nop 0
	v_mul_f32 v4, v4, v8
	v_mul_f32 v5, v5, v9
	v_mul_f32 v8, v10, s58
	v_mul_f32 v9, v11, s58
	s_nop 0
	v_exp_f32_e32 v8, v8
	v_exp_f32_e32 v9, v9
	s_nop 0
	v_mul_f32 v4, v8, v4
	v_mul_f32 v5, v9, v5
	s_nop 0
	v_mul_f32 v8, v6, v4
	v_mul_f32 v9, v7, v5
	v_fma_f32 v4, -v6, v4, v6
	v_fma_f32 v5, -v7, v5, v7
	s_nop 0
	v_cndmask_b32_e32 v10, v4, v8, vcc
	v_cmp_gt_f32_e32 vcc, 0, v7
	v_and_b32_e32 v4, 0x7fffffff, v0
	s_nop 0
	v_cndmask_b32_e32 v11, v5, v9, vcc
	v_and_b32_e32 v5, 0x7fffffff, v1
	v_fma_f32 v4, v4, s28, 1.0
	v_fma_f32 v5, v5, s28, 1.0
	v_mul_f32 v8, v0, v0
	v_mul_f32 v9, v1, v1
	v_rcp_f32_e32 v4, v4
	v_rcp_f32_e32 v5, v5
	v_mul_f32 v8, v8, s58
	v_mul_f32 v9, v9, s58
	v_cmp_gt_f32_e32 vcc, 0, v0
	v_exp_f32_e32 v8, v8
	v_fma_f32 v6, v4, s30, v122
	v_fma_f32 v7, v5, s30, v122
	v_exp_f32_e32 v9, v9
	v_fma_f32 v6, v4, v6, s52
	v_fma_f32 v7, v5, v7, s52
	s_nop 0
	v_fma_f32 v6, v4, v6, s54
	v_fma_f32 v7, v5, v7, s54
	s_nop 0
	v_fma_f32 v6, v4, v6, s56
	v_fma_f32 v7, v5, v7, s56
	s_nop 0
	v_mul_f32 v4, v4, v6
	v_mul_f32 v5, v5, v7
	v_mul_f32 v6, v2, v2
	v_mul_f32 v7, v3, v3
	v_mul_f32 v4, v8, v4
	v_mul_f32 v5, v9, v5
	s_nop 0
	v_mul_f32 v8, v0, v4
	v_mul_f32 v9, v1, v5
	v_fma_f32 v4, -v0, v4, v0
	v_fma_f32 v5, -v1, v5, v1
	v_and_b32_e32 v0, 0x7fffffff, v2
	v_cndmask_b32_e32 v8, v4, v8, vcc
	v_cmp_gt_f32_e32 vcc, 0, v1
	v_and_b32_e32 v1, 0x7fffffff, v3
	v_fma_f32 v0, v0, s28, 1.0
	v_fma_f32 v1, v1, s28, 1.0
	v_cndmask_b32_e32 v9, v5, v9, vcc
	v_rcp_f32_e32 v0, v0
	v_rcp_f32_e32 v1, v1
	v_cmp_gt_f32_e32 vcc, 0, v2
	v_fma_f32 v4, v0, s30, v122
	v_fma_f32 v5, v1, s30, v122
	s_nop 0
	v_fma_f32 v4, v0, v4, s52
	v_fma_f32 v5, v1, v5, s52
	s_nop 0
	v_fma_f32 v4, v0, v4, s54
	v_fma_f32 v5, v1, v5, s54
	s_nop 0
	v_fma_f32 v4, v0, v4, s56
	v_fma_f32 v5, v1, v5, s56
	s_nop 0
	v_mul_f32 v0, v0, v4
	v_mul_f32 v1, v1, v5
	v_mul_f32 v4, v6, s58
	v_mul_f32 v5, v7, s58
	s_nop 0
	v_exp_f32_e32 v4, v4
	v_exp_f32_e32 v5, v5
	s_nop 0
	v_mul_f32 v0, v4, v0
	v_mul_f32 v1, v5, v1
	s_nop 0
	v_mul_f32 v4, v2, v0
	v_mul_f32 v5, v3, v1
	v_fma_f32 v0, -v2, v0, v2
	v_fma_f32 v1, -v3, v1, v3
	s_nop 0
	v_cndmask_b32_e32 v4, v0, v4, vcc
	v_cmp_gt_f32_e32 vcc, 0, v3
	v_cvt_pk_bf16_f32 v0, v12, v13
	s_nop 1
	v_cndmask_b32_e32 v3, v1, v5, vcc
	s_andn2_b64 vcc, exec, s[96:97]
	v_cvt_pk_bf16_f32 v1, v10, v11
	v_cvt_pk_bf16_f32 v2, v8, v9
	v_cvt_pk_bf16_f32 v3, v4, v3
	global_store_dwordx4 v[16:17], v[0:3], off offset:256
	s_cbranch_vccnz .LBB0_109
	s_lshl_b32 s4, s90, 8
	s_ashr_i32 s5, s4, 31
	v_lshl_add_u64 v[0:1], s[4:5], 2, v[138:139]
	global_load_dword v172, v[0:1], off
	global_load_dword v158, v[0:1], off offset:64
	global_load_dword v156, v[0:1], off offset:128
	global_load_dword v154, v[0:1], off offset:192
	global_load_dword v152, v[0:1], off offset:512
	global_load_dword v148, v[0:1], off offset:576
	global_load_dword v146, v[0:1], off offset:640
	global_load_dword v144, v[0:1], off offset:704
	v_readlane_b32 s4, v254, 49
	v_readlane_b32 s5, v254, 50
	s_andn2_b64 vcc, exec, s[4:5]
	s_cbranch_vccnz .LBB0_108
	s_barrier
	s_branch .LBB0_108

; __device__ __forceinline__ f32x2 gelu_pk(f32x2 v) {
;     const f32x2 av = __builtin_elementwise_abs(v), d = av * 0.2316418882f + 1.0f;
;     f32x2 t; t.x = __builtin_amdgcn_rcpf(d.x); t.y = __builtin_amdgcn_rcpf(d.y);
;     f32x2 q = t * 0.5307027145f + (-0.7265760135f); q = q * t + 0.7107068705f; q = q * t + (-0.142248368f); q = q * t + 0.127414796f; q = q * t;
;     const f32x2 s = (v * v) * (-0.72134752044f);
;     f32x2 e; e.x = __builtin_amdgcn_exp2f(s.x); e.y = __builtin_amdgcn_exp2f(s.y);
;     const f32x2 m = v * (q * e), r = v - m;
;     f32x2 o; o.x = v.x < 0.f ? m.x : r.x; o.y = v.y < 0.f ? m.y : r.y; return o;
; }
;     __device__ __forceinline__ void operator()(const f32x4 (&acc)[2][2][4][2], const Unit& u, int wr, int wc, int fr, int fq, const float (&pre)[8]) const {
;     ...
;         if (RS == 2) {
; #pragma unroll
;             for (int bj = 0; bj < 2; ++bj) { csc[bj][0] = *(const GAS f32x4*)(rs + col0 + bj * 128); csc[bj][1] = *(const GAS f32x4*)(rs + col0 + bj * 128 + 4); }
;         }
; #pragma unroll
;         for (int ai = 0; ai < 2; ++ai)
; #pragma unroll
;             for (int m = 0; m < 4; ++m) {
;                 const int row = row0 + ai * 128 + m * 16; bf16_t* rowp = O + (size_t)row * ldc + col0; float rs = 0.f;
;                 float rsc = 1.f; if (RS == 1) rsc = pre[ai * 4 + m];
; #pragma unroll
;                 for (int bj = 0; bj < 2; ++bj) {
;                     f32x4 v0 = acc[ai][bj][m][0], v1 = acc[ai][bj][m][1];
;                     if (RS == 1) { v0 = v0 * rsc; v1 = v1 * rsc; }
;                     if (RS == 2) { v0 = v0 * csc[bj][0]; v1 = v1 * csc[bj][1]; }
;                     if (ACT == 1) { const f32x2 a = gelu_pk((f32x2){v0[0], v0[1]}), b = gelu_pk((f32x2){v0[2], v0[3]}), c = gelu_pk((f32x2){v1[0], v1[1]}), d = gelu_pk((f32x2){v1[2], v1[3]});
;                         v0 = (f32x4){a.x, a.y, b.x, b.y}; v1 = (f32x4){c.x, c.y, d.x, d.y}; }
;                     v0 = v0 * sc; v1 = v1 * sc;
;                     if (STAT == 1) rs += (v0[0] * v0[0] + v0[1] * v0[1]) + (v0[2] * v0[2] + v0[3] * v0[3]) + (v1[0] * v1[0] + v1[1] * v1[1]) + (v1[2] * v1[2] + v1[3] * v1[3]);
;                     if (STAT == 2) {
; #pragma unroll
;                         for (int e = 0; e < 4; ++e) { cs[bj][0][e] += v0[e]; cq[bj][0][e] += v0[e] * v0[e]; cs[bj][1][e] += v1[e]; cq[bj][1][e] += v1[e] * v1[e]; } }
.LBB0_148:
	v_lshl_or_b32 v158, s44, 8, v177
	v_ashrrev_i32_e32 v159, 31, v158
	v_lshl_add_u64 v[54:55], v[158:159], 2, s[66:67]
	global_load_dwordx4 v[70:73], v[54:55], off
	global_load_dwordx4 v[66:69], v[54:55], off offset:16
	global_load_dwordx4 v[50:53], v[54:55], off offset:528
	s_nop 0
	global_load_dwordx4 v[54:57], v[54:55], off offset:512
	s_mov_b32 s44, 0xbf3a00e3
	v_mov_b64_e32 v[160:161], s[44:45]
	v_lshl_add_u32 v170, s90, 8, v33
	v_ashrrev_i32_e32 v171, 31, v170
	v_readlane_b32 s3, v253, 2
	v_readlane_b32 s44, v254, 33
	v_readlane_b32 s45, v254, 34
	v_lshlrev_b64 v[174:175], s3, v[170:171]
	v_lshlrev_b64 v[172:173], 1, v[158:159]
	v_lshl_add_u64 v[174:175], v[174:175], 1, s[44:45]
	v_lshl_add_u64 v[174:175], v[174:175], 0, v[172:173]
	s_waitcnt vmcnt(0)
	v_mul_f32 v142, v142, v70
	v_mul_f32 v143, v143, v71
	v_mul_f32 v138, v138, v66
	v_mul_f32 v139, v139, v67
	v_and_b32_e32 v181, 0x7fffffff, v143
	v_and_b32_e32 v180, 0x7fffffff, v142
	v_mul_f32 v144, v144, v72
	v_mul_f32 v145, v145, v73
	v_and_b32_e32 v199, 0x7fffffff, v139
	v_and_b32_e32 v198, 0x7fffffff, v138
	v_fma_f32 v180, v180, s28, 1.0
	v_fma_f32 v181, v181, s28, 1.0
	v_mul_f32 v140, v140, v68
	v_mul_f32 v141, v141, v69
	v_and_b32_e32 v197, 0x7fffffff, v145
	v_and_b32_e32 v196, 0x7fffffff, v144
	v_fma_f32 v198, v198, s28, 1.0
	v_fma_f32 v199, v199, s28, 1.0
	v_rcp_f32_e32 v180, v180
	v_rcp_f32_e32 v181, v181
	v_and_b32_e32 v205, 0x7fffffff, v141
	v_and_b32_e32 v204, 0x7fffffff, v140
	v_fma_f32 v196, v196, s28, 1.0
	v_fma_f32 v197, v197, s28, 1.0
	v_rcp_f32_e32 v198, v198
	v_rcp_f32_e32 v199, v199
	v_fma_f32 v204, v204, s28, 1.0
	v_fma_f32 v205, v205, s28, 1.0
	v_rcp_f32_e32 v196, v196
	v_rcp_f32_e32 v197, v197
	v_mul_f32 v184, v142, v142
	v_mul_f32 v185, v143, v143
	v_rcp_f32_e32 v204, v204
	v_rcp_f32_e32 v205, v205
	v_mul_f32 v202, v138, v138
	v_mul_f32 v203, v139, v139
	v_mul_f32 v184, v184, s58
	v_mul_f32 v185, v185, s58
	v_fma_f32 v206, v180, s30, v160
	v_fma_f32 v207, v181, s30, v160
	v_mul_f32 v182, v144, v144
	v_mul_f32 v183, v145, v145
	v_mul_f32 v202, v202, s58
	v_mul_f32 v203, v203, s58
	v_exp_f32_e32 v184, v184
	v_exp_f32_e32 v185, v185
	v_fma_f32 v210, v198, s30, v160
	v_fma_f32 v211, v199, s30, v160
	v_fma_f32 v206, v180, v206, s52
	v_fma_f32 v207, v181, v207, s52
	v_mul_f32 v200, v140, v140
	v_mul_f32 v201, v141, v141
	v_mul_f32 v182, v182, s58
	v_mul_f32 v183, v183, s58
	v_exp_f32_e32 v202, v202
	v_exp_f32_e32 v203, v203
	v_fma_f32 v208, v196, s30, v160
	v_fma_f32 v209, v197, s30, v160
	v_fma_f32 v210, v198, v210, s52
	v_fma_f32 v211, v199, v211, s52
	v_fma_f32 v206, v180, v206, s54
	v_fma_f32 v207, v181, v207, s54
	v_mul_f32 v200, v200, s58
	v_mul_f32 v201, v201, s58
	v_exp_f32_e32 v182, v182
	v_exp_f32_e32 v183, v183
	v_fma_f32 v212, v204, s30, v160
	v_fma_f32 v213, v205, s30, v160
	v_fma_f32 v208, v196, v208, s52
	v_fma_f32 v209, v197, v209, s52
	v_fma_f32 v210, v198, v210, s54
	v_fma_f32 v211, v199, v211, s54
	v_fma_f32 v206, v180, v206, s56
	v_fma_f32 v207, v181, v207, s56
	v_exp_f32_e32 v200, v200
	v_exp_f32_e32 v201, v201
	v_fma_f32 v212, v204, v212, s52
	v_fma_f32 v213, v205, v213, s52
	v_fma_f32 v208, v196, v208, s54
	v_fma_f32 v209, v197, v209, s54
	v_fma_f32 v210, v198, v210, s56
	v_fma_f32 v211, v199, v211, s56
	v_mul_f32 v180, v180, v206
	v_mul_f32 v181, v181, v207
	v_fma_f32 v212, v204, v212, s54
	v_fma_f32 v213, v205, v213, s54
	v_fma_f32 v208, v196, v208, s56
	v_fma_f32 v209, v197, v209, s56
	v_mul_f32 v198, v198, v210
	v_mul_f32 v199, v199, v211
	v_mul_f32 v180, v184, v180
	v_mul_f32 v181, v185, v181
	v_fma_f32 v212, v204, v212, s56
	v_fma_f32 v213, v205, v213, s56
	v_mul_f32 v196, v196, v208
	v_mul_f32 v197, v197, v209
	v_mul_f32 v184, v202, v198
	v_mul_f32 v185, v203, v199
	v_mul_f32 v198, v142, v180
	v_mul_f32 v199, v143, v181
	v_fma_f32 v180, -v142, v180, v142
	v_fma_f32 v181, -v143, v181, v143
	v_cmp_gt_f32_e32 vcc, 0, v142
	v_mul_f32 v204, v204, v212
	v_mul_f32 v205, v205, v213
	v_mul_f32 v182, v182, v196
	v_mul_f32 v183, v183, v197
	v_cndmask_b32_e32 v195, v180, v198, vcc
	v_cmp_gt_f32_e32 vcc, 0, v143
	v_mul_f32 v196, v200, v204
	v_mul_f32 v197, v201, v205
	v_mul_f32 v200, v144, v182
	v_mul_f32 v201, v145, v183
	v_fma_f32 v182, -v144, v182, v144
	v_fma_f32 v183, -v145, v183, v145
	v_cndmask_b32_e32 v179, v181, v199, vcc
	v_cmp_gt_f32_e32 vcc, 0, v144
	v_mul_f32 v202, v138, v184
	v_mul_f32 v203, v139, v185
	v_fma_f32 v184, -v138, v184, v138
	v_fma_f32 v185, -v139, v185, v139
	v_cndmask_b32_e32 v171, v182, v200, vcc
	v_cmp_gt_f32_e32 vcc, 0, v145
	v_mul_f32 v204, v140, v196
	v_mul_f32 v205, v141, v197
	v_fma_f32 v196, -v140, v196, v140
	v_fma_f32 v197, -v141, v197, v141
	v_cndmask_b32_e32 v145, v183, v201, vcc
	v_cmp_gt_f32_e32 vcc, 0, v138
	v_mul_f32 v134, v134, v54
	v_mul_f32 v135, v135, v55
	v_cvt_pk_bf16_f32 v180, v195, v179
	v_cvt_pk_bf16_f32 v181, v171, v145
	v_mul_f32 v130, v130, v50
	v_mul_f32 v131, v131, v51
	v_cndmask_b32_e32 v143, v184, v202, vcc
	v_cmp_gt_f32_e32 vcc, 0, v139
	v_mul_f32 v126, v126, v70
	v_mul_f32 v127, v127, v71
	v_mul_f32 v122, v122, v66
	v_mul_f32 v123, v123, v67
	v_cndmask_b32_e32 v144, v185, v203, vcc
	v_cmp_gt_f32_e32 vcc, 0, v140
	v_and_b32_e32 v140, 0x7fffffff, v134
	v_cvt_pk_bf16_f32 v182, v143, v144
	v_mul_f32 v118, v118, v54
	v_mul_f32 v119, v119, v55
	v_cndmask_b32_e32 v142, v196, v204, vcc
	v_cmp_gt_f32_e32 vcc, 0, v141
	v_and_b32_e32 v141, 0x7fffffff, v135
	v_fma_f32 v140, v140, s28, 1.0
	v_fma_f32 v141, v141, s28, 1.0
	v_cndmask_b32_e32 v139, v197, v205, vcc
	v_rcp_f32_e32 v140, v140
	v_rcp_f32_e32 v141, v141
	v_cvt_pk_bf16_f32 v183, v142, v139
	global_store_dwordx4 v[174:175], v[180:183], off
; #define GAS __attribute__((address_space(1)))
; __device__ __forceinline__ f32x2 gelu_pk(f32x2 v) {
;     const f32x2 av = __builtin_elementwise_abs(v), d = av * 0.2316418882f + 1.0f;
;     f32x2 t; t.x = __builtin_amdgcn_rcpf(d.x); t.y = __builtin_amdgcn_rcpf(d.y);
;     f32x2 q = t * 0.5307027145f + (-0.7265760135f); q = q * t + 0.7107068705f; q = q * t + (-0.142248368f); q = q * t + 0.127414796f; q = q * t;
;     const f32x2 s = (v * v) * (-0.72134752044f);
;     f32x2 e; e.x = __builtin_amdgcn_exp2f(s.x); e.y = __builtin_amdgcn_exp2f(s.y);
;     const f32x2 m = v * (q * e), r = v - m;
;     f32x2 o; o.x = v.x < 0.f ? m.x : r.x; o.y = v.y < 0.f ? m.y : r.y; return o;
; }
;     __device__ __forceinline__ void operator()(const f32x4 (&acc)[2][2][4][2], const Unit& u, int wr, int wc, int fr, int fq, const float (&pre)[8]) const {
;     ...
;         for (int ai = 0; ai < 2; ++ai)
; #pragma unroll
;             for (int m = 0; m < 4; ++m) {
;                 const int row = row0 + ai * 128 + m * 16; bf16_t* rowp = O + (size_t)row * ldc + col0; float rs = 0.f;
;                 float rsc = 1.f; if (RS == 1) rsc = pre[ai * 4 + m];
; #pragma unroll
;                 for (int bj = 0; bj < 2; ++bj) {
;                     f32x4 v0 = acc[ai][bj][m][0], v1 = acc[ai][bj][m][1];
;                     if (RS == 1) { v0 = v0 * rsc; v1 = v1 * rsc; }
;                     if (RS == 2) { v0 = v0 * csc[bj][0]; v1 = v1 * csc[bj][1]; }
;                     if (ACT == 1) { const f32x2 a = gelu_pk((f32x2){v0[0], v0[1]}), b = gelu_pk((f32x2){v0[2], v0[3]}), c = gelu_pk((f32x2){v1[0], v1[1]}), d = gelu_pk((f32x2){v1[2], v1[3]});
;                         v0 = (f32x4){a.x, a.y, b.x, b.y}; v1 = (f32x4){c.x, c.y, d.x, d.y}; }
;                     v0 = v0 * sc; v1 = v1 * sc;
;                     if (STAT == 1) rs += (v0[0] * v0[0] + v0[1] * v0[1]) + (v0[2] * v0[2] + v0[3] * v0[3]) + (v1[0] * v1[0] + v1[1] * v1[1]) + (v1[2] * v1[2] + v1[3] * v1[3]);
;                     if (STAT == 2) {
; #pragma unroll
;                         for (int e = 0; e < 4; ++e) { cs[bj][0][e] += v0[e]; cq[bj][0][e] += v0[e] * v0[e]; cs[bj][1][e] += v1[e]; cq[bj][1][e] += v1[e] * v1[e]; } }
;                     u32x4 w; w.x = cvt_pk_bf16(v0[0], v0[1]); w.y = cvt_pk_bf16(v0[2], v0[3]); w.z = cvt_pk_bf16(v1[0], v1[1]); w.w = cvt_pk_bf16(v1[2], v1[3]);
;                     *(GAS u32x4*)(rowp + bj * 128) = w; }
	v_cmp_gt_f32_e32 vcc, 0, v134
	v_add_f32_e32 v198, 0, v195
	v_mul_f32 v182, v132, v52
	v_mul_f32 v183, v133, v53
	v_fma_f32 v132, v140, s30, v160
	v_fma_f32 v133, v141, s30, v160
	v_mul_f32 v180, v136, v56
	v_mul_f32 v181, v137, v57
	v_fma_f32 v132, v140, v132, s52
	v_fma_f32 v133, v141, v133, s52
	v_mul_f32 v136, v134, v134
	v_mul_f32 v137, v135, v135
	v_fma_f32 v132, v140, v132, s54
	v_fma_f32 v133, v141, v133, s54
	v_mul_f32 v136, v136, s58
	v_mul_f32 v137, v137, s58
	v_fma_f32 v132, v140, v132, s56
	v_fma_f32 v133, v141, v133, s56
	v_exp_f32_e32 v136, v136
	v_exp_f32_e32 v137, v137
	v_mul_f32 v132, v140, v132
	v_mul_f32 v133, v141, v133
	v_and_b32_e32 v141, 0x7fffffff, v181
	v_and_b32_e32 v140, 0x7fffffff, v180
	v_fma_f32 v140, v140, s28, 1.0
	v_fma_f32 v141, v141, s28, 1.0
	v_mul_f32 v132, v136, v132
	v_mul_f32 v133, v137, v133
	v_rcp_f32_e32 v196, v140
	v_rcp_f32_e32 v197, v141
	v_mul_f32 v136, v134, v132
	v_mul_f32 v137, v135, v133
	v_fma_f32 v132, -v134, v132, v134
	v_fma_f32 v133, -v135, v133, v135
	v_mul_f32 v184, v180, v180
	v_mul_f32 v185, v181, v181
	v_cndmask_b32_e32 v140, v132, v136, vcc
	v_cmp_gt_f32_e32 vcc, 0, v135
	v_mul_f32 v134, v184, s58
	v_mul_f32 v135, v185, s58
	v_and_b32_e32 v136, 0x7fffffff, v130
	v_cndmask_b32_e32 v138, v133, v137, vcc
	v_fma_f32 v132, v196, s30, v160
	v_fma_f32 v133, v197, s30, v160
	v_exp_f32_e32 v134, v134
	v_fma_f32 v132, v196, v132, s52
	v_fma_f32 v133, v197, v133, s52
	v_exp_f32_e32 v135, v135
	v_fma_f32 v132, v196, v132, s54
	v_fma_f32 v133, v197, v133, s54
	v_and_b32_e32 v137, 0x7fffffff, v131
	v_fma_f32 v132, v196, v132, s56
	v_fma_f32 v133, v197, v133, s56
	v_fma_f32 v136, v136, s28, 1.0
	v_fma_f32 v137, v137, s28, 1.0
	v_mul_f32 v132, v196, v132
	v_mul_f32 v133, v197, v133
	v_rcp_f32_e32 v184, v136
	v_mul_f32 v132, v134, v132
	v_mul_f32 v133, v135, v133
	v_rcp_f32_e32 v185, v137
	v_mul_f32 v134, v180, v132
	v_mul_f32 v135, v181, v133
	v_fma_f32 v132, -v180, v132, v180
	v_fma_f32 v133, -v181, v133, v181
	v_cmp_gt_f32_e32 vcc, 0, v180
	v_mul_f32 v114, v114, v50
	v_mul_f32 v115, v115, v51
	v_mul_f32 v110, v110, v70
	v_mul_f32 v111, v111, v71
	v_cndmask_b32_e32 v137, v132, v134, vcc
	v_cmp_gt_f32_e32 vcc, 0, v181
	v_mul_f32 v180, v182, v182
	v_mul_f32 v181, v183, v183
	v_mul_f32 v106, v106, v66
	v_mul_f32 v107, v107, v67
	v_cndmask_b32_e32 v136, v133, v135, vcc
	v_mul_f32 v134, v130, v130
	v_mul_f32 v135, v131, v131
	v_fma_f32 v132, v184, s30, v160
	v_fma_f32 v133, v185, s30, v160
	v_mul_f32 v134, v134, s58
	v_mul_f32 v135, v135, s58
	v_fma_f32 v132, v184, v132, s52
	v_fma_f32 v133, v185, v133, s52
	v_exp_f32_e32 v134, v134
	v_exp_f32_e32 v135, v135
	v_fma_f32 v132, v184, v132, s54
	v_fma_f32 v133, v185, v133, s54
	v_cmp_gt_f32_e32 vcc, 0, v130
	v_fma_f32 v132, v184, v132, s56
	v_fma_f32 v133, v185, v133, s56
	v_mul_f32 v102, v102, v54
	v_mul_f32 v103, v103, v55
	v_mul_f32 v132, v184, v132
	v_mul_f32 v133, v185, v133
	v_mul_f32 v98, v98, v50
	v_mul_f32 v99, v99, v51
	v_mul_f32 v132, v134, v132
	v_mul_f32 v133, v135, v133
	v_and_b32_e32 v135, 0x7fffffff, v183
	v_and_b32_e32 v134, 0x7fffffff, v182
	v_fma_f32 v134, v134, s28, 1.0
	v_fma_f32 v135, v135, s28, 1.0
	v_mul_f32 v184, v130, v132
	v_mul_f32 v185, v131, v133
	v_rcp_f32_e32 v196, v134
	v_rcp_f32_e32 v197, v135
	v_fma_f32 v132, -v130, v132, v130
	v_fma_f32 v133, -v131, v133, v131
	v_mul_f32 v94, v94, v70
	v_mul_f32 v95, v95, v71
	v_cndmask_b32_e32 v135, v132, v184, vcc
	v_cmp_gt_f32_e32 vcc, 0, v131
	v_fma_f32 v130, v196, s30, v160
	v_fma_f32 v131, v197, s30, v160
	v_mul_f32 v90, v90, v66
	v_mul_f32 v91, v91, v67
	v_cndmask_b32_e32 v134, v133, v185, vcc
	v_mul_f32 v132, v180, s58
	v_mul_f32 v133, v181, s58
	v_fma_f32 v130, v196, v130, s52
	v_fma_f32 v131, v197, v131, s52
	v_exp_f32_e32 v132, v132
	v_exp_f32_e32 v133, v133
	v_fma_f32 v130, v196, v130, s54
	v_fma_f32 v131, v197, v131, s54
	v_cmp_gt_f32_e32 vcc, 0, v182
	v_fma_f32 v130, v196, v130, s56
	v_fma_f32 v131, v197, v131, s56
	v_mul_f32 v86, v86, v54
	v_mul_f32 v87, v87, v55
	v_mul_f32 v130, v196, v130
	v_mul_f32 v131, v197, v131
	v_mul_f32 v82, v82, v50
	v_mul_f32 v83, v83, v51
	v_mul_f32 v130, v132, v130
	v_mul_f32 v131, v133, v131
	v_mul_f32 v78, v78, v70
	v_mul_f32 v79, v79, v71
	v_mul_f32 v180, v182, v130
	v_mul_f32 v181, v183, v131
	v_fma_f32 v130, -v182, v130, v182
	v_fma_f32 v131, -v183, v131, v183
	v_mul_f32 v74, v74, v66
	v_mul_f32 v75, v75, v67
	v_cndmask_b32_e32 v133, v130, v180, vcc
	v_cmp_gt_f32_e32 vcc, 0, v183
	v_cvt_pk_bf16_f32 v180, v140, v138
	v_or_b32_e32 v130, 16, v170
	v_mul_f32 v62, v62, v54
	v_mul_f32 v63, v63, v55
	v_cndmask_b32_e32 v132, v131, v181, vcc
	v_cvt_pk_bf16_f32 v181, v137, v136
	v_cvt_pk_bf16_f32 v182, v135, v134
	v_cvt_pk_bf16_f32 v183, v133, v132
	global_store_dwordx4 v[174:175], v[180:183], off offset:256
	v_and_b32_e32 v175, 0x7fffffff, v127
	v_and_b32_e32 v174, 0x7fffffff, v126
	v_fma_f32 v174, v174, s28, 1.0
	v_fma_f32 v175, v175, s28, 1.0
	v_mul_f32 v180, v128, v72
	v_mul_f32 v181, v129, v73
	v_rcp_f32_e32 v174, v174
	v_rcp_f32_e32 v175, v175
	v_mul_f32 v128, v126, v126
	v_mul_f32 v129, v127, v127
	v_mul_f32 v182, v124, v68
	v_mul_f32 v183, v125, v69
	v_mul_f32 v128, v128, s58
	v_mul_f32 v129, v129, s58
	v_fma_f32 v124, v174, s30, v160
	v_fma_f32 v125, v175, s30, v160
	v_exp_f32_e32 v128, v128
	v_fma_f32 v124, v174, v124, s52
	v_fma_f32 v125, v175, v125, s52
	v_exp_f32_e32 v129, v129
	v_fma_f32 v124, v174, v124, s54
	v_fma_f32 v125, v175, v125, s54
	v_and_b32_e32 v185, 0x7fffffff, v181
	v_and_b32_e32 v184, 0x7fffffff, v180
	v_fma_f32 v124, v174, v124, s56
	v_fma_f32 v125, v175, v125, s56
	v_fma_f32 v184, v184, s28, 1.0
; #define GAS __attribute__((address_space(1)))
; __device__ __forceinline__ f32x2 gelu_pk(f32x2 v) {
;     const f32x2 av = __builtin_elementwise_abs(v), d = av * 0.2316418882f + 1.0f;
;     f32x2 t; t.x = __builtin_amdgcn_rcpf(d.x); t.y = __builtin_amdgcn_rcpf(d.y);
;     f32x2 q = t * 0.5307027145f + (-0.7265760135f); q = q * t + 0.7107068705f; q = q * t + (-0.142248368f); q = q * t + 0.127414796f; q = q * t;
;     const f32x2 s = (v * v) * (-0.72134752044f);
;     f32x2 e; e.x = __builtin_amdgcn_exp2f(s.x); e.y = __builtin_amdgcn_exp2f(s.y);
;     const f32x2 m = v * (q * e), r = v - m;
;     f32x2 o; o.x = v.x < 0.f ? m.x : r.x; o.y = v.y < 0.f ? m.y : r.y; return o;
; }
;     __device__ __forceinline__ void operator()(const f32x4 (&acc)[2][2][4][2], const Unit& u, int wr, int wc, int fr, int fq, const float (&pre)[8]) const {
;     ...
;         for (int ai = 0; ai < 2; ++ai)
; #pragma unroll
;             for (int m = 0; m < 4; ++m) {
;                 const int row = row0 + ai * 128 + m * 16; bf16_t* rowp = O + (size_t)row * ldc + col0; float rs = 0.f;
;                 float rsc = 1.f; if (RS == 1) rsc = pre[ai * 4 + m];
; #pragma unroll
;                 for (int bj = 0; bj < 2; ++bj) {
;                     f32x4 v0 = acc[ai][bj][m][0], v1 = acc[ai][bj][m][1];
;                     if (RS == 1) { v0 = v0 * rsc; v1 = v1 * rsc; }
;                     if (RS == 2) { v0 = v0 * csc[bj][0]; v1 = v1 * csc[bj][1]; }
;                     if (ACT == 1) { const f32x2 a = gelu_pk((f32x2){v0[0], v0[1]}), b = gelu_pk((f32x2){v0[2], v0[3]}), c = gelu_pk((f32x2){v1[0], v1[1]}), d = gelu_pk((f32x2){v1[2], v1[3]});
;                         v0 = (f32x4){a.x, a.y, b.x, b.y}; v1 = (f32x4){c.x, c.y, d.x, d.y}; }
;                     v0 = v0 * sc; v1 = v1 * sc;
;                     if (STAT == 1) rs += (v0[0] * v0[0] + v0[1] * v0[1]) + (v0[2] * v0[2] + v0[3] * v0[3]) + (v1[0] * v1[0] + v1[1] * v1[1]) + (v1[2] * v1[2] + v1[3] * v1[3]);
;                     if (STAT == 2) {
; #pragma unroll
;                         for (int e = 0; e < 4; ++e) { cs[bj][0][e] += v0[e]; cq[bj][0][e] += v0[e] * v0[e]; cs[bj][1][e] += v1[e]; cq[bj][1][e] += v1[e] * v1[e]; } }
;                     u32x4 w; w.x = cvt_pk_bf16(v0[0], v0[1]); w.y = cvt_pk_bf16(v0[2], v0[3]); w.z = cvt_pk_bf16(v1[0], v1[1]); w.w = cvt_pk_bf16(v1[2], v1[3]);
;                     *(GAS u32x4*)(rowp + bj * 128) = w; }
	v_fma_f32 v185, v185, s28, 1.0
	v_mul_f32 v124, v174, v124
	v_mul_f32 v125, v175, v125
	v_rcp_f32_e32 v184, v184
	v_rcp_f32_e32 v185, v185
	v_mul_f32 v124, v128, v124
	v_mul_f32 v125, v129, v125
	v_cmp_gt_f32_e32 vcc, 0, v126
	v_mul_f32 v128, v126, v124
	v_mul_f32 v129, v127, v125
	v_fma_f32 v124, -v126, v124, v126
	v_fma_f32 v125, -v127, v125, v127
	v_mul_f32 v174, v180, v180
	v_mul_f32 v175, v181, v181
	v_cndmask_b32_e32 v196, v124, v128, vcc
	v_cmp_gt_f32_e32 vcc, 0, v127
	v_mul_f32 v126, v174, s58
	v_mul_f32 v127, v175, s58
	v_and_b32_e32 v128, 0x7fffffff, v122
	v_cndmask_b32_e32 v141, v125, v129, vcc
	v_fma_f32 v124, v184, s30, v160
	v_fma_f32 v125, v185, s30, v160
	v_exp_f32_e32 v126, v126
	v_fma_f32 v124, v184, v124, s52
	v_fma_f32 v125, v185, v125, s52
	v_exp_f32_e32 v127, v127
	v_fma_f32 v124, v184, v124, s54
	v_fma_f32 v125, v185, v125, s54
	v_and_b32_e32 v129, 0x7fffffff, v123
	v_fma_f32 v124, v184, v124, s56
	v_fma_f32 v125, v185, v125, s56
	v_fma_f32 v128, v128, s28, 1.0
	v_fma_f32 v129, v129, s28, 1.0
	v_mul_f32 v124, v184, v124
	v_mul_f32 v125, v185, v125
	v_rcp_f32_e32 v174, v128
	v_mul_f32 v124, v126, v124
	v_mul_f32 v125, v127, v125
	v_rcp_f32_e32 v175, v129
	v_mul_f32 v126, v180, v124
	v_mul_f32 v127, v181, v125
	v_fma_f32 v124, -v180, v124, v180
	v_fma_f32 v125, -v181, v125, v181
	v_cmp_gt_f32_e32 vcc, 0, v180
	v_ashrrev_i32_e32 v131, 31, v130
	v_lshlrev_b64 v[130:131], s3, v[130:131]
	v_cndmask_b32_e32 v129, v124, v126, vcc
	v_cmp_gt_f32_e32 vcc, 0, v181
	v_lshl_add_u64 v[130:131], v[130:131], 1, s[44:45]
	v_lshl_add_u64 v[130:131], v[130:131], 0, v[172:173]
	v_cndmask_b32_e32 v128, v125, v127, vcc
	v_mul_f32 v126, v122, v122
	v_mul_f32 v127, v123, v123
	v_fma_f32 v124, v174, s30, v160
	v_fma_f32 v125, v175, s30, v160
	v_mul_f32 v126, v126, s58
	v_mul_f32 v127, v127, s58
	v_fma_f32 v124, v174, v124, s52
	v_fma_f32 v125, v175, v125, s52
	v_exp_f32_e32 v126, v126
	v_exp_f32_e32 v127, v127
	v_fma_f32 v124, v174, v124, s54
	v_fma_f32 v125, v175, v125, s54
	v_cmp_gt_f32_e32 vcc, 0, v122
	v_fma_f32 v124, v174, v124, s56
	v_fma_f32 v125, v175, v125, s56
	v_mul_f32 v58, v58, v50
	v_mul_f32 v59, v59, v51
	v_mul_f32 v124, v174, v124
	v_mul_f32 v125, v175, v125
	v_mul_f32 v174, v182, v182
	v_mul_f32 v175, v183, v183
	v_mul_f32 v124, v126, v124
	v_mul_f32 v125, v127, v125
	v_and_b32_e32 v127, 0x7fffffff, v183
	v_and_b32_e32 v126, 0x7fffffff, v182
	v_fma_f32 v126, v126, s28, 1.0
	v_fma_f32 v127, v127, s28, 1.0
	v_mul_f32 v180, v122, v124
	v_mul_f32 v181, v123, v125
	v_rcp_f32_e32 v184, v126
	v_rcp_f32_e32 v185, v127
	v_fma_f32 v124, -v122, v124, v122
	v_fma_f32 v125, -v123, v125, v123
	v_mul_f32 v46, v46, v70
	v_mul_f32 v47, v47, v71
	v_cndmask_b32_e32 v127, v124, v180, vcc
	v_cmp_gt_f32_e32 vcc, 0, v123
	v_fma_f32 v122, v184, s30, v160
	v_fma_f32 v123, v185, s30, v160
	v_cvt_pk_bf16_f32 v180, v196, v141
	v_mul_f32 v42, v42, v66
	v_mul_f32 v43, v43, v67
	v_cndmask_b32_e32 v126, v125, v181, vcc
	v_mul_f32 v124, v174, s58
	v_mul_f32 v125, v175, s58
	v_fma_f32 v122, v184, v122, s52
	v_fma_f32 v123, v185, v123, s52
	v_exp_f32_e32 v124, v124
	v_exp_f32_e32 v125, v125
	v_fma_f32 v122, v184, v122, s54
	v_fma_f32 v123, v185, v123, s54
	v_cmp_gt_f32_e32 vcc, 0, v182
	v_fma_f32 v122, v184, v122, s56
	v_fma_f32 v123, v185, v123, s56
	v_cvt_pk_bf16_f32 v181, v129, v128
	v_mul_f32 v38, v38, v54
	v_mul_f32 v39, v39, v55
	v_mul_f32 v122, v184, v122
	v_mul_f32 v123, v185, v123
	v_mul_f32 v184, v116, v52
	v_mul_f32 v185, v117, v53
	v_mul_f32 v122, v124, v122
	v_mul_f32 v123, v125, v123
	v_mul_f32 v34, v34, v50
	v_mul_f32 v35, v35, v51
	v_mul_f32 v174, v182, v122
	v_mul_f32 v175, v183, v123
	v_fma_f32 v122, -v182, v122, v182
	v_fma_f32 v123, -v183, v123, v183
	v_cvt_pk_bf16_f32 v182, v127, v126
	v_mul_f32 v28, v28, v70
	v_mul_f32 v29, v29, v71
	v_cndmask_b32_e32 v125, v122, v174, vcc
	v_cmp_gt_f32_e32 vcc, 0, v183
	v_mul_f32_e32 v174, v196, v196
	v_mul_f32 v24, v24, v66
	v_mul_f32 v25, v25, v67
	v_cndmask_b32_e32 v123, v123, v175, vcc
	v_cvt_pk_bf16_f32 v183, v125, v123
	global_store_dwordx4 v[130:131], v[180:183], off
	v_add_f32_e32 v175, v196, v198
	v_cmp_gt_f32_e32 vcc, 0, v118
	v_and_b32_e32 v181, 0x7fffffff, v119
	v_and_b32_e32 v180, 0x7fffffff, v118
	v_fma_f32 v180, v180, s28, 1.0
	v_fma_f32 v181, v181, s28, 1.0
	v_mul_f32 v182, v120, v56
	v_mul_f32 v183, v121, v57
	v_rcp_f32_e32 v180, v180
	v_rcp_f32_e32 v181, v181
	v_mul_f32 v120, v118, v118
	v_mul_f32 v121, v119, v119
	v_and_b32_e32 v197, 0x7fffffff, v183
	v_mul_f32 v120, v120, s58
	v_mul_f32 v121, v121, s58
	v_fma_f32 v116, v180, s30, v160
	v_fma_f32 v117, v181, s30, v160
	v_exp_f32_e32 v120, v120
	v_fma_f32 v116, v180, v116, s52
	v_fma_f32 v117, v181, v117, s52
	v_exp_f32_e32 v121, v121
	v_fma_f32 v116, v180, v116, s54
	v_fma_f32 v117, v181, v117, s54
	v_and_b32_e32 v196, 0x7fffffff, v182
	v_fma_f32 v116, v180, v116, s56
	v_fma_f32 v117, v181, v117, s56
	v_fma_f32 v196, v196, s28, 1.0
	v_fma_f32 v197, v197, s28, 1.0
	v_mul_f32 v116, v180, v116
	v_mul_f32 v117, v181, v117
	v_rcp_f32_e32 v196, v196
	v_rcp_f32_e32 v197, v197
	v_mul_f32 v116, v120, v116
	v_mul_f32 v117, v121, v117
	v_mul_f32 v180, v182, v182
	v_mul_f32 v181, v183, v183
	v_mul_f32 v120, v118, v116
	v_mul_f32 v121, v119, v117
	v_fma_f32 v116, -v118, v116, v118
	v_fma_f32 v117, -v119, v117, v119
	v_mul_f32 v20, v20, v54
	v_mul_f32 v21, v21, v55
	v_cndmask_b32_e32 v124, v116, v120, vcc
	v_cmp_gt_f32_e32 vcc, 0, v119
	v_mul_f32 v118, v180, s58
	v_mul_f32 v119, v181, s58
	v_and_b32_e32 v120, 0x7fffffff, v114
	v_cndmask_b32_e32 v122, v117, v121, vcc
	v_fma_f32 v116, v196, s30, v160
	v_fma_f32 v117, v197, s30, v160
; #define GAS __attribute__((address_space(1)))
; __device__ __forceinline__ f32x2 gelu_pk(f32x2 v) {
;     const f32x2 av = __builtin_elementwise_abs(v), d = av * 0.2316418882f + 1.0f;
;     f32x2 t; t.x = __builtin_amdgcn_rcpf(d.x); t.y = __builtin_amdgcn_rcpf(d.y);
;     f32x2 q = t * 0.5307027145f + (-0.7265760135f); q = q * t + 0.7107068705f; q = q * t + (-0.142248368f); q = q * t + 0.127414796f; q = q * t;
;     const f32x2 s = (v * v) * (-0.72134752044f);
;     f32x2 e; e.x = __builtin_amdgcn_exp2f(s.x); e.y = __builtin_amdgcn_exp2f(s.y);
;     const f32x2 m = v * (q * e), r = v - m;
;     f32x2 o; o.x = v.x < 0.f ? m.x : r.x; o.y = v.y < 0.f ? m.y : r.y; return o;
; }
;     __device__ __forceinline__ void operator()(const f32x4 (&acc)[2][2][4][2], const Unit& u, int wr, int wc, int fr, int fq, const float (&pre)[8]) const {
;     ...
;         for (int ai = 0; ai < 2; ++ai)
; #pragma unroll
;             for (int m = 0; m < 4; ++m) {
;                 const int row = row0 + ai * 128 + m * 16; bf16_t* rowp = O + (size_t)row * ldc + col0; float rs = 0.f;
;                 float rsc = 1.f; if (RS == 1) rsc = pre[ai * 4 + m];
; #pragma unroll
;                 for (int bj = 0; bj < 2; ++bj) {
;                     f32x4 v0 = acc[ai][bj][m][0], v1 = acc[ai][bj][m][1];
;                     if (RS == 1) { v0 = v0 * rsc; v1 = v1 * rsc; }
;                     if (RS == 2) { v0 = v0 * csc[bj][0]; v1 = v1 * csc[bj][1]; }
;                     if (ACT == 1) { const f32x2 a = gelu_pk((f32x2){v0[0], v0[1]}), b = gelu_pk((f32x2){v0[2], v0[3]}), c = gelu_pk((f32x2){v1[0], v1[1]}), d = gelu_pk((f32x2){v1[2], v1[3]});
;                         v0 = (f32x4){a.x, a.y, b.x, b.y}; v1 = (f32x4){c.x, c.y, d.x, d.y}; }
;                     v0 = v0 * sc; v1 = v1 * sc;
;                     if (STAT == 1) rs += (v0[0] * v0[0] + v0[1] * v0[1]) + (v0[2] * v0[2] + v0[3] * v0[3]) + (v1[0] * v1[0] + v1[1] * v1[1]) + (v1[2] * v1[2] + v1[3] * v1[3]);
;                     if (STAT == 2) {
; #pragma unroll
;                         for (int e = 0; e < 4; ++e) { cs[bj][0][e] += v0[e]; cq[bj][0][e] += v0[e] * v0[e]; cs[bj][1][e] += v1[e]; cq[bj][1][e] += v1[e] * v1[e]; } }
;                     u32x4 w; w.x = cvt_pk_bf16(v0[0], v0[1]); w.y = cvt_pk_bf16(v0[2], v0[3]); w.z = cvt_pk_bf16(v1[0], v1[1]); w.w = cvt_pk_bf16(v1[2], v1[3]);
;                     *(GAS u32x4*)(rowp + bj * 128) = w; }
	v_exp_f32_e32 v118, v118
	v_fma_f32 v116, v196, v116, s52
	v_fma_f32 v117, v197, v117, s52
	v_exp_f32_e32 v119, v119
	v_fma_f32 v116, v196, v116, s54
	v_fma_f32 v117, v197, v117, s54
	v_and_b32_e32 v121, 0x7fffffff, v115
	v_fma_f32 v116, v196, v116, s56
	v_fma_f32 v117, v197, v117, s56
	v_fma_f32 v120, v120, s28, 1.0
	v_fma_f32 v121, v121, s28, 1.0
	v_mul_f32 v116, v196, v116
	v_mul_f32 v117, v197, v117
	v_rcp_f32_e32 v180, v120
	v_mul_f32 v116, v118, v116
	v_mul_f32 v117, v119, v117
	v_rcp_f32_e32 v181, v121
	v_mul_f32 v118, v182, v116
	v_mul_f32 v119, v183, v117
	v_fma_f32 v116, -v182, v116, v182
	v_fma_f32 v117, -v183, v117, v183
	v_cmp_gt_f32_e32 vcc, 0, v182
	v_mul_f32 v16, v16, v50
	v_mul_f32 v17, v17, v51
	v_mul_f32 v12, v12, v70
	v_mul_f32 v13, v13, v71
	v_cndmask_b32_e32 v121, v116, v118, vcc
	v_cmp_gt_f32_e32 vcc, 0, v183
	v_mul_f32 v10, v10, v68
	v_mul_f32 v11, v11, v69
	v_mul_f32 v8, v8, v66
	v_mul_f32 v9, v9, v67
	v_cndmask_b32_e32 v120, v117, v119, vcc
	v_mul_f32 v118, v114, v114
	v_mul_f32 v119, v115, v115
	v_fma_f32 v116, v180, s30, v160
	v_fma_f32 v117, v181, s30, v160
	v_mul_f32 v118, v118, s58
	v_mul_f32 v119, v119, s58
	v_fma_f32 v116, v180, v116, s52
	v_fma_f32 v117, v181, v117, s52
	v_exp_f32_e32 v118, v118
	v_exp_f32_e32 v119, v119
	v_fma_f32 v116, v180, v116, s54
	v_fma_f32 v117, v181, v117, s54
	v_cmp_gt_f32_e32 vcc, 0, v114
	v_fma_f32 v116, v180, v116, s56
	v_fma_f32 v117, v181, v117, s56
	v_mul_f32 v14, v14, v72
	v_mul_f32 v15, v15, v73
	v_mul_f32 v116, v180, v116
	v_mul_f32 v117, v181, v117
	v_mul_f32 v180, v184, v184
	v_mul_f32 v181, v185, v185
	v_mul_f32 v116, v118, v116
	v_mul_f32 v117, v119, v117
	v_and_b32_e32 v119, 0x7fffffff, v185
	v_and_b32_e32 v118, 0x7fffffff, v184
	v_fma_f32 v118, v118, s28, 1.0
	v_fma_f32 v119, v119, s28, 1.0
	v_mul_f32 v182, v114, v116
	v_mul_f32 v183, v115, v117
	v_rcp_f32_e32 v196, v118
	v_rcp_f32_e32 v197, v119
	v_fma_f32 v116, -v114, v116, v114
	v_fma_f32 v117, -v115, v117, v115
	v_and_b32_e32 v71, 0x7fffffff, v15
	v_cndmask_b32_e32 v119, v116, v182, vcc
	v_cmp_gt_f32_e32 vcc, 0, v115
	v_fma_f32 v114, v196, s30, v160
	v_fma_f32 v115, v197, s30, v160
	v_and_b32_e32 v70, 0x7fffffff, v14
	v_cndmask_b32_e32 v118, v117, v183, vcc
	v_mul_f32 v116, v180, s58
	v_mul_f32 v117, v181, s58
	v_fma_f32 v114, v196, v114, s52
	v_fma_f32 v115, v197, v115, s52
	v_exp_f32_e32 v116, v116
	v_exp_f32_e32 v117, v117
	v_fma_f32 v114, v196, v114, s54
	v_fma_f32 v115, v197, v115, s54
	v_cmp_gt_f32_e32 vcc, 0, v184
	v_fma_f32 v114, v196, v114, s56
	v_fma_f32 v115, v197, v115, s56
	v_fmac_f32_e32 v174, v195, v195
	v_mul_f32 v114, v196, v114
	v_mul_f32 v115, v197, v115
	v_fma_f32 v70, v70, s28, 1.0
	v_fma_f32 v71, v71, s28, 1.0
	v_mul_f32 v114, v116, v114
	v_mul_f32 v115, v117, v115
	v_rcp_f32_e32 v70, v70
	v_mul_f32 v180, v184, v114
	v_mul_f32 v181, v185, v115
	v_fma_f32 v114, -v184, v114, v184
	v_fma_f32 v115, -v185, v115, v185
	v_rcp_f32_e32 v71, v71
	v_cndmask_b32_e32 v117, v114, v180, vcc
	v_cmp_gt_f32_e32 vcc, 0, v185
	v_cvt_pk_bf16_f32 v180, v124, v122
	v_or_b32_e32 v114, 32, v170
	v_mul_f32 v4, v4, v54
	v_mul_f32 v5, v5, v55
	v_cndmask_b32_e32 v116, v115, v181, vcc
	v_cvt_pk_bf16_f32 v181, v121, v120
	v_cvt_pk_bf16_f32 v182, v119, v118
	v_cvt_pk_bf16_f32 v183, v117, v116
	global_store_dwordx4 v[130:131], v[180:183], off offset:256
	v_and_b32_e32 v131, 0x7fffffff, v111
	v_and_b32_e32 v130, 0x7fffffff, v110
	v_fma_f32 v130, v130, s28, 1.0
	v_fma_f32 v131, v131, s28, 1.0
	v_mul_f32 v182, v108, v68
	v_mul_f32 v183, v109, v69
	v_rcp_f32_e32 v130, v130
	v_rcp_f32_e32 v131, v131
	v_mul_f32 v180, v112, v72
	v_mul_f32 v181, v113, v73
	v_mul_f32 v112, v110, v110
	v_mul_f32 v113, v111, v111
	v_cmp_gt_f32_e32 vcc, 0, v110
	v_fma_f32 v108, v130, s30, v160
	v_fma_f32 v109, v131, s30, v160
	v_mul_f32 v112, v112, s58
	v_mul_f32 v113, v113, s58
	v_fma_f32 v108, v130, v108, s52
	v_fma_f32 v109, v131, v109, s52
	v_exp_f32_e32 v112, v112
	v_fma_f32 v108, v130, v108, s54
	v_fma_f32 v109, v131, v109, s54
	v_exp_f32_e32 v113, v113
	v_fma_f32 v108, v130, v108, s56
	v_fma_f32 v109, v131, v109, s56
	v_mul_f32 v184, v180, v180
	v_mul_f32 v185, v181, v181
	v_mul_f32 v108, v130, v108
	v_mul_f32 v109, v131, v109
	v_and_b32_e32 v131, 0x7fffffff, v181
	v_and_b32_e32 v130, 0x7fffffff, v180
	v_fma_f32 v130, v130, s28, 1.0
	v_fma_f32 v131, v131, s28, 1.0
	v_mul_f32 v108, v112, v108
	v_mul_f32 v109, v113, v109
	v_rcp_f32_e32 v196, v130
	v_rcp_f32_e32 v197, v131
	v_mul_f32 v112, v110, v108
	v_mul_f32 v113, v111, v109
	v_fma_f32 v108, -v110, v108, v110
	v_fma_f32 v109, -v111, v109, v111
	v_ashrrev_i32_e32 v115, 31, v114
	v_cndmask_b32_e32 v131, v108, v112, vcc
	v_cmp_gt_f32_e32 vcc, 0, v111
	v_mul_f32 v110, v184, s58
	v_mul_f32 v111, v185, s58
	v_and_b32_e32 v112, 0x7fffffff, v106
	v_cndmask_b32_e32 v130, v109, v113, vcc
	v_fma_f32 v108, v196, s30, v160
	v_fma_f32 v109, v197, s30, v160
	v_exp_f32_e32 v110, v110
	v_fma_f32 v108, v196, v108, s52
	v_fma_f32 v109, v197, v109, s52
	v_exp_f32_e32 v111, v111
	v_fma_f32 v108, v196, v108, s54
	v_fma_f32 v109, v197, v109, s54
	v_and_b32_e32 v113, 0x7fffffff, v107
	v_fma_f32 v108, v196, v108, s56
	v_fma_f32 v109, v197, v109, s56
	v_fma_f32 v112, v112, s28, 1.0
	v_fma_f32 v113, v113, s28, 1.0
	v_mul_f32 v108, v196, v108
	v_mul_f32 v109, v197, v109
	v_rcp_f32_e32 v184, v112
	v_mul_f32 v108, v110, v108
	v_mul_f32 v109, v111, v109
	v_rcp_f32_e32 v185, v113
	v_mul_f32 v110, v180, v108
	v_mul_f32 v111, v181, v109
	v_fma_f32 v108, -v180, v108, v180
	v_fma_f32 v109, -v181, v109, v181
	v_cmp_gt_f32_e32 vcc, 0, v180
	v_lshlrev_b64 v[114:115], s3, v[114:115]
	v_lshl_add_u64 v[114:115], v[114:115], 1, s[44:45]
; __device__ __forceinline__ unsigned cvt_pk_bf16(float lo, float hi) { unsigned r; asm volatile("v_cvt_pk_bf16_f32 %0, %1, %2" : "=v"(r) : "v"(lo), "v"(hi)); return r; }
; #define GAS __attribute__((address_space(1)))
; __device__ __forceinline__ f32x2 gelu_pk(f32x2 v) {
;     const f32x2 av = __builtin_elementwise_abs(v), d = av * 0.2316418882f + 1.0f;
;     f32x2 t; t.x = __builtin_amdgcn_rcpf(d.x); t.y = __builtin_amdgcn_rcpf(d.y);
;     f32x2 q = t * 0.5307027145f + (-0.7265760135f); q = q * t + 0.7107068705f; q = q * t + (-0.142248368f); q = q * t + 0.127414796f; q = q * t;
;     const f32x2 s = (v * v) * (-0.72134752044f);
;     f32x2 e; e.x = __builtin_amdgcn_exp2f(s.x); e.y = __builtin_amdgcn_exp2f(s.y);
;     const f32x2 m = v * (q * e), r = v - m;
;     f32x2 o; o.x = v.x < 0.f ? m.x : r.x; o.y = v.y < 0.f ? m.y : r.y; return o;
;     __device__ __forceinline__ void operator()(const f32x4 (&acc)[2][2][4][2], const Unit& u, int wr, int wc, int fr, int fq, const float (&pre)[8]) const {
;     ...
;                     f32x4 v0 = acc[ai][bj][m][0], v1 = acc[ai][bj][m][1];
;                     if (RS == 1) { v0 = v0 * rsc; v1 = v1 * rsc; }
;                     if (RS == 2) { v0 = v0 * csc[bj][0]; v1 = v1 * csc[bj][1]; }
;                     if (ACT == 1) { const f32x2 a = gelu_pk((f32x2){v0[0], v0[1]}), b = gelu_pk((f32x2){v0[2], v0[3]}), c = gelu_pk((f32x2){v1[0], v1[1]}), d = gelu_pk((f32x2){v1[2], v1[3]});
;                         v0 = (f32x4){a.x, a.y, b.x, b.y}; v1 = (f32x4){c.x, c.y, d.x, d.y}; }
;                     v0 = v0 * sc; v1 = v1 * sc;
;                     if (STAT == 1) rs += (v0[0] * v0[0] + v0[1] * v0[1]) + (v0[2] * v0[2] + v0[3] * v0[3]) + (v1[0] * v1[0] + v1[1] * v1[1]) + (v1[2] * v1[2] + v1[3] * v1[3]);
;                     if (STAT == 2) {
; #pragma unroll
;                         for (int e = 0; e < 4; ++e) { cs[bj][0][e] += v0[e]; cq[bj][0][e] += v0[e] * v0[e]; cs[bj][1][e] += v1[e]; cq[bj][1][e] += v1[e] * v1[e]; } }
;                     u32x4 w; w.x = cvt_pk_bf16(v0[0], v0[1]); w.y = cvt_pk_bf16(v0[2], v0[3]); w.z = cvt_pk_bf16(v1[0], v1[1]); w.w = cvt_pk_bf16(v1[2], v1[3]);
;                     *(GAS u32x4*)(rowp + bj * 128) = w; }
	v_cndmask_b32_e32 v113, v108, v110, vcc
	v_cmp_gt_f32_e32 vcc, 0, v181
	v_mul_f32 v180, v182, v182
	v_mul_f32 v181, v183, v183
	v_lshl_add_u64 v[114:115], v[114:115], 0, v[172:173]
	v_cndmask_b32_e32 v112, v109, v111, vcc
	v_mul_f32 v110, v106, v106
	v_mul_f32 v111, v107, v107
	v_fma_f32 v108, v184, s30, v160
	v_fma_f32 v109, v185, s30, v160
	v_mul_f32 v110, v110, s58
	v_mul_f32 v111, v111, s58
	v_fma_f32 v108, v184, v108, s52
	v_fma_f32 v109, v185, v109, s52
	v_exp_f32_e32 v110, v110
	v_exp_f32_e32 v111, v111
	v_fma_f32 v108, v184, v108, s54
	v_fma_f32 v109, v185, v109, s54
	v_cmp_gt_f32_e32 vcc, 0, v106
	v_fma_f32 v108, v184, v108, s56
	v_fma_f32 v109, v185, v109, s56
	v_add_f32_e32 v175, v131, v175
	v_mul_f32 v108, v184, v108
	v_mul_f32 v109, v185, v109
	v_fmac_f32_e32 v174, v131, v131
	v_mul_f32 v108, v110, v108
	v_mul_f32 v109, v111, v109
	v_and_b32_e32 v111, 0x7fffffff, v183
	v_and_b32_e32 v110, 0x7fffffff, v182
	v_fma_f32 v110, v110, s28, 1.0
	v_fma_f32 v111, v111, s28, 1.0
	v_mul_f32 v184, v106, v108
	v_mul_f32 v185, v107, v109
	v_rcp_f32_e32 v196, v110
	v_rcp_f32_e32 v197, v111
	v_fma_f32 v108, -v106, v108, v106
	v_fma_f32 v109, -v107, v109, v107
	v_mul_f32 v0, v0, v50
	v_mul_f32 v1, v1, v51
	v_cndmask_b32_e32 v111, v108, v184, vcc
	v_cmp_gt_f32_e32 vcc, 0, v107
	v_fma_f32 v106, v196, s30, v160
	v_fma_f32 v107, v197, s30, v160
	v_mul_f32 v50, v4, v4
	v_mul_f32 v51, v5, v5
	v_cndmask_b32_e32 v110, v109, v185, vcc
	v_mul_f32 v108, v180, s58
	v_mul_f32 v109, v181, s58
	v_fma_f32 v106, v196, v106, s52
	v_fma_f32 v107, v197, v107, s52
	v_exp_f32_e32 v108, v108
	v_exp_f32_e32 v109, v109
	v_fma_f32 v106, v196, v106, s54
	v_fma_f32 v107, v197, v107, s54
	v_cmp_gt_f32_e32 vcc, 0, v182
	v_fma_f32 v106, v196, v106, s56
	v_fma_f32 v107, v197, v107, s56
	v_mul_f32 v50, v50, s58
	v_mul_f32 v51, v51, s58
	v_mul_f32 v106, v196, v106
	v_mul_f32 v107, v197, v107
	v_mul_f32 v6, v6, v56
	v_mul_f32 v7, v7, v57
	v_mul_f32 v106, v108, v106
	v_mul_f32 v107, v109, v107
	v_exp_f32_e32 v50, v50
	v_mul_f32 v180, v182, v106
	v_mul_f32 v181, v183, v107
	v_fma_f32 v106, -v182, v106, v182
	v_fma_f32 v107, -v183, v107, v183
	v_exp_f32_e32 v51, v51
	v_cndmask_b32_e32 v109, v106, v180, vcc
	v_cmp_gt_f32_e32 vcc, 0, v183
	v_and_b32_e32 v106, 0x7fffffff, v102
	v_cvt_pk_bf16_f32 v180, v131, v130
	v_mul_f32 v2, v2, v52
	v_mul_f32 v3, v3, v53
	v_cndmask_b32_e32 v108, v107, v181, vcc
	v_and_b32_e32 v107, 0x7fffffff, v103
	v_fma_f32 v106, v106, s28, 1.0
	v_fma_f32 v107, v107, s28, 1.0
	v_cvt_pk_bf16_f32 v181, v113, v112
	v_cvt_pk_bf16_f32 v182, v111, v110
	v_cvt_pk_bf16_f32 v183, v109, v108
	global_store_dwordx4 v[114:115], v[180:183], off
	v_rcp_f32_e32 v106, v106
	v_rcp_f32_e32 v107, v107
	v_mul_f32 v182, v100, v52
	v_mul_f32 v183, v101, v53
	v_mul_f32 v180, v104, v56
	v_mul_f32 v181, v105, v57
	v_mul_f32 v104, v102, v102
	v_mul_f32 v105, v103, v103
	v_fma_f32 v100, v106, s30, v160
	v_fma_f32 v101, v107, s30, v160
	v_mul_f32 v104, v104, s58
	v_mul_f32 v105, v105, s58
	v_fma_f32 v100, v106, v100, s52
	v_fma_f32 v101, v107, v101, s52
	v_exp_f32_e32 v104, v104
	v_fma_f32 v100, v106, v100, s54
	v_fma_f32 v101, v107, v101, s54
	v_exp_f32_e32 v105, v105
	v_fma_f32 v100, v106, v100, s56
	v_fma_f32 v101, v107, v101, s56
	v_cmp_gt_f32_e32 vcc, 0, v102
	v_mul_f32 v100, v106, v100
	v_mul_f32 v101, v107, v101
	v_and_b32_e32 v107, 0x7fffffff, v181
	v_and_b32_e32 v106, 0x7fffffff, v180
	v_fma_f32 v106, v106, s28, 1.0
	v_fma_f32 v107, v107, s28, 1.0
	v_mul_f32 v100, v104, v100
	v_mul_f32 v101, v105, v101
	v_rcp_f32_e32 v196, v106
	v_rcp_f32_e32 v197, v107
	v_mul_f32 v104, v102, v100
	v_mul_f32 v105, v103, v101
	v_fma_f32 v100, -v102, v100, v102
	v_fma_f32 v101, -v103, v101, v103
	v_mul_f32 v184, v180, v180
	v_mul_f32 v185, v181, v181
	v_cndmask_b32_e32 v107, v100, v104, vcc
	v_cmp_gt_f32_e32 vcc, 0, v103
	v_mul_f32 v102, v184, s58
	v_mul_f32 v103, v185, s58
	v_and_b32_e32 v104, 0x7fffffff, v98
	v_cndmask_b32_e32 v106, v101, v105, vcc
	v_fma_f32 v100, v196, s30, v160
	v_fma_f32 v101, v197, s30, v160
	v_exp_f32_e32 v102, v102
	v_fma_f32 v100, v196, v100, s52
	v_fma_f32 v101, v197, v101, s52
	v_exp_f32_e32 v103, v103
	v_fma_f32 v100, v196, v100, s54
	v_fma_f32 v101, v197, v101, s54
	v_and_b32_e32 v105, 0x7fffffff, v99
	v_fma_f32 v100, v196, v100, s56
	v_fma_f32 v101, v197, v101, s56
	v_fma_f32 v104, v104, s28, 1.0
	v_fma_f32 v105, v105, s28, 1.0
	v_mul_f32 v100, v196, v100
	v_mul_f32 v101, v197, v101
	v_rcp_f32_e32 v184, v104
	v_mul_f32 v100, v102, v100
	v_mul_f32 v101, v103, v101
	v_rcp_f32_e32 v185, v105
	v_mul_f32 v102, v180, v100
	v_mul_f32 v103, v181, v101
	v_fma_f32 v100, -v180, v100, v180
	v_fma_f32 v101, -v181, v101, v181
	v_cmp_gt_f32_e32 vcc, 0, v180
	s_nop 1
	v_cndmask_b32_e32 v105, v100, v102, vcc
	v_cmp_gt_f32_e32 vcc, 0, v181
	v_mul_f32 v180, v182, v182
	v_mul_f32 v181, v183, v183
	s_nop 0
	v_cndmask_b32_e32 v104, v101, v103, vcc
	v_mul_f32 v102, v98, v98
	v_mul_f32 v103, v99, v99
	v_fma_f32 v100, v184, s30, v160
	v_fma_f32 v101, v185, s30, v160
	v_mul_f32 v102, v102, s58
	v_mul_f32 v103, v103, s58
	v_fma_f32 v100, v184, v100, s52
	v_fma_f32 v101, v185, v101, s52
	v_exp_f32_e32 v102, v102
	v_exp_f32_e32 v103, v103
	v_fma_f32 v100, v184, v100, s54
	v_fma_f32 v101, v185, v101, s54
	v_cmp_gt_f32_e32 vcc, 0, v98
	v_fma_f32 v100, v184, v100, s56
	v_fma_f32 v101, v185, v101, s56
	s_nop 0
	v_mul_f32 v100, v184, v100
	v_mul_f32 v101, v185, v101
	s_nop 0
	v_mul_f32 v100, v102, v100
	v_mul_f32 v101, v103, v101
	v_and_b32_e32 v103, 0x7fffffff, v183
	v_and_b32_e32 v102, 0x7fffffff, v182
	v_fma_f32 v102, v102, s28, 1.0
	v_fma_f32 v103, v103, s28, 1.0
	v_mul_f32 v184, v98, v100
; __device__ __forceinline__ unsigned cvt_pk_bf16(float lo, float hi) { unsigned r; asm volatile("v_cvt_pk_bf16_f32 %0, %1, %2" : "=v"(r) : "v"(lo), "v"(hi)); return r; }
; #define GAS __attribute__((address_space(1)))
; __device__ __forceinline__ f32x2 gelu_pk(f32x2 v) {
;     const f32x2 av = __builtin_elementwise_abs(v), d = av * 0.2316418882f + 1.0f;
;     f32x2 t; t.x = __builtin_amdgcn_rcpf(d.x); t.y = __builtin_amdgcn_rcpf(d.y);
;     f32x2 q = t * 0.5307027145f + (-0.7265760135f); q = q * t + 0.7107068705f; q = q * t + (-0.142248368f); q = q * t + 0.127414796f; q = q * t;
;     const f32x2 s = (v * v) * (-0.72134752044f);
;     f32x2 e; e.x = __builtin_amdgcn_exp2f(s.x); e.y = __builtin_amdgcn_exp2f(s.y);
;     const f32x2 m = v * (q * e), r = v - m;
;     f32x2 o; o.x = v.x < 0.f ? m.x : r.x; o.y = v.y < 0.f ? m.y : r.y; return o;
;     __device__ __forceinline__ void operator()(const f32x4 (&acc)[2][2][4][2], const Unit& u, int wr, int wc, int fr, int fq, const float (&pre)[8]) const {
;     ...
;                     f32x4 v0 = acc[ai][bj][m][0], v1 = acc[ai][bj][m][1];
;                     if (RS == 1) { v0 = v0 * rsc; v1 = v1 * rsc; }
;                     if (RS == 2) { v0 = v0 * csc[bj][0]; v1 = v1 * csc[bj][1]; }
;                     if (ACT == 1) { const f32x2 a = gelu_pk((f32x2){v0[0], v0[1]}), b = gelu_pk((f32x2){v0[2], v0[3]}), c = gelu_pk((f32x2){v1[0], v1[1]}), d = gelu_pk((f32x2){v1[2], v1[3]});
;                         v0 = (f32x4){a.x, a.y, b.x, b.y}; v1 = (f32x4){c.x, c.y, d.x, d.y}; }
;                     v0 = v0 * sc; v1 = v1 * sc;
;                     if (STAT == 1) rs += (v0[0] * v0[0] + v0[1] * v0[1]) + (v0[2] * v0[2] + v0[3] * v0[3]) + (v1[0] * v1[0] + v1[1] * v1[1]) + (v1[2] * v1[2] + v1[3] * v1[3]);
;                     if (STAT == 2) {
; #pragma unroll
;                         for (int e = 0; e < 4; ++e) { cs[bj][0][e] += v0[e]; cq[bj][0][e] += v0[e] * v0[e]; cs[bj][1][e] += v1[e]; cq[bj][1][e] += v1[e] * v1[e]; } }
;                     u32x4 w; w.x = cvt_pk_bf16(v0[0], v0[1]); w.y = cvt_pk_bf16(v0[2], v0[3]); w.z = cvt_pk_bf16(v1[0], v1[1]); w.w = cvt_pk_bf16(v1[2], v1[3]);
;                     *(GAS u32x4*)(rowp + bj * 128) = w; }
	v_mul_f32 v185, v99, v101
	v_rcp_f32_e32 v196, v102
	v_rcp_f32_e32 v197, v103
	v_fma_f32 v100, -v98, v100, v98
	v_fma_f32 v101, -v99, v101, v99
	s_nop 0
	v_cndmask_b32_e32 v103, v100, v184, vcc
	v_cmp_gt_f32_e32 vcc, 0, v99
	v_fma_f32 v98, v196, s30, v160
	v_fma_f32 v99, v197, s30, v160
	s_nop 0
	v_cndmask_b32_e32 v102, v101, v185, vcc
	v_mul_f32 v100, v180, s58
	v_mul_f32 v101, v181, s58
	v_fma_f32 v98, v196, v98, s52
	v_fma_f32 v99, v197, v99, s52
	v_exp_f32_e32 v100, v100
	v_exp_f32_e32 v101, v101
	v_fma_f32 v98, v196, v98, s54
	v_fma_f32 v99, v197, v99, s54
	v_cmp_gt_f32_e32 vcc, 0, v182
	v_fma_f32 v98, v196, v98, s56
	v_fma_f32 v99, v197, v99, s56
	s_nop 0
	v_mul_f32 v98, v196, v98
	v_mul_f32 v99, v197, v99
	s_nop 0
	v_mul_f32 v98, v100, v98
	v_mul_f32 v99, v101, v99
	s_nop 0
	v_mul_f32 v180, v182, v98
	v_mul_f32 v181, v183, v99
	v_fma_f32 v98, -v182, v98, v182
	v_fma_f32 v99, -v183, v99, v183
	s_nop 0
	v_cndmask_b32_e32 v101, v98, v180, vcc
	v_cmp_gt_f32_e32 vcc, 0, v183
	v_cvt_pk_bf16_f32 v180, v107, v106
	v_or_b32_e32 v98, 48, v170
	s_nop 0
	v_cndmask_b32_e32 v100, v99, v181, vcc
	v_cvt_pk_bf16_f32 v181, v105, v104
	v_cvt_pk_bf16_f32 v182, v103, v102
	v_cvt_pk_bf16_f32 v183, v101, v100
	global_store_dwordx4 v[114:115], v[180:183], off offset:256
	v_and_b32_e32 v115, 0x7fffffff, v95
	v_and_b32_e32 v114, 0x7fffffff, v94
	v_fma_f32 v114, v114, s28, 1.0
	v_fma_f32 v115, v115, s28, 1.0
	v_mul_f32 v182, v92, v68
	v_mul_f32 v183, v93, v69
	v_rcp_f32_e32 v114, v114
	v_rcp_f32_e32 v115, v115
	v_mul_f32 v180, v96, v72
	v_mul_f32 v181, v97, v73
	v_mul_f32 v96, v94, v94
	v_mul_f32 v97, v95, v95
	v_cmp_gt_f32_e32 vcc, 0, v94
	v_fma_f32 v92, v114, s30, v160
	v_fma_f32 v93, v115, s30, v160
	v_mul_f32 v96, v96, s58
	v_mul_f32 v97, v97, s58
	v_fma_f32 v92, v114, v92, s52
	v_fma_f32 v93, v115, v93, s52
	v_exp_f32_e32 v96, v96
	v_fma_f32 v92, v114, v92, s54
	v_fma_f32 v93, v115, v93, s54
	v_exp_f32_e32 v97, v97
	v_fma_f32 v92, v114, v92, s56
	v_fma_f32 v93, v115, v93, s56
	v_mul_f32 v184, v180, v180
	v_mul_f32 v185, v181, v181
	v_mul_f32 v92, v114, v92
	v_mul_f32 v93, v115, v93
	v_and_b32_e32 v115, 0x7fffffff, v181
	v_and_b32_e32 v114, 0x7fffffff, v180
	v_fma_f32 v114, v114, s28, 1.0
	v_fma_f32 v115, v115, s28, 1.0
	v_mul_f32 v92, v96, v92
	v_mul_f32 v93, v97, v93
	v_rcp_f32_e32 v196, v114
	v_rcp_f32_e32 v197, v115
	v_mul_f32 v96, v94, v92
	v_mul_f32 v97, v95, v93
	v_fma_f32 v92, -v94, v92, v94
	v_fma_f32 v93, -v95, v93, v95
	v_ashrrev_i32_e32 v99, 31, v98
	v_cndmask_b32_e32 v115, v92, v96, vcc
	v_cmp_gt_f32_e32 vcc, 0, v95
	v_mul_f32 v94, v184, s58
	v_mul_f32 v95, v185, s58
	v_and_b32_e32 v96, 0x7fffffff, v90
	v_cndmask_b32_e32 v114, v93, v97, vcc
	v_fma_f32 v92, v196, s30, v160
	v_fma_f32 v93, v197, s30, v160
	v_exp_f32_e32 v94, v94
	v_fma_f32 v92, v196, v92, s52
	v_fma_f32 v93, v197, v93, s52
	v_exp_f32_e32 v95, v95
	v_fma_f32 v92, v196, v92, s54
	v_fma_f32 v93, v197, v93, s54
	v_and_b32_e32 v97, 0x7fffffff, v91
	v_fma_f32 v92, v196, v92, s56
	v_fma_f32 v93, v197, v93, s56
	v_fma_f32 v96, v96, s28, 1.0
	v_fma_f32 v97, v97, s28, 1.0
	v_mul_f32 v92, v196, v92
	v_mul_f32 v93, v197, v93
	v_rcp_f32_e32 v184, v96
	v_mul_f32 v92, v94, v92
	v_mul_f32 v93, v95, v93
	v_rcp_f32_e32 v185, v97
	v_mul_f32 v94, v180, v92
	v_mul_f32 v95, v181, v93
	v_fma_f32 v92, -v180, v92, v180
	v_fma_f32 v93, -v181, v93, v181
	v_cmp_gt_f32_e32 vcc, 0, v180
	v_lshlrev_b64 v[98:99], s3, v[98:99]
	v_lshl_add_u64 v[98:99], v[98:99], 1, s[44:45]
	v_cndmask_b32_e32 v97, v92, v94, vcc
	v_cmp_gt_f32_e32 vcc, 0, v181
	v_mul_f32 v180, v182, v182
	v_mul_f32 v181, v183, v183
	v_lshl_add_u64 v[98:99], v[98:99], 0, v[172:173]
	v_cndmask_b32_e32 v96, v93, v95, vcc
	v_mul_f32 v94, v90, v90
	v_mul_f32 v95, v91, v91
	v_fma_f32 v92, v184, s30, v160
	v_fma_f32 v93, v185, s30, v160
	v_mul_f32 v94, v94, s58
	v_mul_f32 v95, v95, s58
	v_fma_f32 v92, v184, v92, s52
	v_fma_f32 v93, v185, v93, s52
	v_exp_f32_e32 v94, v94
	v_exp_f32_e32 v95, v95
	v_fma_f32 v92, v184, v92, s54
	v_fma_f32 v93, v185, v93, s54
	v_cmp_gt_f32_e32 vcc, 0, v90
	v_fma_f32 v92, v184, v92, s56
	v_fma_f32 v93, v185, v93, s56
	v_add_f32_e32 v131, v115, v175
	v_mul_f32 v92, v184, v92
	v_mul_f32 v93, v185, v93
	v_fmac_f32_e32 v174, v115, v115
	v_mul_f32 v92, v94, v92
	v_mul_f32 v93, v95, v93
	v_and_b32_e32 v95, 0x7fffffff, v183
	v_and_b32_e32 v94, 0x7fffffff, v182
	v_fma_f32 v94, v94, s28, 1.0
	v_fma_f32 v95, v95, s28, 1.0
	v_mul_f32 v184, v90, v92
	v_mul_f32 v185, v91, v93
	v_rcp_f32_e32 v196, v94
	v_rcp_f32_e32 v197, v95
	v_fma_f32 v92, -v90, v92, v90
	v_fma_f32 v93, -v91, v93, v91
	s_nop 0
	v_cndmask_b32_e32 v95, v92, v184, vcc
	v_cmp_gt_f32_e32 vcc, 0, v91
	v_fma_f32 v90, v196, s30, v160
	v_fma_f32 v91, v197, s30, v160
	s_nop 0
	v_cndmask_b32_e32 v94, v93, v185, vcc
	v_mul_f32 v92, v180, s58
	v_mul_f32 v93, v181, s58
	v_fma_f32 v90, v196, v90, s52
	v_fma_f32 v91, v197, v91, s52
	v_exp_f32_e32 v92, v92
	v_exp_f32_e32 v93, v93
	v_fma_f32 v90, v196, v90, s54
	v_fma_f32 v91, v197, v91, s54
	v_cmp_gt_f32_e32 vcc, 0, v182
	v_fma_f32 v90, v196, v90, s56
	v_fma_f32 v91, v197, v91, s56
	s_nop 0
	v_mul_f32 v90, v196, v90
	v_mul_f32 v91, v197, v91
	s_nop 0
	v_mul_f32 v90, v92, v90
	v_mul_f32 v91, v93, v91
	s_nop 0
	v_mul_f32 v180, v182, v90
	v_mul_f32 v181, v183, v91
	v_fma_f32 v90, -v182, v90, v182
	v_fma_f32 v91, -v183, v91, v183
	s_nop 0
	v_cndmask_b32_e32 v93, v90, v180, vcc
	v_cmp_gt_f32_e32 vcc, 0, v183
	v_and_b32_e32 v90, 0x7fffffff, v86
	v_cvt_pk_bf16_f32 v180, v115, v114
	s_nop 0
	v_cndmask_b32_e32 v92, v91, v181, vcc
	v_and_b32_e32 v91, 0x7fffffff, v87
	v_fma_f32 v90, v90, s28, 1.0
	v_fma_f32 v91, v91, s28, 1.0
; __device__ __forceinline__ unsigned cvt_pk_bf16(float lo, float hi) { unsigned r; asm volatile("v_cvt_pk_bf16_f32 %0, %1, %2" : "=v"(r) : "v"(lo), "v"(hi)); return r; }
; #define GAS __attribute__((address_space(1)))
; __device__ __forceinline__ f32x2 gelu_pk(f32x2 v) {
;     const f32x2 av = __builtin_elementwise_abs(v), d = av * 0.2316418882f + 1.0f;
;     f32x2 t; t.x = __builtin_amdgcn_rcpf(d.x); t.y = __builtin_amdgcn_rcpf(d.y);
;     f32x2 q = t * 0.5307027145f + (-0.7265760135f); q = q * t + 0.7107068705f; q = q * t + (-0.142248368f); q = q * t + 0.127414796f; q = q * t;
;     const f32x2 s = (v * v) * (-0.72134752044f);
;     f32x2 e; e.x = __builtin_amdgcn_exp2f(s.x); e.y = __builtin_amdgcn_exp2f(s.y);
;     const f32x2 m = v * (q * e), r = v - m;
;     f32x2 o; o.x = v.x < 0.f ? m.x : r.x; o.y = v.y < 0.f ? m.y : r.y; return o;
;     __device__ __forceinline__ void operator()(const f32x4 (&acc)[2][2][4][2], const Unit& u, int wr, int wc, int fr, int fq, const float (&pre)[8]) const {
;     ...
;                     f32x4 v0 = acc[ai][bj][m][0], v1 = acc[ai][bj][m][1];
;                     if (RS == 1) { v0 = v0 * rsc; v1 = v1 * rsc; }
;                     if (RS == 2) { v0 = v0 * csc[bj][0]; v1 = v1 * csc[bj][1]; }
;                     if (ACT == 1) { const f32x2 a = gelu_pk((f32x2){v0[0], v0[1]}), b = gelu_pk((f32x2){v0[2], v0[3]}), c = gelu_pk((f32x2){v1[0], v1[1]}), d = gelu_pk((f32x2){v1[2], v1[3]});
;                         v0 = (f32x4){a.x, a.y, b.x, b.y}; v1 = (f32x4){c.x, c.y, d.x, d.y}; }
;                     v0 = v0 * sc; v1 = v1 * sc;
;                     if (STAT == 1) rs += (v0[0] * v0[0] + v0[1] * v0[1]) + (v0[2] * v0[2] + v0[3] * v0[3]) + (v1[0] * v1[0] + v1[1] * v1[1]) + (v1[2] * v1[2] + v1[3] * v1[3]);
;                     if (STAT == 2) {
; #pragma unroll
;                         for (int e = 0; e < 4; ++e) { cs[bj][0][e] += v0[e]; cq[bj][0][e] += v0[e] * v0[e]; cs[bj][1][e] += v1[e]; cq[bj][1][e] += v1[e] * v1[e]; } }
;                     u32x4 w; w.x = cvt_pk_bf16(v0[0], v0[1]); w.y = cvt_pk_bf16(v0[2], v0[3]); w.z = cvt_pk_bf16(v1[0], v1[1]); w.w = cvt_pk_bf16(v1[2], v1[3]);
;                     *(GAS u32x4*)(rowp + bj * 128) = w; }
	v_cvt_pk_bf16_f32 v181, v97, v96
	v_cvt_pk_bf16_f32 v182, v95, v94
	v_cvt_pk_bf16_f32 v183, v93, v92
	global_store_dwordx4 v[98:99], v[180:183], off
	v_rcp_f32_e32 v90, v90
	v_rcp_f32_e32 v91, v91
	v_mul_f32 v182, v84, v52
	v_mul_f32 v183, v85, v53
	v_mul_f32 v180, v88, v56
	v_mul_f32 v181, v89, v57
	v_mul_f32 v88, v86, v86
	v_mul_f32 v89, v87, v87
	v_fma_f32 v84, v90, s30, v160
	v_fma_f32 v85, v91, s30, v160
	v_mul_f32 v88, v88, s58
	v_mul_f32 v89, v89, s58
	v_fma_f32 v84, v90, v84, s52
	v_fma_f32 v85, v91, v85, s52
	v_exp_f32_e32 v88, v88
	v_fma_f32 v84, v90, v84, s54
	v_fma_f32 v85, v91, v85, s54
	v_exp_f32_e32 v89, v89
	v_fma_f32 v84, v90, v84, s56
	v_fma_f32 v85, v91, v85, s56
	v_cmp_gt_f32_e32 vcc, 0, v86
	v_mul_f32 v84, v90, v84
	v_mul_f32 v85, v91, v85
	v_and_b32_e32 v91, 0x7fffffff, v181
	v_and_b32_e32 v90, 0x7fffffff, v180
	v_fma_f32 v90, v90, s28, 1.0
	v_fma_f32 v91, v91, s28, 1.0
	v_mul_f32 v84, v88, v84
	v_mul_f32 v85, v89, v85
	v_rcp_f32_e32 v196, v90
	v_rcp_f32_e32 v197, v91
	v_mul_f32 v88, v86, v84
	v_mul_f32 v89, v87, v85
	v_fma_f32 v84, -v86, v84, v86
	v_fma_f32 v85, -v87, v85, v87
	v_mul_f32 v184, v180, v180
	v_mul_f32 v185, v181, v181
	v_cndmask_b32_e32 v91, v84, v88, vcc
	v_cmp_gt_f32_e32 vcc, 0, v87
	v_mul_f32 v86, v184, s58
	v_mul_f32 v87, v185, s58
	v_and_b32_e32 v88, 0x7fffffff, v82
	v_cndmask_b32_e32 v90, v85, v89, vcc
	v_fma_f32 v84, v196, s30, v160
	v_fma_f32 v85, v197, s30, v160
	v_exp_f32_e32 v86, v86
	v_fma_f32 v84, v196, v84, s52
	v_fma_f32 v85, v197, v85, s52
	v_exp_f32_e32 v87, v87
	v_fma_f32 v84, v196, v84, s54
	v_fma_f32 v85, v197, v85, s54
	v_and_b32_e32 v89, 0x7fffffff, v83
	v_fma_f32 v84, v196, v84, s56
	v_fma_f32 v85, v197, v85, s56
	v_fma_f32 v88, v88, s28, 1.0
	v_fma_f32 v89, v89, s28, 1.0
	v_mul_f32 v84, v196, v84
	v_mul_f32 v85, v197, v85
	v_rcp_f32_e32 v184, v88
	v_mul_f32 v84, v86, v84
	v_mul_f32 v85, v87, v85
	v_rcp_f32_e32 v185, v89
	v_mul_f32 v86, v180, v84
	v_mul_f32 v87, v181, v85
	v_fma_f32 v84, -v180, v84, v180
	v_fma_f32 v85, -v181, v85, v181
	v_cmp_gt_f32_e32 vcc, 0, v180
	s_nop 1
	v_cndmask_b32_e32 v89, v84, v86, vcc
	v_cmp_gt_f32_e32 vcc, 0, v181
	v_mul_f32 v180, v182, v182
	v_mul_f32 v181, v183, v183
	s_nop 0
	v_cndmask_b32_e32 v88, v85, v87, vcc
	v_mul_f32 v86, v82, v82
	v_mul_f32 v87, v83, v83
	v_fma_f32 v84, v184, s30, v160
	v_fma_f32 v85, v185, s30, v160
	v_mul_f32 v86, v86, s58
	v_mul_f32 v87, v87, s58
	v_fma_f32 v84, v184, v84, s52
	v_fma_f32 v85, v185, v85, s52
	v_exp_f32_e32 v86, v86
	v_exp_f32_e32 v87, v87
	v_fma_f32 v84, v184, v84, s54
	v_fma_f32 v85, v185, v85, s54
	v_cmp_gt_f32_e32 vcc, 0, v82
	v_fma_f32 v84, v184, v84, s56
	v_fma_f32 v85, v185, v85, s56
	s_nop 0
	v_mul_f32 v84, v184, v84
	v_mul_f32 v85, v185, v85
	s_nop 0
	v_mul_f32 v84, v86, v84
	v_mul_f32 v85, v87, v85
	v_and_b32_e32 v87, 0x7fffffff, v183
	v_and_b32_e32 v86, 0x7fffffff, v182
	v_fma_f32 v86, v86, s28, 1.0
	v_fma_f32 v87, v87, s28, 1.0
	v_mul_f32 v184, v82, v84
	v_mul_f32 v185, v83, v85
	v_rcp_f32_e32 v196, v86
	v_rcp_f32_e32 v197, v87
	v_fma_f32 v84, -v82, v84, v82
	v_fma_f32 v85, -v83, v85, v83
	s_nop 0
	v_cndmask_b32_e32 v87, v84, v184, vcc
	v_cmp_gt_f32_e32 vcc, 0, v83
	v_fma_f32 v82, v196, s30, v160
	v_fma_f32 v83, v197, s30, v160
	s_nop 0
	v_cndmask_b32_e32 v86, v85, v185, vcc
	v_mul_f32 v84, v180, s58
	v_mul_f32 v85, v181, s58
	v_fma_f32 v82, v196, v82, s52
	v_fma_f32 v83, v197, v83, s52
	v_exp_f32_e32 v84, v84
	v_exp_f32_e32 v85, v85
	v_fma_f32 v82, v196, v82, s54
	v_fma_f32 v83, v197, v83, s54
	v_cmp_gt_f32_e32 vcc, 0, v182
	v_fma_f32 v82, v196, v82, s56
	v_fma_f32 v83, v197, v83, s56
	s_nop 0
	v_mul_f32 v82, v196, v82
	v_mul_f32 v83, v197, v83
	s_nop 0
	v_mul_f32 v82, v84, v82
	v_mul_f32 v83, v85, v83
	s_nop 0
	v_mul_f32 v180, v182, v82
	v_mul_f32 v181, v183, v83
	v_fma_f32 v82, -v182, v82, v182
	v_fma_f32 v83, -v183, v83, v183
	s_nop 0
	v_cndmask_b32_e32 v85, v82, v180, vcc
	v_cmp_gt_f32_e32 vcc, 0, v183
	v_cvt_pk_bf16_f32 v180, v91, v90
	v_add_u32_e32 v82, 0x80, v170
	s_nop 0
	v_cndmask_b32_e32 v84, v83, v181, vcc
	v_cvt_pk_bf16_f32 v181, v89, v88
	v_cvt_pk_bf16_f32 v182, v87, v86
	v_cvt_pk_bf16_f32 v183, v85, v84
	global_store_dwordx4 v[98:99], v[180:183], off offset:256
	v_and_b32_e32 v99, 0x7fffffff, v79
	v_and_b32_e32 v98, 0x7fffffff, v78
	v_fma_f32 v98, v98, s28, 1.0
	v_fma_f32 v99, v99, s28, 1.0
	v_mul_f32 v182, v76, v68
	v_mul_f32 v183, v77, v69
	v_rcp_f32_e32 v98, v98
	v_rcp_f32_e32 v99, v99
	v_mul_f32 v180, v80, v72
	v_mul_f32 v181, v81, v73
	v_mul_f32 v80, v78, v78
	v_mul_f32 v81, v79, v79
	v_cmp_gt_f32_e32 vcc, 0, v78
	v_fma_f32 v76, v98, s30, v160
	v_fma_f32 v77, v99, s30, v160
	v_mul_f32 v80, v80, s58
	v_mul_f32 v81, v81, s58
	v_fma_f32 v76, v98, v76, s52
	v_fma_f32 v77, v99, v77, s52
	v_exp_f32_e32 v80, v80
	v_fma_f32 v76, v98, v76, s54
	v_fma_f32 v77, v99, v77, s54
	v_exp_f32_e32 v81, v81
	v_fma_f32 v76, v98, v76, s56
	v_fma_f32 v77, v99, v77, s56
	v_mul_f32 v184, v180, v180
	v_mul_f32 v185, v181, v181
	v_mul_f32 v76, v98, v76
	v_mul_f32 v77, v99, v77
	v_and_b32_e32 v99, 0x7fffffff, v181
	v_and_b32_e32 v98, 0x7fffffff, v180
	v_fma_f32 v98, v98, s28, 1.0
	v_fma_f32 v99, v99, s28, 1.0
	v_mul_f32 v76, v80, v76
	v_mul_f32 v77, v81, v77
	v_rcp_f32_e32 v196, v98
	v_rcp_f32_e32 v197, v99
	v_mul_f32 v80, v78, v76
	v_mul_f32 v81, v79, v77
	v_fma_f32 v76, -v78, v76, v78
	v_fma_f32 v77, -v79, v77, v79
	v_ashrrev_i32_e32 v83, 31, v82
	v_cndmask_b32_e32 v99, v76, v80, vcc
	v_cmp_gt_f32_e32 vcc, 0, v79
	v_mul_f32 v78, v184, s58
	v_mul_f32 v79, v185, s58
	v_and_b32_e32 v80, 0x7fffffff, v74
	v_cndmask_b32_e32 v98, v77, v81, vcc
	v_fma_f32 v76, v196, s30, v160
	v_fma_f32 v77, v197, s30, v160
; __device__ __forceinline__ unsigned cvt_pk_bf16(float lo, float hi) { unsigned r; asm volatile("v_cvt_pk_bf16_f32 %0, %1, %2" : "=v"(r) : "v"(lo), "v"(hi)); return r; }
; #define GAS __attribute__((address_space(1)))
; __device__ __forceinline__ f32x2 gelu_pk(f32x2 v) {
;     const f32x2 av = __builtin_elementwise_abs(v), d = av * 0.2316418882f + 1.0f;
;     f32x2 t; t.x = __builtin_amdgcn_rcpf(d.x); t.y = __builtin_amdgcn_rcpf(d.y);
;     f32x2 q = t * 0.5307027145f + (-0.7265760135f); q = q * t + 0.7107068705f; q = q * t + (-0.142248368f); q = q * t + 0.127414796f; q = q * t;
;     const f32x2 s = (v * v) * (-0.72134752044f);
;     f32x2 e; e.x = __builtin_amdgcn_exp2f(s.x); e.y = __builtin_amdgcn_exp2f(s.y);
;     const f32x2 m = v * (q * e), r = v - m;
;     f32x2 o; o.x = v.x < 0.f ? m.x : r.x; o.y = v.y < 0.f ? m.y : r.y; return o;
;     __device__ __forceinline__ void operator()(const f32x4 (&acc)[2][2][4][2], const Unit& u, int wr, int wc, int fr, int fq, const float (&pre)[8]) const {
;     ...
;                     f32x4 v0 = acc[ai][bj][m][0], v1 = acc[ai][bj][m][1];
;                     if (RS == 1) { v0 = v0 * rsc; v1 = v1 * rsc; }
;                     if (RS == 2) { v0 = v0 * csc[bj][0]; v1 = v1 * csc[bj][1]; }
;                     if (ACT == 1) { const f32x2 a = gelu_pk((f32x2){v0[0], v0[1]}), b = gelu_pk((f32x2){v0[2], v0[3]}), c = gelu_pk((f32x2){v1[0], v1[1]}), d = gelu_pk((f32x2){v1[2], v1[3]});
;                         v0 = (f32x4){a.x, a.y, b.x, b.y}; v1 = (f32x4){c.x, c.y, d.x, d.y}; }
;                     v0 = v0 * sc; v1 = v1 * sc;
;                     if (STAT == 1) rs += (v0[0] * v0[0] + v0[1] * v0[1]) + (v0[2] * v0[2] + v0[3] * v0[3]) + (v1[0] * v1[0] + v1[1] * v1[1]) + (v1[2] * v1[2] + v1[3] * v1[3]);
;                     if (STAT == 2) {
; #pragma unroll
;                         for (int e = 0; e < 4; ++e) { cs[bj][0][e] += v0[e]; cq[bj][0][e] += v0[e] * v0[e]; cs[bj][1][e] += v1[e]; cq[bj][1][e] += v1[e] * v1[e]; } }
;                     u32x4 w; w.x = cvt_pk_bf16(v0[0], v0[1]); w.y = cvt_pk_bf16(v0[2], v0[3]); w.z = cvt_pk_bf16(v1[0], v1[1]); w.w = cvt_pk_bf16(v1[2], v1[3]);
;                     *(GAS u32x4*)(rowp + bj * 128) = w; }
	v_exp_f32_e32 v78, v78
	v_fma_f32 v76, v196, v76, s52
	v_fma_f32 v77, v197, v77, s52
	v_exp_f32_e32 v79, v79
	v_fma_f32 v76, v196, v76, s54
	v_fma_f32 v77, v197, v77, s54
	v_and_b32_e32 v81, 0x7fffffff, v75
	v_fma_f32 v76, v196, v76, s56
	v_fma_f32 v77, v197, v77, s56
	v_fma_f32 v80, v80, s28, 1.0
	v_fma_f32 v81, v81, s28, 1.0
	v_mul_f32 v76, v196, v76
	v_mul_f32 v77, v197, v77
	v_rcp_f32_e32 v184, v80
	v_mul_f32 v76, v78, v76
	v_mul_f32 v77, v79, v77
	v_rcp_f32_e32 v185, v81
	v_mul_f32 v78, v180, v76
	v_mul_f32 v79, v181, v77
	v_fma_f32 v76, -v180, v76, v180
	v_fma_f32 v77, -v181, v77, v181
	v_cmp_gt_f32_e32 vcc, 0, v180
	v_lshlrev_b64 v[82:83], s3, v[82:83]
	v_lshl_add_u64 v[82:83], v[82:83], 1, s[44:45]
	v_cndmask_b32_e32 v81, v76, v78, vcc
	v_cmp_gt_f32_e32 vcc, 0, v181
	v_mul_f32 v180, v182, v182
	v_mul_f32 v181, v183, v183
	v_lshl_add_u64 v[82:83], v[82:83], 0, v[172:173]
	v_cndmask_b32_e32 v80, v77, v79, vcc
	v_mul_f32 v78, v74, v74
	v_mul_f32 v79, v75, v75
	v_fma_f32 v76, v184, s30, v160
	v_fma_f32 v77, v185, s30, v160
	v_mul_f32 v78, v78, s58
	v_mul_f32 v79, v79, s58
	v_fma_f32 v76, v184, v76, s52
	v_fma_f32 v77, v185, v77, s52
	v_exp_f32_e32 v78, v78
	v_exp_f32_e32 v79, v79
	v_fma_f32 v76, v184, v76, s54
	v_fma_f32 v77, v185, v77, s54
	v_cmp_gt_f32_e32 vcc, 0, v74
	v_fma_f32 v76, v184, v76, s56
	v_fma_f32 v77, v185, v77, s56
	v_add_f32_e32 v115, v99, v131
	v_mul_f32 v76, v184, v76
	v_mul_f32 v77, v185, v77
	v_fmac_f32_e32 v174, v99, v99
	v_mul_f32 v76, v78, v76
	v_mul_f32 v77, v79, v77
	v_and_b32_e32 v79, 0x7fffffff, v183
	v_and_b32_e32 v78, 0x7fffffff, v182
	v_fma_f32 v78, v78, s28, 1.0
	v_fma_f32 v79, v79, s28, 1.0
	v_mul_f32 v184, v74, v76
	v_mul_f32 v185, v75, v77
	v_rcp_f32_e32 v196, v78
	v_rcp_f32_e32 v197, v79
	v_fma_f32 v76, -v74, v76, v74
	v_fma_f32 v77, -v75, v77, v75
	s_nop 0
	v_cndmask_b32_e32 v79, v76, v184, vcc
	v_cmp_gt_f32_e32 vcc, 0, v75
	v_fma_f32 v74, v196, s30, v160
	v_fma_f32 v75, v197, s30, v160
	s_nop 0
	v_cndmask_b32_e32 v78, v77, v185, vcc
	v_mul_f32 v76, v180, s58
	v_mul_f32 v77, v181, s58
	v_fma_f32 v74, v196, v74, s52
	v_fma_f32 v75, v197, v75, s52
	v_exp_f32_e32 v76, v76
	v_exp_f32_e32 v77, v77
	v_fma_f32 v74, v196, v74, s54
	v_fma_f32 v75, v197, v75, s54
	v_cmp_gt_f32_e32 vcc, 0, v182
	v_fma_f32 v74, v196, v74, s56
	v_fma_f32 v75, v197, v75, s56
	s_nop 0
	v_mul_f32 v74, v196, v74
	v_mul_f32 v75, v197, v75
	s_nop 0
	v_mul_f32 v74, v76, v74
	v_mul_f32 v75, v77, v75
	s_nop 0
	v_mul_f32 v180, v182, v74
	v_mul_f32 v181, v183, v75
	v_fma_f32 v74, -v182, v74, v182
	v_fma_f32 v75, -v183, v75, v183
	s_nop 0
	v_cndmask_b32_e32 v77, v74, v180, vcc
	v_cmp_gt_f32_e32 vcc, 0, v183
	v_and_b32_e32 v74, 0x7fffffff, v62
	v_cvt_pk_bf16_f32 v180, v99, v98
	s_nop 0
	v_cndmask_b32_e32 v76, v75, v181, vcc
	v_and_b32_e32 v75, 0x7fffffff, v63
	v_fma_f32 v74, v74, s28, 1.0
	v_fma_f32 v75, v75, s28, 1.0
	v_cvt_pk_bf16_f32 v181, v81, v80
	v_cvt_pk_bf16_f32 v182, v79, v78
	v_cvt_pk_bf16_f32 v183, v77, v76
	global_store_dwordx4 v[82:83], v[180:183], off
	v_rcp_f32_e32 v74, v74
	v_rcp_f32_e32 v75, v75
	v_mul_f32 v182, v60, v52
	v_mul_f32 v183, v61, v53
	v_mul_f32 v180, v64, v56
	v_mul_f32 v181, v65, v57
	v_mul_f32 v64, v62, v62
	v_mul_f32 v65, v63, v63
	v_fma_f32 v60, v74, s30, v160
	v_fma_f32 v61, v75, s30, v160
	v_mul_f32 v64, v64, s58
	v_mul_f32 v65, v65, s58
	v_fma_f32 v60, v74, v60, s52
	v_fma_f32 v61, v75, v61, s52
	v_exp_f32_e32 v64, v64
	v_fma_f32 v60, v74, v60, s54
	v_fma_f32 v61, v75, v61, s54
	v_exp_f32_e32 v65, v65
	v_fma_f32 v60, v74, v60, s56
	v_fma_f32 v61, v75, v61, s56
	v_cmp_gt_f32_e32 vcc, 0, v62
	v_mul_f32 v60, v74, v60
	v_mul_f32 v61, v75, v61
	v_and_b32_e32 v75, 0x7fffffff, v181
	v_and_b32_e32 v74, 0x7fffffff, v180
	v_fma_f32 v74, v74, s28, 1.0
	v_fma_f32 v75, v75, s28, 1.0
	v_mul_f32 v60, v64, v60
	v_mul_f32 v61, v65, v61
	v_rcp_f32_e32 v196, v74
	v_rcp_f32_e32 v197, v75
	v_mul_f32 v64, v62, v60
	v_mul_f32 v65, v63, v61
	v_fma_f32 v60, -v62, v60, v62
	v_fma_f32 v61, -v63, v61, v63
	v_mul_f32 v184, v180, v180
	v_mul_f32 v185, v181, v181
	v_cndmask_b32_e32 v75, v60, v64, vcc
	v_cmp_gt_f32_e32 vcc, 0, v63
	v_mul_f32 v62, v184, s58
	v_mul_f32 v63, v185, s58
	v_and_b32_e32 v64, 0x7fffffff, v58
	v_cndmask_b32_e32 v74, v61, v65, vcc
	v_fma_f32 v60, v196, s30, v160
	v_fma_f32 v61, v197, s30, v160
	v_exp_f32_e32 v62, v62
	v_fma_f32 v60, v196, v60, s52
	v_fma_f32 v61, v197, v61, s52
	v_exp_f32_e32 v63, v63
	v_fma_f32 v60, v196, v60, s54
	v_fma_f32 v61, v197, v61, s54
	v_and_b32_e32 v65, 0x7fffffff, v59
	v_fma_f32 v60, v196, v60, s56
	v_fma_f32 v61, v197, v61, s56
	v_fma_f32 v64, v64, s28, 1.0
	v_fma_f32 v65, v65, s28, 1.0
	v_mul_f32 v60, v196, v60
	v_mul_f32 v61, v197, v61
	v_rcp_f32_e32 v184, v64
	v_mul_f32 v60, v62, v60
	v_mul_f32 v61, v63, v61
	v_rcp_f32_e32 v185, v65
	v_mul_f32 v62, v180, v60
	v_mul_f32 v63, v181, v61
	v_fma_f32 v60, -v180, v60, v180
	v_fma_f32 v61, -v181, v61, v181
	v_cmp_gt_f32_e32 vcc, 0, v180
	s_nop 1
	v_cndmask_b32_e32 v65, v60, v62, vcc
	v_cmp_gt_f32_e32 vcc, 0, v181
	v_mul_f32 v180, v182, v182
	v_mul_f32 v181, v183, v183
	s_nop 0
	v_cndmask_b32_e32 v64, v61, v63, vcc
	v_mul_f32 v62, v58, v58
	v_mul_f32 v63, v59, v59
	v_fma_f32 v60, v184, s30, v160
	v_fma_f32 v61, v185, s30, v160
	v_mul_f32 v62, v62, s58
	v_mul_f32 v63, v63, s58
	v_fma_f32 v60, v184, v60, s52
	v_fma_f32 v61, v185, v61, s52
	v_exp_f32_e32 v62, v62
	v_exp_f32_e32 v63, v63
	v_fma_f32 v60, v184, v60, s54
	v_fma_f32 v61, v185, v61, s54
	v_cmp_gt_f32_e32 vcc, 0, v58
	v_fma_f32 v60, v184, v60, s56
	v_fma_f32 v61, v185, v61, s56
	s_nop 0
	v_mul_f32 v60, v184, v60
	v_mul_f32 v61, v185, v61
	s_nop 0
	v_mul_f32 v60, v62, v60
; __device__ __forceinline__ unsigned cvt_pk_bf16(float lo, float hi) { unsigned r; asm volatile("v_cvt_pk_bf16_f32 %0, %1, %2" : "=v"(r) : "v"(lo), "v"(hi)); return r; }
; #define GAS __attribute__((address_space(1)))
; __device__ __forceinline__ f32x2 gelu_pk(f32x2 v) {
;     const f32x2 av = __builtin_elementwise_abs(v), d = av * 0.2316418882f + 1.0f;
;     f32x2 t; t.x = __builtin_amdgcn_rcpf(d.x); t.y = __builtin_amdgcn_rcpf(d.y);
;     f32x2 q = t * 0.5307027145f + (-0.7265760135f); q = q * t + 0.7107068705f; q = q * t + (-0.142248368f); q = q * t + 0.127414796f; q = q * t;
;     const f32x2 s = (v * v) * (-0.72134752044f);
;     f32x2 e; e.x = __builtin_amdgcn_exp2f(s.x); e.y = __builtin_amdgcn_exp2f(s.y);
;     const f32x2 m = v * (q * e), r = v - m;
;     f32x2 o; o.x = v.x < 0.f ? m.x : r.x; o.y = v.y < 0.f ? m.y : r.y; return o;
;     __device__ __forceinline__ void operator()(const f32x4 (&acc)[2][2][4][2], const Unit& u, int wr, int wc, int fr, int fq, const float (&pre)[8]) const {
;     ...
;                     f32x4 v0 = acc[ai][bj][m][0], v1 = acc[ai][bj][m][1];
;                     if (RS == 1) { v0 = v0 * rsc; v1 = v1 * rsc; }
;                     if (RS == 2) { v0 = v0 * csc[bj][0]; v1 = v1 * csc[bj][1]; }
;                     if (ACT == 1) { const f32x2 a = gelu_pk((f32x2){v0[0], v0[1]}), b = gelu_pk((f32x2){v0[2], v0[3]}), c = gelu_pk((f32x2){v1[0], v1[1]}), d = gelu_pk((f32x2){v1[2], v1[3]});
;                         v0 = (f32x4){a.x, a.y, b.x, b.y}; v1 = (f32x4){c.x, c.y, d.x, d.y}; }
;                     v0 = v0 * sc; v1 = v1 * sc;
;                     if (STAT == 1) rs += (v0[0] * v0[0] + v0[1] * v0[1]) + (v0[2] * v0[2] + v0[3] * v0[3]) + (v1[0] * v1[0] + v1[1] * v1[1]) + (v1[2] * v1[2] + v1[3] * v1[3]);
;                     if (STAT == 2) {
; #pragma unroll
;                         for (int e = 0; e < 4; ++e) { cs[bj][0][e] += v0[e]; cq[bj][0][e] += v0[e] * v0[e]; cs[bj][1][e] += v1[e]; cq[bj][1][e] += v1[e] * v1[e]; } }
;                     u32x4 w; w.x = cvt_pk_bf16(v0[0], v0[1]); w.y = cvt_pk_bf16(v0[2], v0[3]); w.z = cvt_pk_bf16(v1[0], v1[1]); w.w = cvt_pk_bf16(v1[2], v1[3]);
;                     *(GAS u32x4*)(rowp + bj * 128) = w; }
	v_mul_f32 v61, v63, v61
	v_and_b32_e32 v63, 0x7fffffff, v183
	v_and_b32_e32 v62, 0x7fffffff, v182
	v_fma_f32 v62, v62, s28, 1.0
	v_fma_f32 v63, v63, s28, 1.0
	v_mul_f32 v184, v58, v60
	v_mul_f32 v185, v59, v61
	v_rcp_f32_e32 v196, v62
	v_rcp_f32_e32 v197, v63
	v_fma_f32 v60, -v58, v60, v58
	v_fma_f32 v61, -v59, v61, v59
	s_nop 0
	v_cndmask_b32_e32 v63, v60, v184, vcc
	v_cmp_gt_f32_e32 vcc, 0, v59
	v_fma_f32 v58, v196, s30, v160
	v_fma_f32 v59, v197, s30, v160
	s_nop 0
	v_cndmask_b32_e32 v62, v61, v185, vcc
	v_mul_f32 v60, v180, s58
	v_mul_f32 v61, v181, s58
	v_fma_f32 v58, v196, v58, s52
	v_fma_f32 v59, v197, v59, s52
	v_exp_f32_e32 v60, v60
	v_exp_f32_e32 v61, v61
	v_fma_f32 v58, v196, v58, s54
	v_fma_f32 v59, v197, v59, s54
	v_cmp_gt_f32_e32 vcc, 0, v182
	v_fma_f32 v58, v196, v58, s56
	v_fma_f32 v59, v197, v59, s56
	s_nop 0
	v_mul_f32 v58, v196, v58
	v_mul_f32 v59, v197, v59
	s_nop 0
	v_mul_f32 v58, v60, v58
	v_mul_f32 v59, v61, v59
	s_nop 0
	v_mul_f32 v180, v182, v58
	v_mul_f32 v181, v183, v59
	v_fma_f32 v58, -v182, v58, v182
	v_fma_f32 v59, -v183, v59, v183
	s_nop 0
	v_cndmask_b32_e32 v61, v58, v180, vcc
	v_cmp_gt_f32_e32 vcc, 0, v183
	v_cvt_pk_bf16_f32 v180, v75, v74
	v_add_u32_e32 v58, 0x90, v170
	s_nop 0
	v_cndmask_b32_e32 v60, v59, v181, vcc
	v_cvt_pk_bf16_f32 v181, v65, v64
	v_cvt_pk_bf16_f32 v182, v63, v62
	v_cvt_pk_bf16_f32 v183, v61, v60
	global_store_dwordx4 v[82:83], v[180:183], off offset:256
	v_and_b32_e32 v83, 0x7fffffff, v47
	v_and_b32_e32 v82, 0x7fffffff, v46
	v_fma_f32 v82, v82, s28, 1.0
	v_fma_f32 v83, v83, s28, 1.0
	v_mul_f32 v182, v44, v68
	v_mul_f32 v183, v45, v69
	v_rcp_f32_e32 v82, v82
	v_rcp_f32_e32 v83, v83
	v_mul_f32 v180, v48, v72
	v_mul_f32 v181, v49, v73
	v_mul_f32 v48, v46, v46
	v_mul_f32 v49, v47, v47
	v_cmp_gt_f32_e32 vcc, 0, v46
	v_fma_f32 v44, v82, s30, v160
	v_fma_f32 v45, v83, s30, v160
	v_mul_f32 v48, v48, s58
	v_mul_f32 v49, v49, s58
	v_fma_f32 v44, v82, v44, s52
	v_fma_f32 v45, v83, v45, s52
	v_exp_f32_e32 v48, v48
	v_fma_f32 v44, v82, v44, s54
	v_fma_f32 v45, v83, v45, s54
	v_exp_f32_e32 v49, v49
	v_fma_f32 v44, v82, v44, s56
	v_fma_f32 v45, v83, v45, s56
	v_mul_f32 v184, v180, v180
	v_mul_f32 v185, v181, v181
	v_mul_f32 v44, v82, v44
	v_mul_f32 v45, v83, v45
	v_and_b32_e32 v83, 0x7fffffff, v181
	v_and_b32_e32 v82, 0x7fffffff, v180
	v_fma_f32 v82, v82, s28, 1.0
	v_fma_f32 v83, v83, s28, 1.0
	v_mul_f32 v44, v48, v44
	v_mul_f32 v45, v49, v45
	v_rcp_f32_e32 v196, v82
	v_rcp_f32_e32 v197, v83
	v_mul_f32 v48, v46, v44
	v_mul_f32 v49, v47, v45
	v_fma_f32 v44, -v46, v44, v46
	v_fma_f32 v45, -v47, v45, v47
	v_ashrrev_i32_e32 v59, 31, v58
	v_cndmask_b32_e32 v83, v44, v48, vcc
	v_cmp_gt_f32_e32 vcc, 0, v47
	v_mul_f32 v46, v184, s58
	v_mul_f32 v47, v185, s58
	v_and_b32_e32 v48, 0x7fffffff, v42
	v_cndmask_b32_e32 v82, v45, v49, vcc
	v_fma_f32 v44, v196, s30, v160
	v_fma_f32 v45, v197, s30, v160
	v_exp_f32_e32 v46, v46
	v_fma_f32 v44, v196, v44, s52
	v_fma_f32 v45, v197, v45, s52
	v_exp_f32_e32 v47, v47
	v_fma_f32 v44, v196, v44, s54
	v_fma_f32 v45, v197, v45, s54
	v_and_b32_e32 v49, 0x7fffffff, v43
	v_fma_f32 v44, v196, v44, s56
	v_fma_f32 v45, v197, v45, s56
	v_fma_f32 v48, v48, s28, 1.0
	v_fma_f32 v49, v49, s28, 1.0
	v_mul_f32 v44, v196, v44
	v_mul_f32 v45, v197, v45
	v_rcp_f32_e32 v184, v48
	v_mul_f32 v44, v46, v44
	v_mul_f32 v45, v47, v45
	v_rcp_f32_e32 v185, v49
	v_mul_f32 v46, v180, v44
	v_mul_f32 v47, v181, v45
	v_fma_f32 v44, -v180, v44, v180
	v_fma_f32 v45, -v181, v45, v181
	v_cmp_gt_f32_e32 vcc, 0, v180
	v_lshlrev_b64 v[58:59], s3, v[58:59]
	v_lshl_add_u64 v[58:59], v[58:59], 1, s[44:45]
	v_cndmask_b32_e32 v49, v44, v46, vcc
	v_cmp_gt_f32_e32 vcc, 0, v181
	v_mul_f32 v180, v182, v182
	v_mul_f32 v181, v183, v183
	v_lshl_add_u64 v[58:59], v[58:59], 0, v[172:173]
	v_cndmask_b32_e32 v48, v45, v47, vcc
	v_mul_f32 v46, v42, v42
	v_mul_f32 v47, v43, v43
	v_fma_f32 v44, v184, s30, v160
	v_fma_f32 v45, v185, s30, v160
	v_mul_f32 v46, v46, s58
	v_mul_f32 v47, v47, s58
	v_fma_f32 v44, v184, v44, s52
	v_fma_f32 v45, v185, v45, s52
	v_exp_f32_e32 v46, v46
	v_exp_f32_e32 v47, v47
	v_fma_f32 v44, v184, v44, s54
	v_fma_f32 v45, v185, v45, s54
	v_cmp_gt_f32_e32 vcc, 0, v42
	v_fma_f32 v44, v184, v44, s56
	v_fma_f32 v45, v185, v45, s56
	v_add_f32_e32 v99, v83, v115
	v_mul_f32 v44, v184, v44
	v_mul_f32 v45, v185, v45
	v_fmac_f32_e32 v174, v83, v83
	v_mul_f32 v44, v46, v44
	v_mul_f32 v45, v47, v45
	v_and_b32_e32 v47, 0x7fffffff, v183
	v_and_b32_e32 v46, 0x7fffffff, v182
	v_fma_f32 v46, v46, s28, 1.0
	v_fma_f32 v47, v47, s28, 1.0
	v_mul_f32 v184, v42, v44
	v_mul_f32 v185, v43, v45
	v_rcp_f32_e32 v196, v46
	v_rcp_f32_e32 v197, v47
	v_fma_f32 v44, -v42, v44, v42
	v_fma_f32 v45, -v43, v45, v43
	s_nop 0
	v_cndmask_b32_e32 v47, v44, v184, vcc
	v_cmp_gt_f32_e32 vcc, 0, v43
	v_fma_f32 v42, v196, s30, v160
	v_fma_f32 v43, v197, s30, v160
	s_nop 0
	v_cndmask_b32_e32 v46, v45, v185, vcc
	v_mul_f32 v44, v180, s58
	v_mul_f32 v45, v181, s58
	v_fma_f32 v42, v196, v42, s52
	v_fma_f32 v43, v197, v43, s52
	v_exp_f32_e32 v44, v44
	v_exp_f32_e32 v45, v45
	v_fma_f32 v42, v196, v42, s54
	v_fma_f32 v43, v197, v43, s54
	v_cmp_gt_f32_e32 vcc, 0, v182
	v_fma_f32 v42, v196, v42, s56
	v_fma_f32 v43, v197, v43, s56
	s_nop 0
	v_mul_f32 v42, v196, v42
	v_mul_f32 v43, v197, v43
	s_nop 0
	v_mul_f32 v42, v44, v42
	v_mul_f32 v43, v45, v43
	s_nop 0
	v_mul_f32 v180, v182, v42
	v_mul_f32 v181, v183, v43
	v_fma_f32 v42, -v182, v42, v182
	v_fma_f32 v43, -v183, v43, v183
	s_nop 0
	v_cndmask_b32_e32 v45, v42, v180, vcc
	v_cmp_gt_f32_e32 vcc, 0, v183
	v_and_b32_e32 v42, 0x7fffffff, v38
	v_cvt_pk_bf16_f32 v180, v83, v82
	s_nop 0
	v_cndmask_b32_e32 v44, v43, v181, vcc
; __device__ __forceinline__ unsigned cvt_pk_bf16(float lo, float hi) { unsigned r; asm volatile("v_cvt_pk_bf16_f32 %0, %1, %2" : "=v"(r) : "v"(lo), "v"(hi)); return r; }
; #define GAS __attribute__((address_space(1)))
; __device__ __forceinline__ f32x2 gelu_pk(f32x2 v) {
;     const f32x2 av = __builtin_elementwise_abs(v), d = av * 0.2316418882f + 1.0f;
;     f32x2 t; t.x = __builtin_amdgcn_rcpf(d.x); t.y = __builtin_amdgcn_rcpf(d.y);
;     f32x2 q = t * 0.5307027145f + (-0.7265760135f); q = q * t + 0.7107068705f; q = q * t + (-0.142248368f); q = q * t + 0.127414796f; q = q * t;
;     const f32x2 s = (v * v) * (-0.72134752044f);
;     f32x2 e; e.x = __builtin_amdgcn_exp2f(s.x); e.y = __builtin_amdgcn_exp2f(s.y);
;     const f32x2 m = v * (q * e), r = v - m;
;     f32x2 o; o.x = v.x < 0.f ? m.x : r.x; o.y = v.y < 0.f ? m.y : r.y; return o;
;     __device__ __forceinline__ void operator()(const f32x4 (&acc)[2][2][4][2], const Unit& u, int wr, int wc, int fr, int fq, const float (&pre)[8]) const {
;     ...
;                     f32x4 v0 = acc[ai][bj][m][0], v1 = acc[ai][bj][m][1];
;                     if (RS == 1) { v0 = v0 * rsc; v1 = v1 * rsc; }
;                     if (RS == 2) { v0 = v0 * csc[bj][0]; v1 = v1 * csc[bj][1]; }
;                     if (ACT == 1) { const f32x2 a = gelu_pk((f32x2){v0[0], v0[1]}), b = gelu_pk((f32x2){v0[2], v0[3]}), c = gelu_pk((f32x2){v1[0], v1[1]}), d = gelu_pk((f32x2){v1[2], v1[3]});
;                         v0 = (f32x4){a.x, a.y, b.x, b.y}; v1 = (f32x4){c.x, c.y, d.x, d.y}; }
;                     v0 = v0 * sc; v1 = v1 * sc;
;                     if (STAT == 1) rs += (v0[0] * v0[0] + v0[1] * v0[1]) + (v0[2] * v0[2] + v0[3] * v0[3]) + (v1[0] * v1[0] + v1[1] * v1[1]) + (v1[2] * v1[2] + v1[3] * v1[3]);
;                     if (STAT == 2) {
; #pragma unroll
;                         for (int e = 0; e < 4; ++e) { cs[bj][0][e] += v0[e]; cq[bj][0][e] += v0[e] * v0[e]; cs[bj][1][e] += v1[e]; cq[bj][1][e] += v1[e] * v1[e]; } }
;                     u32x4 w; w.x = cvt_pk_bf16(v0[0], v0[1]); w.y = cvt_pk_bf16(v0[2], v0[3]); w.z = cvt_pk_bf16(v1[0], v1[1]); w.w = cvt_pk_bf16(v1[2], v1[3]);
;                     *(GAS u32x4*)(rowp + bj * 128) = w; }
	v_and_b32_e32 v43, 0x7fffffff, v39
	v_fma_f32 v42, v42, s28, 1.0
	v_fma_f32 v43, v43, s28, 1.0
	v_cvt_pk_bf16_f32 v181, v49, v48
	v_cvt_pk_bf16_f32 v182, v47, v46
	v_cvt_pk_bf16_f32 v183, v45, v44
	global_store_dwordx4 v[58:59], v[180:183], off
	v_rcp_f32_e32 v42, v42
	v_rcp_f32_e32 v43, v43
	v_mul_f32 v182, v36, v52
	v_mul_f32 v183, v37, v53
	v_mul_f32 v180, v40, v56
	v_mul_f32 v181, v41, v57
	v_mul_f32 v40, v38, v38
	v_mul_f32 v41, v39, v39
	v_fma_f32 v36, v42, s30, v160
	v_fma_f32 v37, v43, s30, v160
	v_mul_f32 v40, v40, s58
	v_mul_f32 v41, v41, s58
	v_fma_f32 v36, v42, v36, s52
	v_fma_f32 v37, v43, v37, s52
	v_exp_f32_e32 v40, v40
	v_fma_f32 v36, v42, v36, s54
	v_fma_f32 v37, v43, v37, s54
	v_exp_f32_e32 v41, v41
	v_fma_f32 v36, v42, v36, s56
	v_fma_f32 v37, v43, v37, s56
	v_cmp_gt_f32_e32 vcc, 0, v38
	v_mul_f32 v36, v42, v36
	v_mul_f32 v37, v43, v37
	v_and_b32_e32 v43, 0x7fffffff, v181
	v_and_b32_e32 v42, 0x7fffffff, v180
	v_fma_f32 v42, v42, s28, 1.0
	v_fma_f32 v43, v43, s28, 1.0
	v_mul_f32 v36, v40, v36
	v_mul_f32 v37, v41, v37
	v_rcp_f32_e32 v196, v42
	v_rcp_f32_e32 v197, v43
	v_mul_f32 v40, v38, v36
	v_mul_f32 v41, v39, v37
	v_fma_f32 v36, -v38, v36, v38
	v_fma_f32 v37, -v39, v37, v39
	v_mul_f32 v184, v180, v180
	v_mul_f32 v185, v181, v181
	v_cndmask_b32_e32 v43, v36, v40, vcc
	v_cmp_gt_f32_e32 vcc, 0, v39
	v_mul_f32 v38, v184, s58
	v_mul_f32 v39, v185, s58
	v_and_b32_e32 v40, 0x7fffffff, v34
	v_cndmask_b32_e32 v42, v37, v41, vcc
	v_fma_f32 v36, v196, s30, v160
	v_fma_f32 v37, v197, s30, v160
	v_exp_f32_e32 v38, v38
	v_fma_f32 v36, v196, v36, s52
	v_fma_f32 v37, v197, v37, s52
	v_exp_f32_e32 v39, v39
	v_fma_f32 v36, v196, v36, s54
	v_fma_f32 v37, v197, v37, s54
	v_and_b32_e32 v41, 0x7fffffff, v35
	v_fma_f32 v36, v196, v36, s56
	v_fma_f32 v37, v197, v37, s56
	v_fma_f32 v40, v40, s28, 1.0
	v_fma_f32 v41, v41, s28, 1.0
	v_mul_f32 v36, v196, v36
	v_mul_f32 v37, v197, v37
	v_rcp_f32_e32 v184, v40
	v_mul_f32 v36, v38, v36
	v_mul_f32 v37, v39, v37
	v_rcp_f32_e32 v185, v41
	v_mul_f32 v38, v180, v36
	v_mul_f32 v39, v181, v37
	v_fma_f32 v36, -v180, v36, v180
	v_fma_f32 v37, -v181, v37, v181
	v_cmp_gt_f32_e32 vcc, 0, v180
	s_nop 1
	v_cndmask_b32_e32 v41, v36, v38, vcc
	v_cmp_gt_f32_e32 vcc, 0, v181
	v_mul_f32 v180, v182, v182
	v_mul_f32 v181, v183, v183
	s_nop 0
	v_cndmask_b32_e32 v40, v37, v39, vcc
	v_mul_f32 v38, v34, v34
	v_mul_f32 v39, v35, v35
	v_fma_f32 v36, v184, s30, v160
	v_fma_f32 v37, v185, s30, v160
	v_mul_f32 v38, v38, s58
	v_mul_f32 v39, v39, s58
	v_fma_f32 v36, v184, v36, s52
	v_fma_f32 v37, v185, v37, s52
	v_exp_f32_e32 v38, v38
	v_exp_f32_e32 v39, v39
	v_fma_f32 v36, v184, v36, s54
	v_fma_f32 v37, v185, v37, s54
	v_cmp_gt_f32_e32 vcc, 0, v34
	v_fma_f32 v36, v184, v36, s56
	v_fma_f32 v37, v185, v37, s56
	s_nop 0
	v_mul_f32 v36, v184, v36
	v_mul_f32 v37, v185, v37
	s_nop 0
	v_mul_f32 v36, v38, v36
	v_mul_f32 v37, v39, v37
	v_and_b32_e32 v39, 0x7fffffff, v183
	v_and_b32_e32 v38, 0x7fffffff, v182
	v_fma_f32 v38, v38, s28, 1.0
	v_fma_f32 v39, v39, s28, 1.0
	v_mul_f32 v184, v34, v36
	v_mul_f32 v185, v35, v37
	v_rcp_f32_e32 v196, v38
	v_rcp_f32_e32 v197, v39
	v_fma_f32 v36, -v34, v36, v34
	v_fma_f32 v37, -v35, v37, v35
	s_nop 0
	v_cndmask_b32_e32 v39, v36, v184, vcc
	v_cmp_gt_f32_e32 vcc, 0, v35
	v_fma_f32 v34, v196, s30, v160
	v_fma_f32 v35, v197, s30, v160
	s_nop 0
	v_cndmask_b32_e32 v38, v37, v185, vcc
	v_mul_f32 v36, v180, s58
	v_mul_f32 v37, v181, s58
	v_fma_f32 v34, v196, v34, s52
	v_fma_f32 v35, v197, v35, s52
	v_exp_f32_e32 v36, v36
	v_exp_f32_e32 v37, v37
	v_fma_f32 v34, v196, v34, s54
	v_fma_f32 v35, v197, v35, s54
	v_cmp_gt_f32_e32 vcc, 0, v182
	v_fma_f32 v34, v196, v34, s56
	v_fma_f32 v35, v197, v35, s56
	s_nop 0
	v_mul_f32 v34, v196, v34
	v_mul_f32 v35, v197, v35
	s_nop 0
	v_mul_f32 v34, v36, v34
	v_mul_f32 v35, v37, v35
	s_nop 0
	v_mul_f32 v180, v182, v34
	v_mul_f32 v181, v183, v35
	v_fma_f32 v34, -v182, v34, v182
	v_fma_f32 v35, -v183, v35, v183
	s_nop 0
	v_cndmask_b32_e32 v37, v34, v180, vcc
	v_cmp_gt_f32_e32 vcc, 0, v183
	v_cvt_pk_bf16_f32 v180, v43, v42
	v_add_u32_e32 v34, 0xa0, v170
	s_nop 0
	v_cndmask_b32_e32 v36, v35, v181, vcc
	v_cvt_pk_bf16_f32 v181, v41, v40
	v_cvt_pk_bf16_f32 v182, v39, v38
	v_cvt_pk_bf16_f32 v183, v37, v36
	global_store_dwordx4 v[58:59], v[180:183], off offset:256
	v_and_b32_e32 v59, 0x7fffffff, v29
	v_and_b32_e32 v58, 0x7fffffff, v28
	v_fma_f32 v58, v58, s28, 1.0
	v_fma_f32 v59, v59, s28, 1.0
	v_mul_f32 v182, v26, v68
	v_mul_f32 v183, v27, v69
	v_rcp_f32_e32 v58, v58
	v_rcp_f32_e32 v59, v59
	v_mul_f32 v180, v30, v72
	v_mul_f32 v181, v31, v73
	v_mul_f32 v30, v28, v28
	v_mul_f32 v31, v29, v29
	v_cmp_gt_f32_e32 vcc, 0, v28
	v_fma_f32 v26, v58, s30, v160
	v_fma_f32 v27, v59, s30, v160
	v_mul_f32 v30, v30, s58
	v_mul_f32 v31, v31, s58
	v_fma_f32 v26, v58, v26, s52
	v_fma_f32 v27, v59, v27, s52
	v_exp_f32_e32 v30, v30
	v_fma_f32 v26, v58, v26, s54
	v_fma_f32 v27, v59, v27, s54
	v_exp_f32_e32 v31, v31
	v_fma_f32 v26, v58, v26, s56
	v_fma_f32 v27, v59, v27, s56
	v_mul_f32 v184, v180, v180
	v_mul_f32 v185, v181, v181
	v_mul_f32 v26, v58, v26
	v_mul_f32 v27, v59, v27
	v_and_b32_e32 v59, 0x7fffffff, v181
	v_and_b32_e32 v58, 0x7fffffff, v180
	v_fma_f32 v58, v58, s28, 1.0
	v_fma_f32 v59, v59, s28, 1.0
	v_mul_f32 v26, v30, v26
	v_mul_f32 v27, v31, v27
	v_rcp_f32_e32 v196, v58
	v_rcp_f32_e32 v197, v59
	v_mul_f32 v30, v28, v26
	v_mul_f32 v31, v29, v27
	v_fma_f32 v26, -v28, v26, v28
	v_fma_f32 v27, -v29, v27, v29
	v_ashrrev_i32_e32 v35, 31, v34
	v_cndmask_b32_e32 v59, v26, v30, vcc
	v_cmp_gt_f32_e32 vcc, 0, v29
	v_mul_f32 v28, v184, s58
	v_mul_f32 v29, v185, s58
	v_and_b32_e32 v30, 0x7fffffff, v24
; __device__ __forceinline__ unsigned cvt_pk_bf16(float lo, float hi) { unsigned r; asm volatile("v_cvt_pk_bf16_f32 %0, %1, %2" : "=v"(r) : "v"(lo), "v"(hi)); return r; }
; #define GAS __attribute__((address_space(1)))
; __device__ __forceinline__ f32x2 gelu_pk(f32x2 v) {
;     const f32x2 av = __builtin_elementwise_abs(v), d = av * 0.2316418882f + 1.0f;
;     f32x2 t; t.x = __builtin_amdgcn_rcpf(d.x); t.y = __builtin_amdgcn_rcpf(d.y);
;     f32x2 q = t * 0.5307027145f + (-0.7265760135f); q = q * t + 0.7107068705f; q = q * t + (-0.142248368f); q = q * t + 0.127414796f; q = q * t;
;     const f32x2 s = (v * v) * (-0.72134752044f);
;     f32x2 e; e.x = __builtin_amdgcn_exp2f(s.x); e.y = __builtin_amdgcn_exp2f(s.y);
;     const f32x2 m = v * (q * e), r = v - m;
;     f32x2 o; o.x = v.x < 0.f ? m.x : r.x; o.y = v.y < 0.f ? m.y : r.y; return o;
;     __device__ __forceinline__ void operator()(const f32x4 (&acc)[2][2][4][2], const Unit& u, int wr, int wc, int fr, int fq, const float (&pre)[8]) const {
;     ...
;                     f32x4 v0 = acc[ai][bj][m][0], v1 = acc[ai][bj][m][1];
;                     if (RS == 1) { v0 = v0 * rsc; v1 = v1 * rsc; }
;                     if (RS == 2) { v0 = v0 * csc[bj][0]; v1 = v1 * csc[bj][1]; }
;                     if (ACT == 1) { const f32x2 a = gelu_pk((f32x2){v0[0], v0[1]}), b = gelu_pk((f32x2){v0[2], v0[3]}), c = gelu_pk((f32x2){v1[0], v1[1]}), d = gelu_pk((f32x2){v1[2], v1[3]});
;                         v0 = (f32x4){a.x, a.y, b.x, b.y}; v1 = (f32x4){c.x, c.y, d.x, d.y}; }
;                     v0 = v0 * sc; v1 = v1 * sc;
;                     if (STAT == 1) rs += (v0[0] * v0[0] + v0[1] * v0[1]) + (v0[2] * v0[2] + v0[3] * v0[3]) + (v1[0] * v1[0] + v1[1] * v1[1]) + (v1[2] * v1[2] + v1[3] * v1[3]);
;                     if (STAT == 2) {
; #pragma unroll
;                         for (int e = 0; e < 4; ++e) { cs[bj][0][e] += v0[e]; cq[bj][0][e] += v0[e] * v0[e]; cs[bj][1][e] += v1[e]; cq[bj][1][e] += v1[e] * v1[e]; } }
;                     u32x4 w; w.x = cvt_pk_bf16(v0[0], v0[1]); w.y = cvt_pk_bf16(v0[2], v0[3]); w.z = cvt_pk_bf16(v1[0], v1[1]); w.w = cvt_pk_bf16(v1[2], v1[3]);
;                     *(GAS u32x4*)(rowp + bj * 128) = w; }
	v_cndmask_b32_e32 v58, v27, v31, vcc
	v_fma_f32 v26, v196, s30, v160
	v_fma_f32 v27, v197, s30, v160
	v_exp_f32_e32 v28, v28
	v_fma_f32 v26, v196, v26, s52
	v_fma_f32 v27, v197, v27, s52
	v_exp_f32_e32 v29, v29
	v_fma_f32 v26, v196, v26, s54
	v_fma_f32 v27, v197, v27, s54
	v_and_b32_e32 v31, 0x7fffffff, v25
	v_fma_f32 v26, v196, v26, s56
	v_fma_f32 v27, v197, v27, s56
	v_fma_f32 v30, v30, s28, 1.0
	v_fma_f32 v31, v31, s28, 1.0
	v_mul_f32 v26, v196, v26
	v_mul_f32 v27, v197, v27
	v_rcp_f32_e32 v184, v30
	v_mul_f32 v26, v28, v26
	v_mul_f32 v27, v29, v27
	v_rcp_f32_e32 v185, v31
	v_mul_f32 v28, v180, v26
	v_mul_f32 v29, v181, v27
	v_fma_f32 v26, -v180, v26, v180
	v_fma_f32 v27, -v181, v27, v181
	v_cmp_gt_f32_e32 vcc, 0, v180
	v_lshlrev_b64 v[34:35], s3, v[34:35]
	v_lshl_add_u64 v[34:35], v[34:35], 1, s[44:45]
	v_cndmask_b32_e32 v31, v26, v28, vcc
	v_cmp_gt_f32_e32 vcc, 0, v181
	v_mul_f32 v180, v182, v182
	v_mul_f32 v181, v183, v183
	v_lshl_add_u64 v[34:35], v[34:35], 0, v[172:173]
	v_cndmask_b32_e32 v30, v27, v29, vcc
	v_mul_f32 v28, v24, v24
	v_mul_f32 v29, v25, v25
	v_fma_f32 v26, v184, s30, v160
	v_fma_f32 v27, v185, s30, v160
	v_mul_f32 v28, v28, s58
	v_mul_f32 v29, v29, s58
	v_fma_f32 v26, v184, v26, s52
	v_fma_f32 v27, v185, v27, s52
	v_exp_f32_e32 v28, v28
	v_exp_f32_e32 v29, v29
	v_fma_f32 v26, v184, v26, s54
	v_fma_f32 v27, v185, v27, s54
	v_cmp_gt_f32_e32 vcc, 0, v24
	v_fma_f32 v26, v184, v26, s56
	v_fma_f32 v27, v185, v27, s56
	v_mul_f32 v68, v12, v12
	v_mul_f32 v69, v13, v13
	v_mul_f32 v26, v184, v26
	v_mul_f32 v27, v185, v27
	v_mul_f32 v68, v68, s58
	v_mul_f32 v69, v69, s58
	v_mul_f32 v26, v28, v26
	v_mul_f32 v27, v29, v27
	v_and_b32_e32 v29, 0x7fffffff, v183
	v_and_b32_e32 v28, 0x7fffffff, v182
	v_fma_f32 v28, v28, s28, 1.0
	v_fma_f32 v29, v29, s28, 1.0
	v_mul_f32 v184, v24, v26
	v_mul_f32 v185, v25, v27
	v_rcp_f32_e32 v196, v28
	v_rcp_f32_e32 v197, v29
	v_fma_f32 v26, -v24, v26, v24
	v_fma_f32 v27, -v25, v27, v25
	v_exp_f32_e32 v68, v68
	v_cndmask_b32_e32 v29, v26, v184, vcc
	v_cmp_gt_f32_e32 vcc, 0, v25
	v_fma_f32 v24, v196, s30, v160
	v_fma_f32 v25, v197, s30, v160
	v_exp_f32_e32 v69, v69
	v_cndmask_b32_e32 v28, v27, v185, vcc
	v_mul_f32 v26, v180, s58
	v_mul_f32 v27, v181, s58
	v_fma_f32 v24, v196, v24, s52
	v_fma_f32 v25, v197, v25, s52
	v_exp_f32_e32 v26, v26
	v_exp_f32_e32 v27, v27
	v_fma_f32 v24, v196, v24, s54
	v_fma_f32 v25, v197, v25, s54
	v_cmp_gt_f32_e32 vcc, 0, v182
	v_fma_f32 v24, v196, v24, s56
	v_fma_f32 v25, v197, v25, s56
	v_add_f32_e32 v83, v59, v99
	v_mul_f32 v24, v196, v24
	v_mul_f32 v25, v197, v25
	v_fmac_f32_e32 v174, v59, v59
	v_mul_f32 v24, v26, v24
	v_mul_f32 v25, v27, v25
	s_nop 0
	v_mul_f32 v180, v182, v24
	v_mul_f32 v181, v183, v25
	v_fma_f32 v24, -v182, v24, v182
	v_fma_f32 v25, -v183, v25, v183
	s_nop 0
	v_cndmask_b32_e32 v27, v24, v180, vcc
	v_cmp_gt_f32_e32 vcc, 0, v183
	v_and_b32_e32 v24, 0x7fffffff, v20
	v_cvt_pk_bf16_f32 v180, v59, v58
	s_nop 0
	v_cndmask_b32_e32 v26, v25, v181, vcc
	v_and_b32_e32 v25, 0x7fffffff, v21
	v_fma_f32 v24, v24, s28, 1.0
	v_fma_f32 v25, v25, s28, 1.0
	v_cvt_pk_bf16_f32 v181, v31, v30
	v_cvt_pk_bf16_f32 v182, v29, v28
	v_cvt_pk_bf16_f32 v183, v27, v26
	global_store_dwordx4 v[34:35], v[180:183], off
	v_rcp_f32_e32 v24, v24
	v_rcp_f32_e32 v25, v25
	v_mul_f32 v182, v18, v52
	v_mul_f32 v183, v19, v53
	v_mul_f32 v180, v22, v56
	v_mul_f32 v181, v23, v57
	v_mul_f32 v22, v20, v20
	v_mul_f32 v23, v21, v21
	v_fma_f32 v18, v24, s30, v160
	v_fma_f32 v19, v25, s30, v160
	v_mul_f32 v22, v22, s58
	v_mul_f32 v23, v23, s58
	v_fma_f32 v18, v24, v18, s52
	v_fma_f32 v19, v25, v19, s52
	v_exp_f32_e32 v22, v22
	v_fma_f32 v18, v24, v18, s54
	v_fma_f32 v19, v25, v19, s54
	v_exp_f32_e32 v23, v23
	v_fma_f32 v18, v24, v18, s56
	v_fma_f32 v19, v25, v19, s56
	v_cmp_gt_f32_e32 vcc, 0, v20
	v_mul_f32 v18, v24, v18
	v_mul_f32 v19, v25, v19
	v_and_b32_e32 v25, 0x7fffffff, v181
	v_and_b32_e32 v24, 0x7fffffff, v180
	v_fma_f32 v24, v24, s28, 1.0
	v_fma_f32 v25, v25, s28, 1.0
	v_mul_f32 v18, v22, v18
	v_mul_f32 v19, v23, v19
	v_rcp_f32_e32 v196, v24
	v_rcp_f32_e32 v197, v25
	v_mul_f32 v22, v20, v18
	v_mul_f32 v23, v21, v19
	v_fma_f32 v18, -v20, v18, v20
	v_fma_f32 v19, -v21, v19, v21
	v_mul_f32 v184, v180, v180
	v_mul_f32 v185, v181, v181
	v_cndmask_b32_e32 v25, v18, v22, vcc
	v_cmp_gt_f32_e32 vcc, 0, v21
	v_mul_f32 v20, v184, s58
	v_mul_f32 v21, v185, s58
	v_and_b32_e32 v22, 0x7fffffff, v16
	v_cndmask_b32_e32 v24, v19, v23, vcc
	v_fma_f32 v18, v196, s30, v160
	v_fma_f32 v19, v197, s30, v160
	v_exp_f32_e32 v20, v20
	v_fma_f32 v18, v196, v18, s52
	v_fma_f32 v19, v197, v19, s52
	v_exp_f32_e32 v21, v21
	v_fma_f32 v18, v196, v18, s54
	v_fma_f32 v19, v197, v19, s54
	v_and_b32_e32 v23, 0x7fffffff, v17
	v_fma_f32 v18, v196, v18, s56
	v_fma_f32 v19, v197, v19, s56
	v_fma_f32 v22, v22, s28, 1.0
	v_fma_f32 v23, v23, s28, 1.0
	v_mul_f32 v18, v196, v18
	v_mul_f32 v19, v197, v19
	v_rcp_f32_e32 v184, v22
	v_mul_f32 v18, v20, v18
	v_mul_f32 v19, v21, v19
	v_rcp_f32_e32 v185, v23
	v_mul_f32 v20, v180, v18
	v_mul_f32 v21, v181, v19
	v_fma_f32 v18, -v180, v18, v180
	v_fma_f32 v19, -v181, v19, v181
	v_cmp_gt_f32_e32 vcc, 0, v180
	v_mul_f32 v52, v6, v6
	v_mul_f32 v53, v7, v7
	s_nop 0
	v_cndmask_b32_e32 v23, v18, v20, vcc
	v_cmp_gt_f32_e32 vcc, 0, v181
	v_mul_f32 v180, v182, v182
	v_mul_f32 v181, v183, v183
	s_nop 0
	v_cndmask_b32_e32 v22, v19, v21, vcc
	v_mul_f32 v20, v16, v16
	v_mul_f32 v21, v17, v17
	v_fma_f32 v18, v184, s30, v160
	v_fma_f32 v19, v185, s30, v160
	v_mul_f32 v20, v20, s58
	v_mul_f32 v21, v21, s58
	v_fma_f32 v18, v184, v18, s52
	v_fma_f32 v19, v185, v19, s52
	v_exp_f32_e32 v20, v20
	v_exp_f32_e32 v21, v21
; __device__ __forceinline__ unsigned cvt_pk_bf16(float lo, float hi) { unsigned r; asm volatile("v_cvt_pk_bf16_f32 %0, %1, %2" : "=v"(r) : "v"(lo), "v"(hi)); return r; }
; #define GAS __attribute__((address_space(1)))
; __device__ __forceinline__ f32x2 gelu_pk(f32x2 v) {
;     const f32x2 av = __builtin_elementwise_abs(v), d = av * 0.2316418882f + 1.0f;
;     f32x2 t; t.x = __builtin_amdgcn_rcpf(d.x); t.y = __builtin_amdgcn_rcpf(d.y);
;     f32x2 q = t * 0.5307027145f + (-0.7265760135f); q = q * t + 0.7107068705f; q = q * t + (-0.142248368f); q = q * t + 0.127414796f; q = q * t;
;     const f32x2 s = (v * v) * (-0.72134752044f);
;     f32x2 e; e.x = __builtin_amdgcn_exp2f(s.x); e.y = __builtin_amdgcn_exp2f(s.y);
;     const f32x2 m = v * (q * e), r = v - m;
;     f32x2 o; o.x = v.x < 0.f ? m.x : r.x; o.y = v.y < 0.f ? m.y : r.y; return o;
;     __device__ __forceinline__ void operator()(const f32x4 (&acc)[2][2][4][2], const Unit& u, int wr, int wc, int fr, int fq, const float (&pre)[8]) const {
;     ...
;                     f32x4 v0 = acc[ai][bj][m][0], v1 = acc[ai][bj][m][1];
;                     if (RS == 1) { v0 = v0 * rsc; v1 = v1 * rsc; }
;                     if (RS == 2) { v0 = v0 * csc[bj][0]; v1 = v1 * csc[bj][1]; }
;                     if (ACT == 1) { const f32x2 a = gelu_pk((f32x2){v0[0], v0[1]}), b = gelu_pk((f32x2){v0[2], v0[3]}), c = gelu_pk((f32x2){v1[0], v1[1]}), d = gelu_pk((f32x2){v1[2], v1[3]});
;                         v0 = (f32x4){a.x, a.y, b.x, b.y}; v1 = (f32x4){c.x, c.y, d.x, d.y}; }
;                     v0 = v0 * sc; v1 = v1 * sc;
;                     if (STAT == 1) rs += (v0[0] * v0[0] + v0[1] * v0[1]) + (v0[2] * v0[2] + v0[3] * v0[3]) + (v1[0] * v1[0] + v1[1] * v1[1]) + (v1[2] * v1[2] + v1[3] * v1[3]);
;                     if (STAT == 2) {
; #pragma unroll
;                         for (int e = 0; e < 4; ++e) { cs[bj][0][e] += v0[e]; cq[bj][0][e] += v0[e] * v0[e]; cs[bj][1][e] += v1[e]; cq[bj][1][e] += v1[e] * v1[e]; } }
;                     u32x4 w; w.x = cvt_pk_bf16(v0[0], v0[1]); w.y = cvt_pk_bf16(v0[2], v0[3]); w.z = cvt_pk_bf16(v1[0], v1[1]); w.w = cvt_pk_bf16(v1[2], v1[3]);
;                     *(GAS u32x4*)(rowp + bj * 128) = w; }
	v_fma_f32 v18, v184, v18, s54
	v_fma_f32 v19, v185, v19, s54
	v_cmp_gt_f32_e32 vcc, 0, v16
	v_fma_f32 v18, v184, v18, s56
	v_fma_f32 v19, v185, v19, s56
	s_nop 0
	v_mul_f32 v18, v184, v18
	v_mul_f32 v19, v185, v19
	s_nop 0
	v_mul_f32 v18, v20, v18
	v_mul_f32 v19, v21, v19
	v_and_b32_e32 v21, 0x7fffffff, v183
	v_and_b32_e32 v20, 0x7fffffff, v182
	v_fma_f32 v20, v20, s28, 1.0
	v_fma_f32 v21, v21, s28, 1.0
	v_mul_f32 v184, v16, v18
	v_mul_f32 v185, v17, v19
	v_rcp_f32_e32 v196, v20
	v_rcp_f32_e32 v197, v21
	v_fma_f32 v18, -v16, v18, v16
	v_fma_f32 v19, -v17, v19, v17
	s_nop 0
	v_cndmask_b32_e32 v21, v18, v184, vcc
	v_cmp_gt_f32_e32 vcc, 0, v17
	v_fma_f32 v16, v196, s30, v160
	v_fma_f32 v17, v197, s30, v160
	s_nop 0
	v_cndmask_b32_e32 v20, v19, v185, vcc
	v_mul_f32 v18, v180, s58
	v_mul_f32 v19, v181, s58
	v_fma_f32 v16, v196, v16, s52
	v_fma_f32 v17, v197, v17, s52
	v_exp_f32_e32 v18, v18
	v_exp_f32_e32 v19, v19
	v_fma_f32 v16, v196, v16, s54
	v_fma_f32 v17, v197, v17, s54
	v_cmp_gt_f32_e32 vcc, 0, v182
	v_fma_f32 v16, v196, v16, s56
	v_fma_f32 v17, v197, v17, s56
	s_nop 0
	v_mul_f32 v16, v196, v16
	v_mul_f32 v17, v197, v17
	s_nop 0
	v_mul_f32 v16, v18, v16
	v_mul_f32 v17, v19, v17
	s_nop 0
	v_mul_f32 v180, v182, v16
	v_mul_f32 v181, v183, v17
	v_fma_f32 v16, -v182, v16, v182
	v_fma_f32 v17, -v183, v17, v183
	s_nop 0
	v_cndmask_b32_e32 v19, v16, v180, vcc
	v_cmp_gt_f32_e32 vcc, 0, v183
	v_cvt_pk_bf16_f32 v180, v25, v24
	v_add_u32_e32 v16, 0xb0, v170
	s_nop 0
	v_cndmask_b32_e32 v18, v17, v181, vcc
	v_cvt_pk_bf16_f32 v181, v23, v22
	v_cvt_pk_bf16_f32 v182, v21, v20
	v_cvt_pk_bf16_f32 v183, v19, v18
	global_store_dwordx4 v[34:35], v[180:183], off offset:256
	v_and_b32_e32 v35, 0x7fffffff, v13
	v_and_b32_e32 v34, 0x7fffffff, v12
	v_fma_f32 v34, v34, s28, 1.0
	v_fma_f32 v35, v35, s28, 1.0
	v_cmp_gt_f32_e32 vcc, 0, v12
	v_rcp_f32_e32 v34, v34
	v_rcp_f32_e32 v35, v35
	v_ashrrev_i32_e32 v17, 31, v16
	v_lshlrev_b64 v[16:17], s3, v[16:17]
	v_lshl_add_u64 v[16:17], v[16:17], 1, s[44:45]
	v_fma_f32 v66, v34, s30, v160
	v_fma_f32 v67, v35, s30, v160
	v_lshl_add_u64 v[16:17], v[16:17], 0, v[172:173]
	v_fma_f32 v66, v34, v66, s52
	v_fma_f32 v67, v35, v67, s52
	s_lshl_b32 s3, s90, 1
	v_fma_f32 v66, v34, v66, s54
	v_fma_f32 v67, v35, v67, s54
	s_ashr_i32 s7, s3, 31
	v_fma_f32 v66, v34, v66, s56
	v_fma_f32 v67, v35, v67, s56
	s_add_u32 s44, s3, s81
	v_mul_f32 v34, v34, v66
	v_mul_f32 v35, v35, v67
	v_mul_f32 v66, v14, v14
	v_mul_f32 v67, v15, v15
	v_mul_f32 v34, v68, v34
	v_mul_f32 v35, v69, v35
	v_readlane_b32 s3, v254, 49
	v_mul_f32 v68, v12, v34
	v_mul_f32 v69, v13, v35
	v_fma_f32 v34, -v12, v34, v12
	v_fma_f32 v35, -v13, v35, v13
	s_addc_u32 s45, s7, s3
	v_cndmask_b32_e32 v72, v34, v68, vcc
	v_cmp_gt_f32_e32 vcc, 0, v13
	v_fma_f32 v12, v70, s30, v160
	v_fma_f32 v13, v71, s30, v160
	v_fmac_f32_e32 v174, v72, v72
	v_cndmask_b32_e32 v59, v35, v69, vcc
	v_mul_f32 v34, v66, s58
	v_mul_f32 v35, v67, s58
	v_fma_f32 v12, v70, v12, s52
	v_fma_f32 v13, v71, v13, s52
	v_exp_f32_e32 v34, v34
	v_exp_f32_e32 v35, v35
	v_fma_f32 v12, v70, v12, s54
	v_fma_f32 v13, v71, v13, s54
	v_cmp_gt_f32_e32 vcc, 0, v14
	v_fma_f32 v12, v70, v12, s56
	v_fma_f32 v13, v71, v13, s56
	s_nop 0
	v_mul_f32 v12, v70, v12
	v_mul_f32 v13, v71, v13
	s_nop 0
	v_mul_f32 v12, v34, v12
	v_mul_f32 v13, v35, v13
	v_and_b32_e32 v35, 0x7fffffff, v9
	v_and_b32_e32 v34, 0x7fffffff, v8
	v_fma_f32 v34, v34, s28, 1.0
	v_fma_f32 v35, v35, s28, 1.0
	v_mul_f32 v66, v14, v12
	v_mul_f32 v67, v15, v13
	v_rcp_f32_e32 v68, v34
	v_rcp_f32_e32 v69, v35
	v_fma_f32 v12, -v14, v12, v14
	v_fma_f32 v13, -v15, v13, v15
	s_nop 0
	v_cndmask_b32_e32 v35, v12, v66, vcc
	v_cmp_gt_f32_e32 vcc, 0, v15
	v_mul_f32 v14, v8, v8
	v_mul_f32 v15, v9, v9
	s_nop 0
	v_cndmask_b32_e32 v34, v13, v67, vcc
	v_fma_f32 v12, v68, s30, v160
	v_fma_f32 v13, v69, s30, v160
	v_mul_f32 v14, v14, s58
	v_mul_f32 v15, v15, s58
	v_fma_f32 v12, v68, v12, s52
	v_fma_f32 v13, v69, v13, s52
	v_exp_f32_e32 v14, v14
	v_exp_f32_e32 v15, v15
	v_fma_f32 v12, v68, v12, s54
	v_fma_f32 v13, v69, v13, s54
	v_cmp_gt_f32_e32 vcc, 0, v8
	v_fma_f32 v12, v68, v12, s56
	v_fma_f32 v13, v69, v13, s56
	v_mul_f32 v66, v10, v10
	v_mul_f32 v67, v11, v11
	v_mul_f32 v12, v68, v12
	v_mul_f32 v13, v69, v13
	s_nop 0
	v_mul_f32 v12, v14, v12
	v_mul_f32 v13, v15, v13
	v_and_b32_e32 v15, 0x7fffffff, v11
	v_and_b32_e32 v14, 0x7fffffff, v10
	v_fma_f32 v14, v14, s28, 1.0
	v_fma_f32 v15, v15, s28, 1.0
	v_mul_f32 v68, v8, v12
	v_mul_f32 v69, v9, v13
	v_rcp_f32_e32 v70, v14
	v_rcp_f32_e32 v71, v15
	v_fma_f32 v12, -v8, v12, v8
	v_fma_f32 v13, -v9, v13, v9
	s_nop 0
	v_cndmask_b32_e32 v15, v12, v68, vcc
	v_cmp_gt_f32_e32 vcc, 0, v9
	v_fma_f32 v8, v70, s30, v160
	v_fma_f32 v9, v71, s30, v160
	s_nop 0
	v_cndmask_b32_e32 v14, v13, v69, vcc
	v_mul_f32 v12, v66, s58
	v_mul_f32 v13, v67, s58
	v_fma_f32 v8, v70, v8, s52
	v_fma_f32 v9, v71, v9, s52
	v_exp_f32_e32 v12, v12
	v_exp_f32_e32 v13, v13
	v_fma_f32 v8, v70, v8, s54
	v_fma_f32 v9, v71, v9, s54
	v_cmp_gt_f32_e32 vcc, 0, v10
	v_fma_f32 v8, v70, v8, s56
	v_fma_f32 v9, v71, v9, s56
	s_nop 0
	v_mul_f32 v8, v70, v8
	v_mul_f32 v9, v71, v9
	s_nop 0
	v_mul_f32 v8, v12, v8
	v_mul_f32 v9, v13, v9
	s_nop 0
	v_mul_f32 v66, v10, v8
	v_mul_f32 v67, v11, v9
	v_fma_f32 v8, -v10, v8, v10
	v_fma_f32 v9, -v11, v9, v11
	s_nop 0
	v_cndmask_b32_e32 v13, v8, v66, vcc
	v_cmp_gt_f32_e32 vcc, 0, v11
	v_cvt_pk_bf16_f32 v8, v72, v59
	v_add_f32_e32 v66, v72, v83
; #define GAS __attribute__((address_space(1)))
; __device__ __forceinline__ f32x2 gelu_pk(f32x2 v) {
;     const f32x2 av = __builtin_elementwise_abs(v), d = av * 0.2316418882f + 1.0f;
;     f32x2 t; t.x = __builtin_amdgcn_rcpf(d.x); t.y = __builtin_amdgcn_rcpf(d.y);
;     f32x2 q = t * 0.5307027145f + (-0.7265760135f); q = q * t + 0.7107068705f; q = q * t + (-0.142248368f); q = q * t + 0.127414796f; q = q * t;
;     const f32x2 s = (v * v) * (-0.72134752044f);
;     f32x2 e; e.x = __builtin_amdgcn_exp2f(s.x); e.y = __builtin_amdgcn_exp2f(s.y);
;     const f32x2 m = v * (q * e), r = v - m;
;     f32x2 o; o.x = v.x < 0.f ? m.x : r.x; o.y = v.y < 0.f ? m.y : r.y; return o;
;     __device__ __forceinline__ void operator()(const f32x4 (&acc)[2][2][4][2], const Unit& u, int wr, int wc, int fr, int fq, const float (&pre)[8]) const {
;     ...
;         if (STAT == 2) {
; #pragma unroll
;             for (int bj = 0; bj < 2; ++bj)
; #pragma unroll
;                 for (int n = 0; n < 2; ++n)
; #pragma unroll
;                     for (int e = 0; e < 4; ++e) { float a = cs[bj][n][e], b = cq[bj][n][e];
; #pragma unroll
;                         for (int o = 1; o < 16; o <<= 1) { a += __shfl_xor(a, o); b += __shfl_xor(b, o); }
;                         if (fr == 0) { const size_t slot = (size_t)(col0 + bj * 128 + 4 * n + e) * 8 + u.pm * 2 + wr; *(GAS float*)(s1 + slot) = a; *(GAS float*)(s2 + slot) = b; } }
	s_nop 0
	v_cndmask_b32_e32 v12, v9, v67, vcc
	v_cvt_pk_bf16_f32 v9, v35, v34
	v_cvt_pk_bf16_f32 v10, v15, v14
	v_cvt_pk_bf16_f32 v11, v13, v12
	global_store_dwordx4 v[16:17], v[8:11], off
	v_cmp_gt_f32_e32 vcc, 0, v4
	s_nop 0
	v_and_b32_e32 v9, 0x7fffffff, v5
	v_and_b32_e32 v8, 0x7fffffff, v4
	v_fma_f32 v8, v8, s28, 1.0
	v_fma_f32 v9, v9, s28, 1.0
	s_nop 0
	v_rcp_f32_e32 v8, v8
	v_rcp_f32_e32 v9, v9
	s_nop 0
	v_fma_f32 v10, v8, s30, v160
	v_fma_f32 v11, v9, s30, v160
	s_nop 0
	v_fma_f32 v10, v8, v10, s52
	v_fma_f32 v11, v9, v11, s52
	s_nop 0
	v_fma_f32 v10, v8, v10, s54
	v_fma_f32 v11, v9, v11, s54
	s_nop 0
	v_fma_f32 v10, v8, v10, s56
	v_fma_f32 v11, v9, v11, s56
	s_nop 0
	v_mul_f32 v8, v8, v10
	v_mul_f32 v9, v9, v11
	v_and_b32_e32 v11, 0x7fffffff, v7
	v_and_b32_e32 v10, 0x7fffffff, v6
	v_fma_f32 v10, v10, s28, 1.0
	v_fma_f32 v11, v11, s28, 1.0
	v_mul_f32 v8, v50, v8
	v_mul_f32 v9, v51, v9
	v_rcp_f32_e32 v54, v10
	v_rcp_f32_e32 v55, v11
	v_mul_f32 v50, v4, v8
	v_mul_f32 v51, v5, v9
	v_fma_f32 v8, -v4, v8, v4
	v_fma_f32 v9, -v5, v9, v5
	s_nop 0
	v_cndmask_b32_e32 v11, v8, v50, vcc
	v_cmp_gt_f32_e32 vcc, 0, v5
	v_fma_f32 v4, v54, s30, v160
	v_fma_f32 v5, v55, s30, v160
	s_nop 0
	v_cndmask_b32_e32 v10, v9, v51, vcc
	v_mul_f32 v8, v52, s58
	v_mul_f32 v9, v53, s58
	v_fma_f32 v4, v54, v4, s52
	v_fma_f32 v5, v55, v5, s52
	v_exp_f32_e32 v8, v8
	v_exp_f32_e32 v9, v9
	v_fma_f32 v4, v54, v4, s54
	v_fma_f32 v5, v55, v5, s54
	v_cmp_gt_f32_e32 vcc, 0, v6
	v_fma_f32 v4, v54, v4, s56
	v_fma_f32 v5, v55, v5, s56
	s_nop 0
	v_mul_f32 v4, v54, v4
	v_mul_f32 v5, v55, v5
	s_nop 0
	v_mul_f32 v4, v8, v4
	v_mul_f32 v5, v9, v5
	v_and_b32_e32 v9, 0x7fffffff, v1
	v_and_b32_e32 v8, 0x7fffffff, v0
	v_fma_f32 v8, v8, s28, 1.0
	v_fma_f32 v9, v9, s28, 1.0
	v_mul_f32 v50, v6, v4
	v_mul_f32 v51, v7, v5
	v_rcp_f32_e32 v52, v8
	v_rcp_f32_e32 v53, v9
	v_fma_f32 v4, -v6, v4, v6
	v_fma_f32 v5, -v7, v5, v7
	s_nop 0
	v_cndmask_b32_e32 v9, v4, v50, vcc
	v_cmp_gt_f32_e32 vcc, 0, v7
	v_mul_f32 v6, v0, v0
	v_mul_f32 v7, v1, v1
	s_nop 0
	v_cndmask_b32_e32 v8, v5, v51, vcc
	v_fma_f32 v4, v52, s30, v160
	v_fma_f32 v5, v53, s30, v160
	v_mul_f32 v6, v6, s58
	v_mul_f32 v7, v7, s58
	v_fma_f32 v4, v52, v4, s52
	v_fma_f32 v5, v53, v5, s52
	v_exp_f32_e32 v6, v6
	v_exp_f32_e32 v7, v7
	v_fma_f32 v4, v52, v4, s54
	v_fma_f32 v5, v53, v5, s54
	v_cmp_gt_f32_e32 vcc, 0, v0
	v_fma_f32 v4, v52, v4, s56
	v_fma_f32 v5, v53, v5, s56
	v_mul_f32 v50, v2, v2
	v_mul_f32 v51, v3, v3
	v_mul_f32 v4, v52, v4
	v_mul_f32 v5, v53, v5
	s_nop 0
	v_mul_f32 v4, v6, v4
	v_mul_f32 v5, v7, v5
	v_and_b32_e32 v7, 0x7fffffff, v3
	v_and_b32_e32 v6, 0x7fffffff, v2
	v_fma_f32 v6, v6, s28, 1.0
	v_fma_f32 v7, v7, s28, 1.0
	v_mul_f32 v52, v0, v4
	v_mul_f32 v53, v1, v5
	v_rcp_f32_e32 v54, v6
	v_rcp_f32_e32 v55, v7
	v_fma_f32 v4, -v0, v4, v0
	v_fma_f32 v5, -v1, v5, v1
	s_nop 0
	v_cndmask_b32_e32 v7, v4, v52, vcc
	v_cmp_gt_f32_e32 vcc, 0, v1
	v_fma_f32 v0, v54, s30, v160
	v_fma_f32 v1, v55, s30, v160
	s_nop 0
	v_cndmask_b32_e32 v6, v5, v53, vcc
	v_mul_f32 v4, v50, s58
	v_mul_f32 v5, v51, s58
	v_fma_f32 v0, v54, v0, s52
	v_fma_f32 v1, v55, v1, s52
	v_exp_f32_e32 v4, v4
	v_exp_f32_e32 v5, v5
	v_fma_f32 v0, v54, v0, s54
	v_fma_f32 v1, v55, v1, s54
	s_nop 0
	v_fma_f32 v0, v54, v0, s56
	v_fma_f32 v1, v55, v1, s56
	s_nop 0
	v_mul_f32 v0, v54, v0
	v_mul_f32 v1, v55, v1
	s_nop 0
	v_mul_f32 v4, v4, v0
	v_mul_f32 v5, v5, v1
	v_and_b32_e32 v0, 64, v191
	v_add_u32_e32 v54, 64, v0
	v_xor_b32_e32 v0, 1, v191
	v_cmp_lt_i32_e32 vcc, v0, v54
	v_mul_f32 v50, v2, v4
	v_mul_f32 v51, v3, v5
	v_fma_f32 v52, -v2, v4, v2
	v_fma_f32 v53, -v3, v5, v3
	v_cndmask_b32_e32 v0, v191, v0, vcc
	v_lshlrev_b32_e32 v0, 2, v0
	ds_bpermute_b32 v1, v0, v66
	v_cmp_gt_f32_e32 vcc, 0, v2
	ds_bpermute_b32 v55, v0, v174
	s_waitcnt lgkmcnt(1)
	v_add_f32_e32 v2, v66, v1
	v_xor_b32_e32 v1, 2, v191
	v_cndmask_b32_e32 v5, v52, v50, vcc
	v_cmp_lt_i32_e32 vcc, v1, v54
	s_waitcnt lgkmcnt(0)
	v_add_f32_e32 v4, v174, v55
	v_cvt_pk_bf16_f32 v50, v11, v10
	v_cndmask_b32_e32 v1, v191, v1, vcc
	v_lshlrev_b32_e32 v1, 2, v1
	ds_bpermute_b32 v52, v1, v2
	ds_bpermute_b32 v55, v1, v4
	v_cmp_gt_f32_e32 vcc, 0, v3
	s_waitcnt lgkmcnt(1)
	v_add_f32_e32 v56, v2, v52
	v_xor_b32_e32 v2, 4, v191
	v_cndmask_b32_e32 v3, v53, v51, vcc
	v_cmp_lt_i32_e32 vcc, v2, v54
	s_waitcnt lgkmcnt(0)
	v_add_f32_e32 v4, v4, v55
	v_cvt_pk_bf16_f32 v51, v9, v8
	v_cvt_pk_bf16_f32 v52, v7, v6
	v_cvt_pk_bf16_f32 v53, v5, v3
	global_store_dwordx4 v[16:17], v[50:53], off offset:256
	v_cndmask_b32_e32 v2, v191, v2, vcc
	v_lshlrev_b32_e32 v2, 2, v2
	ds_bpermute_b32 v57, v2, v4
	ds_bpermute_b32 v55, v2, v56
	s_waitcnt lgkmcnt(1)
	v_add_f32_e32 v17, v4, v57
	v_xor_b32_e32 v4, 8, v191
	v_cmp_lt_i32_e32 vcc, v4, v54
	s_waitcnt lgkmcnt(0)
	v_add_f32_e32 v16, v56, v55
	v_cndmask_b32_e32 v4, v191, v4, vcc
	v_lshlrev_b32_e32 v4, 2, v4
	ds_bpermute_b32 v50, v4, v16
	ds_bpermute_b32 v51, v4, v17
	s_and_saveexec_b64 s[46:47], s[38:39]
	s_cbranch_execz .LBB0_150
	s_waitcnt lgkmcnt(0)
	v_add_f32_e32 v52, v17, v51
	v_add_f32_e32 v53, v16, v50
	v_lshl_add_u64 v[16:17], v[158:159], 3, s[44:45]
	v_readlane_b32 s48, v254, 30
	v_lshlrev_b64 v[16:17], 2, v[16:17]
	v_readlane_b32 s49, v254, 31
	s_nop 1
	v_lshl_add_u64 v[50:51], s[48:49], 0, v[16:17]
	v_readlane_b32 s48, v254, 35
	v_readlane_b32 s49, v254, 36
	global_store_dword v[50:51], v53, off
	s_nop 0
	v_lshl_add_u64 v[16:17], s[48:49], 0, v[16:17]
	global_store_dword v[16:17], v52, off

.LBB0_207:
	v_add_f32_e32 v44, 1.0, v33
	v_add_f32_e32 v46, 1.0, v38
	v_mul_f32_e32 v127, v35, v44
	v_fmac_f32_e32 v44, v44, v35
	v_mul_f32_e32 v128, v47, v46
	v_fmac_f32_e32 v46, v46, v47
	v_mul_f32_e32 v129, v39, v44
	v_fmac_f32_e32 v44, v44, v39
	v_mul_f32_e32 v39, v49, v46
	v_fmac_f32_e32 v46, v46, v49
	v_mul_f32_e32 v49, v37, v44
	v_fmac_f32_e32 v44, v44, v37
	v_mul_f32_e32 v130, v48, v46
	v_fmac_f32_e32 v46, v46, v48
	v_mul_f32_e32 v48, v41, v44
	v_fmac_f32_e32 v44, v44, v41
	v_mul_f32_e32 v131, v140, v46
	v_fmac_f32_e32 v46, v46, v140
	v_mul_f32_e32 v132, v40, v44
	v_fmac_f32_e32 v44, v44, v40
	v_mul_f32_e32 v133, v139, v46
	v_fmac_f32_e32 v46, v46, v139
	v_fma_f32 v35, v44, v34, v44
	v_fma_f32 v37, v46, v36, v46
	v_mul_f32_e32 v134, v42, v35
	v_fmac_f32_e32 v35, v35, v42
	v_mul_f32_e32 v135, v141, v37
	v_fmac_f32_e32 v37, v37, v141
	v_rcp_f32_e32 v45, v35
	v_rcp_f32_e32 v37, v37
	v_and_b32_e32 v41, 64, v191
	v_xor_b32_e32 v40, 32, v191
	v_add_u32_e32 v41, 64, v41
	v_cmp_lt_i32_e32 vcc, v40, v41
	v_mul_f32_e32 v35, v37, v45
	s_nop 0
	v_cndmask_b32_e32 v40, v191, v40, vcc
	v_lshlrev_b32_e32 v40, 2, v40
	ds_bpermute_b32 v40, v40, v35
	v_mul_f32_e32 v35, v95, v35
	s_waitcnt lgkmcnt(0)
	v_mul_f32_e32 v41, v95, v40
	v_cndmask_b32_e64 v47, v95, v41, s[2:3]
	v_mul_f32 v42, v36, v46
	v_mul_f32 v43, v37, v47
	v_mul_f32_e32 v95, v35, v40
	v_mov_b32_e32 v35, v43
	v_mul_f32 v40, v34, v44
	v_mul_f32 v41, v35, v45
	v_add_u32_e32 v46, v83, v121
	v_mul_f32_e32 v33, v33, v41
	v_mul_f32_e32 v34, v127, v41
	v_cvt_pk_bf16_f32 v34, v33, v34
	v_mul_f32_e32 v33, v129, v41
	v_mul_f32_e32 v35, v49, v41
	v_cvt_pk_bf16_f32 v35, v33, v35
	v_mul_f32_e32 v33, v48, v41
	v_mul_f32_e32 v36, v132, v41
	v_cvt_pk_bf16_f32 v36, v33, v36
	v_mul_f32_e32 v33, v40, v41
	v_mul_f32_e32 v37, v134, v41
	v_cvt_pk_bf16_f32 v37, v33, v37
	v_mul_f32_e32 v33, v38, v43
	v_mul_f32_e32 v38, v128, v43
	v_cvt_pk_bf16_f32 v38, v33, v38
	v_mul_f32_e32 v33, v39, v43
	v_mul_f32_e32 v39, v130, v43
	v_cvt_pk_bf16_f32 v39, v33, v39
	v_mul_f32_e32 v33, v131, v43
	v_mul_f32_e32 v40, v133, v43
	v_cvt_pk_bf16_f32 v40, v33, v40
	v_mul_f32_e32 v33, v42, v43
	v_mul_f32_e32 v41, v135, v43
	v_cvt_pk_bf16_f32 v41, v33, v41
	v_add_u32_e32 v33, v83, v120
	ds_read_b128 v[42:45], v33 offset:8192
	s_waitcnt lgkmcnt(0)
	v_mfma_f32_32x32x16_bf16 v[16:31], v[42:45], v[34:37], v[16:31]
	ds_read_b128 v[42:45], v46 offset:8192
	s_waitcnt lgkmcnt(0)
	v_mfma_f32_32x32x16_bf16 v[16:31], v[42:45], v[38:41], v[16:31]
	ds_read_b128 v[42:45], v33 offset:12288
	s_waitcnt lgkmcnt(0)
	v_mfma_f32_32x32x16_bf16 v[0:15], v[42:45], v[34:37], v[0:15]
	ds_read_b128 v[34:37], v46 offset:12288
	s_waitcnt lgkmcnt(0)
	v_mfma_f32_32x32x16_bf16 v[0:15], v[34:37], v[38:41], v[0:15]

.LBB0_212:
	v_add_f32_e32 v44, 1.0, v33
	v_add_f32_e32 v46, 1.0, v38
	v_mul_f32_e32 v127, v35, v44
	v_fmac_f32_e32 v44, v44, v35
	v_mul_f32_e32 v128, v47, v46
	v_fmac_f32_e32 v46, v46, v47
	v_mul_f32_e32 v129, v39, v44
	v_fmac_f32_e32 v44, v44, v39
	v_mul_f32_e32 v39, v49, v46
	v_fmac_f32_e32 v46, v46, v49
	v_mul_f32_e32 v49, v37, v44
	v_fmac_f32_e32 v44, v44, v37
	v_mul_f32_e32 v130, v48, v46
	v_fmac_f32_e32 v46, v46, v48
	v_mul_f32_e32 v48, v41, v44
	v_fmac_f32_e32 v44, v44, v41
	v_mul_f32_e32 v131, v140, v46
	v_fmac_f32_e32 v46, v46, v140
	v_mul_f32_e32 v132, v40, v44
	v_fmac_f32_e32 v44, v44, v40
	v_mul_f32_e32 v133, v139, v46
	v_fmac_f32_e32 v46, v46, v139
	v_fma_f32 v35, v44, v34, v44
	v_fma_f32 v37, v46, v36, v46
	v_mul_f32_e32 v134, v42, v35
	v_fmac_f32_e32 v35, v35, v42
	v_mul_f32_e32 v135, v141, v37
	v_fmac_f32_e32 v37, v37, v141
	v_rcp_f32_e32 v45, v35
	v_rcp_f32_e32 v37, v37
	v_and_b32_e32 v40, 64, v191
	v_xor_b32_e32 v35, 32, v191
	v_add_u32_e32 v40, 64, v40
	v_cmp_lt_i32_e32 vcc, v35, v40
	v_mul_f32_e32 v136, v37, v45
	s_nop 0
	v_cndmask_b32_e32 v35, v191, v35, vcc
	v_lshlrev_b32_e32 v35, 2, v35
	ds_bpermute_b32 v137, v35, v136
	s_waitcnt lgkmcnt(0)
	v_mul_f32_e32 v35, v95, v137
	v_cndmask_b32_e64 v47, v95, v35, s[2:3]
	v_mul_f32 v42, v36, v46
	v_mul_f32 v43, v37, v47
	v_add_u32_e32 v46, v83, v123
	v_mov_b32_e32 v35, v43
	v_mul_f32 v40, v34, v44
	v_mul_f32 v41, v35, v45
	s_nop 0
	v_mul_f32_e32 v33, v33, v41
	v_mul_f32_e32 v34, v127, v41
	v_cvt_pk_bf16_f32 v34, v33, v34
	v_mul_f32_e32 v33, v129, v41
	v_mul_f32_e32 v35, v49, v41
	v_cvt_pk_bf16_f32 v35, v33, v35
	v_mul_f32_e32 v33, v48, v41
	v_mul_f32_e32 v36, v132, v41
	v_cvt_pk_bf16_f32 v36, v33, v36
	v_mul_f32_e32 v33, v40, v41
	v_mul_f32_e32 v37, v134, v41
	v_cvt_pk_bf16_f32 v37, v33, v37
	v_mul_f32_e32 v33, v38, v43
	v_mul_f32_e32 v38, v128, v43
	v_cvt_pk_bf16_f32 v38, v33, v38
	v_mul_f32_e32 v33, v39, v43
	v_mul_f32_e32 v39, v130, v43
	v_cvt_pk_bf16_f32 v39, v33, v39
	v_mul_f32_e32 v33, v131, v43
	v_mul_f32_e32 v40, v133, v43
	v_cvt_pk_bf16_f32 v40, v33, v40
	v_mul_f32_e32 v33, v42, v43
	v_mul_f32_e32 v41, v135, v43
	v_cvt_pk_bf16_f32 v41, v33, v41
	v_add_u32_e32 v33, v83, v122
	ds_read_b128 v[42:45], v33 offset:8192
	s_waitcnt lgkmcnt(0)
	v_mfma_f32_32x32x16_bf16 v[16:31], v[42:45], v[34:37], v[16:31]
	ds_read_b128 v[42:45], v46 offset:8192
	s_waitcnt lgkmcnt(0)
	v_mfma_f32_32x32x16_bf16 v[16:31], v[42:45], v[38:41], v[16:31]
	ds_read_b128 v[42:45], v33 offset:12288
	v_mul_f32_e32 v33, v95, v136
	v_mul_f32_e32 v95, v33, v137
	s_waitcnt lgkmcnt(0)
	v_mfma_f32_32x32x16_bf16 v[0:15], v[42:45], v[34:37], v[0:15]
	ds_read_b128 v[34:37], v46 offset:12288
	s_waitcnt lgkmcnt(0)
	v_mfma_f32_32x32x16_bf16 v[0:15], v[34:37], v[38:41], v[0:15]

.LBB0_227:
	v_add_f32_e32 v44, 1.0, v38
	v_add_f32_e32 v46, 1.0, v39
	v_mul_f32_e32 v130, v35, v44
	v_fmac_f32_e32 v44, v44, v35
	v_mul_f32_e32 v131, v47, v46
	v_fmac_f32_e32 v46, v46, v47
	v_mul_f32_e32 v132, v40, v44
	v_fmac_f32_e32 v44, v44, v40
	v_mul_f32_e32 v133, v49, v46
	v_fmac_f32_e32 v46, v46, v49
	v_mul_f32_e32 v49, v37, v44
	v_fmac_f32_e32 v44, v44, v37
	v_mul_f32_e32 v134, v48, v46
	v_fmac_f32_e32 v46, v46, v48
	v_mul_f32_e32 v48, v42, v44
	v_fmac_f32_e32 v44, v44, v42
	v_mul_f32_e32 v135, v144, v46
	v_fmac_f32_e32 v46, v46, v144
	v_mul_f32_e32 v136, v41, v44
	v_fmac_f32_e32 v44, v44, v41
	v_mul_f32_e32 v137, v143, v46
	v_fmac_f32_e32 v46, v46, v143
	v_fma_f32 v35, v44, v34, v44
	v_fma_f32 v37, v46, v36, v46
	v_mul_f32_e32 v138, v43, v35
	v_fmac_f32_e32 v35, v35, v43
	v_mul_f32_e32 v139, v145, v37
	v_fmac_f32_e32 v37, v37, v145
	v_rcp_f32_e32 v45, v35
	v_rcp_f32_e32 v37, v37
	v_and_b32_e32 v41, 64, v191
	v_xor_b32_e32 v40, 32, v191
	v_add_u32_e32 v41, 64, v41
	v_cmp_lt_i32_e32 vcc, v40, v41
	v_mul_f32_e32 v35, v37, v45
	s_nop 0
	v_cndmask_b32_e32 v40, v191, v40, vcc
	v_lshlrev_b32_e32 v40, 2, v40
	ds_bpermute_b32 v40, v40, v35
	v_mul_f32_e32 v35, v95, v35
	s_waitcnt lgkmcnt(0)
	v_mul_f32_e32 v41, v95, v40
	v_cndmask_b32_e64 v47, v95, v41, s[2:3]
	v_mul_f32 v42, v36, v46
	v_mul_f32 v43, v37, v47
	v_mul_f32_e32 v95, v35, v40
	v_mov_b32_e32 v35, v43
	v_mul_f32 v40, v34, v44
	v_mul_f32 v41, v35, v45
	v_add_u32_e32 v46, v83, v120
	v_mul_f32_e32 v34, v38, v41
	v_mul_f32_e32 v35, v130, v41
	v_cvt_pk_bf16_f32 v34, v34, v35
	v_mul_f32_e32 v35, v132, v41
	v_mul_f32_e32 v36, v49, v41
	v_cvt_pk_bf16_f32 v35, v35, v36
	v_mul_f32_e32 v36, v48, v41
	v_mul_f32_e32 v37, v136, v41
	v_cvt_pk_bf16_f32 v36, v36, v37
	v_mul_f32_e32 v37, v40, v41
	v_mul_f32_e32 v38, v138, v41
	v_cvt_pk_bf16_f32 v37, v37, v38
	v_mul_f32_e32 v38, v39, v43
	v_mul_f32_e32 v39, v131, v43
	v_cvt_pk_bf16_f32 v38, v38, v39
	v_mul_f32_e32 v39, v133, v43
	v_mul_f32_e32 v40, v134, v43
	v_cvt_pk_bf16_f32 v39, v39, v40
	v_mul_f32_e32 v40, v135, v43
	v_mul_f32_e32 v41, v137, v43
	v_cvt_pk_bf16_f32 v40, v40, v41
	v_mul_f32_e32 v41, v42, v43
	v_mul_f32_e32 v42, v139, v43
	v_cvt_pk_bf16_f32 v41, v41, v42
	ds_read_b128 v[42:45], v46 offset:24576
	v_add_u32_e32 v47, v83, v121
	s_waitcnt lgkmcnt(0)
	v_mfma_f32_32x32x16_bf16 v[16:31], v[42:45], v[34:37], v[16:31]
	ds_read_b128 v[42:45], v47 offset:24576
	s_waitcnt lgkmcnt(0)
	v_mfma_f32_32x32x16_bf16 v[16:31], v[42:45], v[38:41], v[16:31]
	ds_read_b128 v[42:45], v46 offset:28672
	s_waitcnt lgkmcnt(0)
	v_mfma_f32_32x32x16_bf16 v[0:15], v[42:45], v[34:37], v[0:15]
	ds_read_b128 v[34:37], v47 offset:28672
	s_waitcnt lgkmcnt(0)
	v_mfma_f32_32x32x16_bf16 v[0:15], v[34:37], v[38:41], v[0:15]

.LBB0_232:
	v_add_f32_e32 v44, 1.0, v33
	v_add_f32_e32 v46, 1.0, v38
	v_mul_f32_e32 v127, v35, v44
	v_fmac_f32_e32 v44, v44, v35
	v_mul_f32_e32 v128, v47, v46
	v_fmac_f32_e32 v46, v46, v47
	v_mul_f32_e32 v129, v39, v44
	v_fmac_f32_e32 v44, v44, v39
	v_mul_f32_e32 v39, v49, v46
	v_fmac_f32_e32 v46, v46, v49
	v_mul_f32_e32 v49, v37, v44
	v_fmac_f32_e32 v44, v44, v37
	v_mul_f32_e32 v130, v48, v46
	v_fmac_f32_e32 v46, v46, v48
	v_mul_f32_e32 v48, v41, v44
	v_fmac_f32_e32 v44, v44, v41
	v_mul_f32_e32 v131, v140, v46
	v_fmac_f32_e32 v46, v46, v140
	v_mul_f32_e32 v132, v40, v44
	v_fmac_f32_e32 v44, v44, v40
	v_mul_f32_e32 v133, v139, v46
	v_fmac_f32_e32 v46, v46, v139
	v_fma_f32 v35, v44, v34, v44
	v_fma_f32 v37, v46, v36, v46
	v_mul_f32_e32 v134, v42, v35
	v_fmac_f32_e32 v35, v35, v42
	v_mul_f32_e32 v135, v141, v37
	v_fmac_f32_e32 v37, v37, v141
	v_rcp_f32_e32 v45, v35
	v_rcp_f32_e32 v37, v37
	v_and_b32_e32 v40, 64, v191
	v_xor_b32_e32 v35, 32, v191
	v_add_u32_e32 v40, 64, v40
	v_cmp_lt_i32_e32 vcc, v35, v40
	v_mul_f32_e32 v136, v37, v45
	s_nop 0
	v_cndmask_b32_e32 v35, v191, v35, vcc
	v_lshlrev_b32_e32 v35, 2, v35
	ds_bpermute_b32 v137, v35, v136
	s_waitcnt lgkmcnt(0)
	v_mul_f32_e32 v35, v95, v137
	v_cndmask_b32_e64 v47, v95, v35, s[2:3]
	v_mul_f32 v42, v36, v46
	v_mul_f32 v43, v37, v47
	v_add_u32_e32 v46, v83, v123
	v_mov_b32_e32 v35, v43
	v_mul_f32 v40, v34, v44
	v_mul_f32 v41, v35, v45
	s_nop 0
	v_mul_f32_e32 v33, v33, v41
	v_mul_f32_e32 v34, v127, v41
	v_cvt_pk_bf16_f32 v34, v33, v34
	v_mul_f32_e32 v33, v129, v41
	v_mul_f32_e32 v35, v49, v41
	v_cvt_pk_bf16_f32 v35, v33, v35
	v_mul_f32_e32 v33, v48, v41
	v_mul_f32_e32 v36, v132, v41
	v_cvt_pk_bf16_f32 v36, v33, v36
	v_mul_f32_e32 v33, v40, v41
	v_mul_f32_e32 v37, v134, v41
	v_cvt_pk_bf16_f32 v37, v33, v37
	v_mul_f32_e32 v33, v38, v43
	v_mul_f32_e32 v38, v128, v43
	v_cvt_pk_bf16_f32 v38, v33, v38
	v_mul_f32_e32 v33, v39, v43
	v_mul_f32_e32 v39, v130, v43
	v_cvt_pk_bf16_f32 v39, v33, v39
	v_mul_f32_e32 v33, v131, v43
	v_mul_f32_e32 v40, v133, v43
	v_cvt_pk_bf16_f32 v40, v33, v40
	v_mul_f32_e32 v33, v42, v43
	v_mul_f32_e32 v41, v135, v43
	v_cvt_pk_bf16_f32 v41, v33, v41
	v_add_u32_e32 v33, v83, v122
	ds_read_b128 v[42:45], v33 offset:24576
	s_waitcnt lgkmcnt(0)
	v_mfma_f32_32x32x16_bf16 v[16:31], v[42:45], v[34:37], v[16:31]
	ds_read_b128 v[42:45], v46 offset:24576
	s_waitcnt lgkmcnt(0)
	v_mfma_f32_32x32x16_bf16 v[16:31], v[42:45], v[38:41], v[16:31]
	ds_read_b128 v[42:45], v33 offset:28672
	v_mul_f32_e32 v33, v95, v136
	v_mul_f32_e32 v95, v33, v137
	s_waitcnt lgkmcnt(0)
	v_mfma_f32_32x32x16_bf16 v[0:15], v[42:45], v[34:37], v[0:15]
	ds_read_b128 v[34:37], v46 offset:28672
	s_waitcnt lgkmcnt(0)
	v_mfma_f32_32x32x16_bf16 v[0:15], v[34:37], v[38:41], v[0:15]

; #define GAS __attribute__((address_space(1)))
; __device__ __forceinline__ float bf_lo(unsigned w) { return __uint_as_float(w << 16); }
; __device__ __forceinline__ float bf_hi(unsigned w) { return __uint_as_float(w & 0xffff0000u); }
; __device__ __forceinline__ float lo_decode(unsigned hi16, int q4) { return __uint_as_float((hi16 << 16) + (unsigned)(q4 << 12)); }
; template <bool HIN_F32, bool LAST>
; __device__ __forceinline__ void fin_compute(FinStage& S, float* out, bf16_t* HI, unsigned char* LO, float* rs, const f32x4 (&gpv)[4], float coef, int row0, int NGW, int lane) {
; #pragma unroll
;     for (int t = 0; t < 2; ++t) { const int row = row0 + t * NGW; float s2 = 0.f;
;         float tot = S.sp[t];
; #pragma unroll
;         for (int o = 1; o < 16; o <<= 1) tot += __shfl_xor(tot, o);
;         const float r = coef * __builtin_amdgcn_rsqf(tot * (1.0f / DM) + RMS_EPS);
; #pragma unroll
;         for (int j = 0; j < 2; ++j) { const int idx = 512 * j + 8 * lane; float v[8];
;             const u32x4 fw = S.fw[t][j];
;             if (HIN_F32) {
; #pragma unroll
;                 for (int e = 0; e < 8; ++e) v[e] = S.v[t][j][e >> 2][e & 3];
;             } else { const u32x4 hw = S.hw[t][j]; const unsigned lw = S.lw[t][j];
; #pragma unroll
;                 for (int e = 0; e < 8; ++e) { const unsigned w = hw[e >> 1]; v[e] = lo_decode((e & 1) ? (w >> 16) : (w & 0xffffu), (int)(lw << (28 - 4 * e)) >> 28); } }
; #pragma unroll
;             for (int e = 0; e < 8; ++e) { const unsigned w = fw[e >> 1]; v[e] += ((e & 1) ? bf_hi(w) : bf_lo(w)) * r * gpv[2 * j + (e >> 2)][e & 3]; }
;             if (LAST) { __builtin_nontemporal_store((f32x4){v[0], v[1], v[2], v[3]}, (GAS f32x4*)(out + (size_t)row * DM + idx)); __builtin_nontemporal_store((f32x4){v[4], v[5], v[6], v[7]}, (GAS f32x4*)(out + (size_t)row * DM + idx + 4)); }
.LBB0_303:
	s_waitcnt vmcnt(7)
	ds_bpermute_b32 v128, v135, v173
	v_lshlrev_b32_e32 v160, 20, v149
	v_lshlrev_b32_e32 v145, 28, v149
	v_lshlrev_b32_e32 v147, 24, v149
	v_and_b32_e32 v171, 0xffff0000, v17
	s_waitcnt lgkmcnt(0)
	v_add_f32_e32 v128, v173, v128
	ds_bpermute_b32 v158, v136, v128
	v_and_b32_sdwa v177, sext(v149), s57 dst_sel:DWORD dst_unused:UNUSED_PAD src0_sel:WORD_0 src1_sel:DWORD
	v_and_b32_e32 v159, 0xffff0000, v21
	v_and_b32_sdwa v160, sext(v160), s57 dst_sel:DWORD dst_unused:UNUSED_PAD src0_sel:WORD_1 src1_sel:DWORD
	v_and_b32_e32 v170, 0xffff0000, v16
	s_waitcnt lgkmcnt(0)
	v_add_f32_e32 v128, v128, v158
	ds_bpermute_b32 v161, v137, v128
	v_lshlrev_b32_e32 v158, 16, v21
	v_lshlrev_b32_e32 v156, 16, v20
	v_and_b32_e32 v157, 0xffff0000, v20
	v_ashrrev_i32_e32 v145, 16, v145
	s_waitcnt lgkmcnt(0)
	v_add_f32_e32 v128, v128, v161
	ds_bpermute_b32 v178, v138, v128
	v_and_b32_sdwa v147, sext(v147), s57 dst_sel:DWORD dst_unused:UNUSED_PAD src0_sel:WORD_1 src1_sel:DWORD
	v_add_u32_e32 v161, v171, v177
	v_lshl_add_u32 v160, v17, 16, v160
	v_add_u32_e32 v171, v170, v147
	s_waitcnt lgkmcnt(0)
	v_add_f32_e32 v128, v128, v178
	v_fmamk_f32 v128, v128, 0x3a800000, v188
	v_rsq_f32_e32 v128, v128
	v_lshl_add_u32 v170, v16, 16, v145
	v_bfe_i32 v147, v149, 8, 16
	v_and_b32_e32 v145, 0xffff0000, v18
	v_mul_f32_e32 v128, v33, v128
	v_mul_f32 v158, v128, v158
	v_mul_f32 v159, v128, v159
	v_mul_f32 v156, v128, v156
	v_mul_f32 v157, v128, v157
	v_fma_f32 v158, v6, v158, v160
	v_fma_f32 v159, v7, v159, v161
	v_bfe_i32 v160, v149, 4, 16
	v_fma_f32 v156, v4, v156, v170
	v_fma_f32 v157, v5, v157, v171
	v_and_b32_e32 v147, 0xfffff000, v147
	v_and_b32_e32 v160, 0xfffff000, v160
	v_lshlrev_b32_e32 v170, 16, v22
	v_and_b32_e32 v171, 0xffff0000, v22
	v_add_u32_e32 v161, v145, v147
	v_lshl_add_u32 v160, v18, 16, v160
	v_mul_f32 v170, v128, v170
	v_mul_f32 v171, v128, v171
	v_bfe_i32 v147, v149, 12, 16
	v_fma_f32 v178, v0, v170, v160
	v_fma_f32 v179, v1, v171, v161
	v_and_b32_e32 v145, 0xffff0000, v19
	v_and_b32_sdwa v160, sext(v149), s57 dst_sel:DWORD dst_unused:UNUSED_PAD src0_sel:WORD_1 src1_sel:DWORD
	v_and_b32_e32 v147, 0xfffff000, v147
	v_lshlrev_b32_e32 v170, 16, v23
	v_and_b32_e32 v171, 0xffff0000, v23
	v_add_u32_e32 v161, v145, v160
	v_lshl_add_u32 v160, v19, 16, v147
	v_mul_f32 v170, v128, v170
	v_mul_f32 v171, v128, v171
	v_lshlrev_b32_e32 v145, 28, v172
	v_lshlrev_b32_e32 v147, 24, v172
	s_waitcnt vmcnt(1)
	ds_bpermute_b32 v177, v135, v176
	v_fma_f32 v180, v2, v170, v160
	v_fma_f32 v181, v3, v171, v161
	global_store_dwordx4 v[126:127], v[156:159], off offset:-2064 nt
	global_store_dwordx4 v[126:127], v[178:181], off offset:-2048 nt
	v_ashrrev_i32_e32 v145, 16, v145
	v_and_b32_e32 v156, 0xffff0000, v24
	v_and_b32_sdwa v147, sext(v147), s57 dst_sel:DWORD dst_unused:UNUSED_PAD src0_sel:WORD_1 src1_sel:DWORD
	v_lshlrev_b32_e32 v158, 16, v28
	v_and_b32_e32 v159, 0xffff0000, v28
	v_lshlrev_b32_e32 v160, 20, v172
	v_add_u32_e32 v157, v156, v147
	v_lshl_add_u32 v156, v24, 16, v145
	v_mul_f32 v158, v128, v158
	v_mul_f32 v159, v128, v159
	v_and_b32_e32 v145, 0xffff0000, v25
	v_and_b32_sdwa v147, sext(v172), s57 dst_sel:DWORD dst_unused:UNUSED_PAD src0_sel:WORD_0 src1_sel:DWORD
	v_fma_f32 v156, v12, v158, v156
	v_fma_f32 v157, v13, v159, v157
	v_and_b32_sdwa v158, sext(v160), s57 dst_sel:DWORD dst_unused:UNUSED_PAD src0_sel:WORD_1 src1_sel:DWORD
	v_add_u32_e32 v159, v145, v147
	v_lshlrev_b32_e32 v160, 16, v29
	v_and_b32_e32 v161, 0xffff0000, v29
	v_bfe_i32 v147, v172, 8, 16
	v_lshl_add_u32 v158, v25, 16, v158
	v_mul_f32 v160, v128, v160
	v_mul_f32 v161, v128, v161
	v_and_b32_e32 v145, 0xffff0000, v26
	v_and_b32_e32 v147, 0xfffff000, v147
	v_fma_f32 v158, v14, v160, v158
	v_fma_f32 v159, v15, v161, v159
	v_add_u32_e32 v161, v145, v147
	s_waitcnt lgkmcnt(0)
	v_add_f32_e32 v145, v176, v177
	ds_bpermute_b32 v147, v136, v145
	v_bfe_i32 v160, v172, 4, 16
	v_and_b32_e32 v160, 0xfffff000, v160
	v_lshlrev_b32_e32 v170, 16, v30
	v_and_b32_e32 v171, 0xffff0000, v30
	s_waitcnt lgkmcnt(0)
	v_add_f32_e32 v145, v145, v147
	ds_bpermute_b32 v147, v137, v145
	v_lshl_add_u32 v160, v26, 16, v160
	v_mul_f32 v170, v128, v170
	v_mul_f32 v171, v128, v171
	v_fma_f32 v178, v8, v170, v160
	v_fma_f32 v179, v9, v171, v161
	v_bfe_i32 v161, v172, 12, 16
	s_waitcnt lgkmcnt(0)
	v_add_f32_e32 v145, v145, v147
	ds_bpermute_b32 v147, v138, v145
	v_and_b32_e32 v160, 0xffff0000, v27
	v_and_b32_sdwa v170, sext(v172), s57 dst_sel:DWORD dst_unused:UNUSED_PAD src0_sel:WORD_1 src1_sel:DWORD
	v_and_b32_e32 v171, 0xfffff000, v161
	v_add_u32_e32 v161, v160, v170
	v_lshl_add_u32 v160, v27, 16, v171
	v_lshlrev_b32_e32 v170, 16, v31
	v_and_b32_e32 v171, 0xffff0000, v31
	v_mul_f32 v170, v128, v170
	v_mul_f32 v171, v128, v171
	s_waitcnt lgkmcnt(0)
; #define GAS __attribute__((address_space(1)))
; template <bool HIN_F32>
; __device__ __forceinline__ void fin_load(FinStage& S, const float* x, const bf16_t* HI, const unsigned char* LO, const bf16_t* f, const float* ss, int row0, int NGW, int lane) {
; #pragma unroll
;     for (int t = 0; t < 2; ++t) { const int row = row0 + t * NGW;
; #pragma unroll
;         for (int j = 0; j < 2; ++j) { const int idx = 512 * j + 8 * lane;
;             if (HIN_F32) { S.v[t][j][0] = __builtin_nontemporal_load((const GAS f32x4*)(x + (size_t)row * DM + idx)); S.v[t][j][1] = __builtin_nontemporal_load((const GAS f32x4*)(x + (size_t)row * DM + idx + 4)); }
;             else { S.hw[t][j] = __builtin_nontemporal_load((const GAS u32x4*)(HI + (size_t)row * DM + idx)); S.lw[t][j] = __builtin_nontemporal_load((const GAS unsigned*)(LO + (size_t)row * (DM / 2) + (idx >> 1))); }
; template <bool HIN_F32, bool LAST>
; __device__ __forceinline__ void fin_compute(FinStage& S, float* out, bf16_t* HI, unsigned char* LO, float* rs, const f32x4 (&gpv)[4], float coef, int row0, int NGW, int lane) {
; #pragma unroll
;     for (int t = 0; t < 2; ++t) { const int row = row0 + t * NGW; float s2 = 0.f;
;         float tot = S.sp[t];
; #pragma unroll
;         for (int o = 1; o < 16; o <<= 1) tot += __shfl_xor(tot, o);
;         const float r = coef * __builtin_amdgcn_rsqf(tot * (1.0f / DM) + RMS_EPS);
; #pragma unroll
;         for (int j = 0; j < 2; ++j) { const int idx = 512 * j + 8 * lane; float v[8];
;             const u32x4 fw = S.fw[t][j];
;             if (HIN_F32) {
; #pragma unroll
;                 for (int e = 0; e < 8; ++e) v[e] = S.v[t][j][e >> 2][e & 3];
;             } else { const u32x4 hw = S.hw[t][j]; const unsigned lw = S.lw[t][j];
; #pragma unroll
;                 for (int e = 0; e < 8; ++e) { const unsigned w = hw[e >> 1]; v[e] = lo_decode((e & 1) ? (w >> 16) : (w & 0xffffu), (int)(lw << (28 - 4 * e)) >> 28); } }
; #pragma unroll
;             for (int e = 0; e < 8; ++e) { const unsigned w = fw[e >> 1]; v[e] += ((e & 1) ? bf_hi(w) : bf_lo(w)) * r * gpv[2 * j + (e >> 2)][e & 3]; }
;             if (LAST) { __builtin_nontemporal_store((f32x4){v[0], v[1], v[2], v[3]}, (GAS f32x4*)(out + (size_t)row * DM + idx)); __builtin_nontemporal_store((f32x4){v[4], v[5], v[6], v[7]}, (GAS f32x4*)(out + (size_t)row * DM + idx + 4)); }
	v_add_f32_e32 v128, v145, v147
	v_fmamk_f32 v128, v128, 0x3a800000, v188
	v_rsq_f32_e32 v128, v128
	v_lshlrev_b32_e32 v145, 28, v174
	v_lshlrev_b32_e32 v147, 24, v174
	v_fma_f32 v180, v10, v170, v160
	v_fma_f32 v181, v11, v171, v161
	global_store_dwordx4 v[126:127], v[156:159], off offset:-16 nt
	global_store_dwordx4 v[126:127], v[178:181], off nt
	v_mul_f32_e32 v128, v33, v128
	v_and_b32_e32 v156, 0xffff0000, v34
	v_ashrrev_i32_e32 v145, 16, v145
	v_and_b32_sdwa v147, sext(v147), s57 dst_sel:DWORD dst_unused:UNUSED_PAD src0_sel:WORD_1 src1_sel:DWORD
	v_lshlrev_b32_e32 v158, 16, v38
	v_and_b32_e32 v159, 0xffff0000, v38
	v_lshlrev_b32_e32 v160, 20, v174
	v_add_u32_e32 v157, v156, v147
	v_lshl_add_u32 v156, v34, 16, v145
	v_mul_f32 v158, v128, v158
	v_mul_f32 v159, v128, v159
	v_fma_f32 v156, v4, v158, v156
	v_fma_f32 v157, v5, v159, v157
	v_and_b32_e32 v145, 0xffff0000, v35
	v_and_b32_sdwa v147, sext(v174), s57 dst_sel:DWORD dst_unused:UNUSED_PAD src0_sel:WORD_0 src1_sel:DWORD
	v_and_b32_sdwa v158, sext(v160), s57 dst_sel:DWORD dst_unused:UNUSED_PAD src0_sel:WORD_1 src1_sel:DWORD
	v_lshlrev_b32_e32 v160, 16, v39
	v_and_b32_e32 v161, 0xffff0000, v39
	v_add_u32_e32 v159, v145, v147
	v_lshl_add_u32 v158, v35, 16, v158
	v_mul_f32 v160, v128, v160
	v_mul_f32 v161, v128, v161
	v_fma_f32 v158, v6, v160, v158
	v_fma_f32 v159, v7, v161, v159
	v_bfe_i32 v147, v174, 8, 16
	v_bfe_i32 v160, v174, 4, 16
	v_and_b32_e32 v145, 0xffff0000, v36
	v_and_b32_e32 v147, 0xfffff000, v147
	v_and_b32_e32 v160, 0xfffff000, v160
	v_lshlrev_b32_e32 v170, 16, v40
	v_and_b32_e32 v171, 0xffff0000, v40
	s_add_i32 s6, s61, s3
	v_add_u32_e32 v161, v145, v147
	v_lshl_add_u32 v160, v36, 16, v160
	v_mul_f32 v170, v128, v170
	v_mul_f32 v171, v128, v171
	v_bfe_i32 v147, v174, 12, 16
	s_ashr_i32 s7, s6, 31
	v_fma_f32 v178, v0, v170, v160
	v_fma_f32 v179, v1, v171, v161
	v_and_b32_e32 v145, 0xffff0000, v37
	v_and_b32_sdwa v160, sext(v174), s57 dst_sel:DWORD dst_unused:UNUSED_PAD src0_sel:WORD_1 src1_sel:DWORD
	v_and_b32_e32 v147, 0xfffff000, v147
	v_lshlrev_b32_e32 v170, 16, v41
	v_and_b32_e32 v171, 0xffff0000, v41
	s_lshl_b64 s[6:7], s[6:7], 12
	v_add_u32_e32 v161, v145, v160
	v_lshl_add_u32 v160, v37, 16, v147
	v_mul_f32 v170, v128, v170
	v_mul_f32 v171, v128, v171
	v_fma_f32 v180, v2, v170, v160
	v_fma_f32 v181, v3, v171, v161
	v_lshl_add_u64 v[160:161], v[118:119], 0, s[6:7]
	v_lshlrev_b32_e32 v145, 28, v175
	v_lshlrev_b32_e32 v147, 24, v175
	global_store_dwordx4 v[160:161], v[156:159], off nt
	global_store_dwordx4 v[160:161], v[178:181], off offset:16 nt
	v_ashrrev_i32_e32 v145, 16, v145
	v_and_b32_e32 v156, 0xffff0000, v42
	v_and_b32_sdwa v147, sext(v147), s57 dst_sel:DWORD dst_unused:UNUSED_PAD src0_sel:WORD_1 src1_sel:DWORD
	s_waitcnt vmcnt(6)
	v_lshlrev_b32_e32 v158, 16, v46
	v_and_b32_e32 v159, 0xffff0000, v46
	v_lshlrev_b32_e32 v170, 20, v175
	v_add_u32_e32 v157, v156, v147
	v_lshl_add_u32 v156, v42, 16, v145
	v_mul_f32 v158, v128, v158
	v_mul_f32 v159, v128, v159
	v_fma_f32 v156, v12, v158, v156
	v_fma_f32 v157, v13, v159, v157
	v_and_b32_e32 v145, 0xffff0000, v43
	v_and_b32_sdwa v147, sext(v175), s57 dst_sel:DWORD dst_unused:UNUSED_PAD src0_sel:WORD_0 src1_sel:DWORD
	v_and_b32_sdwa v158, sext(v170), s57 dst_sel:DWORD dst_unused:UNUSED_PAD src0_sel:WORD_1 src1_sel:DWORD
	v_lshlrev_b32_e32 v170, 16, v47
	v_and_b32_e32 v171, 0xffff0000, v47
	v_add_u32_e32 v159, v145, v147
	v_lshl_add_u32 v158, v43, 16, v158
	v_mul_f32 v170, v128, v170
	v_mul_f32 v171, v128, v171
	v_fma_f32 v158, v14, v170, v158
	v_fma_f32 v159, v15, v171, v159
	v_bfe_i32 v147, v175, 8, 16
	v_bfe_i32 v170, v175, 4, 16
	v_and_b32_e32 v145, 0xffff0000, v44
	v_and_b32_e32 v147, 0xfffff000, v147
	v_and_b32_e32 v170, 0xfffff000, v170
	v_lshlrev_b32_e32 v178, 16, v48
	v_and_b32_e32 v179, 0xffff0000, v48
	s_add_i32 s44, s84, s3
	v_add_u32_e32 v171, v145, v147
	v_lshl_add_u32 v170, v44, 16, v170
	v_mul_f32 v178, v128, v178
	v_mul_f32 v179, v128, v179
	v_bfe_i32 v147, v175, 12, 16
	s_cmp_ge_i32 s44, s51
	v_fma_f32 v178, v8, v178, v170
	v_fma_f32 v179, v9, v179, v171
	v_and_b32_e32 v145, 0xffff0000, v45
	v_and_b32_sdwa v170, sext(v175), s57 dst_sel:DWORD dst_unused:UNUSED_PAD src0_sel:WORD_1 src1_sel:DWORD
	v_and_b32_e32 v147, 0xfffff000, v147
	v_lshlrev_b32_e32 v180, 16, v49
	v_and_b32_e32 v181, 0xffff0000, v49
	s_cselect_b64 s[6:7], -1, 0
	v_add_u32_e32 v171, v145, v170
	v_lshl_add_u32 v170, v45, 16, v147
	v_mul_f32 v180, v128, v180
	v_mul_f32 v181, v128, v181
	s_and_b64 vcc, exec, s[6:7]
	v_fma_f32 v180, v10, v180, v170
	v_fma_f32 v181, v11, v181, v171
	global_store_dwordx4 v[160:161], v[156:159], off offset:2048 nt
	global_store_dwordx4 v[160:161], v[178:181], off offset:2064 nt
	s_cbranch_vccnz .LBB0_307
	v_lshl_add_u64 v[16:17], s[42:43], 0, v[124:125]
	v_add_co_u32_e32 v20, vcc, 0xaa00000, v16
	v_readlane_b32 s9, v253, 47
	s_nop 0
	v_addc_co_u32_e32 v21, vcc, 0, v17, vcc
	v_lshl_add_u64 v[18:19], s[42:43], 0, v[122:123]
	s_add_i32 s40, s9, s3
	v_add_co_u32_e32 v28, vcc, 0x32a00000, v18
	s_ashr_i32 s41, s40, 31
	s_nop 0
	v_addc_co_u32_e32 v29, vcc, 0, v19, vcc
	s_lshl_b64 s[46:47], s[40:41], 9
	v_add_co_u32_e32 v30, vcc, 0x12a00000, v16
	s_add_u32 s46, s0, s46
	s_nop 0
	v_addc_co_u32_e32 v31, vcc, 0, v17, vcc
	v_lshl_add_u64 v[34:35], s[42:43], 0, v[120:121]
	s_addc_u32 s47, s50, s47
	s_lshl_b64 s[48:49], s[40:41], 11
	global_load_dwordx4 v[16:19], v[20:21], off nt
	global_load_dwordx4 v[24:27], v[20:21], off offset:1024 nt
	global_load_dword v149, v[28:29], off nt
	s_nop 0
	global_load_dwordx4 v[20:23], v[30:31], off nt
	global_load_dword v172, v[28:29], off offset:256 nt
	s_nop 0
	global_load_dwordx4 v[28:31], v[30:31], off offset:1024 nt
	s_nop 0
	global_load_dword v173, v[34:35], off
	v_lshl_add_u64 v[42:43], v[114:115], 0, s[48:49]
	v_lshl_add_u64 v[34:35], s[46:47], 0, v[152:153]
	v_lshl_add_u64 v[46:47], v[116:117], 0, s[48:49]
	global_load_dword v174, v[34:35], off nt
	global_load_dwordx4 v[38:41], v[46:47], off nt
	s_nop 0
	global_load_dwordx4 v[34:37], v[42:43], off nt
	s_nop 0
	global_load_dwordx4 v[42:45], v[42:43], off offset:1024 nt
	v_lshl_add_u64 v[48:49], s[46:47], 0, v[154:155]
	s_lshl_b64 s[40:41], s[40:41], 6
	v_lshl_add_u64 v[156:157], v[150:151], 0, s[40:41]
	global_load_dword v175, v[48:49], off nt
	global_load_dword v176, v[156:157], off
	s_nop 0
	global_load_dwordx4 v[46:49], v[46:47], off offset:1024 nt
	s_add_i32 s40, s72, s3
	s_cmp_ge_i32 s40, s51
	s_cbranch_scc0 .LBB0_308

; #define GAS __attribute__((address_space(1)))
; __device__ __forceinline__ float bf_lo(unsigned w) { return __uint_as_float(w << 16); }
; __device__ __forceinline__ float bf_hi(unsigned w) { return __uint_as_float(w & 0xffff0000u); }
; __device__ __forceinline__ float lo_decode(unsigned hi16, int q4) { return __uint_as_float((hi16 << 16) + (unsigned)(q4 << 12)); }
; template <bool HIN_F32, bool LAST>
; __device__ __forceinline__ void fin_compute(FinStage& S, float* out, bf16_t* HI, unsigned char* LO, float* rs, const f32x4 (&gpv)[4], float coef, int row0, int NGW, int lane) {
; #pragma unroll
;     for (int t = 0; t < 2; ++t) { const int row = row0 + t * NGW; float s2 = 0.f;
;         float tot = S.sp[t];
; #pragma unroll
;         for (int o = 1; o < 16; o <<= 1) tot += __shfl_xor(tot, o);
;         const float r = coef * __builtin_amdgcn_rsqf(tot * (1.0f / DM) + RMS_EPS);
; #pragma unroll
;         for (int j = 0; j < 2; ++j) { const int idx = 512 * j + 8 * lane; float v[8];
;             const u32x4 fw = S.fw[t][j];
;             if (HIN_F32) {
; #pragma unroll
;                 for (int e = 0; e < 8; ++e) v[e] = S.v[t][j][e >> 2][e & 3];
;             } else { const u32x4 hw = S.hw[t][j]; const unsigned lw = S.lw[t][j];
; #pragma unroll
;                 for (int e = 0; e < 8; ++e) { const unsigned w = hw[e >> 1]; v[e] = lo_decode((e & 1) ? (w >> 16) : (w & 0xffffu), (int)(lw << (28 - 4 * e)) >> 28); } }
; #pragma unroll
;             for (int e = 0; e < 8; ++e) { const unsigned w = fw[e >> 1]; v[e] += ((e & 1) ? bf_hi(w) : bf_lo(w)) * r * gpv[2 * j + (e >> 2)][e & 3]; }
;             if (LAST) { __builtin_nontemporal_store((f32x4){v[0], v[1], v[2], v[3]}, (GAS f32x4*)(out + (size_t)row * DM + idx)); __builtin_nontemporal_store((f32x4){v[4], v[5], v[6], v[7]}, (GAS f32x4*)(out + (size_t)row * DM + idx + 4)); }
.LBB0_308:
	ds_bpermute_b32 v128, v135, v131
	v_lshlrev_b32_e32 v147, 24, v129
	v_and_b32_e32 v156, 0xffff0000, v54
	v_and_b32_sdwa v147, sext(v147), s57 dst_sel:DWORD dst_unused:UNUSED_PAD src0_sel:WORD_1 src1_sel:DWORD
	v_lshlrev_b32_e32 v158, 16, v50
	s_waitcnt lgkmcnt(0)
	v_add_f32_e32 v128, v131, v128
	ds_bpermute_b32 v145, v136, v128
	v_and_b32_e32 v159, 0xffff0000, v50
	v_lshlrev_b32_e32 v160, 20, v129
	v_add_u32_e32 v157, v156, v147
	v_and_b32_sdwa v147, sext(v129), s57 dst_sel:DWORD dst_unused:UNUSED_PAD src0_sel:WORD_0 src1_sel:DWORD
	s_waitcnt lgkmcnt(0)
	v_add_f32_e32 v128, v128, v145
	ds_bpermute_b32 v145, v137, v128
	v_and_b32_e32 v161, 0xffff0000, v51
	v_lshlrev_b32_e32 v170, 16, v52
	v_and_b32_e32 v171, 0xffff0000, v52
	s_ashr_i32 s41, s40, 31
	s_waitcnt lgkmcnt(0)
	v_add_f32_e32 v128, v128, v145
	ds_bpermute_b32 v145, v138, v128
	s_lshl_b64 s[40:41], s[40:41], 12
	v_readlane_b32 s9, v253, 46
	s_waitcnt lgkmcnt(0)
	v_add_f32_e32 v128, v128, v145
	v_fmamk_f32 v128, v128, 0x3a800000, v188
	v_rsq_f32_e32 v128, v128
	v_lshlrev_b32_e32 v145, 28, v129
	v_ashrrev_i32_e32 v145, 16, v145
	v_lshl_add_u32 v156, v54, 16, v145
	v_mul_f32_e32 v128, v33, v128
	v_mul_f32 v158, v128, v158
	v_mul_f32 v159, v128, v159
	v_fma_f32 v156, v4, v158, v156
	v_fma_f32 v157, v5, v159, v157
	v_and_b32_e32 v145, 0xffff0000, v55
	v_and_b32_sdwa v158, sext(v160), s57 dst_sel:DWORD dst_unused:UNUSED_PAD src0_sel:WORD_1 src1_sel:DWORD
	v_lshlrev_b32_e32 v160, 16, v51
	v_add_u32_e32 v159, v145, v147
	v_lshl_add_u32 v158, v55, 16, v158
	v_mul_f32 v160, v128, v160
	v_mul_f32 v161, v128, v161
	v_fma_f32 v158, v6, v160, v158
	v_fma_f32 v159, v7, v161, v159
	v_bfe_i32 v147, v129, 8, 16
	v_bfe_i32 v160, v129, 4, 16
	v_and_b32_e32 v145, 0xffff0000, v56
	v_and_b32_e32 v147, 0xfffff000, v147
	v_and_b32_e32 v160, 0xfffff000, v160
	v_add_u32_e32 v161, v145, v147
	v_lshl_add_u32 v160, v56, 16, v160
	v_mul_f32 v170, v128, v170
	v_mul_f32 v171, v128, v171
	v_bfe_i32 v147, v129, 12, 16
	v_fma_f32 v178, v0, v170, v160
	v_fma_f32 v179, v1, v171, v161
	v_and_b32_e32 v145, 0xffff0000, v57
	v_and_b32_sdwa v160, sext(v129), s57 dst_sel:DWORD dst_unused:UNUSED_PAD src0_sel:WORD_1 src1_sel:DWORD
	v_and_b32_e32 v147, 0xfffff000, v147
	v_lshlrev_b32_e32 v170, 16, v53
	v_and_b32_e32 v171, 0xffff0000, v53
	v_add_u32_e32 v161, v145, v160
	v_lshl_add_u32 v160, v57, 16, v147
	v_mul_f32 v170, v128, v170
	v_mul_f32 v171, v128, v171
	v_fma_f32 v180, v2, v170, v160
	v_fma_f32 v181, v3, v171, v161
	v_lshl_add_u64 v[160:161], v[118:119], 0, s[40:41]
	v_lshlrev_b32_e32 v145, 28, v130
	v_lshlrev_b32_e32 v147, 24, v130
	global_store_dwordx4 v[160:161], v[156:159], off nt
	global_store_dwordx4 v[160:161], v[178:181], off offset:16 nt
	v_ashrrev_i32_e32 v145, 16, v145
	v_and_b32_e32 v156, 0xffff0000, v58
	v_and_b32_sdwa v147, sext(v147), s57 dst_sel:DWORD dst_unused:UNUSED_PAD src0_sel:WORD_1 src1_sel:DWORD
	v_lshlrev_b32_e32 v158, 16, v62
	v_and_b32_e32 v159, 0xffff0000, v62
	v_lshlrev_b32_e32 v170, 20, v130
	v_add_u32_e32 v157, v156, v147
	v_lshl_add_u32 v156, v58, 16, v145
	v_mul_f32 v158, v128, v158
	v_mul_f32 v159, v128, v159
	v_fma_f32 v156, v12, v158, v156
	v_fma_f32 v157, v13, v159, v157
	v_and_b32_sdwa v158, sext(v170), s57 dst_sel:DWORD dst_unused:UNUSED_PAD src0_sel:WORD_1 src1_sel:DWORD
	v_lshlrev_b32_e32 v170, 16, v63
	v_and_b32_e32 v171, 0xffff0000, v63
	v_lshlrev_b32_e32 v178, 16, v64
	v_and_b32_e32 v179, 0xffff0000, v64
	v_lshlrev_b32_e32 v180, 16, v65
	v_and_b32_e32 v181, 0xffff0000, v65
	v_and_b32_e32 v145, 0xffff0000, v59
	v_and_b32_sdwa v147, sext(v130), s57 dst_sel:DWORD dst_unused:UNUSED_PAD src0_sel:WORD_0 src1_sel:DWORD
	v_mul_f32 v170, v128, v170
	v_mul_f32 v171, v128, v171
	v_mul_f32 v178, v128, v178
	v_mul_f32 v179, v128, v179
	v_mul_f32 v180, v128, v180
	v_mul_f32 v181, v128, v181
	ds_bpermute_b32 v128, v135, v134
	v_add_u32_e32 v159, v145, v147
	v_lshl_add_u32 v158, v59, 16, v158
	v_fma_f32 v158, v14, v170, v158
	v_fma_f32 v159, v15, v171, v159
	v_bfe_i32 v147, v130, 8, 16
	v_bfe_i32 v170, v130, 4, 16
	v_and_b32_e32 v145, 0xffff0000, v60
	v_and_b32_e32 v147, 0xfffff000, v147
	v_and_b32_e32 v170, 0xfffff000, v170
	v_add_u32_e32 v171, v145, v147
	v_lshl_add_u32 v170, v60, 16, v170
	v_fma_f32 v178, v8, v178, v170
	v_fma_f32 v179, v9, v179, v171
	v_and_b32_e32 v145, 0xffff0000, v61
	v_and_b32_sdwa v170, sext(v130), s57 dst_sel:DWORD dst_unused:UNUSED_PAD src0_sel:WORD_1 src1_sel:DWORD
	s_waitcnt lgkmcnt(0)
	v_add_f32_e32 v128, v134, v128
	v_add_u32_e32 v171, v145, v170
	ds_bpermute_b32 v145, v136, v128
	v_bfe_i32 v147, v130, 12, 16
	v_and_b32_e32 v147, 0xfffff000, v147
	v_lshl_add_u32 v170, v61, 16, v147
	v_lshlrev_b32_e32 v147, 24, v132
	s_waitcnt lgkmcnt(0)
; #define GAS __attribute__((address_space(1)))
; __device__ __forceinline__ float bf_lo(unsigned w) { return __uint_as_float(w << 16); }
; __device__ __forceinline__ float bf_hi(unsigned w) { return __uint_as_float(w & 0xffff0000u); }
; __device__ __forceinline__ float lo_decode(unsigned hi16, int q4) { return __uint_as_float((hi16 << 16) + (unsigned)(q4 << 12)); }
; template <bool HIN_F32, bool LAST>
; __device__ __forceinline__ void fin_compute(FinStage& S, float* out, bf16_t* HI, unsigned char* LO, float* rs, const f32x4 (&gpv)[4], float coef, int row0, int NGW, int lane) {
; #pragma unroll
;     for (int t = 0; t < 2; ++t) { const int row = row0 + t * NGW; float s2 = 0.f;
;         float tot = S.sp[t];
; #pragma unroll
;         for (int o = 1; o < 16; o <<= 1) tot += __shfl_xor(tot, o);
;         const float r = coef * __builtin_amdgcn_rsqf(tot * (1.0f / DM) + RMS_EPS);
; #pragma unroll
;         for (int j = 0; j < 2; ++j) { const int idx = 512 * j + 8 * lane; float v[8];
;             const u32x4 fw = S.fw[t][j];
;             if (HIN_F32) {
; #pragma unroll
;                 for (int e = 0; e < 8; ++e) v[e] = S.v[t][j][e >> 2][e & 3];
;             } else { const u32x4 hw = S.hw[t][j]; const unsigned lw = S.lw[t][j];
; #pragma unroll
;                 for (int e = 0; e < 8; ++e) { const unsigned w = hw[e >> 1]; v[e] = lo_decode((e & 1) ? (w >> 16) : (w & 0xffffu), (int)(lw << (28 - 4 * e)) >> 28); } }
; #pragma unroll
;             for (int e = 0; e < 8; ++e) { const unsigned w = fw[e >> 1]; v[e] += ((e & 1) ? bf_hi(w) : bf_lo(w)) * r * gpv[2 * j + (e >> 2)][e & 3]; }
;             if (LAST) { __builtin_nontemporal_store((f32x4){v[0], v[1], v[2], v[3]}, (GAS f32x4*)(out + (size_t)row * DM + idx)); __builtin_nontemporal_store((f32x4){v[4], v[5], v[6], v[7]}, (GAS f32x4*)(out + (size_t)row * DM + idx + 4)); }
	v_add_f32_e32 v128, v128, v145
	ds_bpermute_b32 v145, v137, v128
	v_fma_f32 v180, v10, v180, v170
	v_fma_f32 v181, v11, v181, v171
	global_store_dwordx4 v[160:161], v[156:159], off offset:2048 nt
	global_store_dwordx4 v[160:161], v[178:181], off offset:2064 nt
	v_and_b32_sdwa v147, sext(v147), s57 dst_sel:DWORD dst_unused:UNUSED_PAD src0_sel:WORD_1 src1_sel:DWORD
	v_and_b32_e32 v156, 0xffff0000, v70
	s_waitcnt lgkmcnt(0)
	v_add_f32_e32 v128, v128, v145
	ds_bpermute_b32 v145, v138, v128
	v_lshlrev_b32_e32 v158, 16, v66
	v_and_b32_e32 v159, 0xffff0000, v66
	v_lshlrev_b32_e32 v160, 20, v132
	v_add_u32_e32 v157, v156, v147
	s_waitcnt lgkmcnt(0)
	v_add_f32_e32 v128, v128, v145
	v_fmamk_f32 v128, v128, 0x3a800000, v188
	v_rsq_f32_e32 v128, v128
	v_lshlrev_b32_e32 v145, 28, v132
	v_ashrrev_i32_e32 v145, 16, v145
	v_lshl_add_u32 v156, v70, 16, v145
	v_mul_f32_e32 v128, v33, v128
	v_mul_f32 v158, v128, v158
	v_mul_f32 v159, v128, v159
	v_fma_f32 v156, v4, v158, v156
	v_fma_f32 v157, v5, v159, v157
	v_and_b32_e32 v145, 0xffff0000, v71
	v_and_b32_sdwa v147, sext(v132), s57 dst_sel:DWORD dst_unused:UNUSED_PAD src0_sel:WORD_0 src1_sel:DWORD
	v_and_b32_sdwa v158, sext(v160), s57 dst_sel:DWORD dst_unused:UNUSED_PAD src0_sel:WORD_1 src1_sel:DWORD
	v_lshlrev_b32_e32 v160, 16, v67
	v_and_b32_e32 v161, 0xffff0000, v67
	v_add_u32_e32 v159, v145, v147
	v_lshl_add_u32 v158, v71, 16, v158
	v_mul_f32 v160, v128, v160
	v_mul_f32 v161, v128, v161
	v_fma_f32 v158, v6, v160, v158
	v_fma_f32 v159, v7, v161, v159
	v_bfe_i32 v147, v132, 8, 16
	v_bfe_i32 v160, v132, 4, 16
	v_and_b32_e32 v145, 0xffff0000, v72
	v_and_b32_e32 v147, 0xfffff000, v147
	v_and_b32_e32 v160, 0xfffff000, v160
	v_lshlrev_b32_e32 v170, 16, v68
	v_and_b32_e32 v171, 0xffff0000, v68
	s_add_i32 s40, s9, s3
	v_add_u32_e32 v161, v145, v147
	v_lshl_add_u32 v160, v72, 16, v160
	v_mul_f32 v170, v128, v170
	v_mul_f32 v171, v128, v171
	v_bfe_i32 v147, v132, 12, 16
	s_ashr_i32 s41, s40, 31
	v_fma_f32 v178, v0, v170, v160
	v_fma_f32 v179, v1, v171, v161
	v_and_b32_e32 v145, 0xffff0000, v73
	v_and_b32_sdwa v160, sext(v132), s57 dst_sel:DWORD dst_unused:UNUSED_PAD src0_sel:WORD_1 src1_sel:DWORD
	v_and_b32_e32 v147, 0xfffff000, v147
	v_lshlrev_b32_e32 v170, 16, v69
	v_and_b32_e32 v171, 0xffff0000, v69
	s_lshl_b64 s[40:41], s[40:41], 12
	v_add_u32_e32 v161, v145, v160
	v_lshl_add_u32 v160, v73, 16, v147
	v_mul_f32 v170, v128, v170
	v_mul_f32 v171, v128, v171
	v_fma_f32 v180, v2, v170, v160
	v_fma_f32 v181, v3, v171, v161
	v_lshl_add_u64 v[160:161], v[118:119], 0, s[40:41]
	v_lshlrev_b32_e32 v145, 28, v133
	v_lshlrev_b32_e32 v147, 24, v133
	global_store_dwordx4 v[160:161], v[156:159], off nt
	global_store_dwordx4 v[160:161], v[178:181], off offset:16 nt
	v_ashrrev_i32_e32 v145, 16, v145
	v_and_b32_e32 v156, 0xffff0000, v74
	v_and_b32_sdwa v147, sext(v147), s57 dst_sel:DWORD dst_unused:UNUSED_PAD src0_sel:WORD_1 src1_sel:DWORD
	v_lshlrev_b32_e32 v158, 16, v78
	v_and_b32_e32 v159, 0xffff0000, v78
	v_lshlrev_b32_e32 v170, 20, v133
	v_add_u32_e32 v157, v156, v147
	v_lshl_add_u32 v156, v74, 16, v145
	v_mul_f32 v158, v128, v158
	v_mul_f32 v159, v128, v159
	v_fma_f32 v156, v12, v158, v156
	v_fma_f32 v157, v13, v159, v157
	v_and_b32_e32 v145, 0xffff0000, v75
	v_and_b32_sdwa v147, sext(v133), s57 dst_sel:DWORD dst_unused:UNUSED_PAD src0_sel:WORD_0 src1_sel:DWORD
	v_and_b32_sdwa v158, sext(v170), s57 dst_sel:DWORD dst_unused:UNUSED_PAD src0_sel:WORD_1 src1_sel:DWORD
	v_lshlrev_b32_e32 v170, 16, v79
	v_and_b32_e32 v171, 0xffff0000, v79
	v_add_u32_e32 v159, v145, v147
	v_lshl_add_u32 v158, v75, 16, v158
	v_mul_f32 v170, v128, v170
	v_mul_f32 v171, v128, v171
	v_fma_f32 v158, v14, v170, v158
	v_fma_f32 v159, v15, v171, v159
	v_bfe_i32 v147, v133, 8, 16
	v_bfe_i32 v170, v133, 4, 16
	v_and_b32_e32 v145, 0xffff0000, v76
	v_and_b32_e32 v147, 0xfffff000, v147
	v_and_b32_e32 v170, 0xfffff000, v170
	v_lshlrev_b32_e32 v178, 16, v80
	v_and_b32_e32 v179, 0xffff0000, v80
	v_add_u32_e32 v171, v145, v147
	v_lshl_add_u32 v170, v76, 16, v170
	v_mul_f32 v178, v128, v178
	v_mul_f32 v179, v128, v179
	v_bfe_i32 v147, v133, 12, 16
	v_fma_f32 v178, v8, v178, v170
	v_fma_f32 v179, v9, v179, v171
	v_and_b32_e32 v145, 0xffff0000, v77
	v_and_b32_sdwa v170, sext(v133), s57 dst_sel:DWORD dst_unused:UNUSED_PAD src0_sel:WORD_1 src1_sel:DWORD
	v_and_b32_e32 v147, 0xfffff000, v147
	v_lshlrev_b32_e32 v180, 16, v81
	v_and_b32_e32 v181, 0xffff0000, v81
	v_add_u32_e32 v171, v145, v170
	v_lshl_add_u32 v170, v77, 16, v147
	v_mul_f32 v180, v128, v180
	v_mul_f32 v181, v128, v181
	v_fma_f32 v180, v10, v180, v170
	v_fma_f32 v181, v11, v181, v171
	global_store_dwordx4 v[160:161], v[156:159], off offset:2048 nt
	global_store_dwordx4 v[160:161], v[178:181], off offset:2064 nt
	s_add_i32 s40, s79, s3
	s_cmp_ge_i32 s40, s51
	s_cbranch_scc0 .LBB0_306

; #define GAS __attribute__((address_space(1)))
; __device__ __forceinline__ float bf_lo(unsigned w) { return __uint_as_float(w << 16); }
; __device__ __forceinline__ float bf_hi(unsigned w) { return __uint_as_float(w & 0xffff0000u); }
; __device__ __forceinline__ float lo_decode(unsigned hi16, int q4) { return __uint_as_float((hi16 << 16) + (unsigned)(q4 << 12)); }
; template <bool HIN_F32, bool LAST>
; __device__ __forceinline__ void fin_compute(FinStage& S, float* out, bf16_t* HI, unsigned char* LO, float* rs, const f32x4 (&gpv)[4], float coef, int row0, int NGW, int lane) {
;     ...
;     for (int t = 0; t < 2; ++t) { const int row = row0 + t * NGW; float s2 = 0.f;
;         float tot = S.sp[t];
; #pragma unroll
;         for (int o = 1; o < 16; o <<= 1) tot += __shfl_xor(tot, o);
;         const float r = coef * __builtin_amdgcn_rsqf(tot * (1.0f / DM) + RMS_EPS);
; #pragma unroll
;         for (int j = 0; j < 2; ++j) { const int idx = 512 * j + 8 * lane; float v[8];
;             const u32x4 fw = S.fw[t][j];
;             if (HIN_F32) {
; #pragma unroll
;                 for (int e = 0; e < 8; ++e) v[e] = S.v[t][j][e >> 2][e & 3];
;             } else { const u32x4 hw = S.hw[t][j]; const unsigned lw = S.lw[t][j];
; #pragma unroll
;                 for (int e = 0; e < 8; ++e) { const unsigned w = hw[e >> 1]; v[e] = lo_decode((e & 1) ? (w >> 16) : (w & 0xffffu), (int)(lw << (28 - 4 * e)) >> 28); } }
; #pragma unroll
;             for (int e = 0; e < 8; ++e) { const unsigned w = fw[e >> 1]; v[e] += ((e & 1) ? bf_hi(w) : bf_lo(w)) * r * gpv[2 * j + (e >> 2)][e & 3]; }
;             if (LAST) { __builtin_nontemporal_store((f32x4){v[0], v[1], v[2], v[3]}, (GAS f32x4*)(out + (size_t)row * DM + idx)); __builtin_nontemporal_store((f32x4){v[4], v[5], v[6], v[7]}, (GAS f32x4*)(out + (size_t)row * DM + idx + 4)); }
.LBB0_310:
	s_waitcnt vmcnt(16)
	ds_bpermute_b32 v128, v135, v142
	v_lshlrev_b32_e32 v147, 24, v139
	v_and_b32_e32 v156, 0xffff0000, v94
	v_and_b32_sdwa v147, sext(v147), s57 dst_sel:DWORD dst_unused:UNUSED_PAD src0_sel:WORD_1 src1_sel:DWORD
	v_lshlrev_b32_e32 v158, 16, v82
	s_waitcnt lgkmcnt(0)
	v_add_f32_e32 v128, v142, v128
	ds_bpermute_b32 v145, v136, v128
	v_and_b32_e32 v159, 0xffff0000, v82
	v_lshlrev_b32_e32 v160, 20, v139
	v_add_u32_e32 v157, v156, v147
	v_and_b32_sdwa v147, sext(v139), s57 dst_sel:DWORD dst_unused:UNUSED_PAD src0_sel:WORD_0 src1_sel:DWORD
	s_waitcnt lgkmcnt(0)
	v_add_f32_e32 v128, v128, v145
	ds_bpermute_b32 v145, v137, v128
	v_and_b32_e32 v161, 0xffff0000, v83
	v_lshlrev_b32_e32 v170, 16, v84
	v_and_b32_e32 v171, 0xffff0000, v84
	s_ashr_i32 s9, s8, 31
	s_waitcnt lgkmcnt(0)
	v_add_f32_e32 v128, v128, v145
	ds_bpermute_b32 v145, v138, v128
	s_lshl_b64 s[8:9], s[8:9], 12
	s_waitcnt lgkmcnt(0)
	v_add_f32_e32 v128, v128, v145
	v_fmamk_f32 v128, v128, 0x3a800000, v188
	v_rsq_f32_e32 v128, v128
	v_lshlrev_b32_e32 v145, 28, v139
	v_ashrrev_i32_e32 v145, 16, v145
	v_lshl_add_u32 v156, v94, 16, v145
	v_mul_f32_e32 v128, v33, v128
	s_waitcnt vmcnt(13)
	v_mul_f32 v158, v128, v158
	v_mul_f32 v159, v128, v159
	v_fma_f32 v156, v4, v158, v156
	v_fma_f32 v157, v5, v159, v157
	v_and_b32_e32 v145, 0xffff0000, v95
	v_and_b32_sdwa v158, sext(v160), s57 dst_sel:DWORD dst_unused:UNUSED_PAD src0_sel:WORD_1 src1_sel:DWORD
	v_lshlrev_b32_e32 v160, 16, v83
	v_add_u32_e32 v159, v145, v147
	v_lshl_add_u32 v158, v95, 16, v158
	v_mul_f32 v160, v128, v160
	v_mul_f32 v161, v128, v161
	v_fma_f32 v158, v6, v160, v158
	v_fma_f32 v159, v7, v161, v159
	v_bfe_i32 v147, v139, 8, 16
	v_bfe_i32 v160, v139, 4, 16
	v_and_b32_e32 v145, 0xffff0000, v96
	v_and_b32_e32 v147, 0xfffff000, v147
	v_and_b32_e32 v160, 0xfffff000, v160
	v_add_u32_e32 v161, v145, v147
	v_lshl_add_u32 v160, v96, 16, v160
	v_mul_f32 v170, v128, v170
	v_mul_f32 v171, v128, v171
	v_bfe_i32 v147, v139, 12, 16
	v_fma_f32 v178, v0, v170, v160
	v_fma_f32 v179, v1, v171, v161
	v_and_b32_e32 v145, 0xffff0000, v97
	v_and_b32_sdwa v160, sext(v139), s57 dst_sel:DWORD dst_unused:UNUSED_PAD src0_sel:WORD_1 src1_sel:DWORD
	v_and_b32_e32 v147, 0xfffff000, v147
	v_lshlrev_b32_e32 v170, 16, v85
	v_and_b32_e32 v171, 0xffff0000, v85
	v_add_u32_e32 v161, v145, v160
	v_lshl_add_u32 v160, v97, 16, v147
	v_mul_f32 v170, v128, v170
	v_mul_f32 v171, v128, v171
	v_fma_f32 v180, v2, v170, v160
	v_fma_f32 v181, v3, v171, v161
	v_lshl_add_u64 v[160:161], v[118:119], 0, s[8:9]
	v_lshlrev_b32_e32 v145, 28, v140
	v_lshlrev_b32_e32 v147, 24, v140
	global_store_dwordx4 v[160:161], v[156:159], off nt
	global_store_dwordx4 v[160:161], v[178:181], off offset:16 nt
	v_ashrrev_i32_e32 v145, 16, v145
	v_and_b32_e32 v156, 0xffff0000, v90
	v_and_b32_sdwa v147, sext(v147), s57 dst_sel:DWORD dst_unused:UNUSED_PAD src0_sel:WORD_1 src1_sel:DWORD
	v_lshlrev_b32_e32 v158, 16, v86
	v_and_b32_e32 v159, 0xffff0000, v86
	v_lshlrev_b32_e32 v170, 20, v140
	v_add_u32_e32 v157, v156, v147
	v_lshl_add_u32 v156, v90, 16, v145
	v_mul_f32 v158, v128, v158
	v_mul_f32 v159, v128, v159
	v_fma_f32 v156, v12, v158, v156
	v_fma_f32 v157, v13, v159, v157
	v_and_b32_sdwa v158, sext(v170), s57 dst_sel:DWORD dst_unused:UNUSED_PAD src0_sel:WORD_1 src1_sel:DWORD
	v_lshlrev_b32_e32 v170, 16, v87
	v_and_b32_e32 v171, 0xffff0000, v87
	v_lshlrev_b32_e32 v178, 16, v88
	v_and_b32_e32 v179, 0xffff0000, v88
	v_lshlrev_b32_e32 v180, 16, v89
	v_and_b32_e32 v181, 0xffff0000, v89
	v_and_b32_e32 v145, 0xffff0000, v91
	v_and_b32_sdwa v147, sext(v140), s57 dst_sel:DWORD dst_unused:UNUSED_PAD src0_sel:WORD_0 src1_sel:DWORD
	v_mul_f32 v170, v128, v170
	v_mul_f32 v171, v128, v171
	v_mul_f32 v178, v128, v178
	v_mul_f32 v179, v128, v179
	v_mul_f32 v180, v128, v180
	v_mul_f32 v181, v128, v181
	s_waitcnt vmcnt(11)
	ds_bpermute_b32 v128, v135, v144
	v_add_u32_e32 v159, v145, v147
	v_lshl_add_u32 v158, v91, 16, v158
	v_fma_f32 v158, v14, v170, v158
	v_fma_f32 v159, v15, v171, v159
	v_bfe_i32 v147, v140, 8, 16
	v_bfe_i32 v170, v140, 4, 16
	v_and_b32_e32 v145, 0xffff0000, v92
	v_and_b32_e32 v147, 0xfffff000, v147
	v_and_b32_e32 v170, 0xfffff000, v170
	v_add_u32_e32 v171, v145, v147
	v_lshl_add_u32 v170, v92, 16, v170
	v_fma_f32 v178, v8, v178, v170
	v_fma_f32 v179, v9, v179, v171
	v_and_b32_e32 v145, 0xffff0000, v93
	v_and_b32_sdwa v170, sext(v140), s57 dst_sel:DWORD dst_unused:UNUSED_PAD src0_sel:WORD_1 src1_sel:DWORD
	s_waitcnt lgkmcnt(0)
	v_add_f32_e32 v128, v144, v128
	v_add_u32_e32 v171, v145, v170
	ds_bpermute_b32 v145, v136, v128
	v_bfe_i32 v147, v140, 12, 16
	v_and_b32_e32 v147, 0xfffff000, v147
	v_lshl_add_u32 v170, v93, 16, v147
	v_lshlrev_b32_e32 v147, 24, v141
	s_waitcnt lgkmcnt(0)
; #define GAS __attribute__((address_space(1)))
; __device__ __forceinline__ float bf_lo(unsigned w) { return __uint_as_float(w << 16); }
; __device__ __forceinline__ float bf_hi(unsigned w) { return __uint_as_float(w & 0xffff0000u); }
; __device__ __forceinline__ float lo_decode(unsigned hi16, int q4) { return __uint_as_float((hi16 << 16) + (unsigned)(q4 << 12)); }
; template <bool HIN_F32, bool LAST>
; __device__ __forceinline__ void fin_compute(FinStage& S, float* out, bf16_t* HI, unsigned char* LO, float* rs, const f32x4 (&gpv)[4], float coef, int row0, int NGW, int lane) {
;     ...
;     for (int t = 0; t < 2; ++t) { const int row = row0 + t * NGW; float s2 = 0.f;
;         float tot = S.sp[t];
; #pragma unroll
;         for (int o = 1; o < 16; o <<= 1) tot += __shfl_xor(tot, o);
;         const float r = coef * __builtin_amdgcn_rsqf(tot * (1.0f / DM) + RMS_EPS);
; #pragma unroll
;         for (int j = 0; j < 2; ++j) { const int idx = 512 * j + 8 * lane; float v[8];
;             const u32x4 fw = S.fw[t][j];
;             if (HIN_F32) {
; #pragma unroll
;                 for (int e = 0; e < 8; ++e) v[e] = S.v[t][j][e >> 2][e & 3];
;             } else { const u32x4 hw = S.hw[t][j]; const unsigned lw = S.lw[t][j];
; #pragma unroll
;                 for (int e = 0; e < 8; ++e) { const unsigned w = hw[e >> 1]; v[e] = lo_decode((e & 1) ? (w >> 16) : (w & 0xffffu), (int)(lw << (28 - 4 * e)) >> 28); } }
; #pragma unroll
;             for (int e = 0; e < 8; ++e) { const unsigned w = fw[e >> 1]; v[e] += ((e & 1) ? bf_hi(w) : bf_lo(w)) * r * gpv[2 * j + (e >> 2)][e & 3]; }
;             if (LAST) { __builtin_nontemporal_store((f32x4){v[0], v[1], v[2], v[3]}, (GAS f32x4*)(out + (size_t)row * DM + idx)); __builtin_nontemporal_store((f32x4){v[4], v[5], v[6], v[7]}, (GAS f32x4*)(out + (size_t)row * DM + idx + 4)); }
	v_add_f32_e32 v128, v128, v145
	ds_bpermute_b32 v145, v137, v128
	v_fma_f32 v180, v10, v180, v170
	v_fma_f32 v181, v11, v181, v171
	global_store_dwordx4 v[160:161], v[156:159], off offset:2048 nt
	global_store_dwordx4 v[160:161], v[178:181], off offset:2064 nt
	v_and_b32_sdwa v147, sext(v147), s57 dst_sel:DWORD dst_unused:UNUSED_PAD src0_sel:WORD_1 src1_sel:DWORD
	v_and_b32_e32 v156, 0xffff0000, v106
	s_waitcnt lgkmcnt(0)
	v_add_f32_e32 v128, v128, v145
	ds_bpermute_b32 v145, v138, v128
	v_lshlrev_b32_e32 v158, 16, v98
	v_and_b32_e32 v159, 0xffff0000, v98
	v_lshlrev_b32_e32 v160, 20, v141
	v_add_u32_e32 v157, v156, v147
	s_waitcnt lgkmcnt(0)
	v_add_f32_e32 v128, v128, v145
	v_fmamk_f32 v128, v128, 0x3a800000, v188
	v_rsq_f32_e32 v128, v128
	v_lshlrev_b32_e32 v145, 28, v141
	v_ashrrev_i32_e32 v145, 16, v145
	v_lshl_add_u32 v156, v106, 16, v145
	v_mul_f32_e32 v128, v33, v128
	v_mul_f32 v158, v128, v158
	v_mul_f32 v159, v128, v159
	v_fma_f32 v156, v4, v158, v156
	v_fma_f32 v157, v5, v159, v157
	v_and_b32_e32 v145, 0xffff0000, v107
	v_and_b32_sdwa v147, sext(v141), s57 dst_sel:DWORD dst_unused:UNUSED_PAD src0_sel:WORD_0 src1_sel:DWORD
	v_and_b32_sdwa v158, sext(v160), s57 dst_sel:DWORD dst_unused:UNUSED_PAD src0_sel:WORD_1 src1_sel:DWORD
	v_lshlrev_b32_e32 v160, 16, v99
	v_and_b32_e32 v161, 0xffff0000, v99
	v_add_u32_e32 v159, v145, v147
	v_lshl_add_u32 v158, v107, 16, v158
	v_mul_f32 v160, v128, v160
	v_mul_f32 v161, v128, v161
	v_fma_f32 v158, v6, v160, v158
	v_fma_f32 v159, v7, v161, v159
	v_bfe_i32 v147, v141, 8, 16
	v_bfe_i32 v160, v141, 4, 16
	v_and_b32_e32 v145, 0xffff0000, v108
	v_and_b32_e32 v147, 0xfffff000, v147
	v_and_b32_e32 v160, 0xfffff000, v160
	v_lshlrev_b32_e32 v170, 16, v100
	v_and_b32_e32 v171, 0xffff0000, v100
	s_add_i32 s8, s85, s3
	v_add_u32_e32 v161, v145, v147
	v_lshl_add_u32 v160, v108, 16, v160
	v_mul_f32 v170, v128, v170
	v_mul_f32 v171, v128, v171
	v_bfe_i32 v147, v141, 12, 16
	s_ashr_i32 s9, s8, 31
	v_fma_f32 v178, v0, v170, v160
	v_fma_f32 v179, v1, v171, v161
	v_and_b32_e32 v145, 0xffff0000, v109
	v_and_b32_sdwa v160, sext(v141), s57 dst_sel:DWORD dst_unused:UNUSED_PAD src0_sel:WORD_1 src1_sel:DWORD
	v_and_b32_e32 v147, 0xfffff000, v147
	v_lshlrev_b32_e32 v170, 16, v101
	v_and_b32_e32 v171, 0xffff0000, v101
	s_lshl_b64 s[8:9], s[8:9], 12
	v_add_u32_e32 v161, v145, v160
	v_lshl_add_u32 v160, v109, 16, v147
	v_mul_f32 v170, v128, v170
	v_mul_f32 v171, v128, v171
	v_fma_f32 v180, v2, v170, v160
	v_fma_f32 v181, v3, v171, v161
	v_lshl_add_u64 v[160:161], v[118:119], 0, s[8:9]
	v_lshlrev_b32_e32 v145, 28, v143
	v_lshlrev_b32_e32 v147, 24, v143
	global_store_dwordx4 v[160:161], v[156:159], off nt
	global_store_dwordx4 v[160:161], v[178:181], off offset:16 nt
	v_ashrrev_i32_e32 v145, 16, v145
	v_and_b32_e32 v156, 0xffff0000, v102
	v_and_b32_sdwa v147, sext(v147), s57 dst_sel:DWORD dst_unused:UNUSED_PAD src0_sel:WORD_1 src1_sel:DWORD
	s_waitcnt vmcnt(14)
	v_lshlrev_b32_e32 v158, 16, v110
	v_and_b32_e32 v159, 0xffff0000, v110
	v_lshlrev_b32_e32 v170, 20, v143
	v_add_u32_e32 v157, v156, v147
	v_lshl_add_u32 v156, v102, 16, v145
	v_mul_f32 v158, v128, v158
	v_mul_f32 v159, v128, v159
	v_fma_f32 v156, v12, v158, v156
	v_fma_f32 v157, v13, v159, v157
	v_and_b32_e32 v145, 0xffff0000, v103
	v_and_b32_sdwa v147, sext(v143), s57 dst_sel:DWORD dst_unused:UNUSED_PAD src0_sel:WORD_0 src1_sel:DWORD
	v_and_b32_sdwa v158, sext(v170), s57 dst_sel:DWORD dst_unused:UNUSED_PAD src0_sel:WORD_1 src1_sel:DWORD
	v_lshlrev_b32_e32 v170, 16, v111
	v_and_b32_e32 v171, 0xffff0000, v111
	v_add_u32_e32 v159, v145, v147
	v_lshl_add_u32 v158, v103, 16, v158
	v_mul_f32 v170, v128, v170
	v_mul_f32 v171, v128, v171
	v_fma_f32 v158, v14, v170, v158
	v_fma_f32 v159, v15, v171, v159
	v_bfe_i32 v147, v143, 8, 16
	v_bfe_i32 v170, v143, 4, 16
	v_and_b32_e32 v145, 0xffff0000, v104
	v_and_b32_e32 v147, 0xfffff000, v147
	v_and_b32_e32 v170, 0xfffff000, v170
	v_lshlrev_b32_e32 v178, 16, v112
	v_and_b32_e32 v179, 0xffff0000, v112
	v_add_u32_e32 v171, v145, v147
	v_lshl_add_u32 v170, v104, 16, v170
	v_mul_f32 v178, v128, v178
	v_mul_f32 v179, v128, v179
	v_bfe_i32 v147, v143, 12, 16
	v_fma_f32 v178, v8, v178, v170
	v_fma_f32 v179, v9, v179, v171
	v_and_b32_e32 v145, 0xffff0000, v105
	v_and_b32_sdwa v170, sext(v143), s57 dst_sel:DWORD dst_unused:UNUSED_PAD src0_sel:WORD_1 src1_sel:DWORD
	v_and_b32_e32 v147, 0xfffff000, v147
	v_lshlrev_b32_e32 v180, 16, v113
	v_and_b32_e32 v181, 0xffff0000, v113
	v_add_u32_e32 v171, v145, v170
	v_lshl_add_u32 v170, v105, 16, v147
	v_mul_f32 v180, v128, v180
	v_mul_f32 v181, v128, v181
	v_fma_f32 v180, v10, v180, v170
	v_fma_f32 v181, v11, v181, v171
	global_store_dwordx4 v[160:161], v[156:159], off offset:2048 nt
	global_store_dwordx4 v[160:161], v[178:181], off offset:2064 nt
	s_branch .LBB0_300

; __device__ __forceinline__ unsigned cvt_pk_bf16(float lo, float hi) { unsigned r; asm volatile("v_cvt_pk_bf16_f32 %0, %1, %2" : "=v"(r) : "v"(lo), "v"(hi)); return r; }
; #define GAS __attribute__((address_space(1)))
; __device__ __forceinline__ float silu_mul(float g, float u) { const float e = __builtin_amdgcn_exp2f(-1.4426950408889634f * g); return g * __builtin_amdgcn_rcpf(1.0f + e) * u; }
;     __device__ __forceinline__ void operator()(const f32x4 (&acc)[2][2][4][2], const Unit& u, int wr, int wc, int fr, int fq, const float (&pre)[8]) const {
;         const int row0 = u.pm * 256 + wr * 64 + fr, col0 = u.pn * 128 + wc * 32 + 8 * fq;
; #pragma unroll
;         for (int ai = 0; ai < 2; ++ai)
; #pragma unroll
;             for (int m = 0; m < 4; ++m) {
;                 const float rsc = pre[ai * 4 + m];
;                 const f32x4 g0 = acc[ai][0][m][0] * rsc, g1 = acc[ai][0][m][1] * rsc, u0 = acc[ai][1][m][0] * rsc, u1 = acc[ai][1][m][1] * rsc;
;                 u32x4 w; w.x = cvt_pk_bf16(silu_mul(g0[0], u0[0]), silu_mul(g0[1], u0[1])); w.y = cvt_pk_bf16(silu_mul(g0[2], u0[2]), silu_mul(g0[3], u0[3]));
;                 w.z = cvt_pk_bf16(silu_mul(g1[0], u1[0]), silu_mul(g1[1], u1[1])); w.w = cvt_pk_bf16(silu_mul(g1[2], u1[2]), silu_mul(g1[3], u1[3]));
;                 *(GAS u32x4*)(O + (size_t)(row0 + ai * 128 + m * 16) * DFF + col0) = w; }
.LBB0_447:
	v_mul_f32 v126, v158, v126
	v_mul_f32 v127, v158, v127
	v_mul_f32_e32 v153, 0xbfb8aa3b, v126
	v_exp_f32_e32 v153, v153
	v_mul_f32 v118, v158, v118
	v_mul_f32 v119, v158, v119
	v_mul_f32 v128, v158, v128
	v_mul_f32 v129, v158, v129
	v_mul_f32 v120, v158, v120
	v_mul_f32 v121, v158, v121
	v_add_f32_e32 v153, 1.0, v153
	v_rcp_f32_e32 v153, v153
	v_mul_f32 v122, v158, v122
	v_mul_f32 v123, v158, v123
	v_mul_f32 v114, v158, v114
	v_mul_f32 v115, v158, v115
	v_mul_f32 v124, v158, v124
	v_mul_f32 v125, v158, v125
	v_mul_f32_e32 v126, v126, v153
	v_mul_f32_e32 v118, v126, v118
	v_mul_f32_e32 v126, 0xbfb8aa3b, v127
	v_exp_f32_e32 v126, v126
	v_mul_f32 v116, v158, v116
	v_mul_f32 v117, v158, v117
	v_lshl_or_b32 v160, s44, 7, v147
	v_lshl_add_u32 v151, s46, 8, v33
	v_add_f32_e32 v126, 1.0, v126
	v_rcp_f32_e32 v126, v126
	v_ashrrev_i32_e32 v161, 31, v160
	v_mul_f32 v110, v156, v110
	v_mul_f32 v111, v156, v111
	v_mul_f32 v102, v156, v102
	v_mul_f32 v103, v156, v103
	v_mul_f32_e32 v126, v127, v126
	v_mul_f32_e32 v119, v126, v119
	v_cvt_pk_bf16_f32 v118, v118, v119
	v_mul_f32_e32 v119, 0xbfb8aa3b, v128
	v_exp_f32_e32 v119, v119
	v_mul_f32 v112, v156, v112
	v_mul_f32 v113, v156, v113
	v_mul_f32 v104, v156, v104
	v_mul_f32 v105, v156, v105
	v_mul_f32 v106, v156, v106
	v_mul_f32 v107, v156, v107
	v_add_f32_e32 v119, 1.0, v119
	v_rcp_f32_e32 v119, v119
	v_mul_f32 v108, v156, v108
	v_mul_f32 v109, v156, v109
	v_mul_f32 v94, v154, v94
	v_mul_f32 v95, v154, v95
	v_mul_f32 v86, v154, v86
	v_mul_f32 v87, v154, v87
	v_mul_f32_e32 v119, v128, v119
	v_mul_f32_e32 v119, v119, v120
	v_mul_f32_e32 v120, 0xbfb8aa3b, v129
	v_exp_f32_e32 v120, v120
	v_mul_f32 v96, v154, v96
	v_mul_f32 v97, v154, v97
	v_mul_f32 v88, v154, v88
	v_mul_f32 v89, v154, v89
	v_mul_f32 v90, v154, v90
	v_mul_f32 v91, v154, v91
	v_add_f32_e32 v120, 1.0, v120
	v_rcp_f32_e32 v120, v120
	v_mul_f32 v92, v154, v92
	v_mul_f32 v93, v154, v93
	v_mul_f32 v78, v152, v78
	v_mul_f32 v79, v152, v79
	v_mul_f32 v70, v152, v70
	v_mul_f32 v71, v152, v71
	v_mul_f32_e32 v120, v129, v120
	v_mul_f32_e32 v120, v120, v121
	v_cvt_pk_bf16_f32 v119, v119, v120
	v_mul_f32_e32 v120, 0xbfb8aa3b, v122
	v_exp_f32_e32 v120, v120
	v_mul_f32 v80, v152, v80
	v_mul_f32 v81, v152, v81
	v_mul_f32 v72, v152, v72
	v_mul_f32 v73, v152, v73
	v_mul_f32 v74, v152, v74
	v_mul_f32 v75, v152, v75
	v_add_f32_e32 v120, 1.0, v120
	v_rcp_f32_e32 v120, v120
	v_mul_f32 v76, v152, v76
	v_mul_f32 v77, v152, v77
	v_mul_f32 v62, v150, v62
	v_mul_f32 v63, v150, v63
	v_mul_f32 v54, v150, v54
	v_mul_f32 v55, v150, v55
	v_mul_f32_e32 v120, v122, v120
	v_mul_f32_e32 v114, v120, v114
	v_mul_f32_e32 v120, 0xbfb8aa3b, v123
	v_exp_f32_e32 v120, v120
	v_mul_f32 v64, v150, v64
	v_mul_f32 v65, v150, v65
	v_mul_f32 v56, v150, v56
	v_mul_f32 v57, v150, v57
	v_mul_f32 v58, v150, v58
	v_mul_f32 v59, v150, v59
	v_add_f32_e32 v120, 1.0, v120
	v_rcp_f32_e32 v120, v120
	v_mul_f32 v60, v150, v60
	v_mul_f32 v61, v150, v61
	v_mul_f32 v46, v148, v46
	v_mul_f32 v47, v148, v47
	v_mul_f32 v38, v148, v38
	v_mul_f32 v39, v148, v39
	v_mul_f32_e32 v120, v123, v120
	v_mul_f32_e32 v115, v120, v115
	v_cvt_pk_bf16_f32 v120, v114, v115
	v_mul_f32_e32 v114, 0xbfb8aa3b, v124
	v_mul_f32_e32 v115, 0xbfb8aa3b, v125
	v_exp_f32_e32 v114, v114
	v_exp_f32_e32 v115, v115
	v_mul_f32 v48, v148, v48
	v_mul_f32 v49, v148, v49
	v_mul_f32 v40, v148, v40
	v_mul_f32 v41, v148, v41
	v_add_f32_e32 v114, 1.0, v114
	v_add_f32_e32 v115, 1.0, v115
	v_rcp_f32_e32 v114, v114
	v_rcp_f32_e32 v115, v115
	v_mul_f32 v42, v148, v42
	v_mul_f32 v43, v148, v43
	v_mul_f32 v44, v148, v44
	v_mul_f32 v45, v148, v45
	v_mul_f32_e32 v114, v124, v114
	v_mul_f32_e32 v115, v125, v115
	v_mul_f32_e32 v114, v114, v116
	v_mul_f32_e32 v115, v115, v117
	v_cvt_pk_bf16_f32 v121, v114, v115
	v_mov_b64_e32 v[114:115], s[64:65]
	v_mad_i64_i32 v[122:123], s[38:39], v151, s29, v[114:115]
	v_lshlrev_b64 v[116:117], 1, v[160:161]
	v_lshl_add_u64 v[122:123], v[122:123], 0, v[116:117]
	global_store_dwordx4 v[122:123], v[118:121], off
	v_mul_f32 v28, v146, v28
	v_mul_f32 v29, v146, v29
	v_mul_f32 v20, v146, v20
	v_mul_f32 v21, v146, v21
	v_mul_f32 v118, v156, v100
	v_mul_f32 v119, v156, v101
	v_mul_f32 v100, v156, v98
	v_mul_f32 v101, v156, v99
	v_mul_f32_e32 v98, 0xbfb8aa3b, v110
	v_mul_f32_e32 v99, 0xbfb8aa3b, v111
	v_exp_f32_e32 v98, v98
	v_exp_f32_e32 v99, v99
	v_mul_f32 v30, v146, v30
	v_mul_f32 v31, v146, v31
	v_mul_f32 v22, v146, v22
	v_mul_f32 v23, v146, v23
	v_add_f32_e32 v98, 1.0, v98
	v_add_f32_e32 v99, 1.0, v99
	v_rcp_f32_e32 v98, v98
	v_rcp_f32_e32 v99, v99
	v_mul_f32 v24, v146, v24
	v_mul_f32 v25, v146, v25
	v_mul_f32 v26, v146, v26
	v_mul_f32 v27, v146, v27
	v_mul_f32_e32 v98, v110, v98
	v_mul_f32_e32 v99, v111, v99
	v_mul_f32_e32 v98, v98, v102
	v_mul_f32_e32 v99, v99, v103
	v_cvt_pk_bf16_f32 v98, v98, v99
	v_mul_f32_e32 v99, 0xbfb8aa3b, v112
	v_mul_f32_e32 v102, 0xbfb8aa3b, v113
	v_exp_f32_e32 v99, v99
	v_exp_f32_e32 v102, v102
	v_mul_f32 v12, v144, v12
	v_mul_f32 v13, v144, v13
	v_mul_f32 v4, v144, v4
	v_mul_f32 v5, v144, v5
	v_add_f32_e32 v99, 1.0, v99
	v_add_f32_e32 v102, 1.0, v102
	v_rcp_f32_e32 v99, v99
	v_rcp_f32_e32 v102, v102
	v_mul_f32 v14, v144, v14
	v_mul_f32 v15, v144, v15
	v_mul_f32 v6, v144, v6
	v_mul_f32 v7, v144, v7
	v_mul_f32_e32 v99, v112, v99
	v_mul_f32_e32 v102, v113, v102
	v_mul_f32_e32 v99, v99, v104
	v_mul_f32_e32 v102, v102, v105
	v_cvt_pk_bf16_f32 v99, v99, v102
	v_mul_f32_e32 v102, 0xbfb8aa3b, v106
	v_exp_f32_e32 v102, v102
	v_mul_f32 v8, v144, v8
	v_mul_f32 v9, v144, v9
	v_mul_f32 v10, v144, v10
	v_mul_f32 v11, v144, v11
	s_mov_b64 s[44:45], -1
	v_add_f32_e32 v102, 1.0, v102
	v_rcp_f32_e32 v102, v102
; __device__ __forceinline__ unsigned cvt_pk_bf16(float lo, float hi) { unsigned r; asm volatile("v_cvt_pk_bf16_f32 %0, %1, %2" : "=v"(r) : "v"(lo), "v"(hi)); return r; }
; #define GAS __attribute__((address_space(1)))
; __device__ __forceinline__ float silu_mul(float g, float u) { const float e = __builtin_amdgcn_exp2f(-1.4426950408889634f * g); return g * __builtin_amdgcn_rcpf(1.0f + e) * u; }
;     __device__ __forceinline__ void operator()(const f32x4 (&acc)[2][2][4][2], const Unit& u, int wr, int wc, int fr, int fq, const float (&pre)[8]) const {
;         const int row0 = u.pm * 256 + wr * 64 + fr, col0 = u.pn * 128 + wc * 32 + 8 * fq;
; #pragma unroll
;         for (int ai = 0; ai < 2; ++ai)
; #pragma unroll
;             for (int m = 0; m < 4; ++m) {
;                 const float rsc = pre[ai * 4 + m];
;                 const f32x4 g0 = acc[ai][0][m][0] * rsc, g1 = acc[ai][0][m][1] * rsc, u0 = acc[ai][1][m][0] * rsc, u1 = acc[ai][1][m][1] * rsc;
;                 u32x4 w; w.x = cvt_pk_bf16(silu_mul(g0[0], u0[0]), silu_mul(g0[1], u0[1])); w.y = cvt_pk_bf16(silu_mul(g0[2], u0[2]), silu_mul(g0[3], u0[3]));
;                 w.z = cvt_pk_bf16(silu_mul(g1[0], u1[0]), silu_mul(g1[1], u1[1])); w.w = cvt_pk_bf16(silu_mul(g1[2], u1[2]), silu_mul(g1[3], u1[3]));
;                 *(GAS u32x4*)(O + (size_t)(row0 + ai * 128 + m * 16) * DFF + col0) = w; }
	s_andn2_b64 vcc, exec, s[80:81]
	v_mul_f32_e32 v102, v106, v102
	v_mul_f32_e32 v100, v102, v100
	v_mul_f32_e32 v102, 0xbfb8aa3b, v107
	v_exp_f32_e32 v102, v102
	s_nop 0
	v_add_f32_e32 v102, 1.0, v102
	v_rcp_f32_e32 v102, v102
	s_nop 0
	v_mul_f32_e32 v102, v107, v102
	v_mul_f32_e32 v101, v102, v101
	v_cvt_pk_bf16_f32 v100, v100, v101
	v_mul_f32_e32 v101, 0xbfb8aa3b, v108
	v_mul_f32_e32 v102, 0xbfb8aa3b, v109
	v_exp_f32_e32 v101, v101
	v_exp_f32_e32 v102, v102
	v_add_f32_e32 v101, 1.0, v101
	v_add_f32_e32 v102, 1.0, v102
	v_rcp_f32_e32 v101, v101
	v_rcp_f32_e32 v102, v102
	v_mul_f32_e32 v101, v108, v101
	v_mul_f32_e32 v102, v109, v102
	v_mul_f32_e32 v101, v101, v118
	v_mul_f32_e32 v102, v102, v119
	v_cvt_pk_bf16_f32 v101, v101, v102
	v_or_b32_e32 v102, 16, v151
	v_mad_i64_i32 v[102:103], s[38:39], v102, s29, v[114:115]
	v_lshl_add_u64 v[102:103], v[102:103], 0, v[116:117]
	global_store_dwordx4 v[102:103], v[98:101], off
	s_nop 1
	v_mul_f32 v98, v154, v84
	v_mul_f32 v99, v154, v85
	v_mul_f32 v84, v154, v82
	v_mul_f32 v85, v154, v83
	v_mul_f32_e32 v82, 0xbfb8aa3b, v94
	v_mul_f32_e32 v83, 0xbfb8aa3b, v95
	v_exp_f32_e32 v82, v82
	v_exp_f32_e32 v83, v83
	v_add_f32_e32 v82, 1.0, v82
	v_add_f32_e32 v83, 1.0, v83
	v_rcp_f32_e32 v82, v82
	v_rcp_f32_e32 v83, v83
	v_mul_f32_e32 v82, v94, v82
	v_mul_f32_e32 v83, v95, v83
	v_mul_f32_e32 v82, v82, v86
	v_mul_f32_e32 v83, v83, v87
	v_cvt_pk_bf16_f32 v82, v82, v83
	v_mul_f32_e32 v83, 0xbfb8aa3b, v96
	v_mul_f32_e32 v86, 0xbfb8aa3b, v97
	v_exp_f32_e32 v83, v83
	v_exp_f32_e32 v86, v86
	v_add_f32_e32 v83, 1.0, v83
	v_add_f32_e32 v86, 1.0, v86
	v_rcp_f32_e32 v83, v83
	v_rcp_f32_e32 v86, v86
	v_mul_f32_e32 v83, v96, v83
	v_mul_f32_e32 v86, v97, v86
	v_mul_f32_e32 v83, v83, v88
	v_mul_f32_e32 v86, v86, v89
	v_cvt_pk_bf16_f32 v83, v83, v86
	v_mul_f32_e32 v86, 0xbfb8aa3b, v90
	v_exp_f32_e32 v86, v86
	s_nop 0
	v_add_f32_e32 v86, 1.0, v86
	v_rcp_f32_e32 v86, v86
	s_nop 0
	v_mul_f32_e32 v86, v90, v86
	v_mul_f32_e32 v84, v86, v84
	v_mul_f32_e32 v86, 0xbfb8aa3b, v91
	v_exp_f32_e32 v86, v86
	s_nop 0
	v_add_f32_e32 v86, 1.0, v86
	v_rcp_f32_e32 v86, v86
	s_nop 0
	v_mul_f32_e32 v86, v91, v86
	v_mul_f32_e32 v85, v86, v85
	v_cvt_pk_bf16_f32 v84, v84, v85
	v_mul_f32_e32 v85, 0xbfb8aa3b, v92
	v_mul_f32_e32 v86, 0xbfb8aa3b, v93
	v_exp_f32_e32 v85, v85
	v_exp_f32_e32 v86, v86
	v_add_f32_e32 v85, 1.0, v85
	v_add_f32_e32 v86, 1.0, v86
	v_rcp_f32_e32 v85, v85
	v_rcp_f32_e32 v86, v86
	v_mul_f32_e32 v85, v92, v85
	v_mul_f32_e32 v86, v93, v86
	v_mul_f32_e32 v85, v85, v98
	v_mul_f32_e32 v86, v86, v99
	v_cvt_pk_bf16_f32 v85, v85, v86
	v_or_b32_e32 v86, 32, v151
	v_mad_i64_i32 v[86:87], s[38:39], v86, s29, v[114:115]
	v_lshl_add_u64 v[86:87], v[86:87], 0, v[116:117]
	global_store_dwordx4 v[86:87], v[82:85], off
	s_nop 1
	v_mul_f32 v82, v152, v68
	v_mul_f32 v83, v152, v69
	v_mul_f32 v68, v152, v66
	v_mul_f32 v69, v152, v67
	v_mul_f32_e32 v66, 0xbfb8aa3b, v78
	v_mul_f32_e32 v67, 0xbfb8aa3b, v79
	v_exp_f32_e32 v66, v66
	v_exp_f32_e32 v67, v67
	v_add_f32_e32 v66, 1.0, v66
	v_add_f32_e32 v67, 1.0, v67
	v_rcp_f32_e32 v66, v66
	v_rcp_f32_e32 v67, v67
	v_mul_f32_e32 v66, v78, v66
	v_mul_f32_e32 v67, v79, v67
	v_mul_f32_e32 v66, v66, v70
	v_mul_f32_e32 v67, v67, v71
	v_cvt_pk_bf16_f32 v66, v66, v67
	v_mul_f32_e32 v67, 0xbfb8aa3b, v80
	v_mul_f32_e32 v70, 0xbfb8aa3b, v81
	v_exp_f32_e32 v67, v67
	v_exp_f32_e32 v70, v70
	v_add_f32_e32 v67, 1.0, v67
	v_add_f32_e32 v70, 1.0, v70
	v_rcp_f32_e32 v67, v67
	v_rcp_f32_e32 v70, v70
	v_mul_f32_e32 v67, v80, v67
	v_mul_f32_e32 v70, v81, v70
	v_mul_f32_e32 v67, v67, v72
	v_mul_f32_e32 v70, v70, v73
	v_cvt_pk_bf16_f32 v67, v67, v70
	v_mul_f32_e32 v70, 0xbfb8aa3b, v74
	v_exp_f32_e32 v70, v70
	s_nop 0
	v_add_f32_e32 v70, 1.0, v70
	v_rcp_f32_e32 v70, v70
	s_nop 0
	v_mul_f32_e32 v70, v74, v70
	v_mul_f32_e32 v68, v70, v68
	v_mul_f32_e32 v70, 0xbfb8aa3b, v75
	v_exp_f32_e32 v70, v70
	s_nop 0
	v_add_f32_e32 v70, 1.0, v70
	v_rcp_f32_e32 v70, v70
	s_nop 0
	v_mul_f32_e32 v70, v75, v70
	v_mul_f32_e32 v69, v70, v69
	v_cvt_pk_bf16_f32 v68, v68, v69
	v_mul_f32_e32 v69, 0xbfb8aa3b, v76
	v_mul_f32_e32 v70, 0xbfb8aa3b, v77
	v_exp_f32_e32 v69, v69
	v_exp_f32_e32 v70, v70
	v_add_f32_e32 v69, 1.0, v69
	v_add_f32_e32 v70, 1.0, v70
	v_rcp_f32_e32 v69, v69
	v_rcp_f32_e32 v70, v70
	v_mul_f32_e32 v69, v76, v69
	v_mul_f32_e32 v70, v77, v70
	v_mul_f32_e32 v69, v69, v82
	v_mul_f32_e32 v70, v70, v83
	v_cvt_pk_bf16_f32 v69, v69, v70
	v_or_b32_e32 v70, 48, v151
	v_mad_i64_i32 v[70:71], s[38:39], v70, s29, v[114:115]
	v_lshl_add_u64 v[70:71], v[70:71], 0, v[116:117]
	global_store_dwordx4 v[70:71], v[66:69], off
	s_nop 1
	v_mul_f32 v66, v150, v52
	v_mul_f32 v67, v150, v53
	v_mul_f32 v52, v150, v50
	v_mul_f32 v53, v150, v51
	v_mul_f32_e32 v50, 0xbfb8aa3b, v62
	v_mul_f32_e32 v51, 0xbfb8aa3b, v63
	v_exp_f32_e32 v50, v50
	v_exp_f32_e32 v51, v51
	v_add_u32_e32 v68, 0x80, v151
	v_add_f32_e32 v50, 1.0, v50
	v_add_f32_e32 v51, 1.0, v51
	v_rcp_f32_e32 v50, v50
	v_rcp_f32_e32 v51, v51
	v_mul_f32_e32 v50, v62, v50
	v_mul_f32_e32 v51, v63, v51
	v_mul_f32_e32 v50, v50, v54
	v_mul_f32_e32 v51, v51, v55
	v_cvt_pk_bf16_f32 v50, v50, v51
	v_mul_f32_e32 v51, 0xbfb8aa3b, v64
	v_mul_f32_e32 v54, 0xbfb8aa3b, v65
	v_exp_f32_e32 v51, v51
	v_exp_f32_e32 v54, v54
	v_add_f32_e32 v51, 1.0, v51
	v_add_f32_e32 v54, 1.0, v54
	v_rcp_f32_e32 v51, v51
	v_rcp_f32_e32 v54, v54
	v_mul_f32_e32 v51, v64, v51
	v_mul_f32_e32 v54, v65, v54
	v_mul_f32_e32 v51, v51, v56
	v_mul_f32_e32 v54, v54, v57
	v_cvt_pk_bf16_f32 v51, v51, v54
	v_mul_f32_e32 v54, 0xbfb8aa3b, v58
	v_exp_f32_e32 v54, v54
	s_nop 0
	v_add_f32_e32 v54, 1.0, v54
	v_rcp_f32_e32 v54, v54
	s_nop 0
	v_mul_f32_e32 v54, v58, v54
; __device__ __forceinline__ unsigned cvt_pk_bf16(float lo, float hi) { unsigned r; asm volatile("v_cvt_pk_bf16_f32 %0, %1, %2" : "=v"(r) : "v"(lo), "v"(hi)); return r; }
; #define GAS __attribute__((address_space(1)))
; __device__ __forceinline__ float silu_mul(float g, float u) { const float e = __builtin_amdgcn_exp2f(-1.4426950408889634f * g); return g * __builtin_amdgcn_rcpf(1.0f + e) * u; }
;     __device__ __forceinline__ void prefetch(const Unit& u, int wr, int fr, float (&pre)[8]) const {
; #pragma unroll
;         for (int i = 0; i < 8; ++i) pre[i] = *(const GAS float*)(rs + u.pm * 256 + wr * 64 + fr + (i >> 2) * 128 + (i & 3) * 16);
;     __device__ __forceinline__ void operator()(const f32x4 (&acc)[2][2][4][2], const Unit& u, int wr, int wc, int fr, int fq, const float (&pre)[8]) const {
;         const int row0 = u.pm * 256 + wr * 64 + fr, col0 = u.pn * 128 + wc * 32 + 8 * fq;
; #pragma unroll
;         for (int ai = 0; ai < 2; ++ai)
; #pragma unroll
;             for (int m = 0; m < 4; ++m) {
;                 const float rsc = pre[ai * 4 + m];
;                 const f32x4 g0 = acc[ai][0][m][0] * rsc, g1 = acc[ai][0][m][1] * rsc, u0 = acc[ai][1][m][0] * rsc, u1 = acc[ai][1][m][1] * rsc;
;                 u32x4 w; w.x = cvt_pk_bf16(silu_mul(g0[0], u0[0]), silu_mul(g0[1], u0[1])); w.y = cvt_pk_bf16(silu_mul(g0[2], u0[2]), silu_mul(g0[3], u0[3]));
;                 w.z = cvt_pk_bf16(silu_mul(g1[0], u1[0]), silu_mul(g1[1], u1[1])); w.w = cvt_pk_bf16(silu_mul(g1[2], u1[2]), silu_mul(g1[3], u1[3]));
;                 *(GAS u32x4*)(O + (size_t)(row0 + ai * 128 + m * 16) * DFF + col0) = w; }
	v_mul_f32_e32 v52, v54, v52
	v_mul_f32_e32 v54, 0xbfb8aa3b, v59
	v_exp_f32_e32 v54, v54
	s_nop 0
	v_add_f32_e32 v54, 1.0, v54
	v_rcp_f32_e32 v54, v54
	s_nop 0
	v_mul_f32_e32 v54, v59, v54
	v_mul_f32_e32 v53, v54, v53
	v_cvt_pk_bf16_f32 v52, v52, v53
	v_mul_f32_e32 v53, 0xbfb8aa3b, v60
	v_mul_f32_e32 v54, 0xbfb8aa3b, v61
	v_exp_f32_e32 v53, v53
	v_exp_f32_e32 v54, v54
	v_add_f32_e32 v53, 1.0, v53
	v_add_f32_e32 v54, 1.0, v54
	v_rcp_f32_e32 v53, v53
	v_rcp_f32_e32 v54, v54
	v_mul_f32_e32 v53, v60, v53
	v_mul_f32_e32 v54, v61, v54
	v_mul_f32_e32 v53, v53, v66
	v_mul_f32_e32 v54, v54, v67
	v_cvt_pk_bf16_f32 v53, v53, v54
	v_mad_i64_i32 v[54:55], s[38:39], v68, s29, v[114:115]
	v_lshl_add_u64 v[54:55], v[54:55], 0, v[116:117]
	global_store_dwordx4 v[54:55], v[50:53], off
	s_nop 1
	v_mul_f32 v50, v148, v36
	v_mul_f32 v51, v148, v37
	v_mul_f32 v36, v148, v34
	v_mul_f32 v37, v148, v35
	v_mul_f32_e32 v34, 0xbfb8aa3b, v46
	v_mul_f32_e32 v35, 0xbfb8aa3b, v47
	v_exp_f32_e32 v34, v34
	v_exp_f32_e32 v35, v35
	v_add_f32_e32 v34, 1.0, v34
	v_add_f32_e32 v35, 1.0, v35
	v_rcp_f32_e32 v34, v34
	v_rcp_f32_e32 v35, v35
	v_mul_f32_e32 v34, v46, v34
	v_mul_f32_e32 v35, v47, v35
	v_mul_f32_e32 v34, v34, v38
	v_mul_f32_e32 v35, v35, v39
	v_cvt_pk_bf16_f32 v34, v34, v35
	v_mul_f32_e32 v35, 0xbfb8aa3b, v48
	v_mul_f32_e32 v38, 0xbfb8aa3b, v49
	v_exp_f32_e32 v35, v35
	v_exp_f32_e32 v38, v38
	v_add_f32_e32 v35, 1.0, v35
	v_add_f32_e32 v38, 1.0, v38
	v_rcp_f32_e32 v35, v35
	v_rcp_f32_e32 v38, v38
	v_mul_f32_e32 v35, v48, v35
	v_mul_f32_e32 v38, v49, v38
	v_mul_f32_e32 v35, v35, v40
	v_mul_f32_e32 v38, v38, v41
	v_cvt_pk_bf16_f32 v35, v35, v38
	v_mul_f32_e32 v38, 0xbfb8aa3b, v42
	v_exp_f32_e32 v38, v38
	s_nop 0
	v_add_f32_e32 v38, 1.0, v38
	v_rcp_f32_e32 v38, v38
	s_nop 0
	v_mul_f32_e32 v38, v42, v38
	v_mul_f32_e32 v36, v38, v36
	v_mul_f32_e32 v38, 0xbfb8aa3b, v43
	v_exp_f32_e32 v38, v38
	s_nop 0
	v_add_f32_e32 v38, 1.0, v38
	v_rcp_f32_e32 v38, v38
	s_nop 0
	v_mul_f32_e32 v38, v43, v38
	v_mul_f32_e32 v37, v38, v37
	v_cvt_pk_bf16_f32 v36, v36, v37
	v_mul_f32_e32 v37, 0xbfb8aa3b, v44
	v_mul_f32_e32 v38, 0xbfb8aa3b, v45
	v_exp_f32_e32 v37, v37
	v_exp_f32_e32 v38, v38
	v_add_f32_e32 v37, 1.0, v37
	v_add_f32_e32 v38, 1.0, v38
	v_rcp_f32_e32 v37, v37
	v_rcp_f32_e32 v38, v38
	v_mul_f32_e32 v37, v44, v37
	v_mul_f32_e32 v38, v45, v38
	v_mul_f32_e32 v37, v37, v50
	v_mul_f32_e32 v38, v38, v51
	v_cvt_pk_bf16_f32 v37, v37, v38
	v_add_u32_e32 v38, 0x90, v151
	v_mad_i64_i32 v[38:39], s[38:39], v38, s29, v[114:115]
	v_lshl_add_u64 v[38:39], v[38:39], 0, v[116:117]
	global_store_dwordx4 v[38:39], v[34:37], off
	s_nop 1
	v_mul_f32 v34, v146, v18
	v_mul_f32 v35, v146, v19
	v_mul_f32 v18, v146, v16
	v_mul_f32 v19, v146, v17
	v_mul_f32_e32 v16, 0xbfb8aa3b, v28
	v_mul_f32_e32 v17, 0xbfb8aa3b, v29
	v_exp_f32_e32 v16, v16
	v_exp_f32_e32 v17, v17
	v_add_f32_e32 v16, 1.0, v16
	v_add_f32_e32 v17, 1.0, v17
	v_rcp_f32_e32 v16, v16
	v_rcp_f32_e32 v17, v17
	v_mul_f32_e32 v16, v28, v16
	v_mul_f32_e32 v17, v29, v17
	v_mul_f32_e32 v16, v16, v20
	v_mul_f32_e32 v17, v17, v21
	v_cvt_pk_bf16_f32 v16, v16, v17
	v_mul_f32_e32 v17, 0xbfb8aa3b, v30
	v_mul_f32_e32 v20, 0xbfb8aa3b, v31
	v_exp_f32_e32 v17, v17
	v_exp_f32_e32 v20, v20
	v_add_f32_e32 v17, 1.0, v17
	v_add_f32_e32 v20, 1.0, v20
	v_rcp_f32_e32 v17, v17
	v_rcp_f32_e32 v20, v20
	v_mul_f32_e32 v17, v30, v17
	v_mul_f32_e32 v20, v31, v20
	v_mul_f32_e32 v17, v17, v22
	v_mul_f32_e32 v20, v20, v23
	v_cvt_pk_bf16_f32 v17, v17, v20
	v_mul_f32_e32 v20, 0xbfb8aa3b, v24
	v_exp_f32_e32 v20, v20
	s_nop 0
	v_add_f32_e32 v20, 1.0, v20
	v_rcp_f32_e32 v20, v20
	s_nop 0
	v_mul_f32_e32 v20, v24, v20
	v_mul_f32_e32 v18, v20, v18
	v_mul_f32_e32 v20, 0xbfb8aa3b, v25
	v_exp_f32_e32 v20, v20
	s_nop 0
	v_add_f32_e32 v20, 1.0, v20
	v_rcp_f32_e32 v20, v20
	s_nop 0
	v_mul_f32_e32 v20, v25, v20
	v_mul_f32_e32 v19, v20, v19
	v_cvt_pk_bf16_f32 v18, v18, v19
	v_mul_f32_e32 v19, 0xbfb8aa3b, v26
	v_mul_f32_e32 v20, 0xbfb8aa3b, v27
	v_exp_f32_e32 v19, v19
	v_exp_f32_e32 v20, v20
	v_add_f32_e32 v19, 1.0, v19
	v_add_f32_e32 v20, 1.0, v20
	v_rcp_f32_e32 v19, v19
	v_rcp_f32_e32 v20, v20
	v_mul_f32_e32 v19, v26, v19
	v_mul_f32_e32 v20, v27, v20
	v_mul_f32_e32 v19, v19, v34
	v_mul_f32_e32 v20, v20, v35
	v_cvt_pk_bf16_f32 v19, v19, v20
	v_add_u32_e32 v20, 0xa0, v151
	v_mad_i64_i32 v[20:21], s[38:39], v20, s29, v[114:115]
	v_lshl_add_u64 v[20:21], v[20:21], 0, v[116:117]
	global_store_dwordx4 v[20:21], v[16:19], off
	s_nop 1
	v_mul_f32 v16, v144, v2
	v_mul_f32 v17, v144, v3
	v_mul_f32 v2, v144, v0
	v_mul_f32 v3, v144, v1
	v_mul_f32_e32 v0, 0xbfb8aa3b, v12
	v_mul_f32_e32 v1, 0xbfb8aa3b, v13
	v_exp_f32_e32 v0, v0
	v_exp_f32_e32 v1, v1
	v_add_f32_e32 v0, 1.0, v0
	v_add_f32_e32 v1, 1.0, v1
	v_rcp_f32_e32 v0, v0
	v_rcp_f32_e32 v1, v1
	v_mul_f32_e32 v0, v12, v0
	v_mul_f32_e32 v1, v13, v1
	v_mul_f32_e32 v0, v0, v4
	v_mul_f32_e32 v1, v1, v5
	v_cvt_pk_bf16_f32 v0, v0, v1
	v_mul_f32_e32 v1, 0xbfb8aa3b, v14
	v_mul_f32_e32 v4, 0xbfb8aa3b, v15
	v_exp_f32_e32 v1, v1
	v_exp_f32_e32 v4, v4
	v_add_f32_e32 v1, 1.0, v1
	v_add_f32_e32 v4, 1.0, v4
	v_rcp_f32_e32 v1, v1
	v_rcp_f32_e32 v4, v4
	v_mul_f32_e32 v1, v14, v1
	v_mul_f32_e32 v4, v15, v4
	v_mul_f32_e32 v1, v1, v6
	v_mul_f32_e32 v4, v4, v7
	v_cvt_pk_bf16_f32 v1, v1, v4
	v_mul_f32_e32 v4, 0xbfb8aa3b, v8
	v_exp_f32_e32 v4, v4
	s_nop 0
	v_add_f32_e32 v4, 1.0, v4
	v_rcp_f32_e32 v4, v4
	s_nop 0
	v_mul_f32_e32 v4, v8, v4
	v_mul_f32_e32 v2, v4, v2
	v_mul_f32_e32 v4, 0xbfb8aa3b, v9
	v_exp_f32_e32 v4, v4
	s_nop 0
	v_add_f32_e32 v4, 1.0, v4
	v_rcp_f32_e32 v4, v4
	s_nop 0
	v_mul_f32_e32 v4, v9, v4
	v_mul_f32_e32 v3, v4, v3
	v_cvt_pk_bf16_f32 v2, v2, v3
	v_mul_f32_e32 v3, 0xbfb8aa3b, v10
	v_mul_f32_e32 v4, 0xbfb8aa3b, v11
	v_exp_f32_e32 v3, v3
	v_exp_f32_e32 v4, v4
	v_add_f32_e32 v3, 1.0, v3
	v_add_f32_e32 v4, 1.0, v4
	v_rcp_f32_e32 v3, v3
	v_rcp_f32_e32 v4, v4
	v_mul_f32_e32 v3, v10, v3
	v_mul_f32_e32 v4, v11, v4
	v_mul_f32_e32 v3, v3, v16
	v_mul_f32_e32 v4, v4, v17
	v_cvt_pk_bf16_f32 v3, v3, v4
	v_add_u32_e32 v4, 0xb0, v151
	v_mad_i64_i32 v[4:5], s[38:39], v4, s29, v[114:115]
	v_lshl_add_u64 v[4:5], v[4:5], 0, v[116:117]
	global_store_dwordx4 v[4:5], v[0:3], off
	s_cbranch_vccnz .LBB0_439
	s_lshl_b32 s38, s42, 8
	s_ashr_i32 s39, s38, 31
	v_lshl_add_u64 v[0:1], s[38:39], 2, v[138:139]
	global_load_dword v158, v[0:1], off
	global_load_dword v156, v[0:1], off offset:64
	global_load_dword v154, v[0:1], off offset:128
	global_load_dword v152, v[0:1], off offset:192
	global_load_dword v150, v[0:1], off offset:512
	global_load_dword v148, v[0:1], off offset:576
	global_load_dword v146, v[0:1], off offset:640
	global_load_dword v144, v[0:1], off offset:704
	s_andn2_b64 vcc, exec, s[2:3]
	s_cbranch_vccnz .LBB0_438
	s_barrier
	s_branch .LBB0_438

; __device__ __forceinline__ unsigned cvt_pk_bf16(float lo, float hi) { unsigned r; asm volatile("v_cvt_pk_bf16_f32 %0, %1, %2" : "=v"(r) : "v"(lo), "v"(hi)); return r; }
; #define GAS __attribute__((address_space(1)))
; __device__ __forceinline__ float silu_mul(float g, float u) { const float e = __builtin_amdgcn_exp2f(-1.4426950408889634f * g); return g * __builtin_amdgcn_rcpf(1.0f + e) * u; }
;     __device__ __forceinline__ void operator()(const f32x4 (&acc)[2][2][4][2], const Unit& u, int wr, int wc, int fr, int fq, const float (&pre)[8]) const {
;         const int row0 = u.pm * 256 + wr * 64 + fr, col0 = u.pn * 128 + wc * 32 + 8 * fq;
; #pragma unroll
;         for (int ai = 0; ai < 2; ++ai)
; #pragma unroll
;             for (int m = 0; m < 4; ++m) {
;                 const float rsc = pre[ai * 4 + m];
;                 const f32x4 g0 = acc[ai][0][m][0] * rsc, g1 = acc[ai][0][m][1] * rsc, u0 = acc[ai][1][m][0] * rsc, u1 = acc[ai][1][m][1] * rsc;
;                 u32x4 w; w.x = cvt_pk_bf16(silu_mul(g0[0], u0[0]), silu_mul(g0[1], u0[1])); w.y = cvt_pk_bf16(silu_mul(g0[2], u0[2]), silu_mul(g0[3], u0[3]));
;                 w.z = cvt_pk_bf16(silu_mul(g1[0], u1[0]), silu_mul(g1[1], u1[1])); w.w = cvt_pk_bf16(silu_mul(g1[2], u1[2]), silu_mul(g1[3], u1[3]));
;                 *(GAS u32x4*)(O + (size_t)(row0 + ai * 128 + m * 16) * DFF + col0) = w; }
.LBB0_583:
	v_mul_f32 v126, v158, v126
	v_mul_f32 v127, v158, v127
	v_mul_f32_e32 v153, 0xbfb8aa3b, v126
	v_exp_f32_e32 v153, v153
	v_mul_f32 v118, v158, v118
	v_mul_f32 v119, v158, v119
	v_mul_f32 v128, v158, v128
	v_mul_f32 v129, v158, v129
	v_mul_f32 v120, v158, v120
	v_mul_f32 v121, v158, v121
	v_add_f32_e32 v153, 1.0, v153
	v_rcp_f32_e32 v153, v153
	v_mul_f32 v122, v158, v122
	v_mul_f32 v123, v158, v123
	v_mul_f32 v114, v158, v114
	v_mul_f32 v115, v158, v115
	v_mul_f32 v124, v158, v124
	v_mul_f32 v125, v158, v125
	v_mul_f32_e32 v126, v126, v153
	v_mul_f32_e32 v118, v126, v118
	v_mul_f32_e32 v126, 0xbfb8aa3b, v127
	v_exp_f32_e32 v126, v126
	v_mul_f32 v116, v158, v116
	v_mul_f32 v117, v158, v117
	v_lshl_or_b32 v160, s45, 7, v147
	v_lshl_add_u32 v151, s44, 8, v33
	v_add_f32_e32 v126, 1.0, v126
	v_rcp_f32_e32 v126, v126
	v_ashrrev_i32_e32 v161, 31, v160
	v_mul_f32 v110, v156, v110
	v_mul_f32 v111, v156, v111
	v_mul_f32 v102, v156, v102
	v_mul_f32 v103, v156, v103
	v_mul_f32_e32 v126, v127, v126
	v_mul_f32_e32 v119, v126, v119
	v_cvt_pk_bf16_f32 v118, v118, v119
	v_mul_f32_e32 v119, 0xbfb8aa3b, v128
	v_exp_f32_e32 v119, v119
	v_mul_f32 v112, v156, v112
	v_mul_f32 v113, v156, v113
	v_mul_f32 v104, v156, v104
	v_mul_f32 v105, v156, v105
	v_mul_f32 v106, v156, v106
	v_mul_f32 v107, v156, v107
	v_add_f32_e32 v119, 1.0, v119
	v_rcp_f32_e32 v119, v119
	v_mul_f32 v108, v156, v108
	v_mul_f32 v109, v156, v109
	v_mul_f32 v94, v154, v94
	v_mul_f32 v95, v154, v95
	v_mul_f32 v86, v154, v86
	v_mul_f32 v87, v154, v87
	v_mul_f32_e32 v119, v128, v119
	v_mul_f32_e32 v119, v119, v120
	v_mul_f32_e32 v120, 0xbfb8aa3b, v129
	v_exp_f32_e32 v120, v120
	v_mul_f32 v96, v154, v96
	v_mul_f32 v97, v154, v97
	v_mul_f32 v88, v154, v88
	v_mul_f32 v89, v154, v89
	v_mul_f32 v90, v154, v90
	v_mul_f32 v91, v154, v91
	v_add_f32_e32 v120, 1.0, v120
	v_rcp_f32_e32 v120, v120
	v_mul_f32 v92, v154, v92
	v_mul_f32 v93, v154, v93
	v_mul_f32 v78, v152, v78
	v_mul_f32 v79, v152, v79
	v_mul_f32 v70, v152, v70
	v_mul_f32 v71, v152, v71
	v_mul_f32_e32 v120, v129, v120
	v_mul_f32_e32 v120, v120, v121
	v_cvt_pk_bf16_f32 v119, v119, v120
	v_mul_f32_e32 v120, 0xbfb8aa3b, v122
	v_exp_f32_e32 v120, v120
	v_mul_f32 v80, v152, v80
	v_mul_f32 v81, v152, v81
	v_mul_f32 v72, v152, v72
	v_mul_f32 v73, v152, v73
	v_mul_f32 v74, v152, v74
	v_mul_f32 v75, v152, v75
	v_add_f32_e32 v120, 1.0, v120
	v_rcp_f32_e32 v120, v120
	v_mul_f32 v76, v152, v76
	v_mul_f32 v77, v152, v77
	v_mul_f32 v62, v150, v62
	v_mul_f32 v63, v150, v63
	v_mul_f32 v54, v150, v54
	v_mul_f32 v55, v150, v55
	v_mul_f32_e32 v120, v122, v120
	v_mul_f32_e32 v114, v120, v114
	v_mul_f32_e32 v120, 0xbfb8aa3b, v123
	v_exp_f32_e32 v120, v120
	v_mul_f32 v64, v150, v64
	v_mul_f32 v65, v150, v65
	v_mul_f32 v56, v150, v56
	v_mul_f32 v57, v150, v57
	v_mul_f32 v58, v150, v58
	v_mul_f32 v59, v150, v59
	v_add_f32_e32 v120, 1.0, v120
	v_rcp_f32_e32 v120, v120
	v_mul_f32 v60, v150, v60
	v_mul_f32 v61, v150, v61
	v_mul_f32 v46, v148, v46
	v_mul_f32 v47, v148, v47
	v_mul_f32 v38, v148, v38
	v_mul_f32 v39, v148, v39
	v_mul_f32_e32 v120, v123, v120
	v_mul_f32_e32 v115, v120, v115
	v_cvt_pk_bf16_f32 v120, v114, v115
	v_mul_f32_e32 v114, 0xbfb8aa3b, v124
	v_mul_f32_e32 v115, 0xbfb8aa3b, v125
	v_exp_f32_e32 v114, v114
	v_exp_f32_e32 v115, v115
	v_mul_f32 v48, v148, v48
	v_mul_f32 v49, v148, v49
	v_mul_f32 v40, v148, v40
	v_mul_f32 v41, v148, v41
	v_add_f32_e32 v114, 1.0, v114
	v_add_f32_e32 v115, 1.0, v115
	v_rcp_f32_e32 v114, v114
	v_rcp_f32_e32 v115, v115
	v_mul_f32 v42, v148, v42
	v_mul_f32 v43, v148, v43
	v_mul_f32 v44, v148, v44
	v_mul_f32 v45, v148, v45
	v_mul_f32_e32 v114, v124, v114
	v_mul_f32_e32 v115, v125, v115
	v_mul_f32_e32 v114, v114, v116
	v_mul_f32_e32 v115, v115, v117
	v_cvt_pk_bf16_f32 v121, v114, v115
	v_mov_b64_e32 v[114:115], s[64:65]
	v_mad_i64_i32 v[122:123], s[44:45], v151, s29, v[114:115]
	v_lshlrev_b64 v[116:117], 1, v[160:161]
	v_lshl_add_u64 v[122:123], v[122:123], 0, v[116:117]
	global_store_dwordx4 v[122:123], v[118:121], off
	v_mul_f32 v28, v146, v28
	v_mul_f32 v29, v146, v29
	v_mul_f32 v20, v146, v20
	v_mul_f32 v21, v146, v21
	v_mul_f32 v118, v156, v100
	v_mul_f32 v119, v156, v101
	v_mul_f32 v100, v156, v98
	v_mul_f32 v101, v156, v99
	v_mul_f32_e32 v98, 0xbfb8aa3b, v110
	v_mul_f32_e32 v99, 0xbfb8aa3b, v111
	v_exp_f32_e32 v98, v98
	v_exp_f32_e32 v99, v99
	v_mul_f32 v30, v146, v30
	v_mul_f32 v31, v146, v31
	v_mul_f32 v22, v146, v22
	v_mul_f32 v23, v146, v23
	v_add_f32_e32 v98, 1.0, v98
	v_add_f32_e32 v99, 1.0, v99
	v_rcp_f32_e32 v98, v98
	v_rcp_f32_e32 v99, v99
	v_mul_f32 v24, v146, v24
	v_mul_f32 v25, v146, v25
	v_mul_f32 v26, v146, v26
	v_mul_f32 v27, v146, v27
	v_mul_f32_e32 v98, v110, v98
	v_mul_f32_e32 v99, v111, v99
	v_mul_f32_e32 v98, v98, v102
	v_mul_f32_e32 v99, v99, v103
	v_cvt_pk_bf16_f32 v98, v98, v99
	v_mul_f32_e32 v99, 0xbfb8aa3b, v112
	v_mul_f32_e32 v102, 0xbfb8aa3b, v113
	v_exp_f32_e32 v99, v99
	v_exp_f32_e32 v102, v102
	v_mul_f32 v12, v144, v12
	v_mul_f32 v13, v144, v13
	v_mul_f32 v4, v144, v4
	v_mul_f32 v5, v144, v5
	v_add_f32_e32 v99, 1.0, v99
	v_add_f32_e32 v102, 1.0, v102
	v_rcp_f32_e32 v99, v99
	v_rcp_f32_e32 v102, v102
	v_mul_f32 v14, v144, v14
	v_mul_f32 v15, v144, v15
	v_mul_f32 v6, v144, v6
	v_mul_f32 v7, v144, v7
	v_mul_f32_e32 v99, v112, v99
	v_mul_f32_e32 v102, v113, v102
	v_mul_f32_e32 v99, v99, v104
	v_mul_f32_e32 v102, v102, v105
	v_cvt_pk_bf16_f32 v99, v99, v102
	v_mul_f32_e32 v102, 0xbfb8aa3b, v106
	v_exp_f32_e32 v102, v102
	v_mul_f32 v8, v144, v8
	v_mul_f32 v9, v144, v9
	v_mul_f32 v10, v144, v10
	v_mul_f32 v11, v144, v11
	s_andn2_b64 vcc, exec, s[42:43]
	v_add_f32_e32 v102, 1.0, v102
; __device__ __forceinline__ unsigned cvt_pk_bf16(float lo, float hi) { unsigned r; asm volatile("v_cvt_pk_bf16_f32 %0, %1, %2" : "=v"(r) : "v"(lo), "v"(hi)); return r; }
; #define GAS __attribute__((address_space(1)))
; __device__ __forceinline__ float silu_mul(float g, float u) { const float e = __builtin_amdgcn_exp2f(-1.4426950408889634f * g); return g * __builtin_amdgcn_rcpf(1.0f + e) * u; }
;     __device__ __forceinline__ void operator()(const f32x4 (&acc)[2][2][4][2], const Unit& u, int wr, int wc, int fr, int fq, const float (&pre)[8]) const {
;         const int row0 = u.pm * 256 + wr * 64 + fr, col0 = u.pn * 128 + wc * 32 + 8 * fq;
; #pragma unroll
;         for (int ai = 0; ai < 2; ++ai)
; #pragma unroll
;             for (int m = 0; m < 4; ++m) {
;                 const float rsc = pre[ai * 4 + m];
;                 const f32x4 g0 = acc[ai][0][m][0] * rsc, g1 = acc[ai][0][m][1] * rsc, u0 = acc[ai][1][m][0] * rsc, u1 = acc[ai][1][m][1] * rsc;
;                 u32x4 w; w.x = cvt_pk_bf16(silu_mul(g0[0], u0[0]), silu_mul(g0[1], u0[1])); w.y = cvt_pk_bf16(silu_mul(g0[2], u0[2]), silu_mul(g0[3], u0[3]));
;                 w.z = cvt_pk_bf16(silu_mul(g1[0], u1[0]), silu_mul(g1[1], u1[1])); w.w = cvt_pk_bf16(silu_mul(g1[2], u1[2]), silu_mul(g1[3], u1[3]));
;                 *(GAS u32x4*)(O + (size_t)(row0 + ai * 128 + m * 16) * DFF + col0) = w; }
	v_rcp_f32_e32 v102, v102
	s_nop 0
	v_mul_f32_e32 v102, v106, v102
	v_mul_f32_e32 v100, v102, v100
	v_mul_f32_e32 v102, 0xbfb8aa3b, v107
	v_exp_f32_e32 v102, v102
	s_nop 0
	v_add_f32_e32 v102, 1.0, v102
	v_rcp_f32_e32 v102, v102
	s_nop 0
	v_mul_f32_e32 v102, v107, v102
	v_mul_f32_e32 v101, v102, v101
	v_cvt_pk_bf16_f32 v100, v100, v101
	v_mul_f32_e32 v101, 0xbfb8aa3b, v108
	v_mul_f32_e32 v102, 0xbfb8aa3b, v109
	v_exp_f32_e32 v101, v101
	v_exp_f32_e32 v102, v102
	v_add_f32_e32 v101, 1.0, v101
	v_add_f32_e32 v102, 1.0, v102
	v_rcp_f32_e32 v101, v101
	v_rcp_f32_e32 v102, v102
	v_mul_f32_e32 v101, v108, v101
	v_mul_f32_e32 v102, v109, v102
	v_mul_f32_e32 v101, v101, v118
	v_mul_f32_e32 v102, v102, v119
	v_cvt_pk_bf16_f32 v101, v101, v102
	v_or_b32_e32 v102, 16, v151
	v_mad_i64_i32 v[102:103], s[44:45], v102, s29, v[114:115]
	v_lshl_add_u64 v[102:103], v[102:103], 0, v[116:117]
	global_store_dwordx4 v[102:103], v[98:101], off
	s_nop 1
	v_mul_f32 v98, v154, v84
	v_mul_f32 v99, v154, v85
	v_mul_f32 v84, v154, v82
	v_mul_f32 v85, v154, v83
	v_mul_f32_e32 v82, 0xbfb8aa3b, v94
	v_mul_f32_e32 v83, 0xbfb8aa3b, v95
	v_exp_f32_e32 v82, v82
	v_exp_f32_e32 v83, v83
	v_add_f32_e32 v82, 1.0, v82
	v_add_f32_e32 v83, 1.0, v83
	v_rcp_f32_e32 v82, v82
	v_rcp_f32_e32 v83, v83
	v_mul_f32_e32 v82, v94, v82
	v_mul_f32_e32 v83, v95, v83
	v_mul_f32_e32 v82, v82, v86
	v_mul_f32_e32 v83, v83, v87
	v_cvt_pk_bf16_f32 v82, v82, v83
	v_mul_f32_e32 v83, 0xbfb8aa3b, v96
	v_mul_f32_e32 v86, 0xbfb8aa3b, v97
	v_exp_f32_e32 v83, v83
	v_exp_f32_e32 v86, v86
	v_add_f32_e32 v83, 1.0, v83
	v_add_f32_e32 v86, 1.0, v86
	v_rcp_f32_e32 v83, v83
	v_rcp_f32_e32 v86, v86
	v_mul_f32_e32 v83, v96, v83
	v_mul_f32_e32 v86, v97, v86
	v_mul_f32_e32 v83, v83, v88
	v_mul_f32_e32 v86, v86, v89
	v_cvt_pk_bf16_f32 v83, v83, v86
	v_mul_f32_e32 v86, 0xbfb8aa3b, v90
	v_exp_f32_e32 v86, v86
	s_nop 0
	v_add_f32_e32 v86, 1.0, v86
	v_rcp_f32_e32 v86, v86
	s_nop 0
	v_mul_f32_e32 v86, v90, v86
	v_mul_f32_e32 v84, v86, v84
	v_mul_f32_e32 v86, 0xbfb8aa3b, v91
	v_exp_f32_e32 v86, v86
	s_nop 0
	v_add_f32_e32 v86, 1.0, v86
	v_rcp_f32_e32 v86, v86
	s_nop 0
	v_mul_f32_e32 v86, v91, v86
	v_mul_f32_e32 v85, v86, v85
	v_cvt_pk_bf16_f32 v84, v84, v85
	v_mul_f32_e32 v85, 0xbfb8aa3b, v92
	v_mul_f32_e32 v86, 0xbfb8aa3b, v93
	v_exp_f32_e32 v85, v85
	v_exp_f32_e32 v86, v86
	v_add_f32_e32 v85, 1.0, v85
	v_add_f32_e32 v86, 1.0, v86
	v_rcp_f32_e32 v85, v85
	v_rcp_f32_e32 v86, v86
	v_mul_f32_e32 v85, v92, v85
	v_mul_f32_e32 v86, v93, v86
	v_mul_f32_e32 v85, v85, v98
	v_mul_f32_e32 v86, v86, v99
	v_cvt_pk_bf16_f32 v85, v85, v86
	v_or_b32_e32 v86, 32, v151
	v_mad_i64_i32 v[86:87], s[44:45], v86, s29, v[114:115]
	v_lshl_add_u64 v[86:87], v[86:87], 0, v[116:117]
	global_store_dwordx4 v[86:87], v[82:85], off
	s_nop 1
	v_mul_f32 v82, v152, v68
	v_mul_f32 v83, v152, v69
	v_mul_f32 v68, v152, v66
	v_mul_f32 v69, v152, v67
	v_mul_f32_e32 v66, 0xbfb8aa3b, v78
	v_mul_f32_e32 v67, 0xbfb8aa3b, v79
	v_exp_f32_e32 v66, v66
	v_exp_f32_e32 v67, v67
	v_add_f32_e32 v66, 1.0, v66
	v_add_f32_e32 v67, 1.0, v67
	v_rcp_f32_e32 v66, v66
	v_rcp_f32_e32 v67, v67
	v_mul_f32_e32 v66, v78, v66
	v_mul_f32_e32 v67, v79, v67
	v_mul_f32_e32 v66, v66, v70
	v_mul_f32_e32 v67, v67, v71
	v_cvt_pk_bf16_f32 v66, v66, v67
	v_mul_f32_e32 v67, 0xbfb8aa3b, v80
	v_mul_f32_e32 v70, 0xbfb8aa3b, v81
	v_exp_f32_e32 v67, v67
	v_exp_f32_e32 v70, v70
	v_add_f32_e32 v67, 1.0, v67
	v_add_f32_e32 v70, 1.0, v70
	v_rcp_f32_e32 v67, v67
	v_rcp_f32_e32 v70, v70
	v_mul_f32_e32 v67, v80, v67
	v_mul_f32_e32 v70, v81, v70
	v_mul_f32_e32 v67, v67, v72
	v_mul_f32_e32 v70, v70, v73
	v_cvt_pk_bf16_f32 v67, v67, v70
	v_mul_f32_e32 v70, 0xbfb8aa3b, v74
	v_exp_f32_e32 v70, v70
	s_nop 0
	v_add_f32_e32 v70, 1.0, v70
	v_rcp_f32_e32 v70, v70
	s_nop 0
	v_mul_f32_e32 v70, v74, v70
	v_mul_f32_e32 v68, v70, v68
	v_mul_f32_e32 v70, 0xbfb8aa3b, v75
	v_exp_f32_e32 v70, v70
	s_nop 0
	v_add_f32_e32 v70, 1.0, v70
	v_rcp_f32_e32 v70, v70
	s_nop 0
	v_mul_f32_e32 v70, v75, v70
	v_mul_f32_e32 v69, v70, v69
	v_cvt_pk_bf16_f32 v68, v68, v69
	v_mul_f32_e32 v69, 0xbfb8aa3b, v76
	v_mul_f32_e32 v70, 0xbfb8aa3b, v77
	v_exp_f32_e32 v69, v69
	v_exp_f32_e32 v70, v70
	v_add_f32_e32 v69, 1.0, v69
	v_add_f32_e32 v70, 1.0, v70
	v_rcp_f32_e32 v69, v69
	v_rcp_f32_e32 v70, v70
	v_mul_f32_e32 v69, v76, v69
	v_mul_f32_e32 v70, v77, v70
	v_mul_f32_e32 v69, v69, v82
	v_mul_f32_e32 v70, v70, v83
	v_cvt_pk_bf16_f32 v69, v69, v70
	v_or_b32_e32 v70, 48, v151
	v_mad_i64_i32 v[70:71], s[44:45], v70, s29, v[114:115]
	v_lshl_add_u64 v[70:71], v[70:71], 0, v[116:117]
	global_store_dwordx4 v[70:71], v[66:69], off
	s_nop 1
	v_mul_f32 v66, v150, v52
	v_mul_f32 v67, v150, v53
	v_mul_f32 v52, v150, v50
	v_mul_f32 v53, v150, v51
	v_mul_f32_e32 v50, 0xbfb8aa3b, v62
	v_mul_f32_e32 v51, 0xbfb8aa3b, v63
	v_exp_f32_e32 v50, v50
	v_exp_f32_e32 v51, v51
	v_add_u32_e32 v68, 0x80, v151
	v_add_f32_e32 v50, 1.0, v50
	v_add_f32_e32 v51, 1.0, v51
	v_rcp_f32_e32 v50, v50
	v_rcp_f32_e32 v51, v51
	v_mul_f32_e32 v50, v62, v50
	v_mul_f32_e32 v51, v63, v51
	v_mul_f32_e32 v50, v50, v54
	v_mul_f32_e32 v51, v51, v55
	v_cvt_pk_bf16_f32 v50, v50, v51
	v_mul_f32_e32 v51, 0xbfb8aa3b, v64
	v_mul_f32_e32 v54, 0xbfb8aa3b, v65
	v_exp_f32_e32 v51, v51
	v_exp_f32_e32 v54, v54
	v_add_f32_e32 v51, 1.0, v51
	v_add_f32_e32 v54, 1.0, v54
	v_rcp_f32_e32 v51, v51
	v_rcp_f32_e32 v54, v54
	v_mul_f32_e32 v51, v64, v51
	v_mul_f32_e32 v54, v65, v54
	v_mul_f32_e32 v51, v51, v56
	v_mul_f32_e32 v54, v54, v57
	v_cvt_pk_bf16_f32 v51, v51, v54
	v_mul_f32_e32 v54, 0xbfb8aa3b, v58
	v_exp_f32_e32 v54, v54
	s_nop 0
	v_add_f32_e32 v54, 1.0, v54
	v_rcp_f32_e32 v54, v54
	s_nop 0
	v_mul_f32_e32 v54, v58, v54
; __device__ __forceinline__ unsigned cvt_pk_bf16(float lo, float hi) { unsigned r; asm volatile("v_cvt_pk_bf16_f32 %0, %1, %2" : "=v"(r) : "v"(lo), "v"(hi)); return r; }
; #define GAS __attribute__((address_space(1)))
; __device__ __forceinline__ float silu_mul(float g, float u) { const float e = __builtin_amdgcn_exp2f(-1.4426950408889634f * g); return g * __builtin_amdgcn_rcpf(1.0f + e) * u; }
;     __device__ __forceinline__ void prefetch(const Unit& u, int wr, int fr, float (&pre)[8]) const {
; #pragma unroll
;         for (int i = 0; i < 8; ++i) pre[i] = *(const GAS float*)(rs + u.pm * 256 + wr * 64 + fr + (i >> 2) * 128 + (i & 3) * 16);
;     __device__ __forceinline__ void operator()(const f32x4 (&acc)[2][2][4][2], const Unit& u, int wr, int wc, int fr, int fq, const float (&pre)[8]) const {
;         const int row0 = u.pm * 256 + wr * 64 + fr, col0 = u.pn * 128 + wc * 32 + 8 * fq;
; #pragma unroll
;         for (int ai = 0; ai < 2; ++ai)
; #pragma unroll
;             for (int m = 0; m < 4; ++m) {
;                 const float rsc = pre[ai * 4 + m];
;                 const f32x4 g0 = acc[ai][0][m][0] * rsc, g1 = acc[ai][0][m][1] * rsc, u0 = acc[ai][1][m][0] * rsc, u1 = acc[ai][1][m][1] * rsc;
;                 u32x4 w; w.x = cvt_pk_bf16(silu_mul(g0[0], u0[0]), silu_mul(g0[1], u0[1])); w.y = cvt_pk_bf16(silu_mul(g0[2], u0[2]), silu_mul(g0[3], u0[3]));
;                 w.z = cvt_pk_bf16(silu_mul(g1[0], u1[0]), silu_mul(g1[1], u1[1])); w.w = cvt_pk_bf16(silu_mul(g1[2], u1[2]), silu_mul(g1[3], u1[3]));
;                 *(GAS u32x4*)(O + (size_t)(row0 + ai * 128 + m * 16) * DFF + col0) = w; }
	v_mul_f32_e32 v52, v54, v52
	v_mul_f32_e32 v54, 0xbfb8aa3b, v59
	v_exp_f32_e32 v54, v54
	s_nop 0
	v_add_f32_e32 v54, 1.0, v54
	v_rcp_f32_e32 v54, v54
	s_nop 0
	v_mul_f32_e32 v54, v59, v54
	v_mul_f32_e32 v53, v54, v53
	v_cvt_pk_bf16_f32 v52, v52, v53
	v_mul_f32_e32 v53, 0xbfb8aa3b, v60
	v_mul_f32_e32 v54, 0xbfb8aa3b, v61
	v_exp_f32_e32 v53, v53
	v_exp_f32_e32 v54, v54
	v_add_f32_e32 v53, 1.0, v53
	v_add_f32_e32 v54, 1.0, v54
	v_rcp_f32_e32 v53, v53
	v_rcp_f32_e32 v54, v54
	v_mul_f32_e32 v53, v60, v53
	v_mul_f32_e32 v54, v61, v54
	v_mul_f32_e32 v53, v53, v66
	v_mul_f32_e32 v54, v54, v67
	v_cvt_pk_bf16_f32 v53, v53, v54
	v_mad_i64_i32 v[54:55], s[44:45], v68, s29, v[114:115]
	v_lshl_add_u64 v[54:55], v[54:55], 0, v[116:117]
	global_store_dwordx4 v[54:55], v[50:53], off
	s_nop 1
	v_mul_f32 v50, v148, v36
	v_mul_f32 v51, v148, v37
	v_mul_f32 v36, v148, v34
	v_mul_f32 v37, v148, v35
	v_mul_f32_e32 v34, 0xbfb8aa3b, v46
	v_mul_f32_e32 v35, 0xbfb8aa3b, v47
	v_exp_f32_e32 v34, v34
	v_exp_f32_e32 v35, v35
	v_add_f32_e32 v34, 1.0, v34
	v_add_f32_e32 v35, 1.0, v35
	v_rcp_f32_e32 v34, v34
	v_rcp_f32_e32 v35, v35
	v_mul_f32_e32 v34, v46, v34
	v_mul_f32_e32 v35, v47, v35
	v_mul_f32_e32 v34, v34, v38
	v_mul_f32_e32 v35, v35, v39
	v_cvt_pk_bf16_f32 v34, v34, v35
	v_mul_f32_e32 v35, 0xbfb8aa3b, v48
	v_mul_f32_e32 v38, 0xbfb8aa3b, v49
	v_exp_f32_e32 v35, v35
	v_exp_f32_e32 v38, v38
	v_add_f32_e32 v35, 1.0, v35
	v_add_f32_e32 v38, 1.0, v38
	v_rcp_f32_e32 v35, v35
	v_rcp_f32_e32 v38, v38
	v_mul_f32_e32 v35, v48, v35
	v_mul_f32_e32 v38, v49, v38
	v_mul_f32_e32 v35, v35, v40
	v_mul_f32_e32 v38, v38, v41
	v_cvt_pk_bf16_f32 v35, v35, v38
	v_mul_f32_e32 v38, 0xbfb8aa3b, v42
	v_exp_f32_e32 v38, v38
	s_nop 0
	v_add_f32_e32 v38, 1.0, v38
	v_rcp_f32_e32 v38, v38
	s_nop 0
	v_mul_f32_e32 v38, v42, v38
	v_mul_f32_e32 v36, v38, v36
	v_mul_f32_e32 v38, 0xbfb8aa3b, v43
	v_exp_f32_e32 v38, v38
	s_nop 0
	v_add_f32_e32 v38, 1.0, v38
	v_rcp_f32_e32 v38, v38
	s_nop 0
	v_mul_f32_e32 v38, v43, v38
	v_mul_f32_e32 v37, v38, v37
	v_cvt_pk_bf16_f32 v36, v36, v37
	v_mul_f32_e32 v37, 0xbfb8aa3b, v44
	v_mul_f32_e32 v38, 0xbfb8aa3b, v45
	v_exp_f32_e32 v37, v37
	v_exp_f32_e32 v38, v38
	v_add_f32_e32 v37, 1.0, v37
	v_add_f32_e32 v38, 1.0, v38
	v_rcp_f32_e32 v37, v37
	v_rcp_f32_e32 v38, v38
	v_mul_f32_e32 v37, v44, v37
	v_mul_f32_e32 v38, v45, v38
	v_mul_f32_e32 v37, v37, v50
	v_mul_f32_e32 v38, v38, v51
	v_cvt_pk_bf16_f32 v37, v37, v38
	v_add_u32_e32 v38, 0x90, v151
	v_mad_i64_i32 v[38:39], s[44:45], v38, s29, v[114:115]
	v_lshl_add_u64 v[38:39], v[38:39], 0, v[116:117]
	global_store_dwordx4 v[38:39], v[34:37], off
	s_nop 1
	v_mul_f32 v34, v146, v18
	v_mul_f32 v35, v146, v19
	v_mul_f32 v18, v146, v16
	v_mul_f32 v19, v146, v17
	v_mul_f32_e32 v16, 0xbfb8aa3b, v28
	v_mul_f32_e32 v17, 0xbfb8aa3b, v29
	v_exp_f32_e32 v16, v16
	v_exp_f32_e32 v17, v17
	v_add_f32_e32 v16, 1.0, v16
	v_add_f32_e32 v17, 1.0, v17
	v_rcp_f32_e32 v16, v16
	v_rcp_f32_e32 v17, v17
	v_mul_f32_e32 v16, v28, v16
	v_mul_f32_e32 v17, v29, v17
	v_mul_f32_e32 v16, v16, v20
	v_mul_f32_e32 v17, v17, v21
	v_cvt_pk_bf16_f32 v16, v16, v17
	v_mul_f32_e32 v17, 0xbfb8aa3b, v30
	v_mul_f32_e32 v20, 0xbfb8aa3b, v31
	v_exp_f32_e32 v17, v17
	v_exp_f32_e32 v20, v20
	v_add_f32_e32 v17, 1.0, v17
	v_add_f32_e32 v20, 1.0, v20
	v_rcp_f32_e32 v17, v17
	v_rcp_f32_e32 v20, v20
	v_mul_f32_e32 v17, v30, v17
	v_mul_f32_e32 v20, v31, v20
	v_mul_f32_e32 v17, v17, v22
	v_mul_f32_e32 v20, v20, v23
	v_cvt_pk_bf16_f32 v17, v17, v20
	v_mul_f32_e32 v20, 0xbfb8aa3b, v24
	v_exp_f32_e32 v20, v20
	s_nop 0
	v_add_f32_e32 v20, 1.0, v20
	v_rcp_f32_e32 v20, v20
	s_nop 0
	v_mul_f32_e32 v20, v24, v20
	v_mul_f32_e32 v18, v20, v18
	v_mul_f32_e32 v20, 0xbfb8aa3b, v25
	v_exp_f32_e32 v20, v20
	s_nop 0
	v_add_f32_e32 v20, 1.0, v20
	v_rcp_f32_e32 v20, v20
	s_nop 0
	v_mul_f32_e32 v20, v25, v20
	v_mul_f32_e32 v19, v20, v19
	v_cvt_pk_bf16_f32 v18, v18, v19
	v_mul_f32_e32 v19, 0xbfb8aa3b, v26
	v_mul_f32_e32 v20, 0xbfb8aa3b, v27
	v_exp_f32_e32 v19, v19
	v_exp_f32_e32 v20, v20
	v_add_f32_e32 v19, 1.0, v19
	v_add_f32_e32 v20, 1.0, v20
	v_rcp_f32_e32 v19, v19
	v_rcp_f32_e32 v20, v20
	v_mul_f32_e32 v19, v26, v19
	v_mul_f32_e32 v20, v27, v20
	v_mul_f32_e32 v19, v19, v34
	v_mul_f32_e32 v20, v20, v35
	v_cvt_pk_bf16_f32 v19, v19, v20
	v_add_u32_e32 v20, 0xa0, v151
	v_mad_i64_i32 v[20:21], s[44:45], v20, s29, v[114:115]
	v_lshl_add_u64 v[20:21], v[20:21], 0, v[116:117]
	global_store_dwordx4 v[20:21], v[16:19], off
	s_nop 1
	v_mul_f32 v16, v144, v2
	v_mul_f32 v17, v144, v3
	v_mul_f32 v2, v144, v0
	v_mul_f32 v3, v144, v1
	v_mul_f32_e32 v0, 0xbfb8aa3b, v12
	v_mul_f32_e32 v1, 0xbfb8aa3b, v13
	v_exp_f32_e32 v0, v0
	v_exp_f32_e32 v1, v1
	v_add_f32_e32 v0, 1.0, v0
	v_add_f32_e32 v1, 1.0, v1
	v_rcp_f32_e32 v0, v0
	v_rcp_f32_e32 v1, v1
	v_mul_f32_e32 v0, v12, v0
	v_mul_f32_e32 v1, v13, v1
	v_mul_f32_e32 v0, v0, v4
	v_mul_f32_e32 v1, v1, v5
	v_cvt_pk_bf16_f32 v0, v0, v1
	v_mul_f32_e32 v1, 0xbfb8aa3b, v14
	v_mul_f32_e32 v4, 0xbfb8aa3b, v15
	v_exp_f32_e32 v1, v1
	v_exp_f32_e32 v4, v4
	v_add_f32_e32 v1, 1.0, v1
	v_add_f32_e32 v4, 1.0, v4
	v_rcp_f32_e32 v1, v1
	v_rcp_f32_e32 v4, v4
	v_mul_f32_e32 v1, v14, v1
	v_mul_f32_e32 v4, v15, v4
	v_mul_f32_e32 v1, v1, v6
	v_mul_f32_e32 v4, v4, v7
	v_cvt_pk_bf16_f32 v1, v1, v4
	v_mul_f32_e32 v4, 0xbfb8aa3b, v8
	v_exp_f32_e32 v4, v4
	s_nop 0
	v_add_f32_e32 v4, 1.0, v4
	v_rcp_f32_e32 v4, v4
	s_nop 0
	v_mul_f32_e32 v4, v8, v4
	v_mul_f32_e32 v2, v4, v2
	v_mul_f32_e32 v4, 0xbfb8aa3b, v9
	v_exp_f32_e32 v4, v4
	s_nop 0
	v_add_f32_e32 v4, 1.0, v4
	v_rcp_f32_e32 v4, v4
	s_nop 0
	v_mul_f32_e32 v4, v9, v4
	v_mul_f32_e32 v3, v4, v3
	v_cvt_pk_bf16_f32 v2, v2, v3
	v_mul_f32_e32 v3, 0xbfb8aa3b, v10
	v_mul_f32_e32 v4, 0xbfb8aa3b, v11
	v_exp_f32_e32 v3, v3
	v_exp_f32_e32 v4, v4
	v_add_f32_e32 v3, 1.0, v3
	v_add_f32_e32 v4, 1.0, v4
	v_rcp_f32_e32 v3, v3
	v_rcp_f32_e32 v4, v4
	v_mul_f32_e32 v3, v10, v3
	v_mul_f32_e32 v4, v11, v4
	v_mul_f32_e32 v3, v3, v16
	v_mul_f32_e32 v4, v4, v17
	v_cvt_pk_bf16_f32 v3, v3, v4
	v_add_u32_e32 v4, 0xb0, v151
	v_mad_i64_i32 v[4:5], s[44:45], v4, s29, v[114:115]
	v_lshl_add_u64 v[4:5], v[4:5], 0, v[116:117]
	s_mov_b64 s[44:45], -1
	global_store_dwordx4 v[4:5], v[0:3], off
	s_cbranch_vccnz .LBB0_575
	s_lshl_b32 s42, s8, 8
	s_ashr_i32 s43, s42, 31
	v_lshl_add_u64 v[0:1], s[42:43], 2, v[138:139]
	global_load_dword v158, v[0:1], off
	global_load_dword v156, v[0:1], off offset:64
	global_load_dword v154, v[0:1], off offset:128
	global_load_dword v152, v[0:1], off offset:192
	global_load_dword v150, v[0:1], off offset:512
	global_load_dword v148, v[0:1], off offset:576
	global_load_dword v146, v[0:1], off offset:640
	global_load_dword v144, v[0:1], off offset:704
	s_andn2_b64 vcc, exec, s[2:3]
	s_cbranch_vccnz .LBB0_574
	s_barrier
	s_branch .LBB0_574
